# 8-phase GEMM K-loops: removed the mid-segment setprio 0/1 pair and the repeated lgkmcnt(0) behind the barrier (on top of the scan, adaLN and attention edits)
# speedup vs baseline: 1.0082x; 1.0027x over previous
; #define PG8_STAGE(bufoff, gbase, voff) do { _Pragma("unroll") for (int _i = 0; _i < 2; ++_i) \
;         __builtin_amdgcn_global_load_lds((const unsigned*)((const char*)(gbase) + (voff)[_i]), (LAS unsigned*)(lds + (bufoff) + ldsw + _i * 8192), 16, 0, 0); } while (0)
; #define PG8_LDA(dst, b, h) do { _Pragma("unroll") for (int m = 0; m < 4; ++m) _Pragma("unroll") for (int k = 0; k < 2; ++k) dst[m][k] = *(const LAS bf16x8*)(lds + PG8_SA(b, h) + aoff + m * 2048 + k * 1024); } while (0)
; #define PG8_LDB(dst, b, h) do { _Pragma("unroll") for (int n = 0; n < 2; ++n) _Pragma("unroll") for (int k = 0; k < 2; ++k) dst[n][k] = *(const LAS bf16x8*)(lds + PG8_SB(b, h) + boff + n * 2048 + k * 1024); } while (0)
; #define PG8_MMA(ai, bj, At, Bt) do { __builtin_amdgcn_s_setprio(1); _Pragma("unroll") for (int m = 0; m < 4; ++m) _Pragma("unroll") for (int n = 0; n < 2; ++n) _Pragma("unroll") for (int k = 0; k < 2; ++k) \
;         acc[ai][bj][m][n] = __builtin_amdgcn_mfma_f32_16x16x32_bf16(Bt[n][k], At[m][k], acc[ai][bj][m][n], 0, 0, 0); __builtin_amdgcn_s_setprio(0); } while (0)
; #define PG8_WAIT_V(n) asm volatile("s_waitcnt vmcnt(" #n ")" ::: "memory")
; #define PG8_WAIT_L(n) asm volatile("s_waitcnt lgkmcnt(" #n ")" ::: "memory")
; #define PG8_BAR __builtin_amdgcn_s_barrier()
; #define PG8_SCHED __builtin_amdgcn_sched_barrier(0)
; template <class Desc, class Epi>
; DI void gemm_phase(LAS unsigned char* lds, const Desc& D, const Epi& E, int wv) {
;     ...
;             PG8_LDB(B0, 0, 0); PG8_LDB(B1, 0, 1); PG8_SCHED; PG8_LDA(At, 0, 0); PG8_STAGE(PG8_SA(1, 1), a1 + hstepA, voffA);
;             PG8_WAIT_V(8); PG8_WAIT_L(0); PG8_BAR; PG8_MMA(0, 0, At, B0); PG8_MMA(0, 1, At, B1); PG8_BAR; PG8_SCHED;
;             PG8_LDA(At, 0, 1); PG8_STAGE(PG8_SB(0, 0), b2, voffB); PG8_STAGE(PG8_SB(0, 1), b2 + hstepB, voffB); PG8_STAGE(PG8_SA(0, 0), a2, voffA);
;             PG8_WAIT_V(8); PG8_WAIT_L(0); PG8_BAR; PG8_MMA(1, 0, At, B0); PG8_MMA(1, 1, At, B1); PG8_BAR; PG8_SCHED;
.LBB0_292:
	ds_read_b128 v[152:155], v149
	ds_read_b128 v[156:159], v149 offset:1024
	ds_read_b128 v[160:163], v149 offset:2048
	ds_read_b128 v[164:167], v149 offset:3072
	ds_read_b128 v[168:171], v150
	ds_read_b128 v[172:175], v150 offset:1024
	ds_read_b128 v[176:179], v150 offset:2048
	ds_read_b128 v[180:183], v150 offset:3072
	s_add_u32 s66, s64, 0xfff80080
	s_addc_u32 s67, s65, -1
	s_cmp_eq_u32 s63, 28
	s_cselect_b32 s69, s39, s67
	s_cselect_b32 s68, s38, s66
	s_cselect_b32 s67, s47, s61
	s_cselect_b32 s66, s46, s53
	v_lshl_add_u64 v[146:147], s[64:65], 0, v[138:139]
	s_add_i32 m0, s31, 0xc000
	ds_read_b128 v[184:187], v151
	ds_read_b128 v[188:191], v151 offset:1024
	ds_read_b128 v[192:195], v151 offset:2048
	ds_read_b128 v[196:199], v151 offset:3072
	ds_read_b128 v[200:203], v151 offset:4096
	ds_read_b128 v[204:207], v151 offset:5120
	ds_read_b128 v[208:211], v151 offset:6144
	ds_read_b128 v[212:215], v151 offset:7168
	global_load_lds_dwordx4 v[146:147], off
	v_lshl_add_u64 v[146:147], s[64:65], 0, v[140:141]
	s_add_i32 m0, s31, 0xe000
	s_nop 0
	global_load_lds_dwordx4 v[146:147], off
	s_waitcnt vmcnt(8)
	s_waitcnt lgkmcnt(0)
	s_barrier
	s_setprio 1
	v_mfma_f32_16x16x32_bf16 v[124:127], v[152:155], v[184:187], v[124:127]
	v_mfma_f32_16x16x32_bf16 v[120:123], v[160:163], v[184:187], v[120:123]
	v_mfma_f32_16x16x32_bf16 v[108:111], v[152:155], v[192:195], v[108:111]
	v_mfma_f32_16x16x32_bf16 v[104:107], v[160:163], v[192:195], v[104:107]
	v_mfma_f32_16x16x32_bf16 v[92:95], v[152:155], v[200:203], v[92:95]
	v_mfma_f32_16x16x32_bf16 v[88:91], v[160:163], v[200:203], v[88:91]
	v_mfma_f32_16x16x32_bf16 v[76:79], v[152:155], v[208:211], v[76:79]
	v_mfma_f32_16x16x32_bf16 v[72:75], v[160:163], v[208:211], v[72:75]
	v_mfma_f32_16x16x32_bf16 v[124:127], v[156:159], v[188:191], v[124:127]
	v_mfma_f32_16x16x32_bf16 v[120:123], v[164:167], v[188:191], v[120:123]
	v_mfma_f32_16x16x32_bf16 v[108:111], v[156:159], v[196:199], v[108:111]
	v_mfma_f32_16x16x32_bf16 v[104:107], v[164:167], v[196:199], v[104:107]
	v_mfma_f32_16x16x32_bf16 v[92:95], v[156:159], v[204:207], v[92:95]
	v_mfma_f32_16x16x32_bf16 v[88:91], v[164:167], v[204:207], v[88:91]
	v_mfma_f32_16x16x32_bf16 v[76:79], v[156:159], v[212:215], v[76:79]
	v_mfma_f32_16x16x32_bf16 v[72:75], v[164:167], v[212:215], v[72:75]
	v_mfma_f32_16x16x32_bf16 v[116:119], v[168:171], v[184:187], v[116:119]
	v_mfma_f32_16x16x32_bf16 v[112:115], v[176:179], v[184:187], v[112:115]
	v_mfma_f32_16x16x32_bf16 v[100:103], v[168:171], v[192:195], v[100:103]
	v_mfma_f32_16x16x32_bf16 v[96:99], v[176:179], v[192:195], v[96:99]
	v_mfma_f32_16x16x32_bf16 v[84:87], v[168:171], v[200:203], v[84:87]
	v_mfma_f32_16x16x32_bf16 v[80:83], v[176:179], v[200:203], v[80:83]
	v_mfma_f32_16x16x32_bf16 v[68:71], v[168:171], v[208:211], v[68:71]
	v_mfma_f32_16x16x32_bf16 v[64:67], v[176:179], v[208:211], v[64:67]
	v_mfma_f32_16x16x32_bf16 v[116:119], v[172:175], v[188:191], v[116:119]
	v_mfma_f32_16x16x32_bf16 v[112:115], v[180:183], v[188:191], v[112:115]
	v_mfma_f32_16x16x32_bf16 v[100:103], v[172:175], v[196:199], v[100:103]
	v_mfma_f32_16x16x32_bf16 v[96:99], v[180:183], v[196:199], v[96:99]
	v_mfma_f32_16x16x32_bf16 v[84:87], v[172:175], v[204:207], v[84:87]
	v_mfma_f32_16x16x32_bf16 v[80:83], v[180:183], v[204:207], v[80:83]
	v_mfma_f32_16x16x32_bf16 v[68:71], v[172:175], v[212:215], v[68:71]
	v_mfma_f32_16x16x32_bf16 v[64:67], v[180:183], v[212:215], v[64:67]
	s_setprio 0
	s_barrier
	s_add_i32 s76, s51, s28
	v_lshl_add_u64 v[146:147], s[66:67], 0, v[132:133]
	s_mov_b32 m0, s76
	ds_read_b128 v[184:187], v151 offset:16384
	ds_read_b128 v[188:191], v151 offset:17408
	ds_read_b128 v[192:195], v151 offset:18432
	ds_read_b128 v[196:199], v151 offset:19456
	ds_read_b128 v[200:203], v151 offset:20480
	ds_read_b128 v[204:207], v151 offset:21504
	ds_read_b128 v[208:211], v151 offset:22528
	ds_read_b128 v[212:215], v151 offset:23552
	global_load_lds_dwordx4 v[146:147], off
	s_add_i32 m0, s76, 0x2000
	s_add_u32 s76, s66, 0x80000
	v_lshl_add_u64 v[216:217], s[66:67], 0, v[128:129]
	s_addc_u32 s77, s67, 0
	s_add_i32 s78, s70, s28
	global_load_lds_dwordx4 v[216:217], off
	v_lshl_add_u64 v[218:219], s[76:77], 0, v[132:133]
	s_mov_b32 m0, s78
	v_lshl_add_u64 v[220:221], s[68:69], 0, v[130:131]
	global_load_lds_dwordx4 v[218:219], off
	v_lshl_add_u64 v[218:219], s[76:77], 0, v[128:129]
	s_add_i32 m0, s78, 0x2000
	s_nop 0
	global_load_lds_dwordx4 v[218:219], off
	v_lshl_add_u64 v[218:219], s[68:69], 0, v[134:135]
	s_mov_b32 m0, s31
	s_nop 0
	global_load_lds_dwordx4 v[218:219], off
	s_mov_b32 m0, s34
	s_nop 0
	global_load_lds_dwordx4 v[220:221], off
	s_waitcnt vmcnt(8)
	s_waitcnt lgkmcnt(0)
	s_barrier
; #define PG8_STAGE(bufoff, gbase, voff) do { _Pragma("unroll") for (int _i = 0; _i < 2; ++_i) \
;         __builtin_amdgcn_global_load_lds((const unsigned*)((const char*)(gbase) + (voff)[_i]), (LAS unsigned*)(lds + (bufoff) + ldsw + _i * 8192), 16, 0, 0); } while (0)
; #define PG8_LDA(dst, b, h) do { _Pragma("unroll") for (int m = 0; m < 4; ++m) _Pragma("unroll") for (int k = 0; k < 2; ++k) dst[m][k] = *(const LAS bf16x8*)(lds + PG8_SA(b, h) + aoff + m * 2048 + k * 1024); } while (0)
; #define PG8_LDB(dst, b, h) do { _Pragma("unroll") for (int n = 0; n < 2; ++n) _Pragma("unroll") for (int k = 0; k < 2; ++k) dst[n][k] = *(const LAS bf16x8*)(lds + PG8_SB(b, h) + boff + n * 2048 + k * 1024); } while (0)
; #define PG8_MMA(ai, bj, At, Bt) do { __builtin_amdgcn_s_setprio(1); _Pragma("unroll") for (int m = 0; m < 4; ++m) _Pragma("unroll") for (int n = 0; n < 2; ++n) _Pragma("unroll") for (int k = 0; k < 2; ++k) \
;         acc[ai][bj][m][n] = __builtin_amdgcn_mfma_f32_16x16x32_bf16(Bt[n][k], At[m][k], acc[ai][bj][m][n], 0, 0, 0); __builtin_amdgcn_s_setprio(0); } while (0)
; #define PG8_WAIT_V(n) asm volatile("s_waitcnt vmcnt(" #n ")" ::: "memory")
; #define PG8_WAIT_L(n) asm volatile("s_waitcnt lgkmcnt(" #n ")" ::: "memory")
; #define PG8_BAR __builtin_amdgcn_s_barrier()
; #define PG8_SCHED __builtin_amdgcn_sched_barrier(0)
; template <class Desc, class Epi>
; DI void gemm_phase(LAS unsigned char* lds, const Desc& D, const Epi& E, int wv) {
;     ...
;             PG8_WAIT_V(8); PG8_WAIT_L(0); PG8_BAR; PG8_MMA(1, 0, At, B0); PG8_MMA(1, 1, At, B1); PG8_BAR; PG8_SCHED;
;             PG8_LDB(B0, 1, 0); PG8_LDB(B1, 1, 1); PG8_SCHED; PG8_LDA(At, 1, 0); PG8_STAGE(PG8_SA(0, 1), a2 + hstepA, voffA);
;             PG8_WAIT_V(8); PG8_WAIT_L(0); PG8_BAR; PG8_MMA(0, 0, At, B0); PG8_MMA(0, 1, At, B1); PG8_BAR; PG8_SCHED;
	s_setprio 1
	v_mfma_f32_16x16x32_bf16 v[60:63], v[152:155], v[184:187], v[60:63]
	v_mfma_f32_16x16x32_bf16 v[56:59], v[160:163], v[184:187], v[56:59]
	v_mfma_f32_16x16x32_bf16 v[44:47], v[152:155], v[192:195], v[44:47]
	v_mfma_f32_16x16x32_bf16 v[40:43], v[160:163], v[192:195], v[40:43]
	v_mfma_f32_16x16x32_bf16 v[28:31], v[152:155], v[200:203], v[28:31]
	v_mfma_f32_16x16x32_bf16 v[24:27], v[160:163], v[200:203], v[24:27]
	v_mfma_f32_16x16x32_bf16 v[12:15], v[152:155], v[208:211], v[12:15]
	v_mfma_f32_16x16x32_bf16 v[8:11], v[160:163], v[208:211], v[8:11]
	v_mfma_f32_16x16x32_bf16 v[60:63], v[156:159], v[188:191], v[60:63]
	v_mfma_f32_16x16x32_bf16 v[56:59], v[164:167], v[188:191], v[56:59]
	v_mfma_f32_16x16x32_bf16 v[44:47], v[156:159], v[196:199], v[44:47]
	v_mfma_f32_16x16x32_bf16 v[40:43], v[164:167], v[196:199], v[40:43]
	v_mfma_f32_16x16x32_bf16 v[28:31], v[156:159], v[204:207], v[28:31]
	v_mfma_f32_16x16x32_bf16 v[24:27], v[164:167], v[204:207], v[24:27]
	v_mfma_f32_16x16x32_bf16 v[12:15], v[156:159], v[212:215], v[12:15]
	v_mfma_f32_16x16x32_bf16 v[8:11], v[164:167], v[212:215], v[8:11]
	v_mfma_f32_16x16x32_bf16 v[52:55], v[168:171], v[184:187], v[52:55]
	v_mfma_f32_16x16x32_bf16 v[48:51], v[176:179], v[184:187], v[48:51]
	v_mfma_f32_16x16x32_bf16 v[36:39], v[168:171], v[192:195], v[36:39]
	v_mfma_f32_16x16x32_bf16 v[32:35], v[176:179], v[192:195], v[32:35]
	v_mfma_f32_16x16x32_bf16 v[20:23], v[168:171], v[200:203], v[20:23]
	v_mfma_f32_16x16x32_bf16 v[16:19], v[176:179], v[200:203], v[16:19]
	v_mfma_f32_16x16x32_bf16 v[4:7], v[168:171], v[208:211], v[4:7]
	v_mfma_f32_16x16x32_bf16 v[0:3], v[176:179], v[208:211], v[0:3]
	v_mfma_f32_16x16x32_bf16 v[52:55], v[172:175], v[188:191], v[52:55]
	v_mfma_f32_16x16x32_bf16 v[48:51], v[180:183], v[188:191], v[48:51]
	v_mfma_f32_16x16x32_bf16 v[36:39], v[172:175], v[196:199], v[36:39]
	v_mfma_f32_16x16x32_bf16 v[32:35], v[180:183], v[196:199], v[32:35]
	v_mfma_f32_16x16x32_bf16 v[20:23], v[172:175], v[204:207], v[20:23]
	v_mfma_f32_16x16x32_bf16 v[16:19], v[180:183], v[204:207], v[16:19]
	v_mfma_f32_16x16x32_bf16 v[4:7], v[172:175], v[212:215], v[4:7]
	v_mfma_f32_16x16x32_bf16 v[0:3], v[180:183], v[212:215], v[0:3]
	s_setprio 0
	s_barrier
	s_add_i32 s76, 0, 0x18000
	v_add_u32_e32 v136, s76, v148
	s_add_i32 s77, 0, 0x1c000
	ds_read_b128 v[152:155], v136
	ds_read_b128 v[156:159], v136 offset:1024
	ds_read_b128 v[160:163], v136 offset:2048
	ds_read_b128 v[164:167], v136 offset:3072
	v_add_u32_e32 v136, s77, v148
	ds_read_b128 v[168:171], v136
	ds_read_b128 v[172:175], v136 offset:1024
	ds_read_b128 v[176:179], v136 offset:2048
	ds_read_b128 v[180:183], v136 offset:3072
	s_add_u32 s68, s68, 0x80000
	s_addc_u32 s69, s69, 0
	s_mov_b32 m0, s35
	v_lshl_add_u64 v[222:223], s[68:69], 0, v[134:135]
	ds_read_b128 v[184:187], v151 offset:32768
	ds_read_b128 v[188:191], v151 offset:33792
	ds_read_b128 v[192:195], v151 offset:34816
	ds_read_b128 v[196:199], v151 offset:35840
	ds_read_b128 v[200:203], v151 offset:36864
	ds_read_b128 v[204:207], v151 offset:37888
	ds_read_b128 v[208:211], v151 offset:38912
	ds_read_b128 v[212:215], v151 offset:39936
	global_load_lds_dwordx4 v[222:223], off
	v_lshl_add_u64 v[222:223], s[68:69], 0, v[130:131]
	s_mov_b32 m0, s40
	s_nop 0
	global_load_lds_dwordx4 v[222:223], off
	s_waitcnt vmcnt(8)
	s_waitcnt lgkmcnt(0)
	s_barrier
	s_setprio 1
	v_mfma_f32_16x16x32_bf16 v[124:127], v[152:155], v[184:187], v[124:127]
	v_mfma_f32_16x16x32_bf16 v[120:123], v[160:163], v[184:187], v[120:123]
	v_mfma_f32_16x16x32_bf16 v[108:111], v[152:155], v[192:195], v[108:111]
	v_mfma_f32_16x16x32_bf16 v[104:107], v[160:163], v[192:195], v[104:107]
	v_mfma_f32_16x16x32_bf16 v[92:95], v[152:155], v[200:203], v[92:95]
	v_mfma_f32_16x16x32_bf16 v[88:91], v[160:163], v[200:203], v[88:91]
	v_mfma_f32_16x16x32_bf16 v[76:79], v[152:155], v[208:211], v[76:79]
	v_mfma_f32_16x16x32_bf16 v[72:75], v[160:163], v[208:211], v[72:75]
	v_mfma_f32_16x16x32_bf16 v[124:127], v[156:159], v[188:191], v[124:127]
	v_mfma_f32_16x16x32_bf16 v[120:123], v[164:167], v[188:191], v[120:123]
	v_mfma_f32_16x16x32_bf16 v[108:111], v[156:159], v[196:199], v[108:111]
	v_mfma_f32_16x16x32_bf16 v[104:107], v[164:167], v[196:199], v[104:107]
	v_mfma_f32_16x16x32_bf16 v[92:95], v[156:159], v[204:207], v[92:95]
	v_mfma_f32_16x16x32_bf16 v[88:91], v[164:167], v[204:207], v[88:91]
	v_mfma_f32_16x16x32_bf16 v[76:79], v[156:159], v[212:215], v[76:79]
	v_mfma_f32_16x16x32_bf16 v[72:75], v[164:167], v[212:215], v[72:75]
	v_mfma_f32_16x16x32_bf16 v[116:119], v[168:171], v[184:187], v[116:119]
	v_mfma_f32_16x16x32_bf16 v[112:115], v[176:179], v[184:187], v[112:115]
	v_mfma_f32_16x16x32_bf16 v[100:103], v[168:171], v[192:195], v[100:103]
	v_mfma_f32_16x16x32_bf16 v[96:99], v[176:179], v[192:195], v[96:99]
	v_mfma_f32_16x16x32_bf16 v[84:87], v[168:171], v[200:203], v[84:87]
	v_mfma_f32_16x16x32_bf16 v[80:83], v[176:179], v[200:203], v[80:83]
	v_mfma_f32_16x16x32_bf16 v[68:71], v[168:171], v[208:211], v[68:71]
	v_mfma_f32_16x16x32_bf16 v[64:67], v[176:179], v[208:211], v[64:67]
	v_mfma_f32_16x16x32_bf16 v[116:119], v[172:175], v[188:191], v[116:119]
	v_mfma_f32_16x16x32_bf16 v[112:115], v[180:183], v[188:191], v[112:115]
	v_mfma_f32_16x16x32_bf16 v[100:103], v[172:175], v[196:199], v[100:103]
	v_mfma_f32_16x16x32_bf16 v[96:99], v[180:183], v[196:199], v[96:99]
	v_mfma_f32_16x16x32_bf16 v[84:87], v[172:175], v[204:207], v[84:87]
	v_mfma_f32_16x16x32_bf16 v[80:83], v[180:183], v[204:207], v[80:83]
	v_mfma_f32_16x16x32_bf16 v[68:71], v[172:175], v[212:215], v[68:71]
	v_mfma_f32_16x16x32_bf16 v[64:67], v[180:183], v[212:215], v[64:67]
	s_setprio 0
	s_barrier
; #define PG8_STAGE(bufoff, gbase, voff) do { _Pragma("unroll") for (int _i = 0; _i < 2; ++_i) \
;         __builtin_amdgcn_global_load_lds((const unsigned*)((const char*)(gbase) + (voff)[_i]), (LAS unsigned*)(lds + (bufoff) + ldsw + _i * 8192), 16, 0, 0); } while (0)
; #define PG8_LDA(dst, b, h) do { _Pragma("unroll") for (int m = 0; m < 4; ++m) _Pragma("unroll") for (int k = 0; k < 2; ++k) dst[m][k] = *(const LAS bf16x8*)(lds + PG8_SA(b, h) + aoff + m * 2048 + k * 1024); } while (0)
; #define PG8_MMA(ai, bj, At, Bt) do { __builtin_amdgcn_s_setprio(1); _Pragma("unroll") for (int m = 0; m < 4; ++m) _Pragma("unroll") for (int n = 0; n < 2; ++n) _Pragma("unroll") for (int k = 0; k < 2; ++k) \
;         acc[ai][bj][m][n] = __builtin_amdgcn_mfma_f32_16x16x32_bf16(Bt[n][k], At[m][k], acc[ai][bj][m][n], 0, 0, 0); __builtin_amdgcn_s_setprio(0); } while (0)
; #define PG8_WAIT_V(n) asm volatile("s_waitcnt vmcnt(" #n ")" ::: "memory")
; #define PG8_WAIT_L(n) asm volatile("s_waitcnt lgkmcnt(" #n ")" ::: "memory")
; #define PG8_BAR __builtin_amdgcn_s_barrier()
; #define PG8_SCHED __builtin_amdgcn_sched_barrier(0)
; template <class Desc, class Epi>
; DI void gemm_phase(LAS unsigned char* lds, const Desc& D, const Epi& E, int wv) {
;     ...
;             PG8_LDA(At, 1, 1); PG8_STAGE(PG8_SB(1, 0), b3, voffB); PG8_STAGE(PG8_SB(1, 1), b3 + hstepB, voffB); PG8_STAGE(PG8_SA(1, 0), a3, voffA);
;             PG8_WAIT_V(8); PG8_WAIT_L(0); PG8_BAR; PG8_MMA(1, 0, At, B0); PG8_MMA(1, 1, At, B1); PG8_BAR; PG8_SCHED;
;         }
;         if (wr == 0) PG8_BAR;
	s_add_i32 s68, s76, s28
	v_lshl_add_u64 v[146:147], v[146:147], 0, s[8:9]
	s_mov_b32 m0, s68
	ds_read_b128 v[184:187], v151 offset:49152
	ds_read_b128 v[188:191], v151 offset:50176
	ds_read_b128 v[192:195], v151 offset:51200
	ds_read_b128 v[196:199], v151 offset:52224
	ds_read_b128 v[200:203], v151 offset:53248
	ds_read_b128 v[204:207], v151 offset:54272
	ds_read_b128 v[208:211], v151 offset:55296
	ds_read_b128 v[212:215], v151 offset:56320
	global_load_lds_dwordx4 v[146:147], off
	s_add_i32 m0, s68, 0x2000
	s_add_u32 s66, s66, 0x80080
	v_lshl_add_u64 v[146:147], v[216:217], 0, s[8:9]
	s_addc_u32 s67, s67, 0
	s_add_i32 s68, s77, s28
	global_load_lds_dwordx4 v[146:147], off
	v_lshl_add_u64 v[146:147], s[66:67], 0, v[132:133]
	s_mov_b32 m0, s68
	s_nop 0
	global_load_lds_dwordx4 v[146:147], off
	v_lshl_add_u64 v[146:147], s[66:67], 0, v[128:129]
	s_add_i32 m0, s68, 0x2000
	s_nop 0
	global_load_lds_dwordx4 v[146:147], off
	v_lshl_add_u64 v[146:147], v[218:219], 0, s[8:9]
	s_mov_b32 m0, s48
	s_nop 0
	global_load_lds_dwordx4 v[146:147], off
	v_lshl_add_u64 v[146:147], v[220:221], 0, s[8:9]
	s_mov_b32 m0, s49
	s_nop 0
	global_load_lds_dwordx4 v[146:147], off
	s_waitcnt vmcnt(8)
	s_waitcnt lgkmcnt(0)
	s_barrier
	s_setprio 1
	v_mfma_f32_16x16x32_bf16 v[60:63], v[152:155], v[184:187], v[60:63]
	v_mfma_f32_16x16x32_bf16 v[56:59], v[160:163], v[184:187], v[56:59]
	v_mfma_f32_16x16x32_bf16 v[44:47], v[152:155], v[192:195], v[44:47]
	v_mfma_f32_16x16x32_bf16 v[40:43], v[160:163], v[192:195], v[40:43]
	v_mfma_f32_16x16x32_bf16 v[28:31], v[152:155], v[200:203], v[28:31]
	v_mfma_f32_16x16x32_bf16 v[24:27], v[160:163], v[200:203], v[24:27]
	v_mfma_f32_16x16x32_bf16 v[12:15], v[152:155], v[208:211], v[12:15]
	v_mfma_f32_16x16x32_bf16 v[8:11], v[160:163], v[208:211], v[8:11]
	v_mfma_f32_16x16x32_bf16 v[60:63], v[156:159], v[188:191], v[60:63]
	v_mfma_f32_16x16x32_bf16 v[56:59], v[164:167], v[188:191], v[56:59]
	v_mfma_f32_16x16x32_bf16 v[44:47], v[156:159], v[196:199], v[44:47]
	v_mfma_f32_16x16x32_bf16 v[40:43], v[164:167], v[196:199], v[40:43]
	v_mfma_f32_16x16x32_bf16 v[28:31], v[156:159], v[204:207], v[28:31]
	v_mfma_f32_16x16x32_bf16 v[24:27], v[164:167], v[204:207], v[24:27]
	v_mfma_f32_16x16x32_bf16 v[12:15], v[156:159], v[212:215], v[12:15]
	v_mfma_f32_16x16x32_bf16 v[8:11], v[164:167], v[212:215], v[8:11]
	v_mfma_f32_16x16x32_bf16 v[52:55], v[168:171], v[184:187], v[52:55]
	v_mfma_f32_16x16x32_bf16 v[48:51], v[176:179], v[184:187], v[48:51]
	v_mfma_f32_16x16x32_bf16 v[36:39], v[168:171], v[192:195], v[36:39]
	v_mfma_f32_16x16x32_bf16 v[32:35], v[176:179], v[192:195], v[32:35]
	v_mfma_f32_16x16x32_bf16 v[20:23], v[168:171], v[200:203], v[20:23]
	v_mfma_f32_16x16x32_bf16 v[16:19], v[176:179], v[200:203], v[16:19]
	v_mfma_f32_16x16x32_bf16 v[4:7], v[168:171], v[208:211], v[4:7]
	v_mfma_f32_16x16x32_bf16 v[0:3], v[176:179], v[208:211], v[0:3]
	v_mfma_f32_16x16x32_bf16 v[52:55], v[172:175], v[188:191], v[52:55]
	v_mfma_f32_16x16x32_bf16 v[48:51], v[180:183], v[188:191], v[48:51]
	v_mfma_f32_16x16x32_bf16 v[36:39], v[172:175], v[196:199], v[36:39]
	v_mfma_f32_16x16x32_bf16 v[32:35], v[180:183], v[196:199], v[32:35]
	v_mfma_f32_16x16x32_bf16 v[20:23], v[172:175], v[204:207], v[20:23]
	v_mfma_f32_16x16x32_bf16 v[16:19], v[180:183], v[204:207], v[16:19]
	v_mfma_f32_16x16x32_bf16 v[4:7], v[172:175], v[212:215], v[4:7]
	v_mfma_f32_16x16x32_bf16 v[0:3], v[180:183], v[212:215], v[0:3]
	s_setprio 0
	s_barrier
	s_add_i32 s63, s63, 2
	s_add_u32 s64, s64, 0x100
	s_addc_u32 s65, s65, 0
	s_add_u32 s53, s53, 0x100
	s_addc_u32 s61, s61, 0
	s_cmp_gt_u32 s63, 29
	s_cbranch_scc0 .LBB0_292
	s_and_b64 vcc, exec, s[14:15]
	s_cbranch_vccz .LBB0_295
	s_barrier

; #define PG8_STAGE(bufoff, gbase, voff) do { _Pragma("unroll") for (int _i = 0; _i < 2; ++_i) \
;         __builtin_amdgcn_global_load_lds((const unsigned*)((const char*)(gbase) + (voff)[_i]), (LAS unsigned*)(lds + (bufoff) + ldsw + _i * 8192), 16, 0, 0); } while (0)
; #define PG8_LDA(dst, b, h) do { _Pragma("unroll") for (int m = 0; m < 4; ++m) _Pragma("unroll") for (int k = 0; k < 2; ++k) dst[m][k] = *(const LAS bf16x8*)(lds + PG8_SA(b, h) + aoff + m * 2048 + k * 1024); } while (0)
; #define PG8_LDB(dst, b, h) do { _Pragma("unroll") for (int n = 0; n < 2; ++n) _Pragma("unroll") for (int k = 0; k < 2; ++k) dst[n][k] = *(const LAS bf16x8*)(lds + PG8_SB(b, h) + boff + n * 2048 + k * 1024); } while (0)
; #define PG8_MMA(ai, bj, At, Bt) do { __builtin_amdgcn_s_setprio(1); _Pragma("unroll") for (int m = 0; m < 4; ++m) _Pragma("unroll") for (int n = 0; n < 2; ++n) _Pragma("unroll") for (int k = 0; k < 2; ++k) \
;         acc[ai][bj][m][n] = __builtin_amdgcn_mfma_f32_16x16x32_bf16(Bt[n][k], At[m][k], acc[ai][bj][m][n], 0, 0, 0); __builtin_amdgcn_s_setprio(0); } while (0)
; #define PG8_WAIT_V(n) asm volatile("s_waitcnt vmcnt(" #n ")" ::: "memory")
; #define PG8_WAIT_L(n) asm volatile("s_waitcnt lgkmcnt(" #n ")" ::: "memory")
; #define PG8_BAR __builtin_amdgcn_s_barrier()
; #define PG8_SCHED __builtin_amdgcn_sched_barrier(0)
; template <class Desc, class Epi>
; DI void gemm_phase(LAS unsigned char* lds, const Desc& D, const Epi& E, int wv) {
;     ...
;             const bool last = (t == nt - 2);
;             const char* a1 = cA + (size_t)(t + 1) * kstep;
;             const char* a2 = last ? nA : cA + (size_t)(t + 2) * kstep; const char* b2 = last ? nB : cB + (size_t)(t + 2) * kstep;
;             const char* a3 = a2 + kstep; const char* b3 = b2 + kstep;
;             PG8_LDB(B0, 0, 0); PG8_LDB(B1, 0, 1); PG8_SCHED; PG8_LDA(At, 0, 0); PG8_STAGE(PG8_SA(1, 1), a1 + hstepA, voffA);
;             PG8_WAIT_V(8); PG8_WAIT_L(0); PG8_BAR; PG8_MMA(0, 0, At, B0); PG8_MMA(0, 1, At, B1); PG8_BAR; PG8_SCHED;
;             PG8_LDA(At, 0, 1); PG8_STAGE(PG8_SB(0, 0), b2, voffB); PG8_STAGE(PG8_SB(0, 1), b2 + hstepB, voffB); PG8_STAGE(PG8_SA(0, 0), a2, voffA);
.LBB0_339:
	ds_read_b128 v[142:145], v151
	ds_read_b128 v[146:149], v151 offset:1024
	ds_read_b128 v[158:161], v151 offset:2048
	ds_read_b128 v[162:165], v151 offset:3072
	ds_read_b128 v[166:169], v152
	ds_read_b128 v[170:173], v152 offset:1024
	ds_read_b128 v[174:177], v152 offset:2048
	ds_read_b128 v[178:181], v152 offset:3072
	s_add_u32 s8, s6, 0xfffe0080
	s_addc_u32 s9, s7, -1
	s_cmp_eq_u32 s67, 4
	s_cselect_b32 s65, s61, s9
	s_cselect_b32 s64, s60, s8
	s_cselect_b32 s9, s63, s66
	s_cselect_b32 s8, s62, s53
	v_lshl_add_u64 v[214:215], s[6:7], 0, v[138:139]
	s_add_i32 m0, s3, 0xc000
	ds_read_b128 v[182:185], v153
	ds_read_b128 v[186:189], v153 offset:1024
	ds_read_b128 v[190:193], v153 offset:2048
	ds_read_b128 v[194:197], v153 offset:3072
	ds_read_b128 v[198:201], v153 offset:4096
	ds_read_b128 v[202:205], v153 offset:5120
	ds_read_b128 v[206:209], v153 offset:6144
	ds_read_b128 v[210:213], v153 offset:7168
	global_load_lds_dwordx4 v[214:215], off
	v_lshl_add_u64 v[214:215], s[6:7], 0, v[140:141]
	s_add_i32 m0, s3, 0xe000
	s_nop 0
	global_load_lds_dwordx4 v[214:215], off
	s_waitcnt vmcnt(8)
	s_waitcnt lgkmcnt(0)
	s_barrier
	s_setprio 1
	v_mfma_f32_16x16x32_bf16 v[124:127], v[142:145], v[182:185], v[124:127]
	v_mfma_f32_16x16x32_bf16 v[120:123], v[158:161], v[182:185], v[120:123]
	v_mfma_f32_16x16x32_bf16 v[108:111], v[142:145], v[190:193], v[108:111]
	v_mfma_f32_16x16x32_bf16 v[104:107], v[158:161], v[190:193], v[104:107]
	v_mfma_f32_16x16x32_bf16 v[92:95], v[142:145], v[198:201], v[92:95]
	v_mfma_f32_16x16x32_bf16 v[88:91], v[158:161], v[198:201], v[88:91]
	v_mfma_f32_16x16x32_bf16 v[76:79], v[142:145], v[206:209], v[76:79]
	v_mfma_f32_16x16x32_bf16 v[72:75], v[158:161], v[206:209], v[72:75]
	v_mfma_f32_16x16x32_bf16 v[124:127], v[146:149], v[186:189], v[124:127]
	v_mfma_f32_16x16x32_bf16 v[120:123], v[162:165], v[186:189], v[120:123]
	v_mfma_f32_16x16x32_bf16 v[108:111], v[146:149], v[194:197], v[108:111]
	v_mfma_f32_16x16x32_bf16 v[104:107], v[162:165], v[194:197], v[104:107]
	v_mfma_f32_16x16x32_bf16 v[92:95], v[146:149], v[202:205], v[92:95]
	v_mfma_f32_16x16x32_bf16 v[88:91], v[162:165], v[202:205], v[88:91]
	v_mfma_f32_16x16x32_bf16 v[76:79], v[146:149], v[210:213], v[76:79]
	v_mfma_f32_16x16x32_bf16 v[72:75], v[162:165], v[210:213], v[72:75]
	v_mfma_f32_16x16x32_bf16 v[116:119], v[166:169], v[182:185], v[116:119]
	v_mfma_f32_16x16x32_bf16 v[112:115], v[174:177], v[182:185], v[112:115]
	v_mfma_f32_16x16x32_bf16 v[100:103], v[166:169], v[190:193], v[100:103]
	v_mfma_f32_16x16x32_bf16 v[96:99], v[174:177], v[190:193], v[96:99]
	v_mfma_f32_16x16x32_bf16 v[84:87], v[166:169], v[198:201], v[84:87]
	v_mfma_f32_16x16x32_bf16 v[80:83], v[174:177], v[198:201], v[80:83]
	v_mfma_f32_16x16x32_bf16 v[68:71], v[166:169], v[206:209], v[68:71]
	v_mfma_f32_16x16x32_bf16 v[64:67], v[174:177], v[206:209], v[64:67]
	v_mfma_f32_16x16x32_bf16 v[116:119], v[170:173], v[186:189], v[116:119]
	v_mfma_f32_16x16x32_bf16 v[112:115], v[178:181], v[186:189], v[112:115]
	v_mfma_f32_16x16x32_bf16 v[100:103], v[170:173], v[194:197], v[100:103]
	v_mfma_f32_16x16x32_bf16 v[96:99], v[178:181], v[194:197], v[96:99]
	v_mfma_f32_16x16x32_bf16 v[84:87], v[170:173], v[202:205], v[84:87]
	v_mfma_f32_16x16x32_bf16 v[80:83], v[178:181], v[202:205], v[80:83]
	v_mfma_f32_16x16x32_bf16 v[68:71], v[170:173], v[210:213], v[68:71]
	v_mfma_f32_16x16x32_bf16 v[64:67], v[178:181], v[210:213], v[64:67]
	s_setprio 0
	s_barrier
	s_add_i32 s68, s41, s2
	v_lshl_add_u64 v[214:215], s[8:9], 0, v[130:131]
	s_mov_b32 m0, s68
	ds_read_b128 v[182:185], v153 offset:16384
	ds_read_b128 v[186:189], v153 offset:17408
	ds_read_b128 v[190:193], v153 offset:18432
	ds_read_b128 v[194:197], v153 offset:19456
	ds_read_b128 v[198:201], v153 offset:20480
	ds_read_b128 v[202:205], v153 offset:21504
	ds_read_b128 v[206:209], v153 offset:22528
	ds_read_b128 v[210:213], v153 offset:23552
	global_load_lds_dwordx4 v[214:215], off
	s_add_i32 m0, s68, 0x2000
	s_add_u32 s68, s8, 0x80000
	v_lshl_add_u64 v[216:217], s[8:9], 0, v[134:135]
	s_addc_u32 s69, s9, 0
	s_add_i32 s70, s42, s2
	global_load_lds_dwordx4 v[216:217], off
	v_lshl_add_u64 v[218:219], s[68:69], 0, v[130:131]
	s_mov_b32 m0, s70
	v_lshl_add_u64 v[220:221], s[64:65], 0, v[132:133]
	global_load_lds_dwordx4 v[218:219], off
	v_lshl_add_u64 v[218:219], s[68:69], 0, v[134:135]
	s_add_i32 m0, s70, 0x2000
	s_nop 0
	global_load_lds_dwordx4 v[218:219], off
	v_lshl_add_u64 v[218:219], s[64:65], 0, v[128:129]
	s_mov_b32 m0, s3
	s_nop 0
	global_load_lds_dwordx4 v[218:219], off
	s_mov_b32 m0, s28
	s_nop 0
	global_load_lds_dwordx4 v[220:221], off
	s_waitcnt vmcnt(8)
	s_waitcnt lgkmcnt(0)
	s_barrier
; #define PG8_STAGE(bufoff, gbase, voff) do { _Pragma("unroll") for (int _i = 0; _i < 2; ++_i) \
;         __builtin_amdgcn_global_load_lds((const unsigned*)((const char*)(gbase) + (voff)[_i]), (LAS unsigned*)(lds + (bufoff) + ldsw + _i * 8192), 16, 0, 0); } while (0)
; #define PG8_LDA(dst, b, h) do { _Pragma("unroll") for (int m = 0; m < 4; ++m) _Pragma("unroll") for (int k = 0; k < 2; ++k) dst[m][k] = *(const LAS bf16x8*)(lds + PG8_SA(b, h) + aoff + m * 2048 + k * 1024); } while (0)
; #define PG8_LDB(dst, b, h) do { _Pragma("unroll") for (int n = 0; n < 2; ++n) _Pragma("unroll") for (int k = 0; k < 2; ++k) dst[n][k] = *(const LAS bf16x8*)(lds + PG8_SB(b, h) + boff + n * 2048 + k * 1024); } while (0)
; #define PG8_MMA(ai, bj, At, Bt) do { __builtin_amdgcn_s_setprio(1); _Pragma("unroll") for (int m = 0; m < 4; ++m) _Pragma("unroll") for (int n = 0; n < 2; ++n) _Pragma("unroll") for (int k = 0; k < 2; ++k) \
;         acc[ai][bj][m][n] = __builtin_amdgcn_mfma_f32_16x16x32_bf16(Bt[n][k], At[m][k], acc[ai][bj][m][n], 0, 0, 0); __builtin_amdgcn_s_setprio(0); } while (0)
; #define PG8_WAIT_V(n) asm volatile("s_waitcnt vmcnt(" #n ")" ::: "memory")
; #define PG8_WAIT_L(n) asm volatile("s_waitcnt lgkmcnt(" #n ")" ::: "memory")
; #define PG8_BAR __builtin_amdgcn_s_barrier()
; #define PG8_SCHED __builtin_amdgcn_sched_barrier(0)
; template <class Desc, class Epi>
; DI void gemm_phase(LAS unsigned char* lds, const Desc& D, const Epi& E, int wv) {
;     ...
;             PG8_WAIT_V(8); PG8_WAIT_L(0); PG8_BAR; PG8_MMA(1, 0, At, B0); PG8_MMA(1, 1, At, B1); PG8_BAR; PG8_SCHED;
;             PG8_LDB(B0, 1, 0); PG8_LDB(B1, 1, 1); PG8_SCHED; PG8_LDA(At, 1, 0); PG8_STAGE(PG8_SA(0, 1), a2 + hstepA, voffA);
;             PG8_WAIT_V(8); PG8_WAIT_L(0); PG8_BAR; PG8_MMA(0, 0, At, B0); PG8_MMA(0, 1, At, B1); PG8_BAR; PG8_SCHED;
	s_setprio 1
	v_mfma_f32_16x16x32_bf16 v[60:63], v[142:145], v[182:185], v[60:63]
	v_mfma_f32_16x16x32_bf16 v[56:59], v[158:161], v[182:185], v[56:59]
	v_mfma_f32_16x16x32_bf16 v[44:47], v[142:145], v[190:193], v[44:47]
	v_mfma_f32_16x16x32_bf16 v[40:43], v[158:161], v[190:193], v[40:43]
	v_mfma_f32_16x16x32_bf16 v[28:31], v[142:145], v[198:201], v[28:31]
	v_mfma_f32_16x16x32_bf16 v[24:27], v[158:161], v[198:201], v[24:27]
	v_mfma_f32_16x16x32_bf16 v[12:15], v[142:145], v[206:209], v[12:15]
	v_mfma_f32_16x16x32_bf16 v[8:11], v[158:161], v[206:209], v[8:11]
	v_mfma_f32_16x16x32_bf16 v[60:63], v[146:149], v[186:189], v[60:63]
	v_mfma_f32_16x16x32_bf16 v[56:59], v[162:165], v[186:189], v[56:59]
	v_mfma_f32_16x16x32_bf16 v[44:47], v[146:149], v[194:197], v[44:47]
	v_mfma_f32_16x16x32_bf16 v[40:43], v[162:165], v[194:197], v[40:43]
	v_mfma_f32_16x16x32_bf16 v[28:31], v[146:149], v[202:205], v[28:31]
	v_mfma_f32_16x16x32_bf16 v[24:27], v[162:165], v[202:205], v[24:27]
	v_mfma_f32_16x16x32_bf16 v[12:15], v[146:149], v[210:213], v[12:15]
	v_mfma_f32_16x16x32_bf16 v[8:11], v[162:165], v[210:213], v[8:11]
	v_mfma_f32_16x16x32_bf16 v[52:55], v[166:169], v[182:185], v[52:55]
	v_mfma_f32_16x16x32_bf16 v[48:51], v[174:177], v[182:185], v[48:51]
	v_mfma_f32_16x16x32_bf16 v[36:39], v[166:169], v[190:193], v[36:39]
	v_mfma_f32_16x16x32_bf16 v[32:35], v[174:177], v[190:193], v[32:35]
	v_mfma_f32_16x16x32_bf16 v[20:23], v[166:169], v[198:201], v[20:23]
	v_mfma_f32_16x16x32_bf16 v[16:19], v[174:177], v[198:201], v[16:19]
	v_mfma_f32_16x16x32_bf16 v[4:7], v[166:169], v[206:209], v[4:7]
	v_mfma_f32_16x16x32_bf16 v[0:3], v[174:177], v[206:209], v[0:3]
	v_mfma_f32_16x16x32_bf16 v[52:55], v[170:173], v[186:189], v[52:55]
	v_mfma_f32_16x16x32_bf16 v[48:51], v[178:181], v[186:189], v[48:51]
	v_mfma_f32_16x16x32_bf16 v[36:39], v[170:173], v[194:197], v[36:39]
	v_mfma_f32_16x16x32_bf16 v[32:35], v[178:181], v[194:197], v[32:35]
	v_mfma_f32_16x16x32_bf16 v[20:23], v[170:173], v[202:205], v[20:23]
	v_mfma_f32_16x16x32_bf16 v[16:19], v[178:181], v[202:205], v[16:19]
	v_mfma_f32_16x16x32_bf16 v[4:7], v[170:173], v[210:213], v[4:7]
	v_mfma_f32_16x16x32_bf16 v[0:3], v[178:181], v[210:213], v[0:3]
	s_setprio 0
	s_barrier
	s_add_i32 s68, 0, 0x18000
	v_add_u32_e32 v136, s68, v150
	s_add_i32 s69, 0, 0x1c000
	ds_read_b128 v[142:145], v136
	ds_read_b128 v[146:149], v136 offset:1024
	ds_read_b128 v[158:161], v136 offset:2048
	ds_read_b128 v[162:165], v136 offset:3072
	v_add_u32_e32 v136, s69, v150
	ds_read_b128 v[166:169], v136
	ds_read_b128 v[170:173], v136 offset:1024
	ds_read_b128 v[174:177], v136 offset:2048
	ds_read_b128 v[178:181], v136 offset:3072
	s_add_u32 s64, s64, 0x20000
	s_addc_u32 s65, s65, 0
	s_mov_b32 m0, s29
	v_lshl_add_u64 v[222:223], s[64:65], 0, v[128:129]
	ds_read_b128 v[182:185], v153 offset:32768
	ds_read_b128 v[186:189], v153 offset:33792
	ds_read_b128 v[190:193], v153 offset:34816
	ds_read_b128 v[194:197], v153 offset:35840
	ds_read_b128 v[198:201], v153 offset:36864
	ds_read_b128 v[202:205], v153 offset:37888
	ds_read_b128 v[206:209], v153 offset:38912
	ds_read_b128 v[210:213], v153 offset:39936
	global_load_lds_dwordx4 v[222:223], off
	v_lshl_add_u64 v[222:223], s[64:65], 0, v[132:133]
	s_mov_b32 m0, s30
	s_nop 0
	global_load_lds_dwordx4 v[222:223], off
	s_waitcnt vmcnt(8)
	s_waitcnt lgkmcnt(0)
	s_barrier
	s_setprio 1
	v_mfma_f32_16x16x32_bf16 v[124:127], v[142:145], v[182:185], v[124:127]
	v_mfma_f32_16x16x32_bf16 v[120:123], v[158:161], v[182:185], v[120:123]
	v_mfma_f32_16x16x32_bf16 v[108:111], v[142:145], v[190:193], v[108:111]
	v_mfma_f32_16x16x32_bf16 v[104:107], v[158:161], v[190:193], v[104:107]
	v_mfma_f32_16x16x32_bf16 v[92:95], v[142:145], v[198:201], v[92:95]
	v_mfma_f32_16x16x32_bf16 v[88:91], v[158:161], v[198:201], v[88:91]
	v_mfma_f32_16x16x32_bf16 v[76:79], v[142:145], v[206:209], v[76:79]
	v_mfma_f32_16x16x32_bf16 v[72:75], v[158:161], v[206:209], v[72:75]
	v_mfma_f32_16x16x32_bf16 v[124:127], v[146:149], v[186:189], v[124:127]
	v_mfma_f32_16x16x32_bf16 v[120:123], v[162:165], v[186:189], v[120:123]
	v_mfma_f32_16x16x32_bf16 v[108:111], v[146:149], v[194:197], v[108:111]
	v_mfma_f32_16x16x32_bf16 v[104:107], v[162:165], v[194:197], v[104:107]
	v_mfma_f32_16x16x32_bf16 v[92:95], v[146:149], v[202:205], v[92:95]
	v_mfma_f32_16x16x32_bf16 v[88:91], v[162:165], v[202:205], v[88:91]
	v_mfma_f32_16x16x32_bf16 v[76:79], v[146:149], v[210:213], v[76:79]
	v_mfma_f32_16x16x32_bf16 v[72:75], v[162:165], v[210:213], v[72:75]
	v_mfma_f32_16x16x32_bf16 v[116:119], v[166:169], v[182:185], v[116:119]
	v_mfma_f32_16x16x32_bf16 v[112:115], v[174:177], v[182:185], v[112:115]
	v_mfma_f32_16x16x32_bf16 v[100:103], v[166:169], v[190:193], v[100:103]
	v_mfma_f32_16x16x32_bf16 v[96:99], v[174:177], v[190:193], v[96:99]
	v_mfma_f32_16x16x32_bf16 v[84:87], v[166:169], v[198:201], v[84:87]
	v_mfma_f32_16x16x32_bf16 v[80:83], v[174:177], v[198:201], v[80:83]
	v_mfma_f32_16x16x32_bf16 v[68:71], v[166:169], v[206:209], v[68:71]
	v_mfma_f32_16x16x32_bf16 v[64:67], v[174:177], v[206:209], v[64:67]
	v_mfma_f32_16x16x32_bf16 v[116:119], v[170:173], v[186:189], v[116:119]
	v_mfma_f32_16x16x32_bf16 v[112:115], v[178:181], v[186:189], v[112:115]
	v_mfma_f32_16x16x32_bf16 v[100:103], v[170:173], v[194:197], v[100:103]
	v_mfma_f32_16x16x32_bf16 v[96:99], v[178:181], v[194:197], v[96:99]
	v_mfma_f32_16x16x32_bf16 v[84:87], v[170:173], v[202:205], v[84:87]
	v_mfma_f32_16x16x32_bf16 v[80:83], v[178:181], v[202:205], v[80:83]
	v_mfma_f32_16x16x32_bf16 v[68:71], v[170:173], v[210:213], v[68:71]
	v_mfma_f32_16x16x32_bf16 v[64:67], v[178:181], v[210:213], v[64:67]
	s_setprio 0
	s_barrier
; #define PG8_STAGE(bufoff, gbase, voff) do { _Pragma("unroll") for (int _i = 0; _i < 2; ++_i) \
;         __builtin_amdgcn_global_load_lds((const unsigned*)((const char*)(gbase) + (voff)[_i]), (LAS unsigned*)(lds + (bufoff) + ldsw + _i * 8192), 16, 0, 0); } while (0)
; #define PG8_LDA(dst, b, h) do { _Pragma("unroll") for (int m = 0; m < 4; ++m) _Pragma("unroll") for (int k = 0; k < 2; ++k) dst[m][k] = *(const LAS bf16x8*)(lds + PG8_SA(b, h) + aoff + m * 2048 + k * 1024); } while (0)
; #define PG8_MMA(ai, bj, At, Bt) do { __builtin_amdgcn_s_setprio(1); _Pragma("unroll") for (int m = 0; m < 4; ++m) _Pragma("unroll") for (int n = 0; n < 2; ++n) _Pragma("unroll") for (int k = 0; k < 2; ++k) \
;         acc[ai][bj][m][n] = __builtin_amdgcn_mfma_f32_16x16x32_bf16(Bt[n][k], At[m][k], acc[ai][bj][m][n], 0, 0, 0); __builtin_amdgcn_s_setprio(0); } while (0)
; #define PG8_WAIT_V(n) asm volatile("s_waitcnt vmcnt(" #n ")" ::: "memory")
; #define PG8_WAIT_L(n) asm volatile("s_waitcnt lgkmcnt(" #n ")" ::: "memory")
; #define PG8_BAR __builtin_amdgcn_s_barrier()
; #define PG8_SCHED __builtin_amdgcn_sched_barrier(0)
; template <class Desc, class Epi>
; DI void gemm_phase(LAS unsigned char* lds, const Desc& D, const Epi& E, int wv) {
;     ...
;             PG8_LDA(At, 1, 1); PG8_STAGE(PG8_SB(1, 0), b3, voffB); PG8_STAGE(PG8_SB(1, 1), b3 + hstepB, voffB); PG8_STAGE(PG8_SA(1, 0), a3, voffA);
;             PG8_WAIT_V(8); PG8_WAIT_L(0); PG8_BAR; PG8_MMA(1, 0, At, B0); PG8_MMA(1, 1, At, B1); PG8_BAR; PG8_SCHED;
;         }
;         if (wr == 0) PG8_BAR;
	s_add_i32 s64, s68, s2
	v_lshl_add_u64 v[214:215], v[214:215], 0, s[20:21]
	s_mov_b32 m0, s64
	ds_read_b128 v[182:185], v153 offset:49152
	ds_read_b128 v[186:189], v153 offset:50176
	ds_read_b128 v[190:193], v153 offset:51200
	ds_read_b128 v[194:197], v153 offset:52224
	ds_read_b128 v[198:201], v153 offset:53248
	ds_read_b128 v[202:205], v153 offset:54272
	ds_read_b128 v[206:209], v153 offset:55296
	ds_read_b128 v[210:213], v153 offset:56320
	global_load_lds_dwordx4 v[214:215], off
	s_add_i32 m0, s64, 0x2000
	s_add_u32 s8, s8, 0x80080
	v_lshl_add_u64 v[214:215], v[216:217], 0, s[20:21]
	s_addc_u32 s9, s9, 0
	s_add_i32 s64, s69, s2
	global_load_lds_dwordx4 v[214:215], off
	v_lshl_add_u64 v[214:215], s[8:9], 0, v[130:131]
	s_mov_b32 m0, s64
	s_nop 0
	global_load_lds_dwordx4 v[214:215], off
	v_lshl_add_u64 v[214:215], s[8:9], 0, v[134:135]
	s_add_i32 m0, s64, 0x2000
	s_nop 0
	global_load_lds_dwordx4 v[214:215], off
	v_lshl_add_u64 v[214:215], v[218:219], 0, s[20:21]
	s_mov_b32 m0, s35
	s_nop 0
	global_load_lds_dwordx4 v[214:215], off
	v_lshl_add_u64 v[214:215], v[220:221], 0, s[20:21]
	s_mov_b32 m0, s40
	s_nop 0
	global_load_lds_dwordx4 v[214:215], off
	s_waitcnt vmcnt(8)
	s_waitcnt lgkmcnt(0)
	s_barrier
	s_setprio 1
	v_mfma_f32_16x16x32_bf16 v[60:63], v[142:145], v[182:185], v[60:63]
	v_mfma_f32_16x16x32_bf16 v[56:59], v[158:161], v[182:185], v[56:59]
	v_mfma_f32_16x16x32_bf16 v[44:47], v[142:145], v[190:193], v[44:47]
	v_mfma_f32_16x16x32_bf16 v[40:43], v[158:161], v[190:193], v[40:43]
	v_mfma_f32_16x16x32_bf16 v[28:31], v[142:145], v[198:201], v[28:31]
	v_mfma_f32_16x16x32_bf16 v[24:27], v[158:161], v[198:201], v[24:27]
	v_mfma_f32_16x16x32_bf16 v[12:15], v[142:145], v[206:209], v[12:15]
	v_mfma_f32_16x16x32_bf16 v[8:11], v[158:161], v[206:209], v[8:11]
	v_mfma_f32_16x16x32_bf16 v[60:63], v[146:149], v[186:189], v[60:63]
	v_mfma_f32_16x16x32_bf16 v[56:59], v[162:165], v[186:189], v[56:59]
	v_mfma_f32_16x16x32_bf16 v[44:47], v[146:149], v[194:197], v[44:47]
	v_mfma_f32_16x16x32_bf16 v[40:43], v[162:165], v[194:197], v[40:43]
	v_mfma_f32_16x16x32_bf16 v[28:31], v[146:149], v[202:205], v[28:31]
	v_mfma_f32_16x16x32_bf16 v[24:27], v[162:165], v[202:205], v[24:27]
	v_mfma_f32_16x16x32_bf16 v[12:15], v[146:149], v[210:213], v[12:15]
	v_mfma_f32_16x16x32_bf16 v[8:11], v[162:165], v[210:213], v[8:11]
	v_mfma_f32_16x16x32_bf16 v[52:55], v[166:169], v[182:185], v[52:55]
	v_mfma_f32_16x16x32_bf16 v[48:51], v[174:177], v[182:185], v[48:51]
	v_mfma_f32_16x16x32_bf16 v[36:39], v[166:169], v[190:193], v[36:39]
	v_mfma_f32_16x16x32_bf16 v[32:35], v[174:177], v[190:193], v[32:35]
	v_mfma_f32_16x16x32_bf16 v[20:23], v[166:169], v[198:201], v[20:23]
	v_mfma_f32_16x16x32_bf16 v[16:19], v[174:177], v[198:201], v[16:19]
	v_mfma_f32_16x16x32_bf16 v[4:7], v[166:169], v[206:209], v[4:7]
	v_mfma_f32_16x16x32_bf16 v[0:3], v[174:177], v[206:209], v[0:3]
	v_mfma_f32_16x16x32_bf16 v[52:55], v[170:173], v[186:189], v[52:55]
	v_mfma_f32_16x16x32_bf16 v[48:51], v[178:181], v[186:189], v[48:51]
	v_mfma_f32_16x16x32_bf16 v[36:39], v[170:173], v[194:197], v[36:39]
	v_mfma_f32_16x16x32_bf16 v[32:35], v[178:181], v[194:197], v[32:35]
	v_mfma_f32_16x16x32_bf16 v[20:23], v[170:173], v[202:205], v[20:23]
	v_mfma_f32_16x16x32_bf16 v[16:19], v[178:181], v[202:205], v[16:19]
	v_mfma_f32_16x16x32_bf16 v[4:7], v[170:173], v[210:213], v[4:7]
	v_mfma_f32_16x16x32_bf16 v[0:3], v[178:181], v[210:213], v[0:3]
	s_setprio 0
	s_barrier
	s_add_i32 s67, s67, 2
	s_add_u32 s6, s6, 0x100
	s_addc_u32 s7, s7, 0
	s_add_u32 s53, s53, 0x100
	s_addc_u32 s66, s66, 0
	s_cmp_gt_u32 s67, 5
	s_cbranch_scc0 .LBB0_339
	s_and_b64 vcc, exec, s[22:23]
	s_cbranch_vccz .LBB0_342
	s_barrier

; #define PG8_STAGE(bufoff, gbase, voff) do { _Pragma("unroll") for (int _i = 0; _i < 2; ++_i) \
;         __builtin_amdgcn_global_load_lds((const unsigned*)((const char*)(gbase) + (voff)[_i]), (LAS unsigned*)(lds + (bufoff) + ldsw + _i * 8192), 16, 0, 0); } while (0)
; #define PG8_LDA(dst, b, h) do { _Pragma("unroll") for (int m = 0; m < 4; ++m) _Pragma("unroll") for (int k = 0; k < 2; ++k) dst[m][k] = *(const LAS bf16x8*)(lds + PG8_SA(b, h) + aoff + m * 2048 + k * 1024); } while (0)
; #define PG8_LDB(dst, b, h) do { _Pragma("unroll") for (int n = 0; n < 2; ++n) _Pragma("unroll") for (int k = 0; k < 2; ++k) dst[n][k] = *(const LAS bf16x8*)(lds + PG8_SB(b, h) + boff + n * 2048 + k * 1024); } while (0)
; #define PG8_MMA(ai, bj, At, Bt) do { __builtin_amdgcn_s_setprio(1); _Pragma("unroll") for (int m = 0; m < 4; ++m) _Pragma("unroll") for (int n = 0; n < 2; ++n) _Pragma("unroll") for (int k = 0; k < 2; ++k) \
;         acc[ai][bj][m][n] = __builtin_amdgcn_mfma_f32_16x16x32_bf16(Bt[n][k], At[m][k], acc[ai][bj][m][n], 0, 0, 0); __builtin_amdgcn_s_setprio(0); } while (0)
; #define PG8_WAIT_V(n) asm volatile("s_waitcnt vmcnt(" #n ")" ::: "memory")
; #define PG8_WAIT_L(n) asm volatile("s_waitcnt lgkmcnt(" #n ")" ::: "memory")
; #define PG8_BAR __builtin_amdgcn_s_barrier()
; #define PG8_SCHED __builtin_amdgcn_sched_barrier(0)
; template <class Desc, class Epi>
; DI void gemm_phase(LAS unsigned char* lds, const Desc& D, const Epi& E, int wv) {
;     ...
;             const bool last = (t == nt - 2);
;             const char* a1 = cA + (size_t)(t + 1) * kstep;
;             const char* a2 = last ? nA : cA + (size_t)(t + 2) * kstep; const char* b2 = last ? nB : cB + (size_t)(t + 2) * kstep;
;             const char* a3 = a2 + kstep; const char* b3 = b2 + kstep;
;             PG8_LDB(B0, 0, 0); PG8_LDB(B1, 0, 1); PG8_SCHED; PG8_LDA(At, 0, 0); PG8_STAGE(PG8_SA(1, 1), a1 + hstepA, voffA);
;             PG8_WAIT_V(8); PG8_WAIT_L(0); PG8_BAR; PG8_MMA(0, 0, At, B0); PG8_MMA(0, 1, At, B1); PG8_BAR; PG8_SCHED;
;             PG8_LDA(At, 0, 1); PG8_STAGE(PG8_SB(0, 0), b2, voffB); PG8_STAGE(PG8_SB(0, 1), b2 + hstepB, voffB); PG8_STAGE(PG8_SA(0, 0), a2, voffA);
.LBB0_581:
	ds_read_b128 v[128:131], v185
	ds_read_b128 v[132:135], v185 offset:1024
	ds_read_b128 v[150:153], v185 offset:2048
	ds_read_b128 v[154:157], v185 offset:3072
	ds_read_b128 v[158:161], v186
	ds_read_b128 v[162:165], v186 offset:1024
	ds_read_b128 v[166:169], v186 offset:2048
	ds_read_b128 v[170:173], v186 offset:3072
	s_add_u32 s49, s66, 0xfff00080
	s_addc_u32 s50, s67, -1
	s_cmp_eq_u32 s48, 28
	s_cselect_b32 s71, s19, s50
	s_cselect_b32 s70, s18, s49
	s_cselect_b32 s69, s21, s47
	s_cselect_b32 s68, s20, s1
	v_lshl_add_u64 v[182:183], s[66:67], 0, v[146:147]
	s_add_i32 m0, s3, 0xc000
	ds_read_b128 v[174:177], v187
	ds_read_b128 v[178:181], v187 offset:1024
	ds_read_b128 v[190:193], v187 offset:2048
	ds_read_b128 v[194:197], v187 offset:3072
	ds_read_b128 v[198:201], v187 offset:4096
	ds_read_b128 v[202:205], v187 offset:5120
	ds_read_b128 v[206:209], v187 offset:6144
	ds_read_b128 v[210:213], v187 offset:7168
	global_load_lds_dwordx4 v[182:183], off
	v_lshl_add_u64 v[182:183], s[66:67], 0, v[148:149]
	s_add_i32 m0, s3, 0xe000
	s_nop 0
	global_load_lds_dwordx4 v[182:183], off
	s_waitcnt vmcnt(8)
	s_waitcnt lgkmcnt(0)
	s_barrier
	s_setprio 1
	v_mfma_f32_16x16x32_bf16 v[124:127], v[128:131], v[174:177], v[124:127]
	v_mfma_f32_16x16x32_bf16 v[120:123], v[150:153], v[174:177], v[120:123]
	v_mfma_f32_16x16x32_bf16 v[108:111], v[128:131], v[190:193], v[108:111]
	v_mfma_f32_16x16x32_bf16 v[104:107], v[150:153], v[190:193], v[104:107]
	v_mfma_f32_16x16x32_bf16 v[92:95], v[128:131], v[198:201], v[92:95]
	v_mfma_f32_16x16x32_bf16 v[88:91], v[150:153], v[198:201], v[88:91]
	v_mfma_f32_16x16x32_bf16 v[76:79], v[128:131], v[206:209], v[76:79]
	v_mfma_f32_16x16x32_bf16 v[72:75], v[150:153], v[206:209], v[72:75]
	v_mfma_f32_16x16x32_bf16 v[124:127], v[132:135], v[178:181], v[124:127]
	v_mfma_f32_16x16x32_bf16 v[120:123], v[154:157], v[178:181], v[120:123]
	v_mfma_f32_16x16x32_bf16 v[108:111], v[132:135], v[194:197], v[108:111]
	v_mfma_f32_16x16x32_bf16 v[104:107], v[154:157], v[194:197], v[104:107]
	v_mfma_f32_16x16x32_bf16 v[92:95], v[132:135], v[202:205], v[92:95]
	v_mfma_f32_16x16x32_bf16 v[88:91], v[154:157], v[202:205], v[88:91]
	v_mfma_f32_16x16x32_bf16 v[76:79], v[132:135], v[210:213], v[76:79]
	v_mfma_f32_16x16x32_bf16 v[72:75], v[154:157], v[210:213], v[72:75]
	v_mfma_f32_16x16x32_bf16 v[116:119], v[158:161], v[174:177], v[116:119]
	v_mfma_f32_16x16x32_bf16 v[112:115], v[166:169], v[174:177], v[112:115]
	v_mfma_f32_16x16x32_bf16 v[100:103], v[158:161], v[190:193], v[100:103]
	v_mfma_f32_16x16x32_bf16 v[96:99], v[166:169], v[190:193], v[96:99]
	v_mfma_f32_16x16x32_bf16 v[84:87], v[158:161], v[198:201], v[84:87]
	v_mfma_f32_16x16x32_bf16 v[80:83], v[166:169], v[198:201], v[80:83]
	v_mfma_f32_16x16x32_bf16 v[68:71], v[158:161], v[206:209], v[68:71]
	v_mfma_f32_16x16x32_bf16 v[64:67], v[166:169], v[206:209], v[64:67]
	v_mfma_f32_16x16x32_bf16 v[116:119], v[162:165], v[178:181], v[116:119]
	v_mfma_f32_16x16x32_bf16 v[112:115], v[170:173], v[178:181], v[112:115]
	v_mfma_f32_16x16x32_bf16 v[100:103], v[162:165], v[194:197], v[100:103]
	v_mfma_f32_16x16x32_bf16 v[96:99], v[170:173], v[194:197], v[96:99]
	v_mfma_f32_16x16x32_bf16 v[84:87], v[162:165], v[202:205], v[84:87]
	v_mfma_f32_16x16x32_bf16 v[80:83], v[170:173], v[202:205], v[80:83]
	v_mfma_f32_16x16x32_bf16 v[68:71], v[162:165], v[210:213], v[68:71]
	v_mfma_f32_16x16x32_bf16 v[64:67], v[170:173], v[210:213], v[64:67]
	s_setprio 0
	s_barrier
	s_add_i32 s49, s42, s2
	v_lshl_add_u64 v[182:183], s[68:69], 0, v[140:141]
	s_mov_b32 m0, s49
	ds_read_b128 v[174:177], v187 offset:16384
	ds_read_b128 v[178:181], v187 offset:17408
	ds_read_b128 v[190:193], v187 offset:18432
	ds_read_b128 v[194:197], v187 offset:19456
	ds_read_b128 v[198:201], v187 offset:20480
	ds_read_b128 v[202:205], v187 offset:21504
	ds_read_b128 v[206:209], v187 offset:22528
	ds_read_b128 v[210:213], v187 offset:23552
	global_load_lds_dwordx4 v[182:183], off
	s_add_i32 m0, s49, 0x2000
	s_add_u32 s50, s68, 0x100000
	v_lshl_add_u64 v[214:215], s[68:69], 0, v[136:137]
	s_addc_u32 s51, s69, 0
	s_add_i32 s49, s43, s2
	global_load_lds_dwordx4 v[214:215], off
	v_lshl_add_u64 v[216:217], s[50:51], 0, v[140:141]
	s_mov_b32 m0, s49
	v_lshl_add_u64 v[218:219], s[70:71], 0, v[138:139]
	global_load_lds_dwordx4 v[216:217], off
	v_lshl_add_u64 v[216:217], s[50:51], 0, v[136:137]
	s_add_i32 m0, s49, 0x2000
	s_nop 0
	global_load_lds_dwordx4 v[216:217], off
	v_lshl_add_u64 v[216:217], s[70:71], 0, v[142:143]
	s_mov_b32 m0, s3
	s_nop 0
	global_load_lds_dwordx4 v[216:217], off
	s_mov_b32 m0, s28
	s_nop 0
	global_load_lds_dwordx4 v[218:219], off
	s_waitcnt vmcnt(8)
	s_waitcnt lgkmcnt(0)
	s_barrier
; #define PG8_STAGE(bufoff, gbase, voff) do { _Pragma("unroll") for (int _i = 0; _i < 2; ++_i) \
;         __builtin_amdgcn_global_load_lds((const unsigned*)((const char*)(gbase) + (voff)[_i]), (LAS unsigned*)(lds + (bufoff) + ldsw + _i * 8192), 16, 0, 0); } while (0)
; #define PG8_LDA(dst, b, h) do { _Pragma("unroll") for (int m = 0; m < 4; ++m) _Pragma("unroll") for (int k = 0; k < 2; ++k) dst[m][k] = *(const LAS bf16x8*)(lds + PG8_SA(b, h) + aoff + m * 2048 + k * 1024); } while (0)
; #define PG8_LDB(dst, b, h) do { _Pragma("unroll") for (int n = 0; n < 2; ++n) _Pragma("unroll") for (int k = 0; k < 2; ++k) dst[n][k] = *(const LAS bf16x8*)(lds + PG8_SB(b, h) + boff + n * 2048 + k * 1024); } while (0)
; #define PG8_MMA(ai, bj, At, Bt) do { __builtin_amdgcn_s_setprio(1); _Pragma("unroll") for (int m = 0; m < 4; ++m) _Pragma("unroll") for (int n = 0; n < 2; ++n) _Pragma("unroll") for (int k = 0; k < 2; ++k) \
;         acc[ai][bj][m][n] = __builtin_amdgcn_mfma_f32_16x16x32_bf16(Bt[n][k], At[m][k], acc[ai][bj][m][n], 0, 0, 0); __builtin_amdgcn_s_setprio(0); } while (0)
; #define PG8_WAIT_V(n) asm volatile("s_waitcnt vmcnt(" #n ")" ::: "memory")
; #define PG8_WAIT_L(n) asm volatile("s_waitcnt lgkmcnt(" #n ")" ::: "memory")
; #define PG8_BAR __builtin_amdgcn_s_barrier()
; #define PG8_SCHED __builtin_amdgcn_sched_barrier(0)
; template <class Desc, class Epi>
; DI void gemm_phase(LAS unsigned char* lds, const Desc& D, const Epi& E, int wv) {
;     ...
;             PG8_WAIT_V(8); PG8_WAIT_L(0); PG8_BAR; PG8_MMA(1, 0, At, B0); PG8_MMA(1, 1, At, B1); PG8_BAR; PG8_SCHED;
;             PG8_LDB(B0, 1, 0); PG8_LDB(B1, 1, 1); PG8_SCHED; PG8_LDA(At, 1, 0); PG8_STAGE(PG8_SA(0, 1), a2 + hstepA, voffA);
;             PG8_WAIT_V(8); PG8_WAIT_L(0); PG8_BAR; PG8_MMA(0, 0, At, B0); PG8_MMA(0, 1, At, B1); PG8_BAR; PG8_SCHED;
	s_setprio 1
	v_mfma_f32_16x16x32_bf16 v[60:63], v[128:131], v[174:177], v[60:63]
	v_mfma_f32_16x16x32_bf16 v[56:59], v[150:153], v[174:177], v[56:59]
	v_mfma_f32_16x16x32_bf16 v[44:47], v[128:131], v[190:193], v[44:47]
	v_mfma_f32_16x16x32_bf16 v[40:43], v[150:153], v[190:193], v[40:43]
	v_mfma_f32_16x16x32_bf16 v[28:31], v[128:131], v[198:201], v[28:31]
	v_mfma_f32_16x16x32_bf16 v[24:27], v[150:153], v[198:201], v[24:27]
	v_mfma_f32_16x16x32_bf16 v[12:15], v[128:131], v[206:209], v[12:15]
	v_mfma_f32_16x16x32_bf16 v[8:11], v[150:153], v[206:209], v[8:11]
	v_mfma_f32_16x16x32_bf16 v[60:63], v[132:135], v[178:181], v[60:63]
	v_mfma_f32_16x16x32_bf16 v[56:59], v[154:157], v[178:181], v[56:59]
	v_mfma_f32_16x16x32_bf16 v[44:47], v[132:135], v[194:197], v[44:47]
	v_mfma_f32_16x16x32_bf16 v[40:43], v[154:157], v[194:197], v[40:43]
	v_mfma_f32_16x16x32_bf16 v[28:31], v[132:135], v[202:205], v[28:31]
	v_mfma_f32_16x16x32_bf16 v[24:27], v[154:157], v[202:205], v[24:27]
	v_mfma_f32_16x16x32_bf16 v[12:15], v[132:135], v[210:213], v[12:15]
	v_mfma_f32_16x16x32_bf16 v[8:11], v[154:157], v[210:213], v[8:11]
	v_mfma_f32_16x16x32_bf16 v[52:55], v[158:161], v[174:177], v[52:55]
	v_mfma_f32_16x16x32_bf16 v[48:51], v[166:169], v[174:177], v[48:51]
	v_mfma_f32_16x16x32_bf16 v[36:39], v[158:161], v[190:193], v[36:39]
	v_mfma_f32_16x16x32_bf16 v[32:35], v[166:169], v[190:193], v[32:35]
	v_mfma_f32_16x16x32_bf16 v[20:23], v[158:161], v[198:201], v[20:23]
	v_mfma_f32_16x16x32_bf16 v[16:19], v[166:169], v[198:201], v[16:19]
	v_mfma_f32_16x16x32_bf16 v[4:7], v[158:161], v[206:209], v[4:7]
	v_mfma_f32_16x16x32_bf16 v[0:3], v[166:169], v[206:209], v[0:3]
	v_mfma_f32_16x16x32_bf16 v[52:55], v[162:165], v[178:181], v[52:55]
	v_mfma_f32_16x16x32_bf16 v[48:51], v[170:173], v[178:181], v[48:51]
	v_mfma_f32_16x16x32_bf16 v[36:39], v[162:165], v[194:197], v[36:39]
	v_mfma_f32_16x16x32_bf16 v[32:35], v[170:173], v[194:197], v[32:35]
	v_mfma_f32_16x16x32_bf16 v[20:23], v[162:165], v[202:205], v[20:23]
	v_mfma_f32_16x16x32_bf16 v[16:19], v[170:173], v[202:205], v[16:19]
	v_mfma_f32_16x16x32_bf16 v[4:7], v[162:165], v[210:213], v[4:7]
	v_mfma_f32_16x16x32_bf16 v[0:3], v[170:173], v[210:213], v[0:3]
	s_setprio 0
	s_barrier
	s_add_i32 s49, 0, 0x18000
	v_add_u32_e32 v144, s49, v184
	s_add_i32 s52, 0, 0x1c000
	ds_read_b128 v[128:131], v144
	ds_read_b128 v[132:135], v144 offset:1024
	ds_read_b128 v[150:153], v144 offset:2048
	ds_read_b128 v[154:157], v144 offset:3072
	v_add_u32_e32 v144, s52, v184
	ds_read_b128 v[158:161], v144
	ds_read_b128 v[162:165], v144 offset:1024
	ds_read_b128 v[166:169], v144 offset:2048
	ds_read_b128 v[170:173], v144 offset:3072
	s_add_u32 s50, s70, 0x100000
	s_addc_u32 s51, s71, 0
	s_mov_b32 m0, s29
	v_lshl_add_u64 v[220:221], s[50:51], 0, v[142:143]
	ds_read_b128 v[174:177], v187 offset:32768
	ds_read_b128 v[178:181], v187 offset:33792
	ds_read_b128 v[190:193], v187 offset:34816
	ds_read_b128 v[194:197], v187 offset:35840
	ds_read_b128 v[198:201], v187 offset:36864
	ds_read_b128 v[202:205], v187 offset:37888
	ds_read_b128 v[206:209], v187 offset:38912
	ds_read_b128 v[210:213], v187 offset:39936
	global_load_lds_dwordx4 v[220:221], off
	v_lshl_add_u64 v[220:221], s[50:51], 0, v[138:139]
	s_mov_b32 m0, s30
	s_nop 0
	global_load_lds_dwordx4 v[220:221], off
	s_waitcnt vmcnt(8)
	s_waitcnt lgkmcnt(0)
	s_barrier
	s_setprio 1
	v_mfma_f32_16x16x32_bf16 v[124:127], v[128:131], v[174:177], v[124:127]
	v_mfma_f32_16x16x32_bf16 v[120:123], v[150:153], v[174:177], v[120:123]
	v_mfma_f32_16x16x32_bf16 v[108:111], v[128:131], v[190:193], v[108:111]
	v_mfma_f32_16x16x32_bf16 v[104:107], v[150:153], v[190:193], v[104:107]
	v_mfma_f32_16x16x32_bf16 v[92:95], v[128:131], v[198:201], v[92:95]
	v_mfma_f32_16x16x32_bf16 v[88:91], v[150:153], v[198:201], v[88:91]
	v_mfma_f32_16x16x32_bf16 v[76:79], v[128:131], v[206:209], v[76:79]
	v_mfma_f32_16x16x32_bf16 v[72:75], v[150:153], v[206:209], v[72:75]
	v_mfma_f32_16x16x32_bf16 v[124:127], v[132:135], v[178:181], v[124:127]
	v_mfma_f32_16x16x32_bf16 v[120:123], v[154:157], v[178:181], v[120:123]
	v_mfma_f32_16x16x32_bf16 v[108:111], v[132:135], v[194:197], v[108:111]
	v_mfma_f32_16x16x32_bf16 v[104:107], v[154:157], v[194:197], v[104:107]
	v_mfma_f32_16x16x32_bf16 v[92:95], v[132:135], v[202:205], v[92:95]
	v_mfma_f32_16x16x32_bf16 v[88:91], v[154:157], v[202:205], v[88:91]
	v_mfma_f32_16x16x32_bf16 v[76:79], v[132:135], v[210:213], v[76:79]
	v_mfma_f32_16x16x32_bf16 v[72:75], v[154:157], v[210:213], v[72:75]
	v_mfma_f32_16x16x32_bf16 v[116:119], v[158:161], v[174:177], v[116:119]
	v_mfma_f32_16x16x32_bf16 v[112:115], v[166:169], v[174:177], v[112:115]
	v_mfma_f32_16x16x32_bf16 v[100:103], v[158:161], v[190:193], v[100:103]
	v_mfma_f32_16x16x32_bf16 v[96:99], v[166:169], v[190:193], v[96:99]
	v_mfma_f32_16x16x32_bf16 v[84:87], v[158:161], v[198:201], v[84:87]
	v_mfma_f32_16x16x32_bf16 v[80:83], v[166:169], v[198:201], v[80:83]
	v_mfma_f32_16x16x32_bf16 v[68:71], v[158:161], v[206:209], v[68:71]
	v_mfma_f32_16x16x32_bf16 v[64:67], v[166:169], v[206:209], v[64:67]
	v_mfma_f32_16x16x32_bf16 v[116:119], v[162:165], v[178:181], v[116:119]
	v_mfma_f32_16x16x32_bf16 v[112:115], v[170:173], v[178:181], v[112:115]
	v_mfma_f32_16x16x32_bf16 v[100:103], v[162:165], v[194:197], v[100:103]
	v_mfma_f32_16x16x32_bf16 v[96:99], v[170:173], v[194:197], v[96:99]
	v_mfma_f32_16x16x32_bf16 v[84:87], v[162:165], v[202:205], v[84:87]
	v_mfma_f32_16x16x32_bf16 v[80:83], v[170:173], v[202:205], v[80:83]
	v_mfma_f32_16x16x32_bf16 v[68:71], v[162:165], v[210:213], v[68:71]
	v_mfma_f32_16x16x32_bf16 v[64:67], v[170:173], v[210:213], v[64:67]
	s_setprio 0
	s_barrier
; #define PG8_STAGE(bufoff, gbase, voff) do { _Pragma("unroll") for (int _i = 0; _i < 2; ++_i) \
;         __builtin_amdgcn_global_load_lds((const unsigned*)((const char*)(gbase) + (voff)[_i]), (LAS unsigned*)(lds + (bufoff) + ldsw + _i * 8192), 16, 0, 0); } while (0)
; #define PG8_LDA(dst, b, h) do { _Pragma("unroll") for (int m = 0; m < 4; ++m) _Pragma("unroll") for (int k = 0; k < 2; ++k) dst[m][k] = *(const LAS bf16x8*)(lds + PG8_SA(b, h) + aoff + m * 2048 + k * 1024); } while (0)
; #define PG8_MMA(ai, bj, At, Bt) do { __builtin_amdgcn_s_setprio(1); _Pragma("unroll") for (int m = 0; m < 4; ++m) _Pragma("unroll") for (int n = 0; n < 2; ++n) _Pragma("unroll") for (int k = 0; k < 2; ++k) \
;         acc[ai][bj][m][n] = __builtin_amdgcn_mfma_f32_16x16x32_bf16(Bt[n][k], At[m][k], acc[ai][bj][m][n], 0, 0, 0); __builtin_amdgcn_s_setprio(0); } while (0)
; #define PG8_WAIT_V(n) asm volatile("s_waitcnt vmcnt(" #n ")" ::: "memory")
; #define PG8_WAIT_L(n) asm volatile("s_waitcnt lgkmcnt(" #n ")" ::: "memory")
; #define PG8_BAR __builtin_amdgcn_s_barrier()
; #define PG8_SCHED __builtin_amdgcn_sched_barrier(0)
; template <class Desc, class Epi>
; DI void gemm_phase(LAS unsigned char* lds, const Desc& D, const Epi& E, int wv) {
;     ...
;             PG8_LDA(At, 1, 1); PG8_STAGE(PG8_SB(1, 0), b3, voffB); PG8_STAGE(PG8_SB(1, 1), b3 + hstepB, voffB); PG8_STAGE(PG8_SA(1, 0), a3, voffA);
;             PG8_WAIT_V(8); PG8_WAIT_L(0); PG8_BAR; PG8_MMA(1, 0, At, B0); PG8_MMA(1, 1, At, B1); PG8_BAR; PG8_SCHED;
;         }
;         if (wr == 0) PG8_BAR;
	s_add_i32 s49, s49, s2
	v_lshl_add_u64 v[182:183], v[182:183], 0, s[8:9]
	s_mov_b32 m0, s49
	ds_read_b128 v[174:177], v187 offset:49152
	ds_read_b128 v[178:181], v187 offset:50176
	ds_read_b128 v[190:193], v187 offset:51200
	ds_read_b128 v[194:197], v187 offset:52224
	ds_read_b128 v[198:201], v187 offset:53248
	ds_read_b128 v[202:205], v187 offset:54272
	ds_read_b128 v[206:209], v187 offset:55296
	ds_read_b128 v[210:213], v187 offset:56320
	global_load_lds_dwordx4 v[182:183], off
	s_add_i32 m0, s49, 0x2000
	s_add_u32 s50, s68, 0x100080
	v_lshl_add_u64 v[182:183], v[214:215], 0, s[8:9]
	s_addc_u32 s51, s69, 0
	s_add_i32 s49, s52, s2
	global_load_lds_dwordx4 v[182:183], off
	v_lshl_add_u64 v[182:183], s[50:51], 0, v[140:141]
	s_mov_b32 m0, s49
	s_nop 0
	global_load_lds_dwordx4 v[182:183], off
	v_lshl_add_u64 v[182:183], s[50:51], 0, v[136:137]
	s_add_i32 m0, s49, 0x2000
	s_nop 0
	global_load_lds_dwordx4 v[182:183], off
	v_lshl_add_u64 v[182:183], v[216:217], 0, s[8:9]
	s_mov_b32 m0, s35
	s_nop 0
	global_load_lds_dwordx4 v[182:183], off
	v_lshl_add_u64 v[182:183], v[218:219], 0, s[8:9]
	s_mov_b32 m0, s40
	s_nop 0
	global_load_lds_dwordx4 v[182:183], off
	s_waitcnt vmcnt(8)
	s_waitcnt lgkmcnt(0)
	s_barrier
	s_setprio 1
	v_mfma_f32_16x16x32_bf16 v[60:63], v[128:131], v[174:177], v[60:63]
	v_mfma_f32_16x16x32_bf16 v[56:59], v[150:153], v[174:177], v[56:59]
	v_mfma_f32_16x16x32_bf16 v[44:47], v[128:131], v[190:193], v[44:47]
	v_mfma_f32_16x16x32_bf16 v[40:43], v[150:153], v[190:193], v[40:43]
	v_mfma_f32_16x16x32_bf16 v[28:31], v[128:131], v[198:201], v[28:31]
	v_mfma_f32_16x16x32_bf16 v[24:27], v[150:153], v[198:201], v[24:27]
	v_mfma_f32_16x16x32_bf16 v[12:15], v[128:131], v[206:209], v[12:15]
	v_mfma_f32_16x16x32_bf16 v[8:11], v[150:153], v[206:209], v[8:11]
	v_mfma_f32_16x16x32_bf16 v[60:63], v[132:135], v[178:181], v[60:63]
	v_mfma_f32_16x16x32_bf16 v[56:59], v[154:157], v[178:181], v[56:59]
	v_mfma_f32_16x16x32_bf16 v[44:47], v[132:135], v[194:197], v[44:47]
	v_mfma_f32_16x16x32_bf16 v[40:43], v[154:157], v[194:197], v[40:43]
	v_mfma_f32_16x16x32_bf16 v[28:31], v[132:135], v[202:205], v[28:31]
	v_mfma_f32_16x16x32_bf16 v[24:27], v[154:157], v[202:205], v[24:27]
	v_mfma_f32_16x16x32_bf16 v[12:15], v[132:135], v[210:213], v[12:15]
	v_mfma_f32_16x16x32_bf16 v[8:11], v[154:157], v[210:213], v[8:11]
	v_mfma_f32_16x16x32_bf16 v[52:55], v[158:161], v[174:177], v[52:55]
	v_mfma_f32_16x16x32_bf16 v[48:51], v[166:169], v[174:177], v[48:51]
	v_mfma_f32_16x16x32_bf16 v[36:39], v[158:161], v[190:193], v[36:39]
	v_mfma_f32_16x16x32_bf16 v[32:35], v[166:169], v[190:193], v[32:35]
	v_mfma_f32_16x16x32_bf16 v[20:23], v[158:161], v[198:201], v[20:23]
	v_mfma_f32_16x16x32_bf16 v[16:19], v[166:169], v[198:201], v[16:19]
	v_mfma_f32_16x16x32_bf16 v[4:7], v[158:161], v[206:209], v[4:7]
	v_mfma_f32_16x16x32_bf16 v[0:3], v[166:169], v[206:209], v[0:3]
	v_mfma_f32_16x16x32_bf16 v[52:55], v[162:165], v[178:181], v[52:55]
	v_mfma_f32_16x16x32_bf16 v[48:51], v[170:173], v[178:181], v[48:51]
	v_mfma_f32_16x16x32_bf16 v[36:39], v[162:165], v[194:197], v[36:39]
	v_mfma_f32_16x16x32_bf16 v[32:35], v[170:173], v[194:197], v[32:35]
	v_mfma_f32_16x16x32_bf16 v[20:23], v[162:165], v[202:205], v[20:23]
	v_mfma_f32_16x16x32_bf16 v[16:19], v[170:173], v[202:205], v[16:19]
	v_mfma_f32_16x16x32_bf16 v[4:7], v[162:165], v[210:213], v[4:7]
	v_mfma_f32_16x16x32_bf16 v[0:3], v[170:173], v[210:213], v[0:3]
	s_setprio 0
	s_barrier
	s_add_i32 s48, s48, 2
	s_add_u32 s66, s66, 0x100
	s_addc_u32 s67, s67, 0
	s_add_u32 s1, s1, 0x100
	s_addc_u32 s47, s47, 0
	s_cmp_gt_u32 s48, 29
	s_cbranch_scc0 .LBB0_581
	s_and_b64 vcc, exec, s[14:15]
	s_cbranch_vccz .LBB0_584
	s_barrier

; #define PG8_STAGE(bufoff, gbase, voff) do { _Pragma("unroll") for (int _i = 0; _i < 2; ++_i) \
;         __builtin_amdgcn_global_load_lds((const unsigned*)((const char*)(gbase) + (voff)[_i]), (LAS unsigned*)(lds + (bufoff) + ldsw + _i * 8192), 16, 0, 0); } while (0)
; #define PG8_LDA(dst, b, h) do { _Pragma("unroll") for (int m = 0; m < 4; ++m) _Pragma("unroll") for (int k = 0; k < 2; ++k) dst[m][k] = *(const LAS bf16x8*)(lds + PG8_SA(b, h) + aoff + m * 2048 + k * 1024); } while (0)
; #define PG8_LDB(dst, b, h) do { _Pragma("unroll") for (int n = 0; n < 2; ++n) _Pragma("unroll") for (int k = 0; k < 2; ++k) dst[n][k] = *(const LAS bf16x8*)(lds + PG8_SB(b, h) + boff + n * 2048 + k * 1024); } while (0)
; #define PG8_MMA(ai, bj, At, Bt) do { __builtin_amdgcn_s_setprio(1); _Pragma("unroll") for (int m = 0; m < 4; ++m) _Pragma("unroll") for (int n = 0; n < 2; ++n) _Pragma("unroll") for (int k = 0; k < 2; ++k) \
;         acc[ai][bj][m][n] = __builtin_amdgcn_mfma_f32_16x16x32_bf16(Bt[n][k], At[m][k], acc[ai][bj][m][n], 0, 0, 0); __builtin_amdgcn_s_setprio(0); } while (0)
; #define PG8_WAIT_V(n) asm volatile("s_waitcnt vmcnt(" #n ")" ::: "memory")
; #define PG8_WAIT_L(n) asm volatile("s_waitcnt lgkmcnt(" #n ")" ::: "memory")
; #define PG8_BAR __builtin_amdgcn_s_barrier()
; #define PG8_SCHED __builtin_amdgcn_sched_barrier(0)
; template <class Desc, class Epi>
; DI void gemm_phase(LAS unsigned char* lds, const Desc& D, const Epi& E, int wv) {
;     ...
;             const bool last = (t == nt - 2);
;             const char* a1 = cA + (size_t)(t + 1) * kstep;
;             const char* a2 = last ? nA : cA + (size_t)(t + 2) * kstep; const char* b2 = last ? nB : cB + (size_t)(t + 2) * kstep;
;             const char* a3 = a2 + kstep; const char* b3 = b2 + kstep;
;             PG8_LDB(B0, 0, 0); PG8_LDB(B1, 0, 1); PG8_SCHED; PG8_LDA(At, 0, 0); PG8_STAGE(PG8_SA(1, 1), a1 + hstepA, voffA);
;             PG8_WAIT_V(8); PG8_WAIT_L(0); PG8_BAR; PG8_MMA(0, 0, At, B0); PG8_MMA(0, 1, At, B1); PG8_BAR; PG8_SCHED;
;             PG8_LDA(At, 0, 1); PG8_STAGE(PG8_SB(0, 0), b2, voffB); PG8_STAGE(PG8_SB(0, 1), b2 + hstepB, voffB); PG8_STAGE(PG8_SA(0, 0), a2, voffA);
.LBB0_763:
	ds_read_b128 v[150:153], v147
	ds_read_b128 v[154:157], v147 offset:1024
	ds_read_b128 v[158:161], v147 offset:2048
	ds_read_b128 v[162:165], v147 offset:3072
	ds_read_b128 v[166:169], v148
	ds_read_b128 v[170:173], v148 offset:1024
	ds_read_b128 v[174:177], v148 offset:2048
	ds_read_b128 v[178:181], v148 offset:3072
	s_add_u32 s64, s62, 0x100
	s_addc_u32 s65, s63, 0
	s_add_u32 s50, s21, s62
	s_addc_u32 s51, s23, s63
	s_cmp_eq_u32 s49, 4
	s_cselect_b32 s53, 0, s64
	s_cselect_b32 s52, 0, s65
	s_cselect_b32 s66, s18, s50
	s_cselect_b32 s67, s19, s51
	s_add_u32 s68, s4, s53
	s_addc_u32 s69, s5, s52
	v_lshl_add_u64 v[144:145], v[136:137], 0, s[62:63]
	s_add_i32 m0, s3, 0xc000
	ds_read_b128 v[182:185], v149
	ds_read_b128 v[186:189], v149 offset:1024
	ds_read_b128 v[190:193], v149 offset:2048
	ds_read_b128 v[194:197], v149 offset:3072
	ds_read_b128 v[198:201], v149 offset:4096
	ds_read_b128 v[202:205], v149 offset:5120
	ds_read_b128 v[206:209], v149 offset:6144
	ds_read_b128 v[210:213], v149 offset:7168
	global_load_lds_dwordx4 v[144:145], off
	v_lshl_add_u64 v[144:145], v[138:139], 0, s[62:63]
	s_add_i32 m0, s3, 0xe000
	s_nop 0
	global_load_lds_dwordx4 v[144:145], off
	s_waitcnt vmcnt(8)
	s_waitcnt lgkmcnt(0)
	s_barrier
	s_setprio 1
	v_mfma_f32_16x16x32_bf16 v[124:127], v[150:153], v[182:185], v[124:127]
	v_mfma_f32_16x16x32_bf16 v[120:123], v[158:161], v[182:185], v[120:123]
	v_mfma_f32_16x16x32_bf16 v[108:111], v[150:153], v[190:193], v[108:111]
	v_mfma_f32_16x16x32_bf16 v[104:107], v[158:161], v[190:193], v[104:107]
	v_mfma_f32_16x16x32_bf16 v[92:95], v[150:153], v[198:201], v[92:95]
	v_mfma_f32_16x16x32_bf16 v[88:91], v[158:161], v[198:201], v[88:91]
	v_mfma_f32_16x16x32_bf16 v[76:79], v[150:153], v[206:209], v[76:79]
	v_mfma_f32_16x16x32_bf16 v[72:75], v[158:161], v[206:209], v[72:75]
	v_mfma_f32_16x16x32_bf16 v[124:127], v[154:157], v[186:189], v[124:127]
	v_mfma_f32_16x16x32_bf16 v[120:123], v[162:165], v[186:189], v[120:123]
	v_mfma_f32_16x16x32_bf16 v[108:111], v[154:157], v[194:197], v[108:111]
	v_mfma_f32_16x16x32_bf16 v[104:107], v[162:165], v[194:197], v[104:107]
	v_mfma_f32_16x16x32_bf16 v[92:95], v[154:157], v[202:205], v[92:95]
	v_mfma_f32_16x16x32_bf16 v[88:91], v[162:165], v[202:205], v[88:91]
	v_mfma_f32_16x16x32_bf16 v[76:79], v[154:157], v[210:213], v[76:79]
	v_mfma_f32_16x16x32_bf16 v[72:75], v[162:165], v[210:213], v[72:75]
	v_mfma_f32_16x16x32_bf16 v[116:119], v[166:169], v[182:185], v[116:119]
	v_mfma_f32_16x16x32_bf16 v[112:115], v[174:177], v[182:185], v[112:115]
	v_mfma_f32_16x16x32_bf16 v[100:103], v[166:169], v[190:193], v[100:103]
	v_mfma_f32_16x16x32_bf16 v[96:99], v[174:177], v[190:193], v[96:99]
	v_mfma_f32_16x16x32_bf16 v[84:87], v[166:169], v[198:201], v[84:87]
	v_mfma_f32_16x16x32_bf16 v[80:83], v[174:177], v[198:201], v[80:83]
	v_mfma_f32_16x16x32_bf16 v[68:71], v[166:169], v[206:209], v[68:71]
	v_mfma_f32_16x16x32_bf16 v[64:67], v[174:177], v[206:209], v[64:67]
	v_mfma_f32_16x16x32_bf16 v[116:119], v[170:173], v[186:189], v[116:119]
	v_mfma_f32_16x16x32_bf16 v[112:115], v[178:181], v[186:189], v[112:115]
	v_mfma_f32_16x16x32_bf16 v[100:103], v[170:173], v[194:197], v[100:103]
	v_mfma_f32_16x16x32_bf16 v[96:99], v[178:181], v[194:197], v[96:99]
	v_mfma_f32_16x16x32_bf16 v[84:87], v[170:173], v[202:205], v[84:87]
	v_mfma_f32_16x16x32_bf16 v[80:83], v[178:181], v[202:205], v[80:83]
	v_mfma_f32_16x16x32_bf16 v[68:71], v[170:173], v[210:213], v[68:71]
	v_mfma_f32_16x16x32_bf16 v[64:67], v[178:181], v[210:213], v[64:67]
	s_setprio 0
	s_barrier
	s_add_i32 s50, s43, s2
	v_lshl_add_u64 v[144:145], s[66:67], 0, v[130:131]
	s_mov_b32 m0, s50
	ds_read_b128 v[182:185], v149 offset:16384
	ds_read_b128 v[186:189], v149 offset:17408
	ds_read_b128 v[190:193], v149 offset:18432
	ds_read_b128 v[194:197], v149 offset:19456
	ds_read_b128 v[198:201], v149 offset:20480
	ds_read_b128 v[202:205], v149 offset:21504
	ds_read_b128 v[206:209], v149 offset:22528
	ds_read_b128 v[210:213], v149 offset:23552
	global_load_lds_dwordx4 v[144:145], off
	s_add_i32 m0, s50, 0x2000
	s_add_u32 s50, s66, 0x20000
	v_lshl_add_u64 v[214:215], s[66:67], 0, v[134:135]
	s_addc_u32 s51, s67, 0
	s_add_i32 s52, s46, s2
	global_load_lds_dwordx4 v[214:215], off
	v_lshl_add_u64 v[216:217], s[50:51], 0, v[130:131]
	s_mov_b32 m0, s52
	v_lshl_add_u64 v[218:219], s[68:69], 0, v[132:133]
	global_load_lds_dwordx4 v[216:217], off
	v_lshl_add_u64 v[216:217], s[50:51], 0, v[134:135]
	s_add_i32 m0, s52, 0x2000
	s_nop 0
	global_load_lds_dwordx4 v[216:217], off
	v_lshl_add_u64 v[216:217], s[68:69], 0, v[128:129]
	s_mov_b32 m0, s3
	s_nop 0
	global_load_lds_dwordx4 v[216:217], off
	s_mov_b32 m0, s28
	s_nop 0
	global_load_lds_dwordx4 v[218:219], off
	s_waitcnt vmcnt(8)
	s_waitcnt lgkmcnt(0)
	s_barrier
; #define PG8_STAGE(bufoff, gbase, voff) do { _Pragma("unroll") for (int _i = 0; _i < 2; ++_i) \
;         __builtin_amdgcn_global_load_lds((const unsigned*)((const char*)(gbase) + (voff)[_i]), (LAS unsigned*)(lds + (bufoff) + ldsw + _i * 8192), 16, 0, 0); } while (0)
; #define PG8_LDA(dst, b, h) do { _Pragma("unroll") for (int m = 0; m < 4; ++m) _Pragma("unroll") for (int k = 0; k < 2; ++k) dst[m][k] = *(const LAS bf16x8*)(lds + PG8_SA(b, h) + aoff + m * 2048 + k * 1024); } while (0)
; #define PG8_LDB(dst, b, h) do { _Pragma("unroll") for (int n = 0; n < 2; ++n) _Pragma("unroll") for (int k = 0; k < 2; ++k) dst[n][k] = *(const LAS bf16x8*)(lds + PG8_SB(b, h) + boff + n * 2048 + k * 1024); } while (0)
; #define PG8_MMA(ai, bj, At, Bt) do { __builtin_amdgcn_s_setprio(1); _Pragma("unroll") for (int m = 0; m < 4; ++m) _Pragma("unroll") for (int n = 0; n < 2; ++n) _Pragma("unroll") for (int k = 0; k < 2; ++k) \
;         acc[ai][bj][m][n] = __builtin_amdgcn_mfma_f32_16x16x32_bf16(Bt[n][k], At[m][k], acc[ai][bj][m][n], 0, 0, 0); __builtin_amdgcn_s_setprio(0); } while (0)
; #define PG8_WAIT_V(n) asm volatile("s_waitcnt vmcnt(" #n ")" ::: "memory")
; #define PG8_WAIT_L(n) asm volatile("s_waitcnt lgkmcnt(" #n ")" ::: "memory")
; #define PG8_BAR __builtin_amdgcn_s_barrier()
; #define PG8_SCHED __builtin_amdgcn_sched_barrier(0)
; template <class Desc, class Epi>
; DI void gemm_phase(LAS unsigned char* lds, const Desc& D, const Epi& E, int wv) {
;     ...
;             PG8_WAIT_V(8); PG8_WAIT_L(0); PG8_BAR; PG8_MMA(1, 0, At, B0); PG8_MMA(1, 1, At, B1); PG8_BAR; PG8_SCHED;
;             PG8_LDB(B0, 1, 0); PG8_LDB(B1, 1, 1); PG8_SCHED; PG8_LDA(At, 1, 0); PG8_STAGE(PG8_SA(0, 1), a2 + hstepA, voffA);
;             PG8_WAIT_V(8); PG8_WAIT_L(0); PG8_BAR; PG8_MMA(0, 0, At, B0); PG8_MMA(0, 1, At, B1); PG8_BAR; PG8_SCHED;
	s_setprio 1
	v_mfma_f32_16x16x32_bf16 v[60:63], v[150:153], v[182:185], v[60:63]
	v_mfma_f32_16x16x32_bf16 v[56:59], v[158:161], v[182:185], v[56:59]
	v_mfma_f32_16x16x32_bf16 v[44:47], v[150:153], v[190:193], v[44:47]
	v_mfma_f32_16x16x32_bf16 v[40:43], v[158:161], v[190:193], v[40:43]
	v_mfma_f32_16x16x32_bf16 v[28:31], v[150:153], v[198:201], v[28:31]
	v_mfma_f32_16x16x32_bf16 v[24:27], v[158:161], v[198:201], v[24:27]
	v_mfma_f32_16x16x32_bf16 v[12:15], v[150:153], v[206:209], v[12:15]
	v_mfma_f32_16x16x32_bf16 v[8:11], v[158:161], v[206:209], v[8:11]
	v_mfma_f32_16x16x32_bf16 v[60:63], v[154:157], v[186:189], v[60:63]
	v_mfma_f32_16x16x32_bf16 v[56:59], v[162:165], v[186:189], v[56:59]
	v_mfma_f32_16x16x32_bf16 v[44:47], v[154:157], v[194:197], v[44:47]
	v_mfma_f32_16x16x32_bf16 v[40:43], v[162:165], v[194:197], v[40:43]
	v_mfma_f32_16x16x32_bf16 v[28:31], v[154:157], v[202:205], v[28:31]
	v_mfma_f32_16x16x32_bf16 v[24:27], v[162:165], v[202:205], v[24:27]
	v_mfma_f32_16x16x32_bf16 v[12:15], v[154:157], v[210:213], v[12:15]
	v_mfma_f32_16x16x32_bf16 v[8:11], v[162:165], v[210:213], v[8:11]
	v_mfma_f32_16x16x32_bf16 v[52:55], v[166:169], v[182:185], v[52:55]
	v_mfma_f32_16x16x32_bf16 v[48:51], v[174:177], v[182:185], v[48:51]
	v_mfma_f32_16x16x32_bf16 v[36:39], v[166:169], v[190:193], v[36:39]
	v_mfma_f32_16x16x32_bf16 v[32:35], v[174:177], v[190:193], v[32:35]
	v_mfma_f32_16x16x32_bf16 v[20:23], v[166:169], v[198:201], v[20:23]
	v_mfma_f32_16x16x32_bf16 v[16:19], v[174:177], v[198:201], v[16:19]
	v_mfma_f32_16x16x32_bf16 v[4:7], v[166:169], v[206:209], v[4:7]
	v_mfma_f32_16x16x32_bf16 v[0:3], v[174:177], v[206:209], v[0:3]
	v_mfma_f32_16x16x32_bf16 v[52:55], v[170:173], v[186:189], v[52:55]
	v_mfma_f32_16x16x32_bf16 v[48:51], v[178:181], v[186:189], v[48:51]
	v_mfma_f32_16x16x32_bf16 v[36:39], v[170:173], v[194:197], v[36:39]
	v_mfma_f32_16x16x32_bf16 v[32:35], v[178:181], v[194:197], v[32:35]
	v_mfma_f32_16x16x32_bf16 v[20:23], v[170:173], v[202:205], v[20:23]
	v_mfma_f32_16x16x32_bf16 v[16:19], v[178:181], v[202:205], v[16:19]
	v_mfma_f32_16x16x32_bf16 v[4:7], v[170:173], v[210:213], v[4:7]
	v_mfma_f32_16x16x32_bf16 v[0:3], v[178:181], v[210:213], v[0:3]
	s_setprio 0
	s_barrier
	s_add_i32 s52, 0, 0x18000
	s_add_i32 s53, 0, 0x1c000
	v_add_u32_e32 v162, s52, v146
	v_add_u32_e32 v178, s53, v146
	ds_read_b128 v[150:153], v162
	ds_read_b128 v[154:157], v162 offset:1024
	ds_read_b128 v[158:161], v162 offset:2048
	ds_read_b128 v[162:165], v162 offset:3072
	ds_read_b128 v[166:169], v178
	ds_read_b128 v[170:173], v178 offset:1024
	ds_read_b128 v[174:177], v178 offset:2048
	ds_read_b128 v[178:181], v178 offset:3072
	s_add_u32 s50, s68, 0x20000
	s_addc_u32 s51, s69, 0
	s_mov_b32 m0, s29
	v_lshl_add_u64 v[220:221], s[50:51], 0, v[128:129]
	ds_read_b128 v[182:185], v149 offset:32768
	ds_read_b128 v[186:189], v149 offset:33792
	ds_read_b128 v[190:193], v149 offset:34816
	ds_read_b128 v[194:197], v149 offset:35840
	ds_read_b128 v[198:201], v149 offset:36864
	ds_read_b128 v[202:205], v149 offset:37888
	ds_read_b128 v[206:209], v149 offset:38912
	ds_read_b128 v[210:213], v149 offset:39936
	global_load_lds_dwordx4 v[220:221], off
	v_lshl_add_u64 v[220:221], s[50:51], 0, v[132:133]
	s_mov_b32 m0, s30
	s_nop 0
	global_load_lds_dwordx4 v[220:221], off
	s_waitcnt vmcnt(8)
	s_waitcnt lgkmcnt(0)
	s_barrier
	s_setprio 1
	v_mfma_f32_16x16x32_bf16 v[124:127], v[150:153], v[182:185], v[124:127]
	v_mfma_f32_16x16x32_bf16 v[120:123], v[158:161], v[182:185], v[120:123]
	v_mfma_f32_16x16x32_bf16 v[108:111], v[150:153], v[190:193], v[108:111]
	v_mfma_f32_16x16x32_bf16 v[104:107], v[158:161], v[190:193], v[104:107]
	v_mfma_f32_16x16x32_bf16 v[92:95], v[150:153], v[198:201], v[92:95]
	v_mfma_f32_16x16x32_bf16 v[88:91], v[158:161], v[198:201], v[88:91]
	v_mfma_f32_16x16x32_bf16 v[76:79], v[150:153], v[206:209], v[76:79]
	v_mfma_f32_16x16x32_bf16 v[72:75], v[158:161], v[206:209], v[72:75]
	v_mfma_f32_16x16x32_bf16 v[124:127], v[154:157], v[186:189], v[124:127]
	v_mfma_f32_16x16x32_bf16 v[120:123], v[162:165], v[186:189], v[120:123]
	v_mfma_f32_16x16x32_bf16 v[108:111], v[154:157], v[194:197], v[108:111]
	v_mfma_f32_16x16x32_bf16 v[104:107], v[162:165], v[194:197], v[104:107]
	v_mfma_f32_16x16x32_bf16 v[92:95], v[154:157], v[202:205], v[92:95]
	v_mfma_f32_16x16x32_bf16 v[88:91], v[162:165], v[202:205], v[88:91]
	v_mfma_f32_16x16x32_bf16 v[76:79], v[154:157], v[210:213], v[76:79]
	v_mfma_f32_16x16x32_bf16 v[72:75], v[162:165], v[210:213], v[72:75]
	v_mfma_f32_16x16x32_bf16 v[116:119], v[166:169], v[182:185], v[116:119]
	v_mfma_f32_16x16x32_bf16 v[112:115], v[174:177], v[182:185], v[112:115]
	v_mfma_f32_16x16x32_bf16 v[100:103], v[166:169], v[190:193], v[100:103]
	v_mfma_f32_16x16x32_bf16 v[96:99], v[174:177], v[190:193], v[96:99]
	v_mfma_f32_16x16x32_bf16 v[84:87], v[166:169], v[198:201], v[84:87]
	v_mfma_f32_16x16x32_bf16 v[80:83], v[174:177], v[198:201], v[80:83]
	v_mfma_f32_16x16x32_bf16 v[68:71], v[166:169], v[206:209], v[68:71]
	v_mfma_f32_16x16x32_bf16 v[64:67], v[174:177], v[206:209], v[64:67]
	v_mfma_f32_16x16x32_bf16 v[116:119], v[170:173], v[186:189], v[116:119]
	v_mfma_f32_16x16x32_bf16 v[112:115], v[178:181], v[186:189], v[112:115]
	v_mfma_f32_16x16x32_bf16 v[100:103], v[170:173], v[194:197], v[100:103]
	v_mfma_f32_16x16x32_bf16 v[96:99], v[178:181], v[194:197], v[96:99]
	v_mfma_f32_16x16x32_bf16 v[84:87], v[170:173], v[202:205], v[84:87]
	v_mfma_f32_16x16x32_bf16 v[80:83], v[178:181], v[202:205], v[80:83]
	v_mfma_f32_16x16x32_bf16 v[68:71], v[170:173], v[210:213], v[68:71]
	v_mfma_f32_16x16x32_bf16 v[64:67], v[178:181], v[210:213], v[64:67]
	s_setprio 0
	s_barrier
; #define PG8_STAGE(bufoff, gbase, voff) do { _Pragma("unroll") for (int _i = 0; _i < 2; ++_i) \
;         __builtin_amdgcn_global_load_lds((const unsigned*)((const char*)(gbase) + (voff)[_i]), (LAS unsigned*)(lds + (bufoff) + ldsw + _i * 8192), 16, 0, 0); } while (0)
; #define PG8_LDA(dst, b, h) do { _Pragma("unroll") for (int m = 0; m < 4; ++m) _Pragma("unroll") for (int k = 0; k < 2; ++k) dst[m][k] = *(const LAS bf16x8*)(lds + PG8_SA(b, h) + aoff + m * 2048 + k * 1024); } while (0)
; #define PG8_MMA(ai, bj, At, Bt) do { __builtin_amdgcn_s_setprio(1); _Pragma("unroll") for (int m = 0; m < 4; ++m) _Pragma("unroll") for (int n = 0; n < 2; ++n) _Pragma("unroll") for (int k = 0; k < 2; ++k) \
;         acc[ai][bj][m][n] = __builtin_amdgcn_mfma_f32_16x16x32_bf16(Bt[n][k], At[m][k], acc[ai][bj][m][n], 0, 0, 0); __builtin_amdgcn_s_setprio(0); } while (0)
; #define PG8_WAIT_V(n) asm volatile("s_waitcnt vmcnt(" #n ")" ::: "memory")
; #define PG8_WAIT_L(n) asm volatile("s_waitcnt lgkmcnt(" #n ")" ::: "memory")
; #define PG8_BAR __builtin_amdgcn_s_barrier()
; #define PG8_SCHED __builtin_amdgcn_sched_barrier(0)
; template <class Desc, class Epi>
; DI void gemm_phase(LAS unsigned char* lds, const Desc& D, const Epi& E, int wv) {
;     ...
;             PG8_LDA(At, 1, 1); PG8_STAGE(PG8_SB(1, 0), b3, voffB); PG8_STAGE(PG8_SB(1, 1), b3 + hstepB, voffB); PG8_STAGE(PG8_SA(1, 0), a3, voffA);
;             PG8_WAIT_V(8); PG8_WAIT_L(0); PG8_BAR; PG8_MMA(1, 0, At, B0); PG8_MMA(1, 1, At, B1); PG8_BAR; PG8_SCHED;
;         }
;         if (wr == 0) PG8_BAR;
	s_add_i32 s50, s52, s2
	v_lshl_add_u64 v[144:145], v[144:145], 0, s[8:9]
	s_mov_b32 m0, s50
	ds_read_b128 v[182:185], v149 offset:49152
	ds_read_b128 v[186:189], v149 offset:50176
	ds_read_b128 v[190:193], v149 offset:51200
	ds_read_b128 v[194:197], v149 offset:52224
	ds_read_b128 v[198:201], v149 offset:53248
	ds_read_b128 v[202:205], v149 offset:54272
	ds_read_b128 v[206:209], v149 offset:55296
	ds_read_b128 v[210:213], v149 offset:56320
	global_load_lds_dwordx4 v[144:145], off
	s_add_i32 m0, s50, 0x2000
	s_add_u32 s50, s66, 0x20080
	v_lshl_add_u64 v[144:145], v[214:215], 0, s[8:9]
	s_addc_u32 s51, s67, 0
	s_add_i32 s52, s53, s2
	global_load_lds_dwordx4 v[144:145], off
	v_lshl_add_u64 v[144:145], s[50:51], 0, v[130:131]
	s_mov_b32 m0, s52
	s_nop 0
	global_load_lds_dwordx4 v[144:145], off
	v_lshl_add_u64 v[144:145], s[50:51], 0, v[134:135]
	s_add_i32 m0, s52, 0x2000
	s_nop 0
	global_load_lds_dwordx4 v[144:145], off
	v_lshl_add_u64 v[144:145], v[216:217], 0, s[8:9]
	s_mov_b32 m0, s40
	s_nop 0
	global_load_lds_dwordx4 v[144:145], off
	v_lshl_add_u64 v[144:145], v[218:219], 0, s[8:9]
	s_mov_b32 m0, s41
	s_nop 0
	global_load_lds_dwordx4 v[144:145], off
	s_waitcnt vmcnt(8)
	s_waitcnt lgkmcnt(0)
	s_barrier
	s_setprio 1
	v_mfma_f32_16x16x32_bf16 v[60:63], v[150:153], v[182:185], v[60:63]
	v_mfma_f32_16x16x32_bf16 v[56:59], v[158:161], v[182:185], v[56:59]
	v_mfma_f32_16x16x32_bf16 v[44:47], v[150:153], v[190:193], v[44:47]
	v_mfma_f32_16x16x32_bf16 v[40:43], v[158:161], v[190:193], v[40:43]
	v_mfma_f32_16x16x32_bf16 v[28:31], v[150:153], v[198:201], v[28:31]
	v_mfma_f32_16x16x32_bf16 v[24:27], v[158:161], v[198:201], v[24:27]
	v_mfma_f32_16x16x32_bf16 v[12:15], v[150:153], v[206:209], v[12:15]
	v_mfma_f32_16x16x32_bf16 v[8:11], v[158:161], v[206:209], v[8:11]
	v_mfma_f32_16x16x32_bf16 v[60:63], v[154:157], v[186:189], v[60:63]
	v_mfma_f32_16x16x32_bf16 v[56:59], v[162:165], v[186:189], v[56:59]
	v_mfma_f32_16x16x32_bf16 v[44:47], v[154:157], v[194:197], v[44:47]
	v_mfma_f32_16x16x32_bf16 v[40:43], v[162:165], v[194:197], v[40:43]
	v_mfma_f32_16x16x32_bf16 v[28:31], v[154:157], v[202:205], v[28:31]
	v_mfma_f32_16x16x32_bf16 v[24:27], v[162:165], v[202:205], v[24:27]
	v_mfma_f32_16x16x32_bf16 v[12:15], v[154:157], v[210:213], v[12:15]
	v_mfma_f32_16x16x32_bf16 v[8:11], v[162:165], v[210:213], v[8:11]
	v_mfma_f32_16x16x32_bf16 v[52:55], v[166:169], v[182:185], v[52:55]
	v_mfma_f32_16x16x32_bf16 v[48:51], v[174:177], v[182:185], v[48:51]
	v_mfma_f32_16x16x32_bf16 v[36:39], v[166:169], v[190:193], v[36:39]
	v_mfma_f32_16x16x32_bf16 v[32:35], v[174:177], v[190:193], v[32:35]
	v_mfma_f32_16x16x32_bf16 v[20:23], v[166:169], v[198:201], v[20:23]
	v_mfma_f32_16x16x32_bf16 v[16:19], v[174:177], v[198:201], v[16:19]
	v_mfma_f32_16x16x32_bf16 v[4:7], v[166:169], v[206:209], v[4:7]
	v_mfma_f32_16x16x32_bf16 v[0:3], v[174:177], v[206:209], v[0:3]
	v_mfma_f32_16x16x32_bf16 v[52:55], v[170:173], v[186:189], v[52:55]
	v_mfma_f32_16x16x32_bf16 v[48:51], v[178:181], v[186:189], v[48:51]
	v_mfma_f32_16x16x32_bf16 v[36:39], v[170:173], v[194:197], v[36:39]
	v_mfma_f32_16x16x32_bf16 v[32:35], v[178:181], v[194:197], v[32:35]
	v_mfma_f32_16x16x32_bf16 v[20:23], v[170:173], v[202:205], v[20:23]
	v_mfma_f32_16x16x32_bf16 v[16:19], v[178:181], v[202:205], v[16:19]
	v_mfma_f32_16x16x32_bf16 v[4:7], v[170:173], v[210:213], v[4:7]
	v_mfma_f32_16x16x32_bf16 v[0:3], v[178:181], v[210:213], v[0:3]
	s_setprio 0
	s_barrier
	s_add_i32 s49, s49, 2
	s_cmp_gt_u32 s49, 5
	s_mov_b64 s[62:63], s[64:65]
	s_cbranch_scc0 .LBB0_763
	s_and_b64 vcc, exec, s[14:15]
	s_cbranch_vccz .LBB0_766
	s_barrier

; #define PG8_STAGE(bufoff, gbase, voff) do { _Pragma("unroll") for (int _i = 0; _i < 2; ++_i) \
;         __builtin_amdgcn_global_load_lds((const unsigned*)((const char*)(gbase) + (voff)[_i]), (LAS unsigned*)(lds + (bufoff) + ldsw + _i * 8192), 16, 0, 0); } while (0)
; #define PG8_LDA(dst, b, h) do { _Pragma("unroll") for (int m = 0; m < 4; ++m) _Pragma("unroll") for (int k = 0; k < 2; ++k) dst[m][k] = *(const LAS bf16x8*)(lds + PG8_SA(b, h) + aoff + m * 2048 + k * 1024); } while (0)
; #define PG8_LDB(dst, b, h) do { _Pragma("unroll") for (int n = 0; n < 2; ++n) _Pragma("unroll") for (int k = 0; k < 2; ++k) dst[n][k] = *(const LAS bf16x8*)(lds + PG8_SB(b, h) + boff + n * 2048 + k * 1024); } while (0)
; #define PG8_MMA(ai, bj, At, Bt) do { __builtin_amdgcn_s_setprio(1); _Pragma("unroll") for (int m = 0; m < 4; ++m) _Pragma("unroll") for (int n = 0; n < 2; ++n) _Pragma("unroll") for (int k = 0; k < 2; ++k) \
;         acc[ai][bj][m][n] = __builtin_amdgcn_mfma_f32_16x16x32_bf16(Bt[n][k], At[m][k], acc[ai][bj][m][n], 0, 0, 0); __builtin_amdgcn_s_setprio(0); } while (0)
; #define PG8_WAIT_V(n) asm volatile("s_waitcnt vmcnt(" #n ")" ::: "memory")
; #define PG8_WAIT_L(n) asm volatile("s_waitcnt lgkmcnt(" #n ")" ::: "memory")
; #define PG8_BAR __builtin_amdgcn_s_barrier()
; #define PG8_SCHED __builtin_amdgcn_sched_barrier(0)
; template <class Desc, class Epi>
; DI void gemm_phase(LAS unsigned char* lds, const Desc& D, const Epi& E, int wv) {
;     ...
;             const bool last = (t == nt - 2);
;             const char* a1 = cA + (size_t)(t + 1) * kstep;
;             const char* a2 = last ? nA : cA + (size_t)(t + 2) * kstep; const char* b2 = last ? nB : cB + (size_t)(t + 2) * kstep;
;             const char* a3 = a2 + kstep; const char* b3 = b2 + kstep;
;             PG8_LDB(B0, 0, 0); PG8_LDB(B1, 0, 1); PG8_SCHED; PG8_LDA(At, 0, 0); PG8_STAGE(PG8_SA(1, 1), a1 + hstepA, voffA);
;             PG8_WAIT_V(8); PG8_WAIT_L(0); PG8_BAR; PG8_MMA(0, 0, At, B0); PG8_MMA(0, 1, At, B1); PG8_BAR; PG8_SCHED;
;             PG8_LDA(At, 0, 1); PG8_STAGE(PG8_SB(0, 0), b2, voffB); PG8_STAGE(PG8_SB(0, 1), b2 + hstepB, voffB); PG8_STAGE(PG8_SA(0, 0), a2, voffA);
.LBB0_831:
	ds_read_b128 v[128:131], v169
	ds_read_b128 v[132:135], v169 offset:1024
	ds_read_b128 v[136:139], v169 offset:2048
	ds_read_b128 v[140:143], v169 offset:3072
	ds_read_b128 v[160:163], v170
	ds_read_b128 v[164:167], v170 offset:1024
	ds_read_b128 v[172:175], v170 offset:2048
	ds_read_b128 v[176:179], v170 offset:3072
	s_add_u32 s51, s6, 0xfff80080
	s_addc_u32 s52, s7, -1
	s_cmp_eq_u32 s50, 28
	s_cselect_b32 s69, s19, s52
	s_cselect_b32 s68, s18, s51
	s_cselect_b32 s67, s21, s49
	s_cselect_b32 s66, s20, s23
	v_lshl_add_u64 v[212:213], s[6:7], 0, v[152:153]
	s_add_i32 m0, s28, 0xc000
	ds_read_b128 v[180:183], v171
	ds_read_b128 v[184:187], v171 offset:1024
	ds_read_b128 v[188:191], v171 offset:2048
	ds_read_b128 v[192:195], v171 offset:3072
	ds_read_b128 v[196:199], v171 offset:4096
	ds_read_b128 v[200:203], v171 offset:5120
	ds_read_b128 v[204:207], v171 offset:6144
	ds_read_b128 v[208:211], v171 offset:7168
	global_load_lds_dwordx4 v[212:213], off
	v_lshl_add_u64 v[212:213], s[6:7], 0, v[154:155]
	s_add_i32 m0, s28, 0xe000
	s_nop 0
	global_load_lds_dwordx4 v[212:213], off
	s_waitcnt vmcnt(8)
	s_waitcnt lgkmcnt(0)
	s_barrier
	s_setprio 1
	v_mfma_f32_16x16x32_bf16 v[124:127], v[128:131], v[180:183], v[124:127]
	v_mfma_f32_16x16x32_bf16 v[120:123], v[136:139], v[180:183], v[120:123]
	v_mfma_f32_16x16x32_bf16 v[112:115], v[128:131], v[188:191], v[112:115]
	v_mfma_f32_16x16x32_bf16 v[108:111], v[136:139], v[188:191], v[108:111]
	v_mfma_f32_16x16x32_bf16 v[100:103], v[128:131], v[196:199], v[100:103]
	v_mfma_f32_16x16x32_bf16 v[92:95], v[136:139], v[196:199], v[92:95]
	v_mfma_f32_16x16x32_bf16 v[84:87], v[128:131], v[204:207], v[84:87]
	v_mfma_f32_16x16x32_bf16 v[76:79], v[136:139], v[204:207], v[76:79]
	v_mfma_f32_16x16x32_bf16 v[124:127], v[132:135], v[184:187], v[124:127]
	v_mfma_f32_16x16x32_bf16 v[120:123], v[140:143], v[184:187], v[120:123]
	v_mfma_f32_16x16x32_bf16 v[112:115], v[132:135], v[192:195], v[112:115]
	v_mfma_f32_16x16x32_bf16 v[108:111], v[140:143], v[192:195], v[108:111]
	v_mfma_f32_16x16x32_bf16 v[100:103], v[132:135], v[200:203], v[100:103]
	v_mfma_f32_16x16x32_bf16 v[92:95], v[140:143], v[200:203], v[92:95]
	v_mfma_f32_16x16x32_bf16 v[84:87], v[132:135], v[208:211], v[84:87]
	v_mfma_f32_16x16x32_bf16 v[76:79], v[140:143], v[208:211], v[76:79]
	v_mfma_f32_16x16x32_bf16 v[116:119], v[160:163], v[180:183], v[116:119]
	v_mfma_f32_16x16x32_bf16 v[104:107], v[172:175], v[180:183], v[104:107]
	v_mfma_f32_16x16x32_bf16 v[96:99], v[160:163], v[188:191], v[96:99]
	v_mfma_f32_16x16x32_bf16 v[88:91], v[172:175], v[188:191], v[88:91]
	v_mfma_f32_16x16x32_bf16 v[80:83], v[160:163], v[196:199], v[80:83]
	v_mfma_f32_16x16x32_bf16 v[72:75], v[172:175], v[196:199], v[72:75]
	v_mfma_f32_16x16x32_bf16 v[68:71], v[160:163], v[204:207], v[68:71]
	v_mfma_f32_16x16x32_bf16 v[64:67], v[172:175], v[204:207], v[64:67]
	v_mfma_f32_16x16x32_bf16 v[116:119], v[164:167], v[184:187], v[116:119]
	v_mfma_f32_16x16x32_bf16 v[104:107], v[176:179], v[184:187], v[104:107]
	v_mfma_f32_16x16x32_bf16 v[96:99], v[164:167], v[192:195], v[96:99]
	v_mfma_f32_16x16x32_bf16 v[88:91], v[176:179], v[192:195], v[88:91]
	v_mfma_f32_16x16x32_bf16 v[80:83], v[164:167], v[200:203], v[80:83]
	v_mfma_f32_16x16x32_bf16 v[72:75], v[176:179], v[200:203], v[72:75]
	v_mfma_f32_16x16x32_bf16 v[68:71], v[164:167], v[208:211], v[68:71]
	v_mfma_f32_16x16x32_bf16 v[64:67], v[176:179], v[208:211], v[64:67]
	s_setprio 0
	s_barrier
	s_add_i32 s51, s46, s2
	v_lshl_add_u64 v[212:213], s[66:67], 0, v[148:149]
	s_mov_b32 m0, s51
	ds_read_b128 v[180:183], v171 offset:16384
	ds_read_b128 v[184:187], v171 offset:17408
	ds_read_b128 v[188:191], v171 offset:18432
	ds_read_b128 v[192:195], v171 offset:19456
	ds_read_b128 v[196:199], v171 offset:20480
	ds_read_b128 v[200:203], v171 offset:21504
	ds_read_b128 v[204:207], v171 offset:22528
	ds_read_b128 v[208:211], v171 offset:23552
	global_load_lds_dwordx4 v[212:213], off
	s_add_i32 m0, s51, 0x2000
	s_add_u32 s52, s66, 0x80000
	v_lshl_add_u64 v[214:215], s[66:67], 0, v[144:145]
	s_addc_u32 s53, s67, 0
	s_add_i32 s51, s47, s2
	global_load_lds_dwordx4 v[214:215], off
	v_lshl_add_u64 v[216:217], s[52:53], 0, v[148:149]
	s_mov_b32 m0, s51
	v_lshl_add_u64 v[218:219], s[68:69], 0, v[146:147]
	global_load_lds_dwordx4 v[216:217], off
	v_lshl_add_u64 v[216:217], s[52:53], 0, v[144:145]
	s_add_i32 m0, s51, 0x2000
	s_nop 0
	global_load_lds_dwordx4 v[216:217], off
	v_lshl_add_u64 v[216:217], s[68:69], 0, v[150:151]
	s_mov_b32 m0, s28
	s_nop 0
	global_load_lds_dwordx4 v[216:217], off
	s_mov_b32 m0, s29
	s_nop 0
	global_load_lds_dwordx4 v[218:219], off
	s_waitcnt vmcnt(8)
	s_waitcnt lgkmcnt(0)
	s_barrier
; #define PG8_STAGE(bufoff, gbase, voff) do { _Pragma("unroll") for (int _i = 0; _i < 2; ++_i) \
;         __builtin_amdgcn_global_load_lds((const unsigned*)((const char*)(gbase) + (voff)[_i]), (LAS unsigned*)(lds + (bufoff) + ldsw + _i * 8192), 16, 0, 0); } while (0)
; #define PG8_LDA(dst, b, h) do { _Pragma("unroll") for (int m = 0; m < 4; ++m) _Pragma("unroll") for (int k = 0; k < 2; ++k) dst[m][k] = *(const LAS bf16x8*)(lds + PG8_SA(b, h) + aoff + m * 2048 + k * 1024); } while (0)
; #define PG8_LDB(dst, b, h) do { _Pragma("unroll") for (int n = 0; n < 2; ++n) _Pragma("unroll") for (int k = 0; k < 2; ++k) dst[n][k] = *(const LAS bf16x8*)(lds + PG8_SB(b, h) + boff + n * 2048 + k * 1024); } while (0)
; #define PG8_MMA(ai, bj, At, Bt) do { __builtin_amdgcn_s_setprio(1); _Pragma("unroll") for (int m = 0; m < 4; ++m) _Pragma("unroll") for (int n = 0; n < 2; ++n) _Pragma("unroll") for (int k = 0; k < 2; ++k) \
;         acc[ai][bj][m][n] = __builtin_amdgcn_mfma_f32_16x16x32_bf16(Bt[n][k], At[m][k], acc[ai][bj][m][n], 0, 0, 0); __builtin_amdgcn_s_setprio(0); } while (0)
; #define PG8_WAIT_V(n) asm volatile("s_waitcnt vmcnt(" #n ")" ::: "memory")
; #define PG8_WAIT_L(n) asm volatile("s_waitcnt lgkmcnt(" #n ")" ::: "memory")
; #define PG8_BAR __builtin_amdgcn_s_barrier()
; #define PG8_SCHED __builtin_amdgcn_sched_barrier(0)
; template <class Desc, class Epi>
; DI void gemm_phase(LAS unsigned char* lds, const Desc& D, const Epi& E, int wv) {
;     ...
;             PG8_WAIT_V(8); PG8_WAIT_L(0); PG8_BAR; PG8_MMA(1, 0, At, B0); PG8_MMA(1, 1, At, B1); PG8_BAR; PG8_SCHED;
;             PG8_LDB(B0, 1, 0); PG8_LDB(B1, 1, 1); PG8_SCHED; PG8_LDA(At, 1, 0); PG8_STAGE(PG8_SA(0, 1), a2 + hstepA, voffA);
;             PG8_WAIT_V(8); PG8_WAIT_L(0); PG8_BAR; PG8_MMA(0, 0, At, B0); PG8_MMA(0, 1, At, B1); PG8_BAR; PG8_SCHED;
	s_setprio 1
	v_mfma_f32_16x16x32_bf16 v[60:63], v[128:131], v[180:183], v[60:63]
	v_mfma_f32_16x16x32_bf16 v[56:59], v[136:139], v[180:183], v[56:59]
	v_mfma_f32_16x16x32_bf16 v[52:55], v[128:131], v[188:191], v[52:55]
	v_mfma_f32_16x16x32_bf16 v[44:47], v[136:139], v[188:191], v[44:47]
	v_mfma_f32_16x16x32_bf16 v[36:39], v[128:131], v[196:199], v[36:39]
	v_mfma_f32_16x16x32_bf16 v[28:31], v[136:139], v[196:199], v[28:31]
	v_mfma_f32_16x16x32_bf16 v[20:23], v[128:131], v[204:207], v[20:23]
	v_mfma_f32_16x16x32_bf16 v[12:15], v[136:139], v[204:207], v[12:15]
	v_mfma_f32_16x16x32_bf16 v[60:63], v[132:135], v[184:187], v[60:63]
	v_mfma_f32_16x16x32_bf16 v[56:59], v[140:143], v[184:187], v[56:59]
	v_mfma_f32_16x16x32_bf16 v[52:55], v[132:135], v[192:195], v[52:55]
	v_mfma_f32_16x16x32_bf16 v[44:47], v[140:143], v[192:195], v[44:47]
	v_mfma_f32_16x16x32_bf16 v[36:39], v[132:135], v[200:203], v[36:39]
	v_mfma_f32_16x16x32_bf16 v[28:31], v[140:143], v[200:203], v[28:31]
	v_mfma_f32_16x16x32_bf16 v[20:23], v[132:135], v[208:211], v[20:23]
	v_mfma_f32_16x16x32_bf16 v[12:15], v[140:143], v[208:211], v[12:15]
	v_mfma_f32_16x16x32_bf16 v[48:51], v[160:163], v[180:183], v[48:51]
	v_mfma_f32_16x16x32_bf16 v[40:43], v[172:175], v[180:183], v[40:43]
	v_mfma_f32_16x16x32_bf16 v[32:35], v[160:163], v[188:191], v[32:35]
	v_mfma_f32_16x16x32_bf16 v[24:27], v[172:175], v[188:191], v[24:27]
	v_mfma_f32_16x16x32_bf16 v[16:19], v[160:163], v[196:199], v[16:19]
	v_mfma_f32_16x16x32_bf16 v[8:11], v[172:175], v[196:199], v[8:11]
	v_mfma_f32_16x16x32_bf16 v[4:7], v[160:163], v[204:207], v[4:7]
	v_mfma_f32_16x16x32_bf16 v[0:3], v[172:175], v[204:207], v[0:3]
	v_mfma_f32_16x16x32_bf16 v[48:51], v[164:167], v[184:187], v[48:51]
	v_mfma_f32_16x16x32_bf16 v[40:43], v[176:179], v[184:187], v[40:43]
	v_mfma_f32_16x16x32_bf16 v[32:35], v[164:167], v[192:195], v[32:35]
	v_mfma_f32_16x16x32_bf16 v[24:27], v[176:179], v[192:195], v[24:27]
	v_mfma_f32_16x16x32_bf16 v[16:19], v[164:167], v[200:203], v[16:19]
	v_mfma_f32_16x16x32_bf16 v[8:11], v[176:179], v[200:203], v[8:11]
	v_mfma_f32_16x16x32_bf16 v[4:7], v[164:167], v[208:211], v[4:7]
	v_mfma_f32_16x16x32_bf16 v[0:3], v[176:179], v[208:211], v[0:3]
	s_setprio 0
	s_barrier
	s_add_i32 s51, 0, 0x18000
	s_add_i32 s60, 0, 0x1c000
	v_add_u32_e32 v140, s51, v168
	v_add_u32_e32 v176, s60, v168
	ds_read_b128 v[128:131], v140
	ds_read_b128 v[132:135], v140 offset:1024
	ds_read_b128 v[136:139], v140 offset:2048
	ds_read_b128 v[140:143], v140 offset:3072
	ds_read_b128 v[160:163], v176
	ds_read_b128 v[164:167], v176 offset:1024
	ds_read_b128 v[172:175], v176 offset:2048
	ds_read_b128 v[176:179], v176 offset:3072
	s_add_u32 s52, s68, 0x80000
	s_addc_u32 s53, s69, 0
	s_mov_b32 m0, s30
	v_lshl_add_u64 v[220:221], s[52:53], 0, v[150:151]
	ds_read_b128 v[180:183], v171 offset:32768
	ds_read_b128 v[184:187], v171 offset:33792
	ds_read_b128 v[188:191], v171 offset:34816
	ds_read_b128 v[192:195], v171 offset:35840
	ds_read_b128 v[196:199], v171 offset:36864
	ds_read_b128 v[200:203], v171 offset:37888
	ds_read_b128 v[204:207], v171 offset:38912
	ds_read_b128 v[208:211], v171 offset:39936
	global_load_lds_dwordx4 v[220:221], off
	v_lshl_add_u64 v[220:221], s[52:53], 0, v[146:147]
	s_mov_b32 m0, s31
	s_nop 0
	global_load_lds_dwordx4 v[220:221], off
	s_waitcnt vmcnt(8)
	s_waitcnt lgkmcnt(0)
	s_barrier
	s_setprio 1
	v_mfma_f32_16x16x32_bf16 v[124:127], v[128:131], v[180:183], v[124:127]
	v_mfma_f32_16x16x32_bf16 v[120:123], v[136:139], v[180:183], v[120:123]
	v_mfma_f32_16x16x32_bf16 v[112:115], v[128:131], v[188:191], v[112:115]
	v_mfma_f32_16x16x32_bf16 v[108:111], v[136:139], v[188:191], v[108:111]
	v_mfma_f32_16x16x32_bf16 v[100:103], v[128:131], v[196:199], v[100:103]
	v_mfma_f32_16x16x32_bf16 v[92:95], v[136:139], v[196:199], v[92:95]
	v_mfma_f32_16x16x32_bf16 v[84:87], v[128:131], v[204:207], v[84:87]
	v_mfma_f32_16x16x32_bf16 v[76:79], v[136:139], v[204:207], v[76:79]
	v_mfma_f32_16x16x32_bf16 v[124:127], v[132:135], v[184:187], v[124:127]
	v_mfma_f32_16x16x32_bf16 v[120:123], v[140:143], v[184:187], v[120:123]
	v_mfma_f32_16x16x32_bf16 v[112:115], v[132:135], v[192:195], v[112:115]
	v_mfma_f32_16x16x32_bf16 v[108:111], v[140:143], v[192:195], v[108:111]
	v_mfma_f32_16x16x32_bf16 v[100:103], v[132:135], v[200:203], v[100:103]
	v_mfma_f32_16x16x32_bf16 v[92:95], v[140:143], v[200:203], v[92:95]
	v_mfma_f32_16x16x32_bf16 v[84:87], v[132:135], v[208:211], v[84:87]
	v_mfma_f32_16x16x32_bf16 v[76:79], v[140:143], v[208:211], v[76:79]
	v_mfma_f32_16x16x32_bf16 v[116:119], v[160:163], v[180:183], v[116:119]
	v_mfma_f32_16x16x32_bf16 v[104:107], v[172:175], v[180:183], v[104:107]
	v_mfma_f32_16x16x32_bf16 v[96:99], v[160:163], v[188:191], v[96:99]
	v_mfma_f32_16x16x32_bf16 v[88:91], v[172:175], v[188:191], v[88:91]
	v_mfma_f32_16x16x32_bf16 v[80:83], v[160:163], v[196:199], v[80:83]
	v_mfma_f32_16x16x32_bf16 v[72:75], v[172:175], v[196:199], v[72:75]
	v_mfma_f32_16x16x32_bf16 v[68:71], v[160:163], v[204:207], v[68:71]
	v_mfma_f32_16x16x32_bf16 v[64:67], v[172:175], v[204:207], v[64:67]
	v_mfma_f32_16x16x32_bf16 v[116:119], v[164:167], v[184:187], v[116:119]
	v_mfma_f32_16x16x32_bf16 v[104:107], v[176:179], v[184:187], v[104:107]
	v_mfma_f32_16x16x32_bf16 v[96:99], v[164:167], v[192:195], v[96:99]
	v_mfma_f32_16x16x32_bf16 v[88:91], v[176:179], v[192:195], v[88:91]
	v_mfma_f32_16x16x32_bf16 v[80:83], v[164:167], v[200:203], v[80:83]
	v_mfma_f32_16x16x32_bf16 v[72:75], v[176:179], v[200:203], v[72:75]
	v_mfma_f32_16x16x32_bf16 v[68:71], v[164:167], v[208:211], v[68:71]
	v_mfma_f32_16x16x32_bf16 v[64:67], v[176:179], v[208:211], v[64:67]
	s_setprio 0
	s_barrier
; #define PG8_STAGE(bufoff, gbase, voff) do { _Pragma("unroll") for (int _i = 0; _i < 2; ++_i) \
;         __builtin_amdgcn_global_load_lds((const unsigned*)((const char*)(gbase) + (voff)[_i]), (LAS unsigned*)(lds + (bufoff) + ldsw + _i * 8192), 16, 0, 0); } while (0)
; #define PG8_LDA(dst, b, h) do { _Pragma("unroll") for (int m = 0; m < 4; ++m) _Pragma("unroll") for (int k = 0; k < 2; ++k) dst[m][k] = *(const LAS bf16x8*)(lds + PG8_SA(b, h) + aoff + m * 2048 + k * 1024); } while (0)
; #define PG8_MMA(ai, bj, At, Bt) do { __builtin_amdgcn_s_setprio(1); _Pragma("unroll") for (int m = 0; m < 4; ++m) _Pragma("unroll") for (int n = 0; n < 2; ++n) _Pragma("unroll") for (int k = 0; k < 2; ++k) \
;         acc[ai][bj][m][n] = __builtin_amdgcn_mfma_f32_16x16x32_bf16(Bt[n][k], At[m][k], acc[ai][bj][m][n], 0, 0, 0); __builtin_amdgcn_s_setprio(0); } while (0)
; #define PG8_WAIT_V(n) asm volatile("s_waitcnt vmcnt(" #n ")" ::: "memory")
; #define PG8_WAIT_L(n) asm volatile("s_waitcnt lgkmcnt(" #n ")" ::: "memory")
; #define PG8_BAR __builtin_amdgcn_s_barrier()
; #define PG8_SCHED __builtin_amdgcn_sched_barrier(0)
; template <class Desc, class Epi>
; DI void gemm_phase(LAS unsigned char* lds, const Desc& D, const Epi& E, int wv) {
;     ...
;             PG8_LDA(At, 1, 1); PG8_STAGE(PG8_SB(1, 0), b3, voffB); PG8_STAGE(PG8_SB(1, 1), b3 + hstepB, voffB); PG8_STAGE(PG8_SA(1, 0), a3, voffA);
;             PG8_WAIT_V(8); PG8_WAIT_L(0); PG8_BAR; PG8_MMA(1, 0, At, B0); PG8_MMA(1, 1, At, B1); PG8_BAR; PG8_SCHED;
;         }
;         if (wr == 0) PG8_BAR;
	s_add_i32 s51, s51, s2
	v_lshl_add_u64 v[212:213], v[212:213], 0, s[10:11]
	s_mov_b32 m0, s51
	ds_read_b128 v[180:183], v171 offset:49152
	ds_read_b128 v[184:187], v171 offset:50176
	ds_read_b128 v[188:191], v171 offset:51200
	ds_read_b128 v[192:195], v171 offset:52224
	ds_read_b128 v[196:199], v171 offset:53248
	ds_read_b128 v[200:203], v171 offset:54272
	ds_read_b128 v[204:207], v171 offset:55296
	ds_read_b128 v[208:211], v171 offset:56320
	global_load_lds_dwordx4 v[212:213], off
	s_add_i32 m0, s51, 0x2000
	s_add_u32 s52, s66, 0x80080
	v_lshl_add_u64 v[212:213], v[214:215], 0, s[10:11]
	s_addc_u32 s53, s67, 0
	s_add_i32 s51, s60, s2
	global_load_lds_dwordx4 v[212:213], off
	v_lshl_add_u64 v[212:213], s[52:53], 0, v[148:149]
	s_mov_b32 m0, s51
	s_nop 0
	global_load_lds_dwordx4 v[212:213], off
	v_lshl_add_u64 v[212:213], s[52:53], 0, v[144:145]
	s_add_i32 m0, s51, 0x2000
	s_nop 0
	global_load_lds_dwordx4 v[212:213], off
	v_lshl_add_u64 v[212:213], v[216:217], 0, s[10:11]
	s_mov_b32 m0, s41
	s_nop 0
	global_load_lds_dwordx4 v[212:213], off
	v_lshl_add_u64 v[212:213], v[218:219], 0, s[10:11]
	s_mov_b32 m0, s42
	s_nop 0
	global_load_lds_dwordx4 v[212:213], off
	s_waitcnt vmcnt(8)
	s_waitcnt lgkmcnt(0)
	s_barrier
	s_setprio 1
	v_mfma_f32_16x16x32_bf16 v[60:63], v[128:131], v[180:183], v[60:63]
	v_mfma_f32_16x16x32_bf16 v[56:59], v[136:139], v[180:183], v[56:59]
	v_mfma_f32_16x16x32_bf16 v[52:55], v[128:131], v[188:191], v[52:55]
	v_mfma_f32_16x16x32_bf16 v[44:47], v[136:139], v[188:191], v[44:47]
	v_mfma_f32_16x16x32_bf16 v[36:39], v[128:131], v[196:199], v[36:39]
	v_mfma_f32_16x16x32_bf16 v[28:31], v[136:139], v[196:199], v[28:31]
	v_mfma_f32_16x16x32_bf16 v[20:23], v[128:131], v[204:207], v[20:23]
	v_mfma_f32_16x16x32_bf16 v[12:15], v[136:139], v[204:207], v[12:15]
	v_mfma_f32_16x16x32_bf16 v[60:63], v[132:135], v[184:187], v[60:63]
	v_mfma_f32_16x16x32_bf16 v[56:59], v[140:143], v[184:187], v[56:59]
	v_mfma_f32_16x16x32_bf16 v[52:55], v[132:135], v[192:195], v[52:55]
	v_mfma_f32_16x16x32_bf16 v[44:47], v[140:143], v[192:195], v[44:47]
	v_mfma_f32_16x16x32_bf16 v[36:39], v[132:135], v[200:203], v[36:39]
	v_mfma_f32_16x16x32_bf16 v[28:31], v[140:143], v[200:203], v[28:31]
	v_mfma_f32_16x16x32_bf16 v[20:23], v[132:135], v[208:211], v[20:23]
	v_mfma_f32_16x16x32_bf16 v[12:15], v[140:143], v[208:211], v[12:15]
	v_mfma_f32_16x16x32_bf16 v[48:51], v[160:163], v[180:183], v[48:51]
	v_mfma_f32_16x16x32_bf16 v[40:43], v[172:175], v[180:183], v[40:43]
	v_mfma_f32_16x16x32_bf16 v[32:35], v[160:163], v[188:191], v[32:35]
	v_mfma_f32_16x16x32_bf16 v[24:27], v[172:175], v[188:191], v[24:27]
	v_mfma_f32_16x16x32_bf16 v[16:19], v[160:163], v[196:199], v[16:19]
	v_mfma_f32_16x16x32_bf16 v[8:11], v[172:175], v[196:199], v[8:11]
	v_mfma_f32_16x16x32_bf16 v[4:7], v[160:163], v[204:207], v[4:7]
	v_mfma_f32_16x16x32_bf16 v[0:3], v[172:175], v[204:207], v[0:3]
	v_mfma_f32_16x16x32_bf16 v[48:51], v[164:167], v[184:187], v[48:51]
	v_mfma_f32_16x16x32_bf16 v[40:43], v[176:179], v[184:187], v[40:43]
	v_mfma_f32_16x16x32_bf16 v[32:35], v[164:167], v[192:195], v[32:35]
	v_mfma_f32_16x16x32_bf16 v[24:27], v[176:179], v[192:195], v[24:27]
	v_mfma_f32_16x16x32_bf16 v[16:19], v[164:167], v[200:203], v[16:19]
	v_mfma_f32_16x16x32_bf16 v[8:11], v[176:179], v[200:203], v[8:11]
	v_mfma_f32_16x16x32_bf16 v[4:7], v[164:167], v[208:211], v[4:7]
	v_mfma_f32_16x16x32_bf16 v[0:3], v[176:179], v[208:211], v[0:3]
	s_setprio 0
	s_barrier
	s_add_i32 s50, s50, 2
	s_add_u32 s6, s6, 0x100
	s_addc_u32 s7, s7, 0
	s_add_u32 s23, s23, 0x100
	s_addc_u32 s49, s49, 0
	s_cmp_gt_u32 s50, 29
	s_cbranch_scc0 .LBB0_831
	s_and_b64 vcc, exec, s[14:15]
	s_cbranch_vccz .LBB0_834
	s_barrier

; #define PG8_STAGE(bufoff, gbase, voff) do { _Pragma("unroll") for (int _i = 0; _i < 2; ++_i) \
;         __builtin_amdgcn_global_load_lds((const unsigned*)((const char*)(gbase) + (voff)[_i]), (LAS unsigned*)(lds + (bufoff) + ldsw + _i * 8192), 16, 0, 0); } while (0)
; #define PG8_LDA(dst, b, h) do { _Pragma("unroll") for (int m = 0; m < 4; ++m) _Pragma("unroll") for (int k = 0; k < 2; ++k) dst[m][k] = *(const LAS bf16x8*)(lds + PG8_SA(b, h) + aoff + m * 2048 + k * 1024); } while (0)
; #define PG8_LDB(dst, b, h) do { _Pragma("unroll") for (int n = 0; n < 2; ++n) _Pragma("unroll") for (int k = 0; k < 2; ++k) dst[n][k] = *(const LAS bf16x8*)(lds + PG8_SB(b, h) + boff + n * 2048 + k * 1024); } while (0)
; #define PG8_MMA(ai, bj, At, Bt) do { __builtin_amdgcn_s_setprio(1); _Pragma("unroll") for (int m = 0; m < 4; ++m) _Pragma("unroll") for (int n = 0; n < 2; ++n) _Pragma("unroll") for (int k = 0; k < 2; ++k) \
;         acc[ai][bj][m][n] = __builtin_amdgcn_mfma_f32_16x16x32_bf16(Bt[n][k], At[m][k], acc[ai][bj][m][n], 0, 0, 0); __builtin_amdgcn_s_setprio(0); } while (0)
; #define PG8_WAIT_V(n) asm volatile("s_waitcnt vmcnt(" #n ")" ::: "memory")
; #define PG8_WAIT_L(n) asm volatile("s_waitcnt lgkmcnt(" #n ")" ::: "memory")
; #define PG8_BAR __builtin_amdgcn_s_barrier()
; #define PG8_SCHED __builtin_amdgcn_sched_barrier(0)
; template <class Desc, class Epi>
; DI void gemm_phase(LAS unsigned char* lds, const Desc& D, const Epi& E, int wv) {
;     ...
;             const bool last = (t == nt - 2);
;             const char* a1 = cA + (size_t)(t + 1) * kstep;
;             const char* a2 = last ? nA : cA + (size_t)(t + 2) * kstep; const char* b2 = last ? nB : cB + (size_t)(t + 2) * kstep;
;             const char* a3 = a2 + kstep; const char* b3 = b2 + kstep;
;             PG8_LDB(B0, 0, 0); PG8_LDB(B1, 0, 1); PG8_SCHED; PG8_LDA(At, 0, 0); PG8_STAGE(PG8_SA(1, 1), a1 + hstepA, voffA);
;             PG8_WAIT_V(8); PG8_WAIT_L(0); PG8_BAR; PG8_MMA(0, 0, At, B0); PG8_MMA(0, 1, At, B1); PG8_BAR; PG8_SCHED;
;             PG8_LDA(At, 0, 1); PG8_STAGE(PG8_SB(0, 0), b2, voffB); PG8_STAGE(PG8_SB(0, 1), b2 + hstepB, voffB); PG8_STAGE(PG8_SA(0, 0), a2, voffA);
.LBB0_962:
	ds_read_b128 v[146:149], v157
	ds_read_b128 v[150:153], v157 offset:1024
	ds_read_b128 v[160:163], v157 offset:2048
	ds_read_b128 v[164:167], v157 offset:3072
	ds_read_b128 v[168:171], v158
	ds_read_b128 v[172:175], v158 offset:1024
	ds_read_b128 v[176:179], v158 offset:2048
	ds_read_b128 v[180:183], v158 offset:3072
	s_add_u32 s60, s70, 0xfff80080
	s_addc_u32 s63, s71, -1
	s_cmp_eq_u32 s53, 28
	s_cselect_b32 s75, s65, s63
	s_cselect_b32 s74, s64, s60
	s_cselect_b32 s73, s69, s10
	s_cselect_b32 s72, s68, s9
	v_lshl_add_u64 v[154:155], s[70:71], 0, v[138:139]
	s_add_i32 m0, s3, 0xc000
	ds_read_b128 v[184:187], v159
	ds_read_b128 v[188:191], v159 offset:1024
	ds_read_b128 v[192:195], v159 offset:2048
	ds_read_b128 v[196:199], v159 offset:3072
	ds_read_b128 v[200:203], v159 offset:4096
	ds_read_b128 v[204:207], v159 offset:5120
	ds_read_b128 v[208:211], v159 offset:6144
	ds_read_b128 v[212:215], v159 offset:7168
	global_load_lds_dwordx4 v[154:155], off
	v_lshl_add_u64 v[154:155], s[70:71], 0, v[140:141]
	s_add_i32 m0, s3, 0xe000
	s_nop 0
	global_load_lds_dwordx4 v[154:155], off
	s_waitcnt vmcnt(8)
	s_waitcnt lgkmcnt(0)
	s_barrier
	s_setprio 1
	v_mfma_f32_16x16x32_bf16 v[124:127], v[146:149], v[184:187], v[124:127]
	v_mfma_f32_16x16x32_bf16 v[120:123], v[160:163], v[184:187], v[120:123]
	v_mfma_f32_16x16x32_bf16 v[108:111], v[146:149], v[192:195], v[108:111]
	v_mfma_f32_16x16x32_bf16 v[104:107], v[160:163], v[192:195], v[104:107]
	v_mfma_f32_16x16x32_bf16 v[92:95], v[146:149], v[200:203], v[92:95]
	v_mfma_f32_16x16x32_bf16 v[88:91], v[160:163], v[200:203], v[88:91]
	v_mfma_f32_16x16x32_bf16 v[76:79], v[146:149], v[208:211], v[76:79]
	v_mfma_f32_16x16x32_bf16 v[72:75], v[160:163], v[208:211], v[72:75]
	v_mfma_f32_16x16x32_bf16 v[124:127], v[150:153], v[188:191], v[124:127]
	v_mfma_f32_16x16x32_bf16 v[120:123], v[164:167], v[188:191], v[120:123]
	v_mfma_f32_16x16x32_bf16 v[108:111], v[150:153], v[196:199], v[108:111]
	v_mfma_f32_16x16x32_bf16 v[104:107], v[164:167], v[196:199], v[104:107]
	v_mfma_f32_16x16x32_bf16 v[92:95], v[150:153], v[204:207], v[92:95]
	v_mfma_f32_16x16x32_bf16 v[88:91], v[164:167], v[204:207], v[88:91]
	v_mfma_f32_16x16x32_bf16 v[76:79], v[150:153], v[212:215], v[76:79]
	v_mfma_f32_16x16x32_bf16 v[72:75], v[164:167], v[212:215], v[72:75]
	v_mfma_f32_16x16x32_bf16 v[116:119], v[168:171], v[184:187], v[116:119]
	v_mfma_f32_16x16x32_bf16 v[112:115], v[176:179], v[184:187], v[112:115]
	v_mfma_f32_16x16x32_bf16 v[100:103], v[168:171], v[192:195], v[100:103]
	v_mfma_f32_16x16x32_bf16 v[96:99], v[176:179], v[192:195], v[96:99]
	v_mfma_f32_16x16x32_bf16 v[84:87], v[168:171], v[200:203], v[84:87]
	v_mfma_f32_16x16x32_bf16 v[80:83], v[176:179], v[200:203], v[80:83]
	v_mfma_f32_16x16x32_bf16 v[68:71], v[168:171], v[208:211], v[68:71]
	v_mfma_f32_16x16x32_bf16 v[64:67], v[176:179], v[208:211], v[64:67]
	v_mfma_f32_16x16x32_bf16 v[116:119], v[172:175], v[188:191], v[116:119]
	v_mfma_f32_16x16x32_bf16 v[112:115], v[180:183], v[188:191], v[112:115]
	v_mfma_f32_16x16x32_bf16 v[100:103], v[172:175], v[196:199], v[100:103]
	v_mfma_f32_16x16x32_bf16 v[96:99], v[180:183], v[196:199], v[96:99]
	v_mfma_f32_16x16x32_bf16 v[84:87], v[172:175], v[204:207], v[84:87]
	v_mfma_f32_16x16x32_bf16 v[80:83], v[180:183], v[204:207], v[80:83]
	v_mfma_f32_16x16x32_bf16 v[68:71], v[172:175], v[212:215], v[68:71]
	v_mfma_f32_16x16x32_bf16 v[64:67], v[180:183], v[212:215], v[64:67]
	s_setprio 0
	s_barrier
	s_add_i32 s60, s46, s2
	v_lshl_add_u64 v[154:155], s[72:73], 0, v[130:131]
	s_mov_b32 m0, s60
	ds_read_b128 v[184:187], v159 offset:16384
	ds_read_b128 v[188:191], v159 offset:17408
	ds_read_b128 v[192:195], v159 offset:18432
	ds_read_b128 v[196:199], v159 offset:19456
	ds_read_b128 v[200:203], v159 offset:20480
	ds_read_b128 v[204:207], v159 offset:21504
	ds_read_b128 v[208:211], v159 offset:22528
	ds_read_b128 v[212:215], v159 offset:23552
	global_load_lds_dwordx4 v[154:155], off
	s_add_i32 m0, s60, 0x2000
	s_add_u32 s76, s72, 0x80000
	v_lshl_add_u64 v[216:217], s[72:73], 0, v[134:135]
	s_addc_u32 s77, s73, 0
	s_add_i32 s60, s47, s2
	global_load_lds_dwordx4 v[216:217], off
	v_lshl_add_u64 v[218:219], s[76:77], 0, v[130:131]
	s_mov_b32 m0, s60
	v_lshl_add_u64 v[220:221], s[74:75], 0, v[132:133]
	global_load_lds_dwordx4 v[218:219], off
	v_lshl_add_u64 v[218:219], s[76:77], 0, v[134:135]
	s_add_i32 m0, s60, 0x2000
	s_nop 0
	global_load_lds_dwordx4 v[218:219], off
	v_lshl_add_u64 v[218:219], s[74:75], 0, v[128:129]
	s_mov_b32 m0, s3
	s_nop 0
	global_load_lds_dwordx4 v[218:219], off
	s_mov_b32 m0, s28
	s_nop 0
	global_load_lds_dwordx4 v[220:221], off
	s_waitcnt vmcnt(8)
	s_waitcnt lgkmcnt(0)
	s_barrier
; #define PG8_STAGE(bufoff, gbase, voff) do { _Pragma("unroll") for (int _i = 0; _i < 2; ++_i) \
;         __builtin_amdgcn_global_load_lds((const unsigned*)((const char*)(gbase) + (voff)[_i]), (LAS unsigned*)(lds + (bufoff) + ldsw + _i * 8192), 16, 0, 0); } while (0)
; #define PG8_LDA(dst, b, h) do { _Pragma("unroll") for (int m = 0; m < 4; ++m) _Pragma("unroll") for (int k = 0; k < 2; ++k) dst[m][k] = *(const LAS bf16x8*)(lds + PG8_SA(b, h) + aoff + m * 2048 + k * 1024); } while (0)
; #define PG8_LDB(dst, b, h) do { _Pragma("unroll") for (int n = 0; n < 2; ++n) _Pragma("unroll") for (int k = 0; k < 2; ++k) dst[n][k] = *(const LAS bf16x8*)(lds + PG8_SB(b, h) + boff + n * 2048 + k * 1024); } while (0)
; #define PG8_MMA(ai, bj, At, Bt) do { __builtin_amdgcn_s_setprio(1); _Pragma("unroll") for (int m = 0; m < 4; ++m) _Pragma("unroll") for (int n = 0; n < 2; ++n) _Pragma("unroll") for (int k = 0; k < 2; ++k) \
;         acc[ai][bj][m][n] = __builtin_amdgcn_mfma_f32_16x16x32_bf16(Bt[n][k], At[m][k], acc[ai][bj][m][n], 0, 0, 0); __builtin_amdgcn_s_setprio(0); } while (0)
; #define PG8_WAIT_V(n) asm volatile("s_waitcnt vmcnt(" #n ")" ::: "memory")
; #define PG8_WAIT_L(n) asm volatile("s_waitcnt lgkmcnt(" #n ")" ::: "memory")
; #define PG8_BAR __builtin_amdgcn_s_barrier()
; #define PG8_SCHED __builtin_amdgcn_sched_barrier(0)
; template <class Desc, class Epi>
; DI void gemm_phase(LAS unsigned char* lds, const Desc& D, const Epi& E, int wv) {
;     ...
;             PG8_WAIT_V(8); PG8_WAIT_L(0); PG8_BAR; PG8_MMA(1, 0, At, B0); PG8_MMA(1, 1, At, B1); PG8_BAR; PG8_SCHED;
;             PG8_LDB(B0, 1, 0); PG8_LDB(B1, 1, 1); PG8_SCHED; PG8_LDA(At, 1, 0); PG8_STAGE(PG8_SA(0, 1), a2 + hstepA, voffA);
;             PG8_WAIT_V(8); PG8_WAIT_L(0); PG8_BAR; PG8_MMA(0, 0, At, B0); PG8_MMA(0, 1, At, B1); PG8_BAR; PG8_SCHED;
	s_setprio 1
	v_mfma_f32_16x16x32_bf16 v[60:63], v[146:149], v[184:187], v[60:63]
	v_mfma_f32_16x16x32_bf16 v[56:59], v[160:163], v[184:187], v[56:59]
	v_mfma_f32_16x16x32_bf16 v[44:47], v[146:149], v[192:195], v[44:47]
	v_mfma_f32_16x16x32_bf16 v[40:43], v[160:163], v[192:195], v[40:43]
	v_mfma_f32_16x16x32_bf16 v[28:31], v[146:149], v[200:203], v[28:31]
	v_mfma_f32_16x16x32_bf16 v[24:27], v[160:163], v[200:203], v[24:27]
	v_mfma_f32_16x16x32_bf16 v[12:15], v[146:149], v[208:211], v[12:15]
	v_mfma_f32_16x16x32_bf16 v[8:11], v[160:163], v[208:211], v[8:11]
	v_mfma_f32_16x16x32_bf16 v[60:63], v[150:153], v[188:191], v[60:63]
	v_mfma_f32_16x16x32_bf16 v[56:59], v[164:167], v[188:191], v[56:59]
	v_mfma_f32_16x16x32_bf16 v[44:47], v[150:153], v[196:199], v[44:47]
	v_mfma_f32_16x16x32_bf16 v[40:43], v[164:167], v[196:199], v[40:43]
	v_mfma_f32_16x16x32_bf16 v[28:31], v[150:153], v[204:207], v[28:31]
	v_mfma_f32_16x16x32_bf16 v[24:27], v[164:167], v[204:207], v[24:27]
	v_mfma_f32_16x16x32_bf16 v[12:15], v[150:153], v[212:215], v[12:15]
	v_mfma_f32_16x16x32_bf16 v[8:11], v[164:167], v[212:215], v[8:11]
	v_mfma_f32_16x16x32_bf16 v[52:55], v[168:171], v[184:187], v[52:55]
	v_mfma_f32_16x16x32_bf16 v[48:51], v[176:179], v[184:187], v[48:51]
	v_mfma_f32_16x16x32_bf16 v[36:39], v[168:171], v[192:195], v[36:39]
	v_mfma_f32_16x16x32_bf16 v[32:35], v[176:179], v[192:195], v[32:35]
	v_mfma_f32_16x16x32_bf16 v[20:23], v[168:171], v[200:203], v[20:23]
	v_mfma_f32_16x16x32_bf16 v[16:19], v[176:179], v[200:203], v[16:19]
	v_mfma_f32_16x16x32_bf16 v[4:7], v[168:171], v[208:211], v[4:7]
	v_mfma_f32_16x16x32_bf16 v[0:3], v[176:179], v[208:211], v[0:3]
	v_mfma_f32_16x16x32_bf16 v[52:55], v[172:175], v[188:191], v[52:55]
	v_mfma_f32_16x16x32_bf16 v[48:51], v[180:183], v[188:191], v[48:51]
	v_mfma_f32_16x16x32_bf16 v[36:39], v[172:175], v[196:199], v[36:39]
	v_mfma_f32_16x16x32_bf16 v[32:35], v[180:183], v[196:199], v[32:35]
	v_mfma_f32_16x16x32_bf16 v[20:23], v[172:175], v[204:207], v[20:23]
	v_mfma_f32_16x16x32_bf16 v[16:19], v[180:183], v[204:207], v[16:19]
	v_mfma_f32_16x16x32_bf16 v[4:7], v[172:175], v[212:215], v[4:7]
	v_mfma_f32_16x16x32_bf16 v[0:3], v[180:183], v[212:215], v[0:3]
	s_setprio 0
	s_barrier
	s_add_i32 s60, 0, 0x18000
	v_add_u32_e32 v136, s60, v156
	s_add_i32 s63, 0, 0x1c000
	ds_read_b128 v[146:149], v136
	ds_read_b128 v[150:153], v136 offset:1024
	ds_read_b128 v[160:163], v136 offset:2048
	ds_read_b128 v[164:167], v136 offset:3072
	v_add_u32_e32 v136, s63, v156
	ds_read_b128 v[168:171], v136
	ds_read_b128 v[172:175], v136 offset:1024
	ds_read_b128 v[176:179], v136 offset:2048
	ds_read_b128 v[180:183], v136 offset:3072
	s_add_u32 s74, s74, 0x80000
	s_addc_u32 s75, s75, 0
	s_mov_b32 m0, s29
	v_lshl_add_u64 v[222:223], s[74:75], 0, v[128:129]
	ds_read_b128 v[184:187], v159 offset:32768
	ds_read_b128 v[188:191], v159 offset:33792
	ds_read_b128 v[192:195], v159 offset:34816
	ds_read_b128 v[196:199], v159 offset:35840
	ds_read_b128 v[200:203], v159 offset:36864
	ds_read_b128 v[204:207], v159 offset:37888
	ds_read_b128 v[208:211], v159 offset:38912
	ds_read_b128 v[212:215], v159 offset:39936
	global_load_lds_dwordx4 v[222:223], off
	v_lshl_add_u64 v[222:223], s[74:75], 0, v[132:133]
	s_mov_b32 m0, s30
	s_nop 0
	global_load_lds_dwordx4 v[222:223], off
	s_waitcnt vmcnt(8)
	s_waitcnt lgkmcnt(0)
	s_barrier
	s_setprio 1
	v_mfma_f32_16x16x32_bf16 v[124:127], v[146:149], v[184:187], v[124:127]
	v_mfma_f32_16x16x32_bf16 v[120:123], v[160:163], v[184:187], v[120:123]
	v_mfma_f32_16x16x32_bf16 v[108:111], v[146:149], v[192:195], v[108:111]
	v_mfma_f32_16x16x32_bf16 v[104:107], v[160:163], v[192:195], v[104:107]
	v_mfma_f32_16x16x32_bf16 v[92:95], v[146:149], v[200:203], v[92:95]
	v_mfma_f32_16x16x32_bf16 v[88:91], v[160:163], v[200:203], v[88:91]
	v_mfma_f32_16x16x32_bf16 v[76:79], v[146:149], v[208:211], v[76:79]
	v_mfma_f32_16x16x32_bf16 v[72:75], v[160:163], v[208:211], v[72:75]
	v_mfma_f32_16x16x32_bf16 v[124:127], v[150:153], v[188:191], v[124:127]
	v_mfma_f32_16x16x32_bf16 v[120:123], v[164:167], v[188:191], v[120:123]
	v_mfma_f32_16x16x32_bf16 v[108:111], v[150:153], v[196:199], v[108:111]
	v_mfma_f32_16x16x32_bf16 v[104:107], v[164:167], v[196:199], v[104:107]
	v_mfma_f32_16x16x32_bf16 v[92:95], v[150:153], v[204:207], v[92:95]
	v_mfma_f32_16x16x32_bf16 v[88:91], v[164:167], v[204:207], v[88:91]
	v_mfma_f32_16x16x32_bf16 v[76:79], v[150:153], v[212:215], v[76:79]
	v_mfma_f32_16x16x32_bf16 v[72:75], v[164:167], v[212:215], v[72:75]
	v_mfma_f32_16x16x32_bf16 v[116:119], v[168:171], v[184:187], v[116:119]
	v_mfma_f32_16x16x32_bf16 v[112:115], v[176:179], v[184:187], v[112:115]
	v_mfma_f32_16x16x32_bf16 v[100:103], v[168:171], v[192:195], v[100:103]
	v_mfma_f32_16x16x32_bf16 v[96:99], v[176:179], v[192:195], v[96:99]
	v_mfma_f32_16x16x32_bf16 v[84:87], v[168:171], v[200:203], v[84:87]
	v_mfma_f32_16x16x32_bf16 v[80:83], v[176:179], v[200:203], v[80:83]
	v_mfma_f32_16x16x32_bf16 v[68:71], v[168:171], v[208:211], v[68:71]
	v_mfma_f32_16x16x32_bf16 v[64:67], v[176:179], v[208:211], v[64:67]
	v_mfma_f32_16x16x32_bf16 v[116:119], v[172:175], v[188:191], v[116:119]
	v_mfma_f32_16x16x32_bf16 v[112:115], v[180:183], v[188:191], v[112:115]
	v_mfma_f32_16x16x32_bf16 v[100:103], v[172:175], v[196:199], v[100:103]
	v_mfma_f32_16x16x32_bf16 v[96:99], v[180:183], v[196:199], v[96:99]
	v_mfma_f32_16x16x32_bf16 v[84:87], v[172:175], v[204:207], v[84:87]
	v_mfma_f32_16x16x32_bf16 v[80:83], v[180:183], v[204:207], v[80:83]
	v_mfma_f32_16x16x32_bf16 v[68:71], v[172:175], v[212:215], v[68:71]
	v_mfma_f32_16x16x32_bf16 v[64:67], v[180:183], v[212:215], v[64:67]
	s_setprio 0
	s_barrier
; #define PG8_STAGE(bufoff, gbase, voff) do { _Pragma("unroll") for (int _i = 0; _i < 2; ++_i) \
;         __builtin_amdgcn_global_load_lds((const unsigned*)((const char*)(gbase) + (voff)[_i]), (LAS unsigned*)(lds + (bufoff) + ldsw + _i * 8192), 16, 0, 0); } while (0)
; #define PG8_LDA(dst, b, h) do { _Pragma("unroll") for (int m = 0; m < 4; ++m) _Pragma("unroll") for (int k = 0; k < 2; ++k) dst[m][k] = *(const LAS bf16x8*)(lds + PG8_SA(b, h) + aoff + m * 2048 + k * 1024); } while (0)
; #define PG8_MMA(ai, bj, At, Bt) do { __builtin_amdgcn_s_setprio(1); _Pragma("unroll") for (int m = 0; m < 4; ++m) _Pragma("unroll") for (int n = 0; n < 2; ++n) _Pragma("unroll") for (int k = 0; k < 2; ++k) \
;         acc[ai][bj][m][n] = __builtin_amdgcn_mfma_f32_16x16x32_bf16(Bt[n][k], At[m][k], acc[ai][bj][m][n], 0, 0, 0); __builtin_amdgcn_s_setprio(0); } while (0)
; #define PG8_WAIT_V(n) asm volatile("s_waitcnt vmcnt(" #n ")" ::: "memory")
; #define PG8_WAIT_L(n) asm volatile("s_waitcnt lgkmcnt(" #n ")" ::: "memory")
; #define PG8_BAR __builtin_amdgcn_s_barrier()
; #define PG8_SCHED __builtin_amdgcn_sched_barrier(0)
; template <class Desc, class Epi>
; DI void gemm_phase(LAS unsigned char* lds, const Desc& D, const Epi& E, int wv) {
;     ...
;             PG8_LDA(At, 1, 1); PG8_STAGE(PG8_SB(1, 0), b3, voffB); PG8_STAGE(PG8_SB(1, 1), b3 + hstepB, voffB); PG8_STAGE(PG8_SA(1, 0), a3, voffA);
;             PG8_WAIT_V(8); PG8_WAIT_L(0); PG8_BAR; PG8_MMA(1, 0, At, B0); PG8_MMA(1, 1, At, B1); PG8_BAR; PG8_SCHED;
;         }
;         if (wr == 0) PG8_BAR;
	s_add_i32 s60, s60, s2
	v_lshl_add_u64 v[154:155], v[154:155], 0, s[14:15]
	s_mov_b32 m0, s60
	ds_read_b128 v[184:187], v159 offset:49152
	ds_read_b128 v[188:191], v159 offset:50176
	ds_read_b128 v[192:195], v159 offset:51200
	ds_read_b128 v[196:199], v159 offset:52224
	ds_read_b128 v[200:203], v159 offset:53248
	ds_read_b128 v[204:207], v159 offset:54272
	ds_read_b128 v[208:211], v159 offset:55296
	ds_read_b128 v[212:215], v159 offset:56320
	global_load_lds_dwordx4 v[154:155], off
	s_add_i32 m0, s60, 0x2000
	s_add_u32 s72, s72, 0x80080
	v_lshl_add_u64 v[154:155], v[216:217], 0, s[14:15]
	s_addc_u32 s73, s73, 0
	s_add_i32 s60, s63, s2
	global_load_lds_dwordx4 v[154:155], off
	v_lshl_add_u64 v[154:155], s[72:73], 0, v[130:131]
	s_mov_b32 m0, s60
	s_nop 0
	global_load_lds_dwordx4 v[154:155], off
	v_lshl_add_u64 v[154:155], s[72:73], 0, v[134:135]
	s_add_i32 m0, s60, 0x2000
	s_nop 0
	global_load_lds_dwordx4 v[154:155], off
	v_lshl_add_u64 v[154:155], v[218:219], 0, s[14:15]
	s_mov_b32 m0, s41
	s_nop 0
	global_load_lds_dwordx4 v[154:155], off
	v_lshl_add_u64 v[154:155], v[220:221], 0, s[14:15]
	s_mov_b32 m0, s42
	s_nop 0
	global_load_lds_dwordx4 v[154:155], off
	s_waitcnt vmcnt(8)
	s_waitcnt lgkmcnt(0)
	s_barrier
	s_setprio 1
	v_mfma_f32_16x16x32_bf16 v[60:63], v[146:149], v[184:187], v[60:63]
	v_mfma_f32_16x16x32_bf16 v[56:59], v[160:163], v[184:187], v[56:59]
	v_mfma_f32_16x16x32_bf16 v[44:47], v[146:149], v[192:195], v[44:47]
	v_mfma_f32_16x16x32_bf16 v[40:43], v[160:163], v[192:195], v[40:43]
	v_mfma_f32_16x16x32_bf16 v[28:31], v[146:149], v[200:203], v[28:31]
	v_mfma_f32_16x16x32_bf16 v[24:27], v[160:163], v[200:203], v[24:27]
	v_mfma_f32_16x16x32_bf16 v[12:15], v[146:149], v[208:211], v[12:15]
	v_mfma_f32_16x16x32_bf16 v[8:11], v[160:163], v[208:211], v[8:11]
	v_mfma_f32_16x16x32_bf16 v[60:63], v[150:153], v[188:191], v[60:63]
	v_mfma_f32_16x16x32_bf16 v[56:59], v[164:167], v[188:191], v[56:59]
	v_mfma_f32_16x16x32_bf16 v[44:47], v[150:153], v[196:199], v[44:47]
	v_mfma_f32_16x16x32_bf16 v[40:43], v[164:167], v[196:199], v[40:43]
	v_mfma_f32_16x16x32_bf16 v[28:31], v[150:153], v[204:207], v[28:31]
	v_mfma_f32_16x16x32_bf16 v[24:27], v[164:167], v[204:207], v[24:27]
	v_mfma_f32_16x16x32_bf16 v[12:15], v[150:153], v[212:215], v[12:15]
	v_mfma_f32_16x16x32_bf16 v[8:11], v[164:167], v[212:215], v[8:11]
	v_mfma_f32_16x16x32_bf16 v[52:55], v[168:171], v[184:187], v[52:55]
	v_mfma_f32_16x16x32_bf16 v[48:51], v[176:179], v[184:187], v[48:51]
	v_mfma_f32_16x16x32_bf16 v[36:39], v[168:171], v[192:195], v[36:39]
	v_mfma_f32_16x16x32_bf16 v[32:35], v[176:179], v[192:195], v[32:35]
	v_mfma_f32_16x16x32_bf16 v[20:23], v[168:171], v[200:203], v[20:23]
	v_mfma_f32_16x16x32_bf16 v[16:19], v[176:179], v[200:203], v[16:19]
	v_mfma_f32_16x16x32_bf16 v[4:7], v[168:171], v[208:211], v[4:7]
	v_mfma_f32_16x16x32_bf16 v[0:3], v[176:179], v[208:211], v[0:3]
	v_mfma_f32_16x16x32_bf16 v[52:55], v[172:175], v[188:191], v[52:55]
	v_mfma_f32_16x16x32_bf16 v[48:51], v[180:183], v[188:191], v[48:51]
	v_mfma_f32_16x16x32_bf16 v[36:39], v[172:175], v[196:199], v[36:39]
	v_mfma_f32_16x16x32_bf16 v[32:35], v[180:183], v[196:199], v[32:35]
	v_mfma_f32_16x16x32_bf16 v[20:23], v[172:175], v[204:207], v[20:23]
	v_mfma_f32_16x16x32_bf16 v[16:19], v[180:183], v[204:207], v[16:19]
	v_mfma_f32_16x16x32_bf16 v[4:7], v[172:175], v[212:215], v[4:7]
	v_mfma_f32_16x16x32_bf16 v[0:3], v[180:183], v[212:215], v[0:3]
	s_setprio 0
	s_barrier
	s_add_i32 s53, s53, 2
	s_add_u32 s70, s70, 0x100
	s_addc_u32 s71, s71, 0
	s_add_u32 s9, s9, 0x100
	s_addc_u32 s10, s10, 0
	s_cmp_gt_u32 s53, 29
	s_cbranch_scc0 .LBB0_962
	s_and_b64 vcc, exec, s[20:21]
	s_cbranch_vccz .LBB0_965
	s_barrier

; #define PG8_STAGE(bufoff, gbase, voff) do { _Pragma("unroll") for (int _i = 0; _i < 2; ++_i) \
;         __builtin_amdgcn_global_load_lds((const unsigned*)((const char*)(gbase) + (voff)[_i]), (LAS unsigned*)(lds + (bufoff) + ldsw + _i * 8192), 16, 0, 0); } while (0)
; #define PG8_LDA(dst, b, h) do { _Pragma("unroll") for (int m = 0; m < 4; ++m) _Pragma("unroll") for (int k = 0; k < 2; ++k) dst[m][k] = *(const LAS bf16x8*)(lds + PG8_SA(b, h) + aoff + m * 2048 + k * 1024); } while (0)
; #define PG8_LDB(dst, b, h) do { _Pragma("unroll") for (int n = 0; n < 2; ++n) _Pragma("unroll") for (int k = 0; k < 2; ++k) dst[n][k] = *(const LAS bf16x8*)(lds + PG8_SB(b, h) + boff + n * 2048 + k * 1024); } while (0)
; #define PG8_MMA(ai, bj, At, Bt) do { __builtin_amdgcn_s_setprio(1); _Pragma("unroll") for (int m = 0; m < 4; ++m) _Pragma("unroll") for (int n = 0; n < 2; ++n) _Pragma("unroll") for (int k = 0; k < 2; ++k) \
;         acc[ai][bj][m][n] = __builtin_amdgcn_mfma_f32_16x16x32_bf16(Bt[n][k], At[m][k], acc[ai][bj][m][n], 0, 0, 0); __builtin_amdgcn_s_setprio(0); } while (0)
; #define PG8_WAIT_V(n) asm volatile("s_waitcnt vmcnt(" #n ")" ::: "memory")
; #define PG8_WAIT_L(n) asm volatile("s_waitcnt lgkmcnt(" #n ")" ::: "memory")
; #define PG8_BAR __builtin_amdgcn_s_barrier()
; #define PG8_SCHED __builtin_amdgcn_sched_barrier(0)
; template <class Desc, class Epi>
; DI void gemm_phase(LAS unsigned char* lds, const Desc& D, const Epi& E, int wv) {
;     ...
;             const bool last = (t == nt - 2);
;             const char* a1 = cA + (size_t)(t + 1) * kstep;
;             const char* a2 = last ? nA : cA + (size_t)(t + 2) * kstep; const char* b2 = last ? nB : cB + (size_t)(t + 2) * kstep;
;             const char* a3 = a2 + kstep; const char* b3 = b2 + kstep;
;             PG8_LDB(B0, 0, 0); PG8_LDB(B1, 0, 1); PG8_SCHED; PG8_LDA(At, 0, 0); PG8_STAGE(PG8_SA(1, 1), a1 + hstepA, voffA);
;             PG8_WAIT_V(8); PG8_WAIT_L(0); PG8_BAR; PG8_MMA(0, 0, At, B0); PG8_MMA(0, 1, At, B1); PG8_BAR; PG8_SCHED;
;             PG8_LDA(At, 0, 1); PG8_STAGE(PG8_SB(0, 0), b2, voffB); PG8_STAGE(PG8_SB(0, 1), b2 + hstepB, voffB); PG8_STAGE(PG8_SA(0, 0), a2, voffA);
.LBB0_1313:
	ds_read_b128 v[146:149], v157
	ds_read_b128 v[150:153], v157 offset:1024
	ds_read_b128 v[160:163], v157 offset:2048
	ds_read_b128 v[164:167], v157 offset:3072
	ds_read_b128 v[168:171], v158
	ds_read_b128 v[172:175], v158 offset:1024
	ds_read_b128 v[176:179], v158 offset:2048
	ds_read_b128 v[180:183], v158 offset:3072
	s_add_u32 s40, s22, 0xfff80080
	s_addc_u32 s41, s23, -1
	s_cmp_eq_u32 s50, 28
	s_cselect_b32 s63, s15, s41
	s_cselect_b32 s62, s14, s40
	s_cselect_b32 s41, s17, s21
	s_cselect_b32 s40, s16, s19
	v_lshl_add_u64 v[154:155], s[22:23], 0, v[138:139]
	s_add_i32 m0, s28, 0xc000
	ds_read_b128 v[184:187], v159
	ds_read_b128 v[188:191], v159 offset:1024
	ds_read_b128 v[192:195], v159 offset:2048
	ds_read_b128 v[196:199], v159 offset:3072
	ds_read_b128 v[200:203], v159 offset:4096
	ds_read_b128 v[204:207], v159 offset:5120
	ds_read_b128 v[208:211], v159 offset:6144
	ds_read_b128 v[212:215], v159 offset:7168
	global_load_lds_dwordx4 v[154:155], off
	v_lshl_add_u64 v[154:155], s[22:23], 0, v[140:141]
	s_add_i32 m0, s28, 0xe000
	s_nop 0
	global_load_lds_dwordx4 v[154:155], off
	s_waitcnt vmcnt(8)
	s_waitcnt lgkmcnt(0)
	s_barrier
	s_setprio 1
	v_mfma_f32_16x16x32_bf16 v[124:127], v[146:149], v[184:187], v[124:127]
	v_mfma_f32_16x16x32_bf16 v[120:123], v[160:163], v[184:187], v[120:123]
	v_mfma_f32_16x16x32_bf16 v[108:111], v[146:149], v[192:195], v[108:111]
	v_mfma_f32_16x16x32_bf16 v[104:107], v[160:163], v[192:195], v[104:107]
	v_mfma_f32_16x16x32_bf16 v[92:95], v[146:149], v[200:203], v[92:95]
	v_mfma_f32_16x16x32_bf16 v[88:91], v[160:163], v[200:203], v[88:91]
	v_mfma_f32_16x16x32_bf16 v[76:79], v[146:149], v[208:211], v[76:79]
	v_mfma_f32_16x16x32_bf16 v[72:75], v[160:163], v[208:211], v[72:75]
	v_mfma_f32_16x16x32_bf16 v[124:127], v[150:153], v[188:191], v[124:127]
	v_mfma_f32_16x16x32_bf16 v[120:123], v[164:167], v[188:191], v[120:123]
	v_mfma_f32_16x16x32_bf16 v[108:111], v[150:153], v[196:199], v[108:111]
	v_mfma_f32_16x16x32_bf16 v[104:107], v[164:167], v[196:199], v[104:107]
	v_mfma_f32_16x16x32_bf16 v[92:95], v[150:153], v[204:207], v[92:95]
	v_mfma_f32_16x16x32_bf16 v[88:91], v[164:167], v[204:207], v[88:91]
	v_mfma_f32_16x16x32_bf16 v[76:79], v[150:153], v[212:215], v[76:79]
	v_mfma_f32_16x16x32_bf16 v[72:75], v[164:167], v[212:215], v[72:75]
	v_mfma_f32_16x16x32_bf16 v[116:119], v[168:171], v[184:187], v[116:119]
	v_mfma_f32_16x16x32_bf16 v[112:115], v[176:179], v[184:187], v[112:115]
	v_mfma_f32_16x16x32_bf16 v[100:103], v[168:171], v[192:195], v[100:103]
	v_mfma_f32_16x16x32_bf16 v[96:99], v[176:179], v[192:195], v[96:99]
	v_mfma_f32_16x16x32_bf16 v[84:87], v[168:171], v[200:203], v[84:87]
	v_mfma_f32_16x16x32_bf16 v[80:83], v[176:179], v[200:203], v[80:83]
	v_mfma_f32_16x16x32_bf16 v[68:71], v[168:171], v[208:211], v[68:71]
	v_mfma_f32_16x16x32_bf16 v[64:67], v[176:179], v[208:211], v[64:67]
	v_mfma_f32_16x16x32_bf16 v[116:119], v[172:175], v[188:191], v[116:119]
	v_mfma_f32_16x16x32_bf16 v[112:115], v[180:183], v[188:191], v[112:115]
	v_mfma_f32_16x16x32_bf16 v[100:103], v[172:175], v[196:199], v[100:103]
	v_mfma_f32_16x16x32_bf16 v[96:99], v[180:183], v[196:199], v[96:99]
	v_mfma_f32_16x16x32_bf16 v[84:87], v[172:175], v[204:207], v[84:87]
	v_mfma_f32_16x16x32_bf16 v[80:83], v[180:183], v[204:207], v[80:83]
	v_mfma_f32_16x16x32_bf16 v[68:71], v[172:175], v[212:215], v[68:71]
	v_mfma_f32_16x16x32_bf16 v[64:67], v[180:183], v[212:215], v[64:67]
	s_setprio 0
	s_barrier
	s_add_i32 s51, s48, s2
	v_lshl_add_u64 v[154:155], s[40:41], 0, v[132:133]
	s_mov_b32 m0, s51
	ds_read_b128 v[184:187], v159 offset:16384
	ds_read_b128 v[188:191], v159 offset:17408
	ds_read_b128 v[192:195], v159 offset:18432
	ds_read_b128 v[196:199], v159 offset:19456
	ds_read_b128 v[200:203], v159 offset:20480
	ds_read_b128 v[204:207], v159 offset:21504
	ds_read_b128 v[208:211], v159 offset:22528
	ds_read_b128 v[212:215], v159 offset:23552
	global_load_lds_dwordx4 v[154:155], off
	s_add_i32 m0, s51, 0x2000
	s_add_u32 s52, s40, 0x80000
	v_lshl_add_u64 v[216:217], s[40:41], 0, v[128:129]
	s_addc_u32 s53, s41, 0
	s_add_i32 s51, s49, s2
	global_load_lds_dwordx4 v[216:217], off
	v_lshl_add_u64 v[218:219], s[52:53], 0, v[132:133]
	s_mov_b32 m0, s51
	v_lshl_add_u64 v[220:221], s[62:63], 0, v[130:131]
	global_load_lds_dwordx4 v[218:219], off
	v_lshl_add_u64 v[218:219], s[52:53], 0, v[128:129]
	s_add_i32 m0, s51, 0x2000
	s_nop 0
	global_load_lds_dwordx4 v[218:219], off
	v_lshl_add_u64 v[218:219], s[62:63], 0, v[134:135]
	s_mov_b32 m0, s28
	s_nop 0
	global_load_lds_dwordx4 v[218:219], off
	s_mov_b32 m0, s29
	s_nop 0
	global_load_lds_dwordx4 v[220:221], off
	s_waitcnt vmcnt(8)
	s_waitcnt lgkmcnt(0)
	s_barrier
; #define PG8_STAGE(bufoff, gbase, voff) do { _Pragma("unroll") for (int _i = 0; _i < 2; ++_i) \
;         __builtin_amdgcn_global_load_lds((const unsigned*)((const char*)(gbase) + (voff)[_i]), (LAS unsigned*)(lds + (bufoff) + ldsw + _i * 8192), 16, 0, 0); } while (0)
; #define PG8_LDA(dst, b, h) do { _Pragma("unroll") for (int m = 0; m < 4; ++m) _Pragma("unroll") for (int k = 0; k < 2; ++k) dst[m][k] = *(const LAS bf16x8*)(lds + PG8_SA(b, h) + aoff + m * 2048 + k * 1024); } while (0)
; #define PG8_LDB(dst, b, h) do { _Pragma("unroll") for (int n = 0; n < 2; ++n) _Pragma("unroll") for (int k = 0; k < 2; ++k) dst[n][k] = *(const LAS bf16x8*)(lds + PG8_SB(b, h) + boff + n * 2048 + k * 1024); } while (0)
; #define PG8_MMA(ai, bj, At, Bt) do { __builtin_amdgcn_s_setprio(1); _Pragma("unroll") for (int m = 0; m < 4; ++m) _Pragma("unroll") for (int n = 0; n < 2; ++n) _Pragma("unroll") for (int k = 0; k < 2; ++k) \
;         acc[ai][bj][m][n] = __builtin_amdgcn_mfma_f32_16x16x32_bf16(Bt[n][k], At[m][k], acc[ai][bj][m][n], 0, 0, 0); __builtin_amdgcn_s_setprio(0); } while (0)
; #define PG8_WAIT_V(n) asm volatile("s_waitcnt vmcnt(" #n ")" ::: "memory")
; #define PG8_WAIT_L(n) asm volatile("s_waitcnt lgkmcnt(" #n ")" ::: "memory")
; #define PG8_BAR __builtin_amdgcn_s_barrier()
; #define PG8_SCHED __builtin_amdgcn_sched_barrier(0)
; template <class Desc, class Epi>
; DI void gemm_phase(LAS unsigned char* lds, const Desc& D, const Epi& E, int wv) {
;     ...
;             PG8_WAIT_V(8); PG8_WAIT_L(0); PG8_BAR; PG8_MMA(1, 0, At, B0); PG8_MMA(1, 1, At, B1); PG8_BAR; PG8_SCHED;
;             PG8_LDB(B0, 1, 0); PG8_LDB(B1, 1, 1); PG8_SCHED; PG8_LDA(At, 1, 0); PG8_STAGE(PG8_SA(0, 1), a2 + hstepA, voffA);
;             PG8_WAIT_V(8); PG8_WAIT_L(0); PG8_BAR; PG8_MMA(0, 0, At, B0); PG8_MMA(0, 1, At, B1); PG8_BAR; PG8_SCHED;
	s_setprio 1
	v_mfma_f32_16x16x32_bf16 v[60:63], v[146:149], v[184:187], v[60:63]
	v_mfma_f32_16x16x32_bf16 v[56:59], v[160:163], v[184:187], v[56:59]
	v_mfma_f32_16x16x32_bf16 v[44:47], v[146:149], v[192:195], v[44:47]
	v_mfma_f32_16x16x32_bf16 v[40:43], v[160:163], v[192:195], v[40:43]
	v_mfma_f32_16x16x32_bf16 v[28:31], v[146:149], v[200:203], v[28:31]
	v_mfma_f32_16x16x32_bf16 v[24:27], v[160:163], v[200:203], v[24:27]
	v_mfma_f32_16x16x32_bf16 v[12:15], v[146:149], v[208:211], v[12:15]
	v_mfma_f32_16x16x32_bf16 v[8:11], v[160:163], v[208:211], v[8:11]
	v_mfma_f32_16x16x32_bf16 v[60:63], v[150:153], v[188:191], v[60:63]
	v_mfma_f32_16x16x32_bf16 v[56:59], v[164:167], v[188:191], v[56:59]
	v_mfma_f32_16x16x32_bf16 v[44:47], v[150:153], v[196:199], v[44:47]
	v_mfma_f32_16x16x32_bf16 v[40:43], v[164:167], v[196:199], v[40:43]
	v_mfma_f32_16x16x32_bf16 v[28:31], v[150:153], v[204:207], v[28:31]
	v_mfma_f32_16x16x32_bf16 v[24:27], v[164:167], v[204:207], v[24:27]
	v_mfma_f32_16x16x32_bf16 v[12:15], v[150:153], v[212:215], v[12:15]
	v_mfma_f32_16x16x32_bf16 v[8:11], v[164:167], v[212:215], v[8:11]
	v_mfma_f32_16x16x32_bf16 v[52:55], v[168:171], v[184:187], v[52:55]
	v_mfma_f32_16x16x32_bf16 v[48:51], v[176:179], v[184:187], v[48:51]
	v_mfma_f32_16x16x32_bf16 v[36:39], v[168:171], v[192:195], v[36:39]
	v_mfma_f32_16x16x32_bf16 v[32:35], v[176:179], v[192:195], v[32:35]
	v_mfma_f32_16x16x32_bf16 v[20:23], v[168:171], v[200:203], v[20:23]
	v_mfma_f32_16x16x32_bf16 v[16:19], v[176:179], v[200:203], v[16:19]
	v_mfma_f32_16x16x32_bf16 v[4:7], v[168:171], v[208:211], v[4:7]
	v_mfma_f32_16x16x32_bf16 v[0:3], v[176:179], v[208:211], v[0:3]
	v_mfma_f32_16x16x32_bf16 v[52:55], v[172:175], v[188:191], v[52:55]
	v_mfma_f32_16x16x32_bf16 v[48:51], v[180:183], v[188:191], v[48:51]
	v_mfma_f32_16x16x32_bf16 v[36:39], v[172:175], v[196:199], v[36:39]
	v_mfma_f32_16x16x32_bf16 v[32:35], v[180:183], v[196:199], v[32:35]
	v_mfma_f32_16x16x32_bf16 v[20:23], v[172:175], v[204:207], v[20:23]
	v_mfma_f32_16x16x32_bf16 v[16:19], v[180:183], v[204:207], v[16:19]
	v_mfma_f32_16x16x32_bf16 v[4:7], v[172:175], v[212:215], v[4:7]
	v_mfma_f32_16x16x32_bf16 v[0:3], v[180:183], v[212:215], v[0:3]
	s_setprio 0
	s_barrier
	s_add_i32 s51, 0, 0x18000
	v_add_u32_e32 v136, s51, v156
	s_add_i32 s60, 0, 0x1c000
	ds_read_b128 v[146:149], v136
	ds_read_b128 v[150:153], v136 offset:1024
	ds_read_b128 v[160:163], v136 offset:2048
	ds_read_b128 v[164:167], v136 offset:3072
	v_add_u32_e32 v136, s60, v156
	ds_read_b128 v[168:171], v136
	ds_read_b128 v[172:175], v136 offset:1024
	ds_read_b128 v[176:179], v136 offset:2048
	ds_read_b128 v[180:183], v136 offset:3072
	s_add_u32 s52, s62, 0x80000
	s_addc_u32 s53, s63, 0
	s_mov_b32 m0, s30
	v_lshl_add_u64 v[222:223], s[52:53], 0, v[134:135]
	ds_read_b128 v[184:187], v159 offset:32768
	ds_read_b128 v[188:191], v159 offset:33792
	ds_read_b128 v[192:195], v159 offset:34816
	ds_read_b128 v[196:199], v159 offset:35840
	ds_read_b128 v[200:203], v159 offset:36864
	ds_read_b128 v[204:207], v159 offset:37888
	ds_read_b128 v[208:211], v159 offset:38912
	ds_read_b128 v[212:215], v159 offset:39936
	global_load_lds_dwordx4 v[222:223], off
	v_lshl_add_u64 v[222:223], s[52:53], 0, v[130:131]
	s_mov_b32 m0, s31
	s_nop 0
	global_load_lds_dwordx4 v[222:223], off
	s_waitcnt vmcnt(8)
	s_waitcnt lgkmcnt(0)
	s_barrier
	s_setprio 1
	v_mfma_f32_16x16x32_bf16 v[124:127], v[146:149], v[184:187], v[124:127]
	v_mfma_f32_16x16x32_bf16 v[120:123], v[160:163], v[184:187], v[120:123]
	v_mfma_f32_16x16x32_bf16 v[108:111], v[146:149], v[192:195], v[108:111]
	v_mfma_f32_16x16x32_bf16 v[104:107], v[160:163], v[192:195], v[104:107]
	v_mfma_f32_16x16x32_bf16 v[92:95], v[146:149], v[200:203], v[92:95]
	v_mfma_f32_16x16x32_bf16 v[88:91], v[160:163], v[200:203], v[88:91]
	v_mfma_f32_16x16x32_bf16 v[76:79], v[146:149], v[208:211], v[76:79]
	v_mfma_f32_16x16x32_bf16 v[72:75], v[160:163], v[208:211], v[72:75]
	v_mfma_f32_16x16x32_bf16 v[124:127], v[150:153], v[188:191], v[124:127]
	v_mfma_f32_16x16x32_bf16 v[120:123], v[164:167], v[188:191], v[120:123]
	v_mfma_f32_16x16x32_bf16 v[108:111], v[150:153], v[196:199], v[108:111]
	v_mfma_f32_16x16x32_bf16 v[104:107], v[164:167], v[196:199], v[104:107]
	v_mfma_f32_16x16x32_bf16 v[92:95], v[150:153], v[204:207], v[92:95]
	v_mfma_f32_16x16x32_bf16 v[88:91], v[164:167], v[204:207], v[88:91]
	v_mfma_f32_16x16x32_bf16 v[76:79], v[150:153], v[212:215], v[76:79]
	v_mfma_f32_16x16x32_bf16 v[72:75], v[164:167], v[212:215], v[72:75]
	v_mfma_f32_16x16x32_bf16 v[116:119], v[168:171], v[184:187], v[116:119]
	v_mfma_f32_16x16x32_bf16 v[112:115], v[176:179], v[184:187], v[112:115]
	v_mfma_f32_16x16x32_bf16 v[100:103], v[168:171], v[192:195], v[100:103]
	v_mfma_f32_16x16x32_bf16 v[96:99], v[176:179], v[192:195], v[96:99]
	v_mfma_f32_16x16x32_bf16 v[84:87], v[168:171], v[200:203], v[84:87]
	v_mfma_f32_16x16x32_bf16 v[80:83], v[176:179], v[200:203], v[80:83]
	v_mfma_f32_16x16x32_bf16 v[68:71], v[168:171], v[208:211], v[68:71]
	v_mfma_f32_16x16x32_bf16 v[64:67], v[176:179], v[208:211], v[64:67]
	v_mfma_f32_16x16x32_bf16 v[116:119], v[172:175], v[188:191], v[116:119]
	v_mfma_f32_16x16x32_bf16 v[112:115], v[180:183], v[188:191], v[112:115]
	v_mfma_f32_16x16x32_bf16 v[100:103], v[172:175], v[196:199], v[100:103]
	v_mfma_f32_16x16x32_bf16 v[96:99], v[180:183], v[196:199], v[96:99]
	v_mfma_f32_16x16x32_bf16 v[84:87], v[172:175], v[204:207], v[84:87]
	v_mfma_f32_16x16x32_bf16 v[80:83], v[180:183], v[204:207], v[80:83]
	v_mfma_f32_16x16x32_bf16 v[68:71], v[172:175], v[212:215], v[68:71]
	v_mfma_f32_16x16x32_bf16 v[64:67], v[180:183], v[212:215], v[64:67]
	s_setprio 0
	s_barrier
; #define PG8_STAGE(bufoff, gbase, voff) do { _Pragma("unroll") for (int _i = 0; _i < 2; ++_i) \
;         __builtin_amdgcn_global_load_lds((const unsigned*)((const char*)(gbase) + (voff)[_i]), (LAS unsigned*)(lds + (bufoff) + ldsw + _i * 8192), 16, 0, 0); } while (0)
; #define PG8_LDA(dst, b, h) do { _Pragma("unroll") for (int m = 0; m < 4; ++m) _Pragma("unroll") for (int k = 0; k < 2; ++k) dst[m][k] = *(const LAS bf16x8*)(lds + PG8_SA(b, h) + aoff + m * 2048 + k * 1024); } while (0)
; #define PG8_MMA(ai, bj, At, Bt) do { __builtin_amdgcn_s_setprio(1); _Pragma("unroll") for (int m = 0; m < 4; ++m) _Pragma("unroll") for (int n = 0; n < 2; ++n) _Pragma("unroll") for (int k = 0; k < 2; ++k) \
;         acc[ai][bj][m][n] = __builtin_amdgcn_mfma_f32_16x16x32_bf16(Bt[n][k], At[m][k], acc[ai][bj][m][n], 0, 0, 0); __builtin_amdgcn_s_setprio(0); } while (0)
; #define PG8_WAIT_V(n) asm volatile("s_waitcnt vmcnt(" #n ")" ::: "memory")
; #define PG8_WAIT_L(n) asm volatile("s_waitcnt lgkmcnt(" #n ")" ::: "memory")
; #define PG8_BAR __builtin_amdgcn_s_barrier()
; #define PG8_SCHED __builtin_amdgcn_sched_barrier(0)
; template <class Desc, class Epi>
; DI void gemm_phase(LAS unsigned char* lds, const Desc& D, const Epi& E, int wv) {
;     ...
;             PG8_LDA(At, 1, 1); PG8_STAGE(PG8_SB(1, 0), b3, voffB); PG8_STAGE(PG8_SB(1, 1), b3 + hstepB, voffB); PG8_STAGE(PG8_SA(1, 0), a3, voffA);
;             PG8_WAIT_V(8); PG8_WAIT_L(0); PG8_BAR; PG8_MMA(1, 0, At, B0); PG8_MMA(1, 1, At, B1); PG8_BAR; PG8_SCHED;
;         }
;         if (wr == 0) PG8_BAR;
	s_add_i32 s51, s51, s2
	v_lshl_add_u64 v[154:155], v[154:155], 0, s[10:11]
	s_mov_b32 m0, s51
	ds_read_b128 v[184:187], v159 offset:49152
	ds_read_b128 v[188:191], v159 offset:50176
	ds_read_b128 v[192:195], v159 offset:51200
	ds_read_b128 v[196:199], v159 offset:52224
	ds_read_b128 v[200:203], v159 offset:53248
	ds_read_b128 v[204:207], v159 offset:54272
	ds_read_b128 v[208:211], v159 offset:55296
	ds_read_b128 v[212:215], v159 offset:56320
	global_load_lds_dwordx4 v[154:155], off
	s_add_i32 m0, s51, 0x2000
	s_add_u32 s40, s40, 0x80080
	v_lshl_add_u64 v[154:155], v[216:217], 0, s[10:11]
	s_addc_u32 s41, s41, 0
	s_add_i32 s51, s60, s2
	global_load_lds_dwordx4 v[154:155], off
	v_lshl_add_u64 v[154:155], s[40:41], 0, v[132:133]
	s_mov_b32 m0, s51
	s_nop 0
	global_load_lds_dwordx4 v[154:155], off
	v_lshl_add_u64 v[154:155], s[40:41], 0, v[128:129]
	s_add_i32 m0, s51, 0x2000
	s_nop 0
	global_load_lds_dwordx4 v[154:155], off
	v_lshl_add_u64 v[154:155], v[218:219], 0, s[10:11]
	s_mov_b32 m0, s43
	s_nop 0
	global_load_lds_dwordx4 v[154:155], off
	v_lshl_add_u64 v[154:155], v[220:221], 0, s[10:11]
	s_mov_b32 m0, s46
	s_nop 0
	global_load_lds_dwordx4 v[154:155], off
	s_waitcnt vmcnt(8)
	s_waitcnt lgkmcnt(0)
	s_barrier
	s_setprio 1
	v_mfma_f32_16x16x32_bf16 v[60:63], v[146:149], v[184:187], v[60:63]
	v_mfma_f32_16x16x32_bf16 v[56:59], v[160:163], v[184:187], v[56:59]
	v_mfma_f32_16x16x32_bf16 v[44:47], v[146:149], v[192:195], v[44:47]
	v_mfma_f32_16x16x32_bf16 v[40:43], v[160:163], v[192:195], v[40:43]
	v_mfma_f32_16x16x32_bf16 v[28:31], v[146:149], v[200:203], v[28:31]
	v_mfma_f32_16x16x32_bf16 v[24:27], v[160:163], v[200:203], v[24:27]
	v_mfma_f32_16x16x32_bf16 v[12:15], v[146:149], v[208:211], v[12:15]
	v_mfma_f32_16x16x32_bf16 v[8:11], v[160:163], v[208:211], v[8:11]
	v_mfma_f32_16x16x32_bf16 v[60:63], v[150:153], v[188:191], v[60:63]
	v_mfma_f32_16x16x32_bf16 v[56:59], v[164:167], v[188:191], v[56:59]
	v_mfma_f32_16x16x32_bf16 v[44:47], v[150:153], v[196:199], v[44:47]
	v_mfma_f32_16x16x32_bf16 v[40:43], v[164:167], v[196:199], v[40:43]
	v_mfma_f32_16x16x32_bf16 v[28:31], v[150:153], v[204:207], v[28:31]
	v_mfma_f32_16x16x32_bf16 v[24:27], v[164:167], v[204:207], v[24:27]
	v_mfma_f32_16x16x32_bf16 v[12:15], v[150:153], v[212:215], v[12:15]
	v_mfma_f32_16x16x32_bf16 v[8:11], v[164:167], v[212:215], v[8:11]
	v_mfma_f32_16x16x32_bf16 v[52:55], v[168:171], v[184:187], v[52:55]
	v_mfma_f32_16x16x32_bf16 v[48:51], v[176:179], v[184:187], v[48:51]
	v_mfma_f32_16x16x32_bf16 v[36:39], v[168:171], v[192:195], v[36:39]
	v_mfma_f32_16x16x32_bf16 v[32:35], v[176:179], v[192:195], v[32:35]
	v_mfma_f32_16x16x32_bf16 v[20:23], v[168:171], v[200:203], v[20:23]
	v_mfma_f32_16x16x32_bf16 v[16:19], v[176:179], v[200:203], v[16:19]
	v_mfma_f32_16x16x32_bf16 v[4:7], v[168:171], v[208:211], v[4:7]
	v_mfma_f32_16x16x32_bf16 v[0:3], v[176:179], v[208:211], v[0:3]
	v_mfma_f32_16x16x32_bf16 v[52:55], v[172:175], v[188:191], v[52:55]
	v_mfma_f32_16x16x32_bf16 v[48:51], v[180:183], v[188:191], v[48:51]
	v_mfma_f32_16x16x32_bf16 v[36:39], v[172:175], v[196:199], v[36:39]
	v_mfma_f32_16x16x32_bf16 v[32:35], v[180:183], v[196:199], v[32:35]
	v_mfma_f32_16x16x32_bf16 v[20:23], v[172:175], v[204:207], v[20:23]
	v_mfma_f32_16x16x32_bf16 v[16:19], v[180:183], v[204:207], v[16:19]
	v_mfma_f32_16x16x32_bf16 v[4:7], v[172:175], v[212:215], v[4:7]
	v_mfma_f32_16x16x32_bf16 v[0:3], v[180:183], v[212:215], v[0:3]
	s_setprio 0
	s_barrier
	s_add_i32 s50, s50, 2
	s_add_u32 s22, s22, 0x100
	s_addc_u32 s23, s23, 0
	s_add_u32 s19, s19, 0x100
	s_addc_u32 s21, s21, 0
	s_cmp_gt_u32 s50, 29
	s_cbranch_scc0 .LBB0_1313
	s_and_b64 vcc, exec, s[12:13]
	s_cbranch_vccz .LBB0_1316
	s_barrier

; #define PG8_STAGE(bufoff, gbase, voff) do { _Pragma("unroll") for (int _i = 0; _i < 2; ++_i) \
;         __builtin_amdgcn_global_load_lds((const unsigned*)((const char*)(gbase) + (voff)[_i]), (LAS unsigned*)(lds + (bufoff) + ldsw + _i * 8192), 16, 0, 0); } while (0)
; #define PG8_LDA(dst, b, h) do { _Pragma("unroll") for (int m = 0; m < 4; ++m) _Pragma("unroll") for (int k = 0; k < 2; ++k) dst[m][k] = *(const LAS bf16x8*)(lds + PG8_SA(b, h) + aoff + m * 2048 + k * 1024); } while (0)
; #define PG8_LDB(dst, b, h) do { _Pragma("unroll") for (int n = 0; n < 2; ++n) _Pragma("unroll") for (int k = 0; k < 2; ++k) dst[n][k] = *(const LAS bf16x8*)(lds + PG8_SB(b, h) + boff + n * 2048 + k * 1024); } while (0)
; #define PG8_MMA(ai, bj, At, Bt) do { __builtin_amdgcn_s_setprio(1); _Pragma("unroll") for (int m = 0; m < 4; ++m) _Pragma("unroll") for (int n = 0; n < 2; ++n) _Pragma("unroll") for (int k = 0; k < 2; ++k) \
;         acc[ai][bj][m][n] = __builtin_amdgcn_mfma_f32_16x16x32_bf16(Bt[n][k], At[m][k], acc[ai][bj][m][n], 0, 0, 0); __builtin_amdgcn_s_setprio(0); } while (0)
; #define PG8_WAIT_V(n) asm volatile("s_waitcnt vmcnt(" #n ")" ::: "memory")
; #define PG8_WAIT_L(n) asm volatile("s_waitcnt lgkmcnt(" #n ")" ::: "memory")
; #define PG8_BAR __builtin_amdgcn_s_barrier()
; #define PG8_SCHED __builtin_amdgcn_sched_barrier(0)
; template <class Desc, class Epi>
; DI void gemm_phase(LAS unsigned char* lds, const Desc& D, const Epi& E, int wv) {
;     ...
;             const bool last = (t == nt - 2);
;             const char* a1 = cA + (size_t)(t + 1) * kstep;
;             const char* a2 = last ? nA : cA + (size_t)(t + 2) * kstep; const char* b2 = last ? nB : cB + (size_t)(t + 2) * kstep;
;             const char* a3 = a2 + kstep; const char* b3 = b2 + kstep;
;             PG8_LDB(B0, 0, 0); PG8_LDB(B1, 0, 1); PG8_SCHED; PG8_LDA(At, 0, 0); PG8_STAGE(PG8_SA(1, 1), a1 + hstepA, voffA);
;             PG8_WAIT_V(8); PG8_WAIT_L(0); PG8_BAR; PG8_MMA(0, 0, At, B0); PG8_MMA(0, 1, At, B1); PG8_BAR; PG8_SCHED;
;             PG8_LDA(At, 0, 1); PG8_STAGE(PG8_SB(0, 0), b2, voffB); PG8_STAGE(PG8_SB(0, 1), b2 + hstepB, voffB); PG8_STAGE(PG8_SA(0, 0), a2, voffA);
.LBB0_1501:
	ds_read_b128 v[128:131], v230
	ds_read_b128 v[132:135], v230 offset:1024
	ds_read_b128 v[136:139], v230 offset:2048
	ds_read_b128 v[140:143], v230 offset:3072
	ds_read_b128 v[144:147], v231
	ds_read_b128 v[148:151], v231 offset:1024
	ds_read_b128 v[152:155], v231 offset:2048
	ds_read_b128 v[156:159], v231 offset:3072
	s_add_u32 s22, s20, 0xfff80080
	s_addc_u32 s23, s21, -1
	s_cmp_eq_u32 s64, 28
	s_cselect_b32 s41, s11, s23
	s_cselect_b32 s40, s10, s22
	s_cselect_b32 s23, s13, s17
	s_cselect_b32 s22, s12, s15
	v_lshl_add_u64 v[192:193], s[20:21], 0, v[216:217]
	s_add_i32 m0, s30, 0xc000
	ds_read_b128 v[160:163], v232
	ds_read_b128 v[164:167], v232 offset:1024
	ds_read_b128 v[168:171], v232 offset:2048
	ds_read_b128 v[172:175], v232 offset:3072
	ds_read_b128 v[176:179], v232 offset:4096
	ds_read_b128 v[180:183], v232 offset:5120
	ds_read_b128 v[184:187], v232 offset:6144
	ds_read_b128 v[188:191], v232 offset:7168
	global_load_lds_dwordx4 v[192:193], off
	v_lshl_add_u64 v[192:193], s[20:21], 0, v[218:219]
	s_add_i32 m0, s30, 0xe000
	s_nop 0
	global_load_lds_dwordx4 v[192:193], off
	s_waitcnt vmcnt(8)
	s_waitcnt lgkmcnt(0)
	s_barrier
	s_setprio 1
	v_mfma_f32_16x16x32_bf16 v[124:127], v[128:131], v[160:163], v[124:127]
	v_mfma_f32_16x16x32_bf16 v[120:123], v[136:139], v[160:163], v[120:123]
	v_mfma_f32_16x16x32_bf16 v[112:115], v[128:131], v[168:171], v[112:115]
	v_mfma_f32_16x16x32_bf16 v[104:107], v[136:139], v[168:171], v[104:107]
	v_mfma_f32_16x16x32_bf16 v[96:99], v[128:131], v[176:179], v[96:99]
	v_mfma_f32_16x16x32_bf16 v[88:91], v[136:139], v[176:179], v[88:91]
	v_mfma_f32_16x16x32_bf16 v[80:83], v[128:131], v[184:187], v[80:83]
	v_mfma_f32_16x16x32_bf16 v[72:75], v[136:139], v[184:187], v[72:75]
	v_mfma_f32_16x16x32_bf16 v[124:127], v[132:135], v[164:167], v[124:127]
	v_mfma_f32_16x16x32_bf16 v[120:123], v[140:143], v[164:167], v[120:123]
	v_mfma_f32_16x16x32_bf16 v[112:115], v[132:135], v[172:175], v[112:115]
	v_mfma_f32_16x16x32_bf16 v[104:107], v[140:143], v[172:175], v[104:107]
	v_mfma_f32_16x16x32_bf16 v[96:99], v[132:135], v[180:183], v[96:99]
	v_mfma_f32_16x16x32_bf16 v[88:91], v[140:143], v[180:183], v[88:91]
	v_mfma_f32_16x16x32_bf16 v[80:83], v[132:135], v[188:191], v[80:83]
	v_mfma_f32_16x16x32_bf16 v[72:75], v[140:143], v[188:191], v[72:75]
	v_mfma_f32_16x16x32_bf16 v[116:119], v[144:147], v[160:163], v[116:119]
	v_mfma_f32_16x16x32_bf16 v[108:111], v[152:155], v[160:163], v[108:111]
	v_mfma_f32_16x16x32_bf16 v[100:103], v[144:147], v[168:171], v[100:103]
	v_mfma_f32_16x16x32_bf16 v[92:95], v[152:155], v[168:171], v[92:95]
	v_mfma_f32_16x16x32_bf16 v[84:87], v[144:147], v[176:179], v[84:87]
	v_mfma_f32_16x16x32_bf16 v[76:79], v[152:155], v[176:179], v[76:79]
	v_mfma_f32_16x16x32_bf16 v[68:71], v[144:147], v[184:187], v[68:71]
	v_mfma_f32_16x16x32_bf16 v[64:67], v[152:155], v[184:187], v[64:67]
	v_mfma_f32_16x16x32_bf16 v[116:119], v[148:151], v[164:167], v[116:119]
	v_mfma_f32_16x16x32_bf16 v[108:111], v[156:159], v[164:167], v[108:111]
	v_mfma_f32_16x16x32_bf16 v[100:103], v[148:151], v[172:175], v[100:103]
	v_mfma_f32_16x16x32_bf16 v[92:95], v[156:159], v[172:175], v[92:95]
	v_mfma_f32_16x16x32_bf16 v[84:87], v[148:151], v[180:183], v[84:87]
	v_mfma_f32_16x16x32_bf16 v[76:79], v[156:159], v[180:183], v[76:79]
	v_mfma_f32_16x16x32_bf16 v[68:71], v[148:151], v[188:191], v[68:71]
	v_mfma_f32_16x16x32_bf16 v[64:67], v[156:159], v[188:191], v[64:67]
	s_setprio 0
	s_barrier
	s_add_i32 s65, s51, s28
	v_lshl_add_u64 v[192:193], s[22:23], 0, v[212:213]
	s_mov_b32 m0, s65
	ds_read_b128 v[160:163], v232 offset:16384
	ds_read_b128 v[164:167], v232 offset:17408
	ds_read_b128 v[168:171], v232 offset:18432
	ds_read_b128 v[172:175], v232 offset:19456
	ds_read_b128 v[176:179], v232 offset:20480
	ds_read_b128 v[180:183], v232 offset:21504
	ds_read_b128 v[184:187], v232 offset:22528
	ds_read_b128 v[188:191], v232 offset:23552
	global_load_lds_dwordx4 v[192:193], off
	s_add_i32 m0, s65, 0x2000
	s_add_u32 s66, s22, 0x80000
	v_lshl_add_u64 v[194:195], s[22:23], 0, v[208:209]
	s_addc_u32 s67, s23, 0
	s_add_i32 s65, s52, s28
	global_load_lds_dwordx4 v[194:195], off
	v_lshl_add_u64 v[196:197], s[66:67], 0, v[212:213]
	s_mov_b32 m0, s65
	v_lshl_add_u64 v[198:199], s[40:41], 0, v[210:211]
	global_load_lds_dwordx4 v[196:197], off
	v_lshl_add_u64 v[196:197], s[66:67], 0, v[208:209]
	s_add_i32 m0, s65, 0x2000
	s_nop 0
	global_load_lds_dwordx4 v[196:197], off
	v_lshl_add_u64 v[196:197], s[40:41], 0, v[214:215]
	s_mov_b32 m0, s30
	s_nop 0
	global_load_lds_dwordx4 v[196:197], off
	s_mov_b32 m0, s31
	s_nop 0
	global_load_lds_dwordx4 v[198:199], off
	s_waitcnt vmcnt(8)
	s_waitcnt lgkmcnt(0)
	s_barrier
; #define PG8_STAGE(bufoff, gbase, voff) do { _Pragma("unroll") for (int _i = 0; _i < 2; ++_i) \
;         __builtin_amdgcn_global_load_lds((const unsigned*)((const char*)(gbase) + (voff)[_i]), (LAS unsigned*)(lds + (bufoff) + ldsw + _i * 8192), 16, 0, 0); } while (0)
; #define PG8_LDA(dst, b, h) do { _Pragma("unroll") for (int m = 0; m < 4; ++m) _Pragma("unroll") for (int k = 0; k < 2; ++k) dst[m][k] = *(const LAS bf16x8*)(lds + PG8_SA(b, h) + aoff + m * 2048 + k * 1024); } while (0)
; #define PG8_LDB(dst, b, h) do { _Pragma("unroll") for (int n = 0; n < 2; ++n) _Pragma("unroll") for (int k = 0; k < 2; ++k) dst[n][k] = *(const LAS bf16x8*)(lds + PG8_SB(b, h) + boff + n * 2048 + k * 1024); } while (0)
; #define PG8_MMA(ai, bj, At, Bt) do { __builtin_amdgcn_s_setprio(1); _Pragma("unroll") for (int m = 0; m < 4; ++m) _Pragma("unroll") for (int n = 0; n < 2; ++n) _Pragma("unroll") for (int k = 0; k < 2; ++k) \
;         acc[ai][bj][m][n] = __builtin_amdgcn_mfma_f32_16x16x32_bf16(Bt[n][k], At[m][k], acc[ai][bj][m][n], 0, 0, 0); __builtin_amdgcn_s_setprio(0); } while (0)
; #define PG8_WAIT_V(n) asm volatile("s_waitcnt vmcnt(" #n ")" ::: "memory")
; #define PG8_WAIT_L(n) asm volatile("s_waitcnt lgkmcnt(" #n ")" ::: "memory")
; #define PG8_BAR __builtin_amdgcn_s_barrier()
; #define PG8_SCHED __builtin_amdgcn_sched_barrier(0)
; template <class Desc, class Epi>
; DI void gemm_phase(LAS unsigned char* lds, const Desc& D, const Epi& E, int wv) {
;     ...
;             PG8_WAIT_V(8); PG8_WAIT_L(0); PG8_BAR; PG8_MMA(1, 0, At, B0); PG8_MMA(1, 1, At, B1); PG8_BAR; PG8_SCHED;
;             PG8_LDB(B0, 1, 0); PG8_LDB(B1, 1, 1); PG8_SCHED; PG8_LDA(At, 1, 0); PG8_STAGE(PG8_SA(0, 1), a2 + hstepA, voffA);
;             PG8_WAIT_V(8); PG8_WAIT_L(0); PG8_BAR; PG8_MMA(0, 0, At, B0); PG8_MMA(0, 1, At, B1); PG8_BAR; PG8_SCHED;
	s_setprio 1
	v_mfma_f32_16x16x32_bf16 v[60:63], v[128:131], v[160:163], v[60:63]
	v_mfma_f32_16x16x32_bf16 v[56:59], v[136:139], v[160:163], v[56:59]
	v_mfma_f32_16x16x32_bf16 v[48:51], v[128:131], v[168:171], v[48:51]
	v_mfma_f32_16x16x32_bf16 v[40:43], v[136:139], v[168:171], v[40:43]
	v_mfma_f32_16x16x32_bf16 v[32:35], v[128:131], v[176:179], v[32:35]
	v_mfma_f32_16x16x32_bf16 v[24:27], v[136:139], v[176:179], v[24:27]
	v_mfma_f32_16x16x32_bf16 v[16:19], v[128:131], v[184:187], v[16:19]
	v_mfma_f32_16x16x32_bf16 v[8:11], v[136:139], v[184:187], v[8:11]
	v_mfma_f32_16x16x32_bf16 v[60:63], v[132:135], v[164:167], v[60:63]
	v_mfma_f32_16x16x32_bf16 v[56:59], v[140:143], v[164:167], v[56:59]
	v_mfma_f32_16x16x32_bf16 v[48:51], v[132:135], v[172:175], v[48:51]
	v_mfma_f32_16x16x32_bf16 v[40:43], v[140:143], v[172:175], v[40:43]
	v_mfma_f32_16x16x32_bf16 v[32:35], v[132:135], v[180:183], v[32:35]
	v_mfma_f32_16x16x32_bf16 v[24:27], v[140:143], v[180:183], v[24:27]
	v_mfma_f32_16x16x32_bf16 v[16:19], v[132:135], v[188:191], v[16:19]
	v_mfma_f32_16x16x32_bf16 v[8:11], v[140:143], v[188:191], v[8:11]
	v_mfma_f32_16x16x32_bf16 v[52:55], v[144:147], v[160:163], v[52:55]
	v_mfma_f32_16x16x32_bf16 v[44:47], v[152:155], v[160:163], v[44:47]
	v_mfma_f32_16x16x32_bf16 v[36:39], v[144:147], v[168:171], v[36:39]
	v_mfma_f32_16x16x32_bf16 v[28:31], v[152:155], v[168:171], v[28:31]
	v_mfma_f32_16x16x32_bf16 v[20:23], v[144:147], v[176:179], v[20:23]
	v_mfma_f32_16x16x32_bf16 v[12:15], v[152:155], v[176:179], v[12:15]
	v_mfma_f32_16x16x32_bf16 v[4:7], v[144:147], v[184:187], v[4:7]
	v_mfma_f32_16x16x32_bf16 v[0:3], v[152:155], v[184:187], v[0:3]
	v_mfma_f32_16x16x32_bf16 v[52:55], v[148:151], v[164:167], v[52:55]
	v_mfma_f32_16x16x32_bf16 v[44:47], v[156:159], v[164:167], v[44:47]
	v_mfma_f32_16x16x32_bf16 v[36:39], v[148:151], v[172:175], v[36:39]
	v_mfma_f32_16x16x32_bf16 v[28:31], v[156:159], v[172:175], v[28:31]
	v_mfma_f32_16x16x32_bf16 v[20:23], v[148:151], v[180:183], v[20:23]
	v_mfma_f32_16x16x32_bf16 v[12:15], v[156:159], v[180:183], v[12:15]
	v_mfma_f32_16x16x32_bf16 v[4:7], v[148:151], v[188:191], v[4:7]
	v_mfma_f32_16x16x32_bf16 v[0:3], v[156:159], v[188:191], v[0:3]
	s_setprio 0
	s_barrier
	s_add_i32 s65, 0, 0x18000
	s_add_i32 s66, 0, 0x1c000
	v_add_u32_e32 v140, s65, v229
	v_add_u32_e32 v156, s66, v229
	ds_read_b128 v[128:131], v140
	ds_read_b128 v[132:135], v140 offset:1024
	ds_read_b128 v[136:139], v140 offset:2048
	ds_read_b128 v[140:143], v140 offset:3072
	ds_read_b128 v[144:147], v156
	ds_read_b128 v[148:151], v156 offset:1024
	ds_read_b128 v[152:155], v156 offset:2048
	ds_read_b128 v[156:159], v156 offset:3072
	s_add_u32 s40, s40, 0x80000
	s_addc_u32 s41, s41, 0
	s_mov_b32 m0, s34
	v_lshl_add_u64 v[200:201], s[40:41], 0, v[214:215]
	ds_read_b128 v[160:163], v232 offset:32768
	ds_read_b128 v[164:167], v232 offset:33792
	ds_read_b128 v[168:171], v232 offset:34816
	ds_read_b128 v[172:175], v232 offset:35840
	ds_read_b128 v[176:179], v232 offset:36864
	ds_read_b128 v[180:183], v232 offset:37888
	ds_read_b128 v[184:187], v232 offset:38912
	ds_read_b128 v[188:191], v232 offset:39936
	global_load_lds_dwordx4 v[200:201], off
	v_lshl_add_u64 v[200:201], s[40:41], 0, v[210:211]
	s_mov_b32 m0, s35
	s_nop 0
	global_load_lds_dwordx4 v[200:201], off
	s_waitcnt vmcnt(8)
	s_waitcnt lgkmcnt(0)
	s_barrier
	s_setprio 1
	v_mfma_f32_16x16x32_bf16 v[124:127], v[128:131], v[160:163], v[124:127]
	v_mfma_f32_16x16x32_bf16 v[120:123], v[136:139], v[160:163], v[120:123]
	v_mfma_f32_16x16x32_bf16 v[112:115], v[128:131], v[168:171], v[112:115]
	v_mfma_f32_16x16x32_bf16 v[104:107], v[136:139], v[168:171], v[104:107]
	v_mfma_f32_16x16x32_bf16 v[96:99], v[128:131], v[176:179], v[96:99]
	v_mfma_f32_16x16x32_bf16 v[88:91], v[136:139], v[176:179], v[88:91]
	v_mfma_f32_16x16x32_bf16 v[80:83], v[128:131], v[184:187], v[80:83]
	v_mfma_f32_16x16x32_bf16 v[72:75], v[136:139], v[184:187], v[72:75]
	v_mfma_f32_16x16x32_bf16 v[124:127], v[132:135], v[164:167], v[124:127]
	v_mfma_f32_16x16x32_bf16 v[120:123], v[140:143], v[164:167], v[120:123]
	v_mfma_f32_16x16x32_bf16 v[112:115], v[132:135], v[172:175], v[112:115]
	v_mfma_f32_16x16x32_bf16 v[104:107], v[140:143], v[172:175], v[104:107]
	v_mfma_f32_16x16x32_bf16 v[96:99], v[132:135], v[180:183], v[96:99]
	v_mfma_f32_16x16x32_bf16 v[88:91], v[140:143], v[180:183], v[88:91]
	v_mfma_f32_16x16x32_bf16 v[80:83], v[132:135], v[188:191], v[80:83]
	v_mfma_f32_16x16x32_bf16 v[72:75], v[140:143], v[188:191], v[72:75]
	v_mfma_f32_16x16x32_bf16 v[116:119], v[144:147], v[160:163], v[116:119]
	v_mfma_f32_16x16x32_bf16 v[108:111], v[152:155], v[160:163], v[108:111]
	v_mfma_f32_16x16x32_bf16 v[100:103], v[144:147], v[168:171], v[100:103]
	v_mfma_f32_16x16x32_bf16 v[92:95], v[152:155], v[168:171], v[92:95]
	v_mfma_f32_16x16x32_bf16 v[84:87], v[144:147], v[176:179], v[84:87]
	v_mfma_f32_16x16x32_bf16 v[76:79], v[152:155], v[176:179], v[76:79]
	v_mfma_f32_16x16x32_bf16 v[68:71], v[144:147], v[184:187], v[68:71]
	v_mfma_f32_16x16x32_bf16 v[64:67], v[152:155], v[184:187], v[64:67]
	v_mfma_f32_16x16x32_bf16 v[116:119], v[148:151], v[164:167], v[116:119]
	v_mfma_f32_16x16x32_bf16 v[108:111], v[156:159], v[164:167], v[108:111]
	v_mfma_f32_16x16x32_bf16 v[100:103], v[148:151], v[172:175], v[100:103]
	v_mfma_f32_16x16x32_bf16 v[92:95], v[156:159], v[172:175], v[92:95]
	v_mfma_f32_16x16x32_bf16 v[84:87], v[148:151], v[180:183], v[84:87]
	v_mfma_f32_16x16x32_bf16 v[76:79], v[156:159], v[180:183], v[76:79]
	v_mfma_f32_16x16x32_bf16 v[68:71], v[148:151], v[188:191], v[68:71]
	v_mfma_f32_16x16x32_bf16 v[64:67], v[156:159], v[188:191], v[64:67]
	s_setprio 0
	s_barrier
; #define PG8_STAGE(bufoff, gbase, voff) do { _Pragma("unroll") for (int _i = 0; _i < 2; ++_i) \
;         __builtin_amdgcn_global_load_lds((const unsigned*)((const char*)(gbase) + (voff)[_i]), (LAS unsigned*)(lds + (bufoff) + ldsw + _i * 8192), 16, 0, 0); } while (0)
; #define PG8_LDA(dst, b, h) do { _Pragma("unroll") for (int m = 0; m < 4; ++m) _Pragma("unroll") for (int k = 0; k < 2; ++k) dst[m][k] = *(const LAS bf16x8*)(lds + PG8_SA(b, h) + aoff + m * 2048 + k * 1024); } while (0)
; #define PG8_MMA(ai, bj, At, Bt) do { __builtin_amdgcn_s_setprio(1); _Pragma("unroll") for (int m = 0; m < 4; ++m) _Pragma("unroll") for (int n = 0; n < 2; ++n) _Pragma("unroll") for (int k = 0; k < 2; ++k) \
;         acc[ai][bj][m][n] = __builtin_amdgcn_mfma_f32_16x16x32_bf16(Bt[n][k], At[m][k], acc[ai][bj][m][n], 0, 0, 0); __builtin_amdgcn_s_setprio(0); } while (0)
; #define PG8_WAIT_V(n) asm volatile("s_waitcnt vmcnt(" #n ")" ::: "memory")
; #define PG8_WAIT_L(n) asm volatile("s_waitcnt lgkmcnt(" #n ")" ::: "memory")
; #define PG8_BAR __builtin_amdgcn_s_barrier()
; #define PG8_SCHED __builtin_amdgcn_sched_barrier(0)
; template <class Desc, class Epi>
; DI void gemm_phase(LAS unsigned char* lds, const Desc& D, const Epi& E, int wv) {
;     ...
;             PG8_LDA(At, 1, 1); PG8_STAGE(PG8_SB(1, 0), b3, voffB); PG8_STAGE(PG8_SB(1, 1), b3 + hstepB, voffB); PG8_STAGE(PG8_SA(1, 0), a3, voffA);
;             PG8_WAIT_V(8); PG8_WAIT_L(0); PG8_BAR; PG8_MMA(1, 0, At, B0); PG8_MMA(1, 1, At, B1); PG8_BAR; PG8_SCHED;
;         }
;         if (wr == 0) PG8_BAR;
	s_add_i32 s40, s65, s28
	v_lshl_add_u64 v[192:193], v[192:193], 0, s[6:7]
	s_mov_b32 m0, s40
	ds_read_b128 v[160:163], v232 offset:49152
	ds_read_b128 v[164:167], v232 offset:50176
	ds_read_b128 v[168:171], v232 offset:51200
	ds_read_b128 v[172:175], v232 offset:52224
	ds_read_b128 v[176:179], v232 offset:53248
	ds_read_b128 v[180:183], v232 offset:54272
	ds_read_b128 v[184:187], v232 offset:55296
	ds_read_b128 v[188:191], v232 offset:56320
	global_load_lds_dwordx4 v[192:193], off
	s_add_i32 m0, s40, 0x2000
	s_add_u32 s22, s22, 0x80080
	v_lshl_add_u64 v[192:193], v[194:195], 0, s[6:7]
	s_addc_u32 s23, s23, 0
	s_add_i32 s40, s66, s28
	global_load_lds_dwordx4 v[192:193], off
	v_lshl_add_u64 v[192:193], s[22:23], 0, v[212:213]
	s_mov_b32 m0, s40
	s_nop 0
	global_load_lds_dwordx4 v[192:193], off
	v_lshl_add_u64 v[192:193], s[22:23], 0, v[208:209]
	s_add_i32 m0, s40, 0x2000
	s_nop 0
	global_load_lds_dwordx4 v[192:193], off
	v_lshl_add_u64 v[192:193], v[196:197], 0, s[6:7]
	s_mov_b32 m0, s47
	s_nop 0
	global_load_lds_dwordx4 v[192:193], off
	v_lshl_add_u64 v[192:193], v[198:199], 0, s[6:7]
	s_mov_b32 m0, s48
	s_nop 0
	global_load_lds_dwordx4 v[192:193], off
	s_waitcnt vmcnt(8)
	s_waitcnt lgkmcnt(0)
	s_barrier
	s_setprio 1
	v_mfma_f32_16x16x32_bf16 v[60:63], v[128:131], v[160:163], v[60:63]
	v_mfma_f32_16x16x32_bf16 v[56:59], v[136:139], v[160:163], v[56:59]
	v_mfma_f32_16x16x32_bf16 v[48:51], v[128:131], v[168:171], v[48:51]
	v_mfma_f32_16x16x32_bf16 v[40:43], v[136:139], v[168:171], v[40:43]
	v_mfma_f32_16x16x32_bf16 v[32:35], v[128:131], v[176:179], v[32:35]
	v_mfma_f32_16x16x32_bf16 v[24:27], v[136:139], v[176:179], v[24:27]
	v_mfma_f32_16x16x32_bf16 v[16:19], v[128:131], v[184:187], v[16:19]
	v_mfma_f32_16x16x32_bf16 v[8:11], v[136:139], v[184:187], v[8:11]
	v_mfma_f32_16x16x32_bf16 v[60:63], v[132:135], v[164:167], v[60:63]
	v_mfma_f32_16x16x32_bf16 v[56:59], v[140:143], v[164:167], v[56:59]
	v_mfma_f32_16x16x32_bf16 v[48:51], v[132:135], v[172:175], v[48:51]
	v_mfma_f32_16x16x32_bf16 v[40:43], v[140:143], v[172:175], v[40:43]
	v_mfma_f32_16x16x32_bf16 v[32:35], v[132:135], v[180:183], v[32:35]
	v_mfma_f32_16x16x32_bf16 v[24:27], v[140:143], v[180:183], v[24:27]
	v_mfma_f32_16x16x32_bf16 v[16:19], v[132:135], v[188:191], v[16:19]
	v_mfma_f32_16x16x32_bf16 v[8:11], v[140:143], v[188:191], v[8:11]
	v_mfma_f32_16x16x32_bf16 v[52:55], v[144:147], v[160:163], v[52:55]
	v_mfma_f32_16x16x32_bf16 v[44:47], v[152:155], v[160:163], v[44:47]
	v_mfma_f32_16x16x32_bf16 v[36:39], v[144:147], v[168:171], v[36:39]
	v_mfma_f32_16x16x32_bf16 v[28:31], v[152:155], v[168:171], v[28:31]
	v_mfma_f32_16x16x32_bf16 v[20:23], v[144:147], v[176:179], v[20:23]
	v_mfma_f32_16x16x32_bf16 v[12:15], v[152:155], v[176:179], v[12:15]
	v_mfma_f32_16x16x32_bf16 v[4:7], v[144:147], v[184:187], v[4:7]
	v_mfma_f32_16x16x32_bf16 v[0:3], v[152:155], v[184:187], v[0:3]
	v_mfma_f32_16x16x32_bf16 v[52:55], v[148:151], v[164:167], v[52:55]
	v_mfma_f32_16x16x32_bf16 v[44:47], v[156:159], v[164:167], v[44:47]
	v_mfma_f32_16x16x32_bf16 v[36:39], v[148:151], v[172:175], v[36:39]
	v_mfma_f32_16x16x32_bf16 v[28:31], v[156:159], v[172:175], v[28:31]
	v_mfma_f32_16x16x32_bf16 v[20:23], v[148:151], v[180:183], v[20:23]
	v_mfma_f32_16x16x32_bf16 v[12:15], v[156:159], v[180:183], v[12:15]
	v_mfma_f32_16x16x32_bf16 v[4:7], v[148:151], v[188:191], v[4:7]
	v_mfma_f32_16x16x32_bf16 v[0:3], v[156:159], v[188:191], v[0:3]
	s_setprio 0
	s_barrier
	s_add_i32 s64, s64, 2
	s_add_u32 s20, s20, 0x100
	s_addc_u32 s21, s21, 0
	s_add_u32 s15, s15, 0x100
	s_addc_u32 s17, s17, 0
	s_cmp_gt_u32 s64, 29
	s_cbranch_scc0 .LBB0_1501
	s_and_b64 vcc, exec, s[8:9]
	s_cbranch_vccz .LBB0_1504
	s_barrier

; #define PG8_STAGE(bufoff, gbase, voff) do { _Pragma("unroll") for (int _i = 0; _i < 2; ++_i) \
;         __builtin_amdgcn_global_load_lds((const unsigned*)((const char*)(gbase) + (voff)[_i]), (LAS unsigned*)(lds + (bufoff) + ldsw + _i * 8192), 16, 0, 0); } while (0)
; #define PG8_LDA(dst, b, h) do { _Pragma("unroll") for (int m = 0; m < 4; ++m) _Pragma("unroll") for (int k = 0; k < 2; ++k) dst[m][k] = *(const LAS bf16x8*)(lds + PG8_SA(b, h) + aoff + m * 2048 + k * 1024); } while (0)
; #define PG8_LDB(dst, b, h) do { _Pragma("unroll") for (int n = 0; n < 2; ++n) _Pragma("unroll") for (int k = 0; k < 2; ++k) dst[n][k] = *(const LAS bf16x8*)(lds + PG8_SB(b, h) + boff + n * 2048 + k * 1024); } while (0)
; #define PG8_MMA(ai, bj, At, Bt) do { __builtin_amdgcn_s_setprio(1); _Pragma("unroll") for (int m = 0; m < 4; ++m) _Pragma("unroll") for (int n = 0; n < 2; ++n) _Pragma("unroll") for (int k = 0; k < 2; ++k) \
;         acc[ai][bj][m][n] = __builtin_amdgcn_mfma_f32_16x16x32_bf16(Bt[n][k], At[m][k], acc[ai][bj][m][n], 0, 0, 0); __builtin_amdgcn_s_setprio(0); } while (0)
; #define PG8_WAIT_V(n) asm volatile("s_waitcnt vmcnt(" #n ")" ::: "memory")
; #define PG8_WAIT_L(n) asm volatile("s_waitcnt lgkmcnt(" #n ")" ::: "memory")
; #define PG8_BAR __builtin_amdgcn_s_barrier()
; #define PG8_SCHED __builtin_amdgcn_sched_barrier(0)
; template <class Desc, class Epi>
; DI void gemm_phase(LAS unsigned char* lds, const Desc& D, const Epi& E, int wv) {
;     ...
;             const bool last = (t == nt - 2);
;             const char* a1 = cA + (size_t)(t + 1) * kstep;
;             const char* a2 = last ? nA : cA + (size_t)(t + 2) * kstep; const char* b2 = last ? nB : cB + (size_t)(t + 2) * kstep;
;             const char* a3 = a2 + kstep; const char* b3 = b2 + kstep;
;             PG8_LDB(B0, 0, 0); PG8_LDB(B1, 0, 1); PG8_SCHED; PG8_LDA(At, 0, 0); PG8_STAGE(PG8_SA(1, 1), a1 + hstepA, voffA);
;             PG8_WAIT_V(8); PG8_WAIT_L(0); PG8_BAR; PG8_MMA(0, 0, At, B0); PG8_MMA(0, 1, At, B1); PG8_BAR; PG8_SCHED;
;             PG8_LDA(At, 0, 1); PG8_STAGE(PG8_SB(0, 0), b2, voffB); PG8_STAGE(PG8_SB(0, 1), b2 + hstepB, voffB); PG8_STAGE(PG8_SA(0, 0), a2, voffA);
.LBB0_1632:
	ds_read_b128 v[146:149], v155
	ds_read_b128 v[150:153], v155 offset:1024
	ds_read_b128 v[158:161], v155 offset:2048
	ds_read_b128 v[162:165], v155 offset:3072
	ds_read_b128 v[166:169], v156
	ds_read_b128 v[170:173], v156 offset:1024
	ds_read_b128 v[174:177], v156 offset:2048
	ds_read_b128 v[178:181], v156 offset:3072
	s_add_u32 s17, s62, 0xfff80080
	s_addc_u32 s19, s63, -1
	s_cmp_eq_u32 s8, 28
	s_cselect_b32 s67, s21, s19
	s_cselect_b32 s66, s20, s17
	s_cselect_b32 s65, s23, s7
	s_cselect_b32 s64, s22, s5
	v_lshl_add_u64 v[214:215], s[62:63], 0, v[138:139]
	s_add_i32 m0, s29, 0xc000
	ds_read_b128 v[182:185], v157
	ds_read_b128 v[186:189], v157 offset:1024
	ds_read_b128 v[190:193], v157 offset:2048
	ds_read_b128 v[194:197], v157 offset:3072
	ds_read_b128 v[198:201], v157 offset:4096
	ds_read_b128 v[202:205], v157 offset:5120
	ds_read_b128 v[206:209], v157 offset:6144
	ds_read_b128 v[210:213], v157 offset:7168
	global_load_lds_dwordx4 v[214:215], off
	v_lshl_add_u64 v[214:215], s[62:63], 0, v[140:141]
	s_add_i32 m0, s29, 0xe000
	s_nop 0
	global_load_lds_dwordx4 v[214:215], off
	s_waitcnt vmcnt(8)
	s_waitcnt lgkmcnt(0)
	s_barrier
	s_setprio 1
	v_mfma_f32_16x16x32_bf16 v[124:127], v[146:149], v[182:185], v[124:127]
	v_mfma_f32_16x16x32_bf16 v[120:123], v[158:161], v[182:185], v[120:123]
	v_mfma_f32_16x16x32_bf16 v[108:111], v[146:149], v[190:193], v[108:111]
	v_mfma_f32_16x16x32_bf16 v[104:107], v[158:161], v[190:193], v[104:107]
	v_mfma_f32_16x16x32_bf16 v[92:95], v[146:149], v[198:201], v[92:95]
	v_mfma_f32_16x16x32_bf16 v[88:91], v[158:161], v[198:201], v[88:91]
	v_mfma_f32_16x16x32_bf16 v[76:79], v[146:149], v[206:209], v[76:79]
	v_mfma_f32_16x16x32_bf16 v[72:75], v[158:161], v[206:209], v[72:75]
	v_mfma_f32_16x16x32_bf16 v[124:127], v[150:153], v[186:189], v[124:127]
	v_mfma_f32_16x16x32_bf16 v[120:123], v[162:165], v[186:189], v[120:123]
	v_mfma_f32_16x16x32_bf16 v[108:111], v[150:153], v[194:197], v[108:111]
	v_mfma_f32_16x16x32_bf16 v[104:107], v[162:165], v[194:197], v[104:107]
	v_mfma_f32_16x16x32_bf16 v[92:95], v[150:153], v[202:205], v[92:95]
	v_mfma_f32_16x16x32_bf16 v[88:91], v[162:165], v[202:205], v[88:91]
	v_mfma_f32_16x16x32_bf16 v[76:79], v[150:153], v[210:213], v[76:79]
	v_mfma_f32_16x16x32_bf16 v[72:75], v[162:165], v[210:213], v[72:75]
	v_mfma_f32_16x16x32_bf16 v[116:119], v[166:169], v[182:185], v[116:119]
	v_mfma_f32_16x16x32_bf16 v[112:115], v[174:177], v[182:185], v[112:115]
	v_mfma_f32_16x16x32_bf16 v[100:103], v[166:169], v[190:193], v[100:103]
	v_mfma_f32_16x16x32_bf16 v[96:99], v[174:177], v[190:193], v[96:99]
	v_mfma_f32_16x16x32_bf16 v[84:87], v[166:169], v[198:201], v[84:87]
	v_mfma_f32_16x16x32_bf16 v[80:83], v[174:177], v[198:201], v[80:83]
	v_mfma_f32_16x16x32_bf16 v[68:71], v[166:169], v[206:209], v[68:71]
	v_mfma_f32_16x16x32_bf16 v[64:67], v[174:177], v[206:209], v[64:67]
	v_mfma_f32_16x16x32_bf16 v[116:119], v[170:173], v[186:189], v[116:119]
	v_mfma_f32_16x16x32_bf16 v[112:115], v[178:181], v[186:189], v[112:115]
	v_mfma_f32_16x16x32_bf16 v[100:103], v[170:173], v[194:197], v[100:103]
	v_mfma_f32_16x16x32_bf16 v[96:99], v[178:181], v[194:197], v[96:99]
	v_mfma_f32_16x16x32_bf16 v[84:87], v[170:173], v[202:205], v[84:87]
	v_mfma_f32_16x16x32_bf16 v[80:83], v[178:181], v[202:205], v[80:83]
	v_mfma_f32_16x16x32_bf16 v[68:71], v[170:173], v[210:213], v[68:71]
	v_mfma_f32_16x16x32_bf16 v[64:67], v[178:181], v[210:213], v[64:67]
	s_setprio 0
	s_barrier
	s_add_i32 s17, s50, s28
	v_lshl_add_u64 v[214:215], s[64:65], 0, v[130:131]
	s_mov_b32 m0, s17
	ds_read_b128 v[182:185], v157 offset:16384
	ds_read_b128 v[186:189], v157 offset:17408
	ds_read_b128 v[190:193], v157 offset:18432
	ds_read_b128 v[194:197], v157 offset:19456
	ds_read_b128 v[198:201], v157 offset:20480
	ds_read_b128 v[202:205], v157 offset:21504
	ds_read_b128 v[206:209], v157 offset:22528
	ds_read_b128 v[210:213], v157 offset:23552
	global_load_lds_dwordx4 v[214:215], off
	s_add_i32 m0, s17, 0x2000
	s_add_u32 s68, s64, 0x80000
	v_lshl_add_u64 v[216:217], s[64:65], 0, v[134:135]
	s_addc_u32 s69, s65, 0
	s_add_i32 s17, s51, s28
	global_load_lds_dwordx4 v[216:217], off
	v_lshl_add_u64 v[218:219], s[68:69], 0, v[130:131]
	s_mov_b32 m0, s17
	v_lshl_add_u64 v[220:221], s[66:67], 0, v[132:133]
	global_load_lds_dwordx4 v[218:219], off
	v_lshl_add_u64 v[218:219], s[68:69], 0, v[134:135]
	s_add_i32 m0, s17, 0x2000
	s_nop 0
	global_load_lds_dwordx4 v[218:219], off
	v_lshl_add_u64 v[218:219], s[66:67], 0, v[128:129]
	s_mov_b32 m0, s29
	s_nop 0
	global_load_lds_dwordx4 v[218:219], off
	s_mov_b32 m0, s30
	s_nop 0
	global_load_lds_dwordx4 v[220:221], off
	s_waitcnt vmcnt(8)
	s_waitcnt lgkmcnt(0)
	s_barrier
; #define PG8_STAGE(bufoff, gbase, voff) do { _Pragma("unroll") for (int _i = 0; _i < 2; ++_i) \
;         __builtin_amdgcn_global_load_lds((const unsigned*)((const char*)(gbase) + (voff)[_i]), (LAS unsigned*)(lds + (bufoff) + ldsw + _i * 8192), 16, 0, 0); } while (0)
; #define PG8_LDA(dst, b, h) do { _Pragma("unroll") for (int m = 0; m < 4; ++m) _Pragma("unroll") for (int k = 0; k < 2; ++k) dst[m][k] = *(const LAS bf16x8*)(lds + PG8_SA(b, h) + aoff + m * 2048 + k * 1024); } while (0)
; #define PG8_LDB(dst, b, h) do { _Pragma("unroll") for (int n = 0; n < 2; ++n) _Pragma("unroll") for (int k = 0; k < 2; ++k) dst[n][k] = *(const LAS bf16x8*)(lds + PG8_SB(b, h) + boff + n * 2048 + k * 1024); } while (0)
; #define PG8_MMA(ai, bj, At, Bt) do { __builtin_amdgcn_s_setprio(1); _Pragma("unroll") for (int m = 0; m < 4; ++m) _Pragma("unroll") for (int n = 0; n < 2; ++n) _Pragma("unroll") for (int k = 0; k < 2; ++k) \
;         acc[ai][bj][m][n] = __builtin_amdgcn_mfma_f32_16x16x32_bf16(Bt[n][k], At[m][k], acc[ai][bj][m][n], 0, 0, 0); __builtin_amdgcn_s_setprio(0); } while (0)
; #define PG8_WAIT_V(n) asm volatile("s_waitcnt vmcnt(" #n ")" ::: "memory")
; #define PG8_WAIT_L(n) asm volatile("s_waitcnt lgkmcnt(" #n ")" ::: "memory")
; #define PG8_BAR __builtin_amdgcn_s_barrier()
; #define PG8_SCHED __builtin_amdgcn_sched_barrier(0)
; template <class Desc, class Epi>
; DI void gemm_phase(LAS unsigned char* lds, const Desc& D, const Epi& E, int wv) {
;     ...
;             PG8_WAIT_V(8); PG8_WAIT_L(0); PG8_BAR; PG8_MMA(1, 0, At, B0); PG8_MMA(1, 1, At, B1); PG8_BAR; PG8_SCHED;
;             PG8_LDB(B0, 1, 0); PG8_LDB(B1, 1, 1); PG8_SCHED; PG8_LDA(At, 1, 0); PG8_STAGE(PG8_SA(0, 1), a2 + hstepA, voffA);
;             PG8_WAIT_V(8); PG8_WAIT_L(0); PG8_BAR; PG8_MMA(0, 0, At, B0); PG8_MMA(0, 1, At, B1); PG8_BAR; PG8_SCHED;
	s_setprio 1
	v_mfma_f32_16x16x32_bf16 v[60:63], v[146:149], v[182:185], v[60:63]
	v_mfma_f32_16x16x32_bf16 v[56:59], v[158:161], v[182:185], v[56:59]
	v_mfma_f32_16x16x32_bf16 v[44:47], v[146:149], v[190:193], v[44:47]
	v_mfma_f32_16x16x32_bf16 v[40:43], v[158:161], v[190:193], v[40:43]
	v_mfma_f32_16x16x32_bf16 v[28:31], v[146:149], v[198:201], v[28:31]
	v_mfma_f32_16x16x32_bf16 v[24:27], v[158:161], v[198:201], v[24:27]
	v_mfma_f32_16x16x32_bf16 v[12:15], v[146:149], v[206:209], v[12:15]
	v_mfma_f32_16x16x32_bf16 v[8:11], v[158:161], v[206:209], v[8:11]
	v_mfma_f32_16x16x32_bf16 v[60:63], v[150:153], v[186:189], v[60:63]
	v_mfma_f32_16x16x32_bf16 v[56:59], v[162:165], v[186:189], v[56:59]
	v_mfma_f32_16x16x32_bf16 v[44:47], v[150:153], v[194:197], v[44:47]
	v_mfma_f32_16x16x32_bf16 v[40:43], v[162:165], v[194:197], v[40:43]
	v_mfma_f32_16x16x32_bf16 v[28:31], v[150:153], v[202:205], v[28:31]
	v_mfma_f32_16x16x32_bf16 v[24:27], v[162:165], v[202:205], v[24:27]
	v_mfma_f32_16x16x32_bf16 v[12:15], v[150:153], v[210:213], v[12:15]
	v_mfma_f32_16x16x32_bf16 v[8:11], v[162:165], v[210:213], v[8:11]
	v_mfma_f32_16x16x32_bf16 v[52:55], v[166:169], v[182:185], v[52:55]
	v_mfma_f32_16x16x32_bf16 v[48:51], v[174:177], v[182:185], v[48:51]
	v_mfma_f32_16x16x32_bf16 v[36:39], v[166:169], v[190:193], v[36:39]
	v_mfma_f32_16x16x32_bf16 v[32:35], v[174:177], v[190:193], v[32:35]
	v_mfma_f32_16x16x32_bf16 v[20:23], v[166:169], v[198:201], v[20:23]
	v_mfma_f32_16x16x32_bf16 v[16:19], v[174:177], v[198:201], v[16:19]
	v_mfma_f32_16x16x32_bf16 v[4:7], v[166:169], v[206:209], v[4:7]
	v_mfma_f32_16x16x32_bf16 v[0:3], v[174:177], v[206:209], v[0:3]
	v_mfma_f32_16x16x32_bf16 v[52:55], v[170:173], v[186:189], v[52:55]
	v_mfma_f32_16x16x32_bf16 v[48:51], v[178:181], v[186:189], v[48:51]
	v_mfma_f32_16x16x32_bf16 v[36:39], v[170:173], v[194:197], v[36:39]
	v_mfma_f32_16x16x32_bf16 v[32:35], v[178:181], v[194:197], v[32:35]
	v_mfma_f32_16x16x32_bf16 v[20:23], v[170:173], v[202:205], v[20:23]
	v_mfma_f32_16x16x32_bf16 v[16:19], v[178:181], v[202:205], v[16:19]
	v_mfma_f32_16x16x32_bf16 v[4:7], v[170:173], v[210:213], v[4:7]
	v_mfma_f32_16x16x32_bf16 v[0:3], v[178:181], v[210:213], v[0:3]
	s_setprio 0
	s_barrier
	s_add_i32 s17, 0, 0x18000
	v_add_u32_e32 v136, s17, v154
	s_add_i32 s19, 0, 0x1c000
	ds_read_b128 v[146:149], v136
	ds_read_b128 v[150:153], v136 offset:1024
	ds_read_b128 v[158:161], v136 offset:2048
	ds_read_b128 v[162:165], v136 offset:3072
	v_add_u32_e32 v136, s19, v154
	ds_read_b128 v[166:169], v136
	ds_read_b128 v[170:173], v136 offset:1024
	ds_read_b128 v[174:177], v136 offset:2048
	ds_read_b128 v[178:181], v136 offset:3072
	s_add_u32 s66, s66, 0x80000
	s_addc_u32 s67, s67, 0
	s_mov_b32 m0, s31
	v_lshl_add_u64 v[222:223], s[66:67], 0, v[128:129]
	ds_read_b128 v[182:185], v157 offset:32768
	ds_read_b128 v[186:189], v157 offset:33792
	ds_read_b128 v[190:193], v157 offset:34816
	ds_read_b128 v[194:197], v157 offset:35840
	ds_read_b128 v[198:201], v157 offset:36864
	ds_read_b128 v[202:205], v157 offset:37888
	ds_read_b128 v[206:209], v157 offset:38912
	ds_read_b128 v[210:213], v157 offset:39936
	global_load_lds_dwordx4 v[222:223], off
	v_lshl_add_u64 v[222:223], s[66:67], 0, v[132:133]
	s_mov_b32 m0, s34
	s_nop 0
	global_load_lds_dwordx4 v[222:223], off
	s_waitcnt vmcnt(8)
	s_waitcnt lgkmcnt(0)
	s_barrier
	s_setprio 1
	v_mfma_f32_16x16x32_bf16 v[124:127], v[146:149], v[182:185], v[124:127]
	v_mfma_f32_16x16x32_bf16 v[120:123], v[158:161], v[182:185], v[120:123]
	v_mfma_f32_16x16x32_bf16 v[108:111], v[146:149], v[190:193], v[108:111]
	v_mfma_f32_16x16x32_bf16 v[104:107], v[158:161], v[190:193], v[104:107]
	v_mfma_f32_16x16x32_bf16 v[92:95], v[146:149], v[198:201], v[92:95]
	v_mfma_f32_16x16x32_bf16 v[88:91], v[158:161], v[198:201], v[88:91]
	v_mfma_f32_16x16x32_bf16 v[76:79], v[146:149], v[206:209], v[76:79]
	v_mfma_f32_16x16x32_bf16 v[72:75], v[158:161], v[206:209], v[72:75]
	v_mfma_f32_16x16x32_bf16 v[124:127], v[150:153], v[186:189], v[124:127]
	v_mfma_f32_16x16x32_bf16 v[120:123], v[162:165], v[186:189], v[120:123]
	v_mfma_f32_16x16x32_bf16 v[108:111], v[150:153], v[194:197], v[108:111]
	v_mfma_f32_16x16x32_bf16 v[104:107], v[162:165], v[194:197], v[104:107]
	v_mfma_f32_16x16x32_bf16 v[92:95], v[150:153], v[202:205], v[92:95]
	v_mfma_f32_16x16x32_bf16 v[88:91], v[162:165], v[202:205], v[88:91]
	v_mfma_f32_16x16x32_bf16 v[76:79], v[150:153], v[210:213], v[76:79]
	v_mfma_f32_16x16x32_bf16 v[72:75], v[162:165], v[210:213], v[72:75]
	v_mfma_f32_16x16x32_bf16 v[116:119], v[166:169], v[182:185], v[116:119]
	v_mfma_f32_16x16x32_bf16 v[112:115], v[174:177], v[182:185], v[112:115]
	v_mfma_f32_16x16x32_bf16 v[100:103], v[166:169], v[190:193], v[100:103]
	v_mfma_f32_16x16x32_bf16 v[96:99], v[174:177], v[190:193], v[96:99]
	v_mfma_f32_16x16x32_bf16 v[84:87], v[166:169], v[198:201], v[84:87]
	v_mfma_f32_16x16x32_bf16 v[80:83], v[174:177], v[198:201], v[80:83]
	v_mfma_f32_16x16x32_bf16 v[68:71], v[166:169], v[206:209], v[68:71]
	v_mfma_f32_16x16x32_bf16 v[64:67], v[174:177], v[206:209], v[64:67]
	v_mfma_f32_16x16x32_bf16 v[116:119], v[170:173], v[186:189], v[116:119]
	v_mfma_f32_16x16x32_bf16 v[112:115], v[178:181], v[186:189], v[112:115]
	v_mfma_f32_16x16x32_bf16 v[100:103], v[170:173], v[194:197], v[100:103]
	v_mfma_f32_16x16x32_bf16 v[96:99], v[178:181], v[194:197], v[96:99]
	v_mfma_f32_16x16x32_bf16 v[84:87], v[170:173], v[202:205], v[84:87]
	v_mfma_f32_16x16x32_bf16 v[80:83], v[178:181], v[202:205], v[80:83]
	v_mfma_f32_16x16x32_bf16 v[68:71], v[170:173], v[210:213], v[68:71]
	v_mfma_f32_16x16x32_bf16 v[64:67], v[178:181], v[210:213], v[64:67]
	s_setprio 0
	s_barrier
; #define PG8_STAGE(bufoff, gbase, voff) do { _Pragma("unroll") for (int _i = 0; _i < 2; ++_i) \
;         __builtin_amdgcn_global_load_lds((const unsigned*)((const char*)(gbase) + (voff)[_i]), (LAS unsigned*)(lds + (bufoff) + ldsw + _i * 8192), 16, 0, 0); } while (0)
; #define PG8_LDA(dst, b, h) do { _Pragma("unroll") for (int m = 0; m < 4; ++m) _Pragma("unroll") for (int k = 0; k < 2; ++k) dst[m][k] = *(const LAS bf16x8*)(lds + PG8_SA(b, h) + aoff + m * 2048 + k * 1024); } while (0)
; #define PG8_MMA(ai, bj, At, Bt) do { __builtin_amdgcn_s_setprio(1); _Pragma("unroll") for (int m = 0; m < 4; ++m) _Pragma("unroll") for (int n = 0; n < 2; ++n) _Pragma("unroll") for (int k = 0; k < 2; ++k) \
;         acc[ai][bj][m][n] = __builtin_amdgcn_mfma_f32_16x16x32_bf16(Bt[n][k], At[m][k], acc[ai][bj][m][n], 0, 0, 0); __builtin_amdgcn_s_setprio(0); } while (0)
; #define PG8_WAIT_V(n) asm volatile("s_waitcnt vmcnt(" #n ")" ::: "memory")
; #define PG8_WAIT_L(n) asm volatile("s_waitcnt lgkmcnt(" #n ")" ::: "memory")
; #define PG8_BAR __builtin_amdgcn_s_barrier()
; #define PG8_SCHED __builtin_amdgcn_sched_barrier(0)
; template <class Desc, class Epi>
; DI void gemm_phase(LAS unsigned char* lds, const Desc& D, const Epi& E, int wv) {
;     ...
;             PG8_LDA(At, 1, 1); PG8_STAGE(PG8_SB(1, 0), b3, voffB); PG8_STAGE(PG8_SB(1, 1), b3 + hstepB, voffB); PG8_STAGE(PG8_SA(1, 0), a3, voffA);
;             PG8_WAIT_V(8); PG8_WAIT_L(0); PG8_BAR; PG8_MMA(1, 0, At, B0); PG8_MMA(1, 1, At, B1); PG8_BAR; PG8_SCHED;
;         }
;         if (wr == 0) PG8_BAR;
	s_add_i32 s17, s17, s28
	v_lshl_add_u64 v[214:215], v[214:215], 0, s[12:13]
	s_mov_b32 m0, s17
	ds_read_b128 v[182:185], v157 offset:49152
	ds_read_b128 v[186:189], v157 offset:50176
	ds_read_b128 v[190:193], v157 offset:51200
	ds_read_b128 v[194:197], v157 offset:52224
	ds_read_b128 v[198:201], v157 offset:53248
	ds_read_b128 v[202:205], v157 offset:54272
	ds_read_b128 v[206:209], v157 offset:55296
	ds_read_b128 v[210:213], v157 offset:56320
	global_load_lds_dwordx4 v[214:215], off
	s_add_i32 m0, s17, 0x2000
	s_add_u32 s64, s64, 0x80080
	v_lshl_add_u64 v[214:215], v[216:217], 0, s[12:13]
	s_addc_u32 s65, s65, 0
	s_add_i32 s17, s19, s28
	global_load_lds_dwordx4 v[214:215], off
	v_lshl_add_u64 v[214:215], s[64:65], 0, v[130:131]
	s_mov_b32 m0, s17
	s_nop 0
	global_load_lds_dwordx4 v[214:215], off
	v_lshl_add_u64 v[214:215], s[64:65], 0, v[134:135]
	s_add_i32 m0, s17, 0x2000
	s_nop 0
	global_load_lds_dwordx4 v[214:215], off
	v_lshl_add_u64 v[214:215], v[218:219], 0, s[12:13]
	s_mov_b32 m0, s47
	s_nop 0
	global_load_lds_dwordx4 v[214:215], off
	v_lshl_add_u64 v[214:215], v[220:221], 0, s[12:13]
	s_mov_b32 m0, s48
	s_nop 0
	global_load_lds_dwordx4 v[214:215], off
	s_waitcnt vmcnt(8)
	s_waitcnt lgkmcnt(0)
	s_barrier
	s_setprio 1
	v_mfma_f32_16x16x32_bf16 v[60:63], v[146:149], v[182:185], v[60:63]
	v_mfma_f32_16x16x32_bf16 v[56:59], v[158:161], v[182:185], v[56:59]
	v_mfma_f32_16x16x32_bf16 v[44:47], v[146:149], v[190:193], v[44:47]
	v_mfma_f32_16x16x32_bf16 v[40:43], v[158:161], v[190:193], v[40:43]
	v_mfma_f32_16x16x32_bf16 v[28:31], v[146:149], v[198:201], v[28:31]
	v_mfma_f32_16x16x32_bf16 v[24:27], v[158:161], v[198:201], v[24:27]
	v_mfma_f32_16x16x32_bf16 v[12:15], v[146:149], v[206:209], v[12:15]
	v_mfma_f32_16x16x32_bf16 v[8:11], v[158:161], v[206:209], v[8:11]
	v_mfma_f32_16x16x32_bf16 v[60:63], v[150:153], v[186:189], v[60:63]
	v_mfma_f32_16x16x32_bf16 v[56:59], v[162:165], v[186:189], v[56:59]
	v_mfma_f32_16x16x32_bf16 v[44:47], v[150:153], v[194:197], v[44:47]
	v_mfma_f32_16x16x32_bf16 v[40:43], v[162:165], v[194:197], v[40:43]
	v_mfma_f32_16x16x32_bf16 v[28:31], v[150:153], v[202:205], v[28:31]
	v_mfma_f32_16x16x32_bf16 v[24:27], v[162:165], v[202:205], v[24:27]
	v_mfma_f32_16x16x32_bf16 v[12:15], v[150:153], v[210:213], v[12:15]
	v_mfma_f32_16x16x32_bf16 v[8:11], v[162:165], v[210:213], v[8:11]
	v_mfma_f32_16x16x32_bf16 v[52:55], v[166:169], v[182:185], v[52:55]
	v_mfma_f32_16x16x32_bf16 v[48:51], v[174:177], v[182:185], v[48:51]
	v_mfma_f32_16x16x32_bf16 v[36:39], v[166:169], v[190:193], v[36:39]
	v_mfma_f32_16x16x32_bf16 v[32:35], v[174:177], v[190:193], v[32:35]
	v_mfma_f32_16x16x32_bf16 v[20:23], v[166:169], v[198:201], v[20:23]
	v_mfma_f32_16x16x32_bf16 v[16:19], v[174:177], v[198:201], v[16:19]
	v_mfma_f32_16x16x32_bf16 v[4:7], v[166:169], v[206:209], v[4:7]
	v_mfma_f32_16x16x32_bf16 v[0:3], v[174:177], v[206:209], v[0:3]
	v_mfma_f32_16x16x32_bf16 v[52:55], v[170:173], v[186:189], v[52:55]
	v_mfma_f32_16x16x32_bf16 v[48:51], v[178:181], v[186:189], v[48:51]
	v_mfma_f32_16x16x32_bf16 v[36:39], v[170:173], v[194:197], v[36:39]
	v_mfma_f32_16x16x32_bf16 v[32:35], v[178:181], v[194:197], v[32:35]
	v_mfma_f32_16x16x32_bf16 v[20:23], v[170:173], v[202:205], v[20:23]
	v_mfma_f32_16x16x32_bf16 v[16:19], v[178:181], v[202:205], v[16:19]
	v_mfma_f32_16x16x32_bf16 v[4:7], v[170:173], v[210:213], v[4:7]
	v_mfma_f32_16x16x32_bf16 v[0:3], v[178:181], v[210:213], v[0:3]
	s_setprio 0
	s_barrier
	s_add_i32 s8, s8, 2
	s_add_u32 s62, s62, 0x100
	s_addc_u32 s63, s63, 0
	s_add_u32 s5, s5, 0x100
	s_addc_u32 s7, s7, 0
	s_cmp_gt_u32 s8, 29
	s_cbranch_scc0 .LBB0_1632
	s_and_b64 vcc, exec, s[14:15]
	s_cbranch_vccz .LBB0_1635
	s_barrier

; #define PG8_STAGE(bufoff, gbase, voff) do { _Pragma("unroll") for (int _i = 0; _i < 2; ++_i) \
;         __builtin_amdgcn_global_load_lds((const unsigned*)((const char*)(gbase) + (voff)[_i]), (LAS unsigned*)(lds + (bufoff) + ldsw + _i * 8192), 16, 0, 0); } while (0)
; #define PG8_LDA(dst, b, h) do { _Pragma("unroll") for (int m = 0; m < 4; ++m) _Pragma("unroll") for (int k = 0; k < 2; ++k) dst[m][k] = *(const LAS bf16x8*)(lds + PG8_SA(b, h) + aoff + m * 2048 + k * 1024); } while (0)
; #define PG8_LDB(dst, b, h) do { _Pragma("unroll") for (int n = 0; n < 2; ++n) _Pragma("unroll") for (int k = 0; k < 2; ++k) dst[n][k] = *(const LAS bf16x8*)(lds + PG8_SB(b, h) + boff + n * 2048 + k * 1024); } while (0)
; #define PG8_MMA(ai, bj, At, Bt) do { __builtin_amdgcn_s_setprio(1); _Pragma("unroll") for (int m = 0; m < 4; ++m) _Pragma("unroll") for (int n = 0; n < 2; ++n) _Pragma("unroll") for (int k = 0; k < 2; ++k) \
;         acc[ai][bj][m][n] = __builtin_amdgcn_mfma_f32_16x16x32_bf16(Bt[n][k], At[m][k], acc[ai][bj][m][n], 0, 0, 0); __builtin_amdgcn_s_setprio(0); } while (0)
; #define PG8_WAIT_V(n) asm volatile("s_waitcnt vmcnt(" #n ")" ::: "memory")
; #define PG8_WAIT_L(n) asm volatile("s_waitcnt lgkmcnt(" #n ")" ::: "memory")
; #define PG8_BAR __builtin_amdgcn_s_barrier()
; #define PG8_SCHED __builtin_amdgcn_sched_barrier(0)
; template <class Desc, class Epi>
; DI void gemm_phase(LAS unsigned char* lds, const Desc& D, const Epi& E, int wv) {
;     ...
;             const bool last = (t == nt - 2);
;             const char* a1 = cA + (size_t)(t + 1) * kstep;
;             const char* a2 = last ? nA : cA + (size_t)(t + 2) * kstep; const char* b2 = last ? nB : cB + (size_t)(t + 2) * kstep;
;             const char* a3 = a2 + kstep; const char* b3 = b2 + kstep;
;             PG8_LDB(B0, 0, 0); PG8_LDB(B1, 0, 1); PG8_SCHED; PG8_LDA(At, 0, 0); PG8_STAGE(PG8_SA(1, 1), a1 + hstepA, voffA);
;             PG8_WAIT_V(8); PG8_WAIT_L(0); PG8_BAR; PG8_MMA(0, 0, At, B0); PG8_MMA(0, 1, At, B1); PG8_BAR; PG8_SCHED;
;             PG8_LDA(At, 0, 1); PG8_STAGE(PG8_SB(0, 0), b2, voffB); PG8_STAGE(PG8_SB(0, 1), b2 + hstepB, voffB); PG8_STAGE(PG8_SA(0, 0), a2, voffA);
.LBB0_2088:
	ds_read_b128 v[128:131], v221
	ds_read_b128 v[132:135], v221 offset:1024
	ds_read_b128 v[136:139], v221 offset:2048
	ds_read_b128 v[140:143], v221 offset:3072
	ds_read_b128 v[144:147], v222
	ds_read_b128 v[148:151], v222 offset:1024
	ds_read_b128 v[152:155], v222 offset:2048
	ds_read_b128 v[156:159], v222 offset:3072
	s_add_u32 s42, s40, 0xfff80080
	s_addc_u32 s43, s41, -1
	s_cmp_eq_u32 s66, 28
	s_cselect_b32 s49, s15, s43
	s_cselect_b32 s48, s14, s42
	s_cselect_b32 s43, s17, s21
	s_cselect_b32 s42, s16, s19
	v_lshl_add_u64 v[192:193], s[40:41], 0, v[208:209]
	s_add_i32 m0, s29, 0xc000
	ds_read_b128 v[160:163], v223
	ds_read_b128 v[164:167], v223 offset:1024
	ds_read_b128 v[168:171], v223 offset:2048
	ds_read_b128 v[172:175], v223 offset:3072
	ds_read_b128 v[176:179], v223 offset:4096
	ds_read_b128 v[180:183], v223 offset:5120
	ds_read_b128 v[184:187], v223 offset:6144
	ds_read_b128 v[188:191], v223 offset:7168
	global_load_lds_dwordx4 v[192:193], off
	v_lshl_add_u64 v[192:193], s[40:41], 0, v[210:211]
	s_add_i32 m0, s29, 0xe000
	s_nop 0
	global_load_lds_dwordx4 v[192:193], off
	s_waitcnt vmcnt(8)
	s_waitcnt lgkmcnt(0)
	s_barrier
	s_setprio 1
	v_mfma_f32_16x16x32_bf16 v[124:127], v[128:131], v[160:163], v[124:127]
	v_mfma_f32_16x16x32_bf16 v[120:123], v[136:139], v[160:163], v[120:123]
	v_mfma_f32_16x16x32_bf16 v[112:115], v[128:131], v[168:171], v[112:115]
	v_mfma_f32_16x16x32_bf16 v[104:107], v[136:139], v[168:171], v[104:107]
	v_mfma_f32_16x16x32_bf16 v[96:99], v[128:131], v[176:179], v[96:99]
	v_mfma_f32_16x16x32_bf16 v[88:91], v[136:139], v[176:179], v[88:91]
	v_mfma_f32_16x16x32_bf16 v[80:83], v[128:131], v[184:187], v[80:83]
	v_mfma_f32_16x16x32_bf16 v[72:75], v[136:139], v[184:187], v[72:75]
	v_mfma_f32_16x16x32_bf16 v[124:127], v[132:135], v[164:167], v[124:127]
	v_mfma_f32_16x16x32_bf16 v[120:123], v[140:143], v[164:167], v[120:123]
	v_mfma_f32_16x16x32_bf16 v[112:115], v[132:135], v[172:175], v[112:115]
	v_mfma_f32_16x16x32_bf16 v[104:107], v[140:143], v[172:175], v[104:107]
	v_mfma_f32_16x16x32_bf16 v[96:99], v[132:135], v[180:183], v[96:99]
	v_mfma_f32_16x16x32_bf16 v[88:91], v[140:143], v[180:183], v[88:91]
	v_mfma_f32_16x16x32_bf16 v[80:83], v[132:135], v[188:191], v[80:83]
	v_mfma_f32_16x16x32_bf16 v[72:75], v[140:143], v[188:191], v[72:75]
	v_mfma_f32_16x16x32_bf16 v[116:119], v[144:147], v[160:163], v[116:119]
	v_mfma_f32_16x16x32_bf16 v[108:111], v[152:155], v[160:163], v[108:111]
	v_mfma_f32_16x16x32_bf16 v[100:103], v[144:147], v[168:171], v[100:103]
	v_mfma_f32_16x16x32_bf16 v[92:95], v[152:155], v[168:171], v[92:95]
	v_mfma_f32_16x16x32_bf16 v[84:87], v[144:147], v[176:179], v[84:87]
	v_mfma_f32_16x16x32_bf16 v[76:79], v[152:155], v[176:179], v[76:79]
	v_mfma_f32_16x16x32_bf16 v[68:71], v[144:147], v[184:187], v[68:71]
	v_mfma_f32_16x16x32_bf16 v[64:67], v[152:155], v[184:187], v[64:67]
	v_mfma_f32_16x16x32_bf16 v[116:119], v[148:151], v[164:167], v[116:119]
	v_mfma_f32_16x16x32_bf16 v[108:111], v[156:159], v[164:167], v[108:111]
	v_mfma_f32_16x16x32_bf16 v[100:103], v[148:151], v[172:175], v[100:103]
	v_mfma_f32_16x16x32_bf16 v[92:95], v[156:159], v[172:175], v[92:95]
	v_mfma_f32_16x16x32_bf16 v[84:87], v[148:151], v[180:183], v[84:87]
	v_mfma_f32_16x16x32_bf16 v[76:79], v[156:159], v[180:183], v[76:79]
	v_mfma_f32_16x16x32_bf16 v[68:71], v[148:151], v[188:191], v[68:71]
	v_mfma_f32_16x16x32_bf16 v[64:67], v[156:159], v[188:191], v[64:67]
	s_setprio 0
	s_barrier
	s_add_i32 s67, s53, s28
	v_lshl_add_u64 v[192:193], s[42:43], 0, v[202:203]
	s_mov_b32 m0, s67
	ds_read_b128 v[160:163], v223 offset:16384
	ds_read_b128 v[164:167], v223 offset:17408
	ds_read_b128 v[168:171], v223 offset:18432
	ds_read_b128 v[172:175], v223 offset:19456
	ds_read_b128 v[176:179], v223 offset:20480
	ds_read_b128 v[180:183], v223 offset:21504
	ds_read_b128 v[184:187], v223 offset:22528
	ds_read_b128 v[188:191], v223 offset:23552
	global_load_lds_dwordx4 v[192:193], off
	s_add_i32 m0, s67, 0x2000
	s_add_u32 s68, s42, 0x80000
	v_lshl_add_u64 v[194:195], s[42:43], 0, v[206:207]
	s_addc_u32 s69, s43, 0
	s_add_i32 s67, s60, s28
	global_load_lds_dwordx4 v[194:195], off
	v_lshl_add_u64 v[196:197], s[68:69], 0, v[202:203]
	s_mov_b32 m0, s67
	v_lshl_add_u64 v[198:199], s[48:49], 0, v[204:205]
	global_load_lds_dwordx4 v[196:197], off
	v_lshl_add_u64 v[196:197], s[68:69], 0, v[206:207]
	s_add_i32 m0, s67, 0x2000
	s_nop 0
	global_load_lds_dwordx4 v[196:197], off
	v_lshl_add_u64 v[196:197], s[48:49], 0, v[200:201]
	s_mov_b32 m0, s29
	s_nop 0
	global_load_lds_dwordx4 v[196:197], off
	s_mov_b32 m0, s30
	s_nop 0
	global_load_lds_dwordx4 v[198:199], off
	s_waitcnt vmcnt(8)
	s_waitcnt lgkmcnt(0)
	s_barrier
; #define PG8_STAGE(bufoff, gbase, voff) do { _Pragma("unroll") for (int _i = 0; _i < 2; ++_i) \
;         __builtin_amdgcn_global_load_lds((const unsigned*)((const char*)(gbase) + (voff)[_i]), (LAS unsigned*)(lds + (bufoff) + ldsw + _i * 8192), 16, 0, 0); } while (0)
; #define PG8_LDA(dst, b, h) do { _Pragma("unroll") for (int m = 0; m < 4; ++m) _Pragma("unroll") for (int k = 0; k < 2; ++k) dst[m][k] = *(const LAS bf16x8*)(lds + PG8_SA(b, h) + aoff + m * 2048 + k * 1024); } while (0)
; #define PG8_LDB(dst, b, h) do { _Pragma("unroll") for (int n = 0; n < 2; ++n) _Pragma("unroll") for (int k = 0; k < 2; ++k) dst[n][k] = *(const LAS bf16x8*)(lds + PG8_SB(b, h) + boff + n * 2048 + k * 1024); } while (0)
; #define PG8_MMA(ai, bj, At, Bt) do { __builtin_amdgcn_s_setprio(1); _Pragma("unroll") for (int m = 0; m < 4; ++m) _Pragma("unroll") for (int n = 0; n < 2; ++n) _Pragma("unroll") for (int k = 0; k < 2; ++k) \
;         acc[ai][bj][m][n] = __builtin_amdgcn_mfma_f32_16x16x32_bf16(Bt[n][k], At[m][k], acc[ai][bj][m][n], 0, 0, 0); __builtin_amdgcn_s_setprio(0); } while (0)
; #define PG8_WAIT_V(n) asm volatile("s_waitcnt vmcnt(" #n ")" ::: "memory")
; #define PG8_WAIT_L(n) asm volatile("s_waitcnt lgkmcnt(" #n ")" ::: "memory")
; #define PG8_BAR __builtin_amdgcn_s_barrier()
; #define PG8_SCHED __builtin_amdgcn_sched_barrier(0)
; template <class Desc, class Epi>
; DI void gemm_phase(LAS unsigned char* lds, const Desc& D, const Epi& E, int wv) {
;     ...
;             PG8_WAIT_V(8); PG8_WAIT_L(0); PG8_BAR; PG8_MMA(1, 0, At, B0); PG8_MMA(1, 1, At, B1); PG8_BAR; PG8_SCHED;
;             PG8_LDB(B0, 1, 0); PG8_LDB(B1, 1, 1); PG8_SCHED; PG8_LDA(At, 1, 0); PG8_STAGE(PG8_SA(0, 1), a2 + hstepA, voffA);
;             PG8_WAIT_V(8); PG8_WAIT_L(0); PG8_BAR; PG8_MMA(0, 0, At, B0); PG8_MMA(0, 1, At, B1); PG8_BAR; PG8_SCHED;
	s_setprio 1
	v_mfma_f32_16x16x32_bf16 v[60:63], v[128:131], v[160:163], v[60:63]
	v_mfma_f32_16x16x32_bf16 v[56:59], v[136:139], v[160:163], v[56:59]
	v_mfma_f32_16x16x32_bf16 v[48:51], v[128:131], v[168:171], v[48:51]
	v_mfma_f32_16x16x32_bf16 v[40:43], v[136:139], v[168:171], v[40:43]
	v_mfma_f32_16x16x32_bf16 v[32:35], v[128:131], v[176:179], v[32:35]
	v_mfma_f32_16x16x32_bf16 v[24:27], v[136:139], v[176:179], v[24:27]
	v_mfma_f32_16x16x32_bf16 v[16:19], v[128:131], v[184:187], v[16:19]
	v_mfma_f32_16x16x32_bf16 v[8:11], v[136:139], v[184:187], v[8:11]
	v_mfma_f32_16x16x32_bf16 v[60:63], v[132:135], v[164:167], v[60:63]
	v_mfma_f32_16x16x32_bf16 v[56:59], v[140:143], v[164:167], v[56:59]
	v_mfma_f32_16x16x32_bf16 v[48:51], v[132:135], v[172:175], v[48:51]
	v_mfma_f32_16x16x32_bf16 v[40:43], v[140:143], v[172:175], v[40:43]
	v_mfma_f32_16x16x32_bf16 v[32:35], v[132:135], v[180:183], v[32:35]
	v_mfma_f32_16x16x32_bf16 v[24:27], v[140:143], v[180:183], v[24:27]
	v_mfma_f32_16x16x32_bf16 v[16:19], v[132:135], v[188:191], v[16:19]
	v_mfma_f32_16x16x32_bf16 v[8:11], v[140:143], v[188:191], v[8:11]
	v_mfma_f32_16x16x32_bf16 v[52:55], v[144:147], v[160:163], v[52:55]
	v_mfma_f32_16x16x32_bf16 v[44:47], v[152:155], v[160:163], v[44:47]
	v_mfma_f32_16x16x32_bf16 v[36:39], v[144:147], v[168:171], v[36:39]
	v_mfma_f32_16x16x32_bf16 v[28:31], v[152:155], v[168:171], v[28:31]
	v_mfma_f32_16x16x32_bf16 v[20:23], v[144:147], v[176:179], v[20:23]
	v_mfma_f32_16x16x32_bf16 v[12:15], v[152:155], v[176:179], v[12:15]
	v_mfma_f32_16x16x32_bf16 v[4:7], v[144:147], v[184:187], v[4:7]
	v_mfma_f32_16x16x32_bf16 v[0:3], v[152:155], v[184:187], v[0:3]
	v_mfma_f32_16x16x32_bf16 v[52:55], v[148:151], v[164:167], v[52:55]
	v_mfma_f32_16x16x32_bf16 v[44:47], v[156:159], v[164:167], v[44:47]
	v_mfma_f32_16x16x32_bf16 v[36:39], v[148:151], v[172:175], v[36:39]
	v_mfma_f32_16x16x32_bf16 v[28:31], v[156:159], v[172:175], v[28:31]
	v_mfma_f32_16x16x32_bf16 v[20:23], v[148:151], v[180:183], v[20:23]
	v_mfma_f32_16x16x32_bf16 v[12:15], v[156:159], v[180:183], v[12:15]
	v_mfma_f32_16x16x32_bf16 v[4:7], v[148:151], v[188:191], v[4:7]
	v_mfma_f32_16x16x32_bf16 v[0:3], v[156:159], v[188:191], v[0:3]
	s_setprio 0
	s_barrier
	s_add_i32 s67, 0, 0x18000
	s_add_i32 s68, 0, 0x1c000
	v_add_u32_e32 v140, s67, v220
	v_add_u32_e32 v156, s68, v220
	ds_read_b128 v[128:131], v140
	ds_read_b128 v[132:135], v140 offset:1024
	ds_read_b128 v[136:139], v140 offset:2048
	ds_read_b128 v[140:143], v140 offset:3072
	ds_read_b128 v[144:147], v156
	ds_read_b128 v[148:151], v156 offset:1024
	ds_read_b128 v[152:155], v156 offset:2048
	ds_read_b128 v[156:159], v156 offset:3072
	s_add_u32 s48, s48, 0x80000
	s_addc_u32 s49, s49, 0
	s_mov_b32 m0, s31
	v_lshl_add_u64 v[216:217], s[48:49], 0, v[200:201]
	ds_read_b128 v[160:163], v223 offset:32768
	ds_read_b128 v[164:167], v223 offset:33792
	ds_read_b128 v[168:171], v223 offset:34816
	ds_read_b128 v[172:175], v223 offset:35840
	ds_read_b128 v[176:179], v223 offset:36864
	ds_read_b128 v[180:183], v223 offset:37888
	ds_read_b128 v[184:187], v223 offset:38912
	ds_read_b128 v[188:191], v223 offset:39936
	global_load_lds_dwordx4 v[216:217], off
	v_lshl_add_u64 v[216:217], s[48:49], 0, v[204:205]
	s_mov_b32 m0, s34
	s_nop 0
	global_load_lds_dwordx4 v[216:217], off
	s_waitcnt vmcnt(8)
	s_waitcnt lgkmcnt(0)
	s_barrier
	s_setprio 1
	v_mfma_f32_16x16x32_bf16 v[124:127], v[128:131], v[160:163], v[124:127]
	v_mfma_f32_16x16x32_bf16 v[120:123], v[136:139], v[160:163], v[120:123]
	v_mfma_f32_16x16x32_bf16 v[112:115], v[128:131], v[168:171], v[112:115]
	v_mfma_f32_16x16x32_bf16 v[104:107], v[136:139], v[168:171], v[104:107]
	v_mfma_f32_16x16x32_bf16 v[96:99], v[128:131], v[176:179], v[96:99]
	v_mfma_f32_16x16x32_bf16 v[88:91], v[136:139], v[176:179], v[88:91]
	v_mfma_f32_16x16x32_bf16 v[80:83], v[128:131], v[184:187], v[80:83]
	v_mfma_f32_16x16x32_bf16 v[72:75], v[136:139], v[184:187], v[72:75]
	v_mfma_f32_16x16x32_bf16 v[124:127], v[132:135], v[164:167], v[124:127]
	v_mfma_f32_16x16x32_bf16 v[120:123], v[140:143], v[164:167], v[120:123]
	v_mfma_f32_16x16x32_bf16 v[112:115], v[132:135], v[172:175], v[112:115]
	v_mfma_f32_16x16x32_bf16 v[104:107], v[140:143], v[172:175], v[104:107]
	v_mfma_f32_16x16x32_bf16 v[96:99], v[132:135], v[180:183], v[96:99]
	v_mfma_f32_16x16x32_bf16 v[88:91], v[140:143], v[180:183], v[88:91]
	v_mfma_f32_16x16x32_bf16 v[80:83], v[132:135], v[188:191], v[80:83]
	v_mfma_f32_16x16x32_bf16 v[72:75], v[140:143], v[188:191], v[72:75]
	v_mfma_f32_16x16x32_bf16 v[116:119], v[144:147], v[160:163], v[116:119]
	v_mfma_f32_16x16x32_bf16 v[108:111], v[152:155], v[160:163], v[108:111]
	v_mfma_f32_16x16x32_bf16 v[100:103], v[144:147], v[168:171], v[100:103]
	v_mfma_f32_16x16x32_bf16 v[92:95], v[152:155], v[168:171], v[92:95]
	v_mfma_f32_16x16x32_bf16 v[84:87], v[144:147], v[176:179], v[84:87]
	v_mfma_f32_16x16x32_bf16 v[76:79], v[152:155], v[176:179], v[76:79]
	v_mfma_f32_16x16x32_bf16 v[68:71], v[144:147], v[184:187], v[68:71]
	v_mfma_f32_16x16x32_bf16 v[64:67], v[152:155], v[184:187], v[64:67]
	v_mfma_f32_16x16x32_bf16 v[116:119], v[148:151], v[164:167], v[116:119]
	v_mfma_f32_16x16x32_bf16 v[108:111], v[156:159], v[164:167], v[108:111]
	v_mfma_f32_16x16x32_bf16 v[100:103], v[148:151], v[172:175], v[100:103]
	v_mfma_f32_16x16x32_bf16 v[92:95], v[156:159], v[172:175], v[92:95]
	v_mfma_f32_16x16x32_bf16 v[84:87], v[148:151], v[180:183], v[84:87]
	v_mfma_f32_16x16x32_bf16 v[76:79], v[156:159], v[180:183], v[76:79]
	v_mfma_f32_16x16x32_bf16 v[68:71], v[148:151], v[188:191], v[68:71]
	v_mfma_f32_16x16x32_bf16 v[64:67], v[156:159], v[188:191], v[64:67]
	s_setprio 0
	s_barrier
; #define PG8_STAGE(bufoff, gbase, voff) do { _Pragma("unroll") for (int _i = 0; _i < 2; ++_i) \
;         __builtin_amdgcn_global_load_lds((const unsigned*)((const char*)(gbase) + (voff)[_i]), (LAS unsigned*)(lds + (bufoff) + ldsw + _i * 8192), 16, 0, 0); } while (0)
; #define PG8_LDA(dst, b, h) do { _Pragma("unroll") for (int m = 0; m < 4; ++m) _Pragma("unroll") for (int k = 0; k < 2; ++k) dst[m][k] = *(const LAS bf16x8*)(lds + PG8_SA(b, h) + aoff + m * 2048 + k * 1024); } while (0)
; #define PG8_MMA(ai, bj, At, Bt) do { __builtin_amdgcn_s_setprio(1); _Pragma("unroll") for (int m = 0; m < 4; ++m) _Pragma("unroll") for (int n = 0; n < 2; ++n) _Pragma("unroll") for (int k = 0; k < 2; ++k) \
;         acc[ai][bj][m][n] = __builtin_amdgcn_mfma_f32_16x16x32_bf16(Bt[n][k], At[m][k], acc[ai][bj][m][n], 0, 0, 0); __builtin_amdgcn_s_setprio(0); } while (0)
; #define PG8_WAIT_V(n) asm volatile("s_waitcnt vmcnt(" #n ")" ::: "memory")
; #define PG8_WAIT_L(n) asm volatile("s_waitcnt lgkmcnt(" #n ")" ::: "memory")
; #define PG8_BAR __builtin_amdgcn_s_barrier()
; #define PG8_SCHED __builtin_amdgcn_sched_barrier(0)
; template <class Desc, class Epi>
; DI void gemm_phase(LAS unsigned char* lds, const Desc& D, const Epi& E, int wv) {
;     ...
;             PG8_LDA(At, 1, 1); PG8_STAGE(PG8_SB(1, 0), b3, voffB); PG8_STAGE(PG8_SB(1, 1), b3 + hstepB, voffB); PG8_STAGE(PG8_SA(1, 0), a3, voffA);
;             PG8_WAIT_V(8); PG8_WAIT_L(0); PG8_BAR; PG8_MMA(1, 0, At, B0); PG8_MMA(1, 1, At, B1); PG8_BAR; PG8_SCHED;
;         }
;         if (wr == 0) PG8_BAR;
	s_add_i32 s48, s67, s28
	v_lshl_add_u64 v[192:193], v[192:193], 0, s[8:9]
	s_mov_b32 m0, s48
	ds_read_b128 v[160:163], v223 offset:49152
	ds_read_b128 v[164:167], v223 offset:50176
	ds_read_b128 v[168:171], v223 offset:51200
	ds_read_b128 v[172:175], v223 offset:52224
	ds_read_b128 v[176:179], v223 offset:53248
	ds_read_b128 v[180:183], v223 offset:54272
	ds_read_b128 v[184:187], v223 offset:55296
	ds_read_b128 v[188:191], v223 offset:56320
	global_load_lds_dwordx4 v[192:193], off
	s_add_i32 m0, s48, 0x2000
	s_add_u32 s42, s42, 0x80080
	v_lshl_add_u64 v[192:193], v[194:195], 0, s[8:9]
	s_addc_u32 s43, s43, 0
	s_add_i32 s48, s68, s28
	global_load_lds_dwordx4 v[192:193], off
	v_lshl_add_u64 v[192:193], s[42:43], 0, v[202:203]
	s_mov_b32 m0, s48
	s_nop 0
	global_load_lds_dwordx4 v[192:193], off
	v_lshl_add_u64 v[192:193], s[42:43], 0, v[206:207]
	s_add_i32 m0, s48, 0x2000
	s_nop 0
	global_load_lds_dwordx4 v[192:193], off
	v_lshl_add_u64 v[192:193], v[196:197], 0, s[8:9]
	s_mov_b32 m0, s50
	s_nop 0
	global_load_lds_dwordx4 v[192:193], off
	v_lshl_add_u64 v[192:193], v[198:199], 0, s[8:9]
	s_mov_b32 m0, s51
	s_nop 0
	global_load_lds_dwordx4 v[192:193], off
	s_waitcnt vmcnt(8)
	s_waitcnt lgkmcnt(0)
	s_barrier
	s_setprio 1
	v_mfma_f32_16x16x32_bf16 v[60:63], v[128:131], v[160:163], v[60:63]
	v_mfma_f32_16x16x32_bf16 v[56:59], v[136:139], v[160:163], v[56:59]
	v_mfma_f32_16x16x32_bf16 v[48:51], v[128:131], v[168:171], v[48:51]
	v_mfma_f32_16x16x32_bf16 v[40:43], v[136:139], v[168:171], v[40:43]
	v_mfma_f32_16x16x32_bf16 v[32:35], v[128:131], v[176:179], v[32:35]
	v_mfma_f32_16x16x32_bf16 v[24:27], v[136:139], v[176:179], v[24:27]
	v_mfma_f32_16x16x32_bf16 v[16:19], v[128:131], v[184:187], v[16:19]
	v_mfma_f32_16x16x32_bf16 v[8:11], v[136:139], v[184:187], v[8:11]
	v_mfma_f32_16x16x32_bf16 v[60:63], v[132:135], v[164:167], v[60:63]
	v_mfma_f32_16x16x32_bf16 v[56:59], v[140:143], v[164:167], v[56:59]
	v_mfma_f32_16x16x32_bf16 v[48:51], v[132:135], v[172:175], v[48:51]
	v_mfma_f32_16x16x32_bf16 v[40:43], v[140:143], v[172:175], v[40:43]
	v_mfma_f32_16x16x32_bf16 v[32:35], v[132:135], v[180:183], v[32:35]
	v_mfma_f32_16x16x32_bf16 v[24:27], v[140:143], v[180:183], v[24:27]
	v_mfma_f32_16x16x32_bf16 v[16:19], v[132:135], v[188:191], v[16:19]
	v_mfma_f32_16x16x32_bf16 v[8:11], v[140:143], v[188:191], v[8:11]
	v_mfma_f32_16x16x32_bf16 v[52:55], v[144:147], v[160:163], v[52:55]
	v_mfma_f32_16x16x32_bf16 v[44:47], v[152:155], v[160:163], v[44:47]
	v_mfma_f32_16x16x32_bf16 v[36:39], v[144:147], v[168:171], v[36:39]
	v_mfma_f32_16x16x32_bf16 v[28:31], v[152:155], v[168:171], v[28:31]
	v_mfma_f32_16x16x32_bf16 v[20:23], v[144:147], v[176:179], v[20:23]
	v_mfma_f32_16x16x32_bf16 v[12:15], v[152:155], v[176:179], v[12:15]
	v_mfma_f32_16x16x32_bf16 v[4:7], v[144:147], v[184:187], v[4:7]
	v_mfma_f32_16x16x32_bf16 v[0:3], v[152:155], v[184:187], v[0:3]
	v_mfma_f32_16x16x32_bf16 v[52:55], v[148:151], v[164:167], v[52:55]
	v_mfma_f32_16x16x32_bf16 v[44:47], v[156:159], v[164:167], v[44:47]
	v_mfma_f32_16x16x32_bf16 v[36:39], v[148:151], v[172:175], v[36:39]
	v_mfma_f32_16x16x32_bf16 v[28:31], v[156:159], v[172:175], v[28:31]
	v_mfma_f32_16x16x32_bf16 v[20:23], v[148:151], v[180:183], v[20:23]
	v_mfma_f32_16x16x32_bf16 v[12:15], v[156:159], v[180:183], v[12:15]
	v_mfma_f32_16x16x32_bf16 v[4:7], v[148:151], v[188:191], v[4:7]
	v_mfma_f32_16x16x32_bf16 v[0:3], v[156:159], v[188:191], v[0:3]
	s_setprio 0
	s_barrier
	s_add_i32 s66, s66, 2
	s_add_u32 s40, s40, 0x100
	s_addc_u32 s41, s41, 0
	s_add_u32 s19, s19, 0x100
	s_addc_u32 s21, s21, 0
	s_cmp_gt_u32 s66, 29
	s_cbranch_scc0 .LBB0_2088
	s_and_b64 vcc, exec, s[10:11]
	s_cbranch_vccz .LBB0_2091
	s_barrier

; #define PG8_STAGE(bufoff, gbase, voff) do { _Pragma("unroll") for (int _i = 0; _i < 2; ++_i) \
;         __builtin_amdgcn_global_load_lds((const unsigned*)((const char*)(gbase) + (voff)[_i]), (LAS unsigned*)(lds + (bufoff) + ldsw + _i * 8192), 16, 0, 0); } while (0)
; #define PG8_LDA(dst, b, h) do { _Pragma("unroll") for (int m = 0; m < 4; ++m) _Pragma("unroll") for (int k = 0; k < 2; ++k) dst[m][k] = *(const LAS bf16x8*)(lds + PG8_SA(b, h) + aoff + m * 2048 + k * 1024); } while (0)
; #define PG8_LDB(dst, b, h) do { _Pragma("unroll") for (int n = 0; n < 2; ++n) _Pragma("unroll") for (int k = 0; k < 2; ++k) dst[n][k] = *(const LAS bf16x8*)(lds + PG8_SB(b, h) + boff + n * 2048 + k * 1024); } while (0)
; #define PG8_MMA(ai, bj, At, Bt) do { __builtin_amdgcn_s_setprio(1); _Pragma("unroll") for (int m = 0; m < 4; ++m) _Pragma("unroll") for (int n = 0; n < 2; ++n) _Pragma("unroll") for (int k = 0; k < 2; ++k) \
;         acc[ai][bj][m][n] = __builtin_amdgcn_mfma_f32_16x16x32_bf16(Bt[n][k], At[m][k], acc[ai][bj][m][n], 0, 0, 0); __builtin_amdgcn_s_setprio(0); } while (0)
; #define PG8_WAIT_V(n) asm volatile("s_waitcnt vmcnt(" #n ")" ::: "memory")
; #define PG8_WAIT_L(n) asm volatile("s_waitcnt lgkmcnt(" #n ")" ::: "memory")
; #define PG8_BAR __builtin_amdgcn_s_barrier()
; #define PG8_SCHED __builtin_amdgcn_sched_barrier(0)
; template <class Desc, class Epi>
; DI void gemm_phase(LAS unsigned char* lds, const Desc& D, const Epi& E, int wv) {
;     ...
;         for (int t = 0; t < nt; t += 2) {
;             const bool last = (t == nt - 2);
;             const char* a1 = cA + (size_t)(t + 1) * kstep;
;             const char* a2 = last ? nA : cA + (size_t)(t + 2) * kstep; const char* b2 = last ? nB : cB + (size_t)(t + 2) * kstep;
;             const char* a3 = a2 + kstep; const char* b3 = b2 + kstep;
;             PG8_LDB(B0, 0, 0); PG8_LDB(B1, 0, 1); PG8_SCHED; PG8_LDA(At, 0, 0); PG8_STAGE(PG8_SA(1, 1), a1 + hstepA, voffA);
;             PG8_WAIT_V(8); PG8_WAIT_L(0); PG8_BAR; PG8_MMA(0, 0, At, B0); PG8_MMA(0, 1, At, B1); PG8_BAR; PG8_SCHED;
;             PG8_LDA(At, 0, 1); PG8_STAGE(PG8_SB(0, 0), b2, voffB); PG8_STAGE(PG8_SB(0, 1), b2 + hstepB, voffB); PG8_STAGE(PG8_SA(0, 0), a2, voffA);
.LBB0_2213:
	ds_read_b128 v[152:155], v149
	ds_read_b128 v[156:159], v149 offset:1024
	ds_read_b128 v[160:163], v149 offset:2048
	ds_read_b128 v[164:167], v149 offset:3072
	ds_read_b128 v[168:171], v150
	ds_read_b128 v[172:175], v150 offset:1024
	ds_read_b128 v[176:179], v150 offset:2048
	ds_read_b128 v[180:183], v150 offset:3072
	s_add_u32 s48, s42, 0xfff80080
	s_addc_u32 s49, s43, -1
	s_cmp_eq_u32 s41, 28
	s_cselect_b32 s51, s19, s49
	s_cselect_b32 s50, s18, s48
	s_cselect_b32 s49, s21, s25
	s_cselect_b32 s48, s20, s23
	v_lshl_add_u64 v[146:147], s[42:43], 0, v[138:139]
	s_add_i32 m0, s30, 0xc000
	ds_read_b128 v[184:187], v151
	ds_read_b128 v[188:191], v151 offset:1024
	ds_read_b128 v[192:195], v151 offset:2048
	ds_read_b128 v[196:199], v151 offset:3072
	ds_read_b128 v[200:203], v151 offset:4096
	ds_read_b128 v[204:207], v151 offset:5120
	ds_read_b128 v[208:211], v151 offset:6144
	ds_read_b128 v[212:215], v151 offset:7168
	global_load_lds_dwordx4 v[146:147], off
	v_lshl_add_u64 v[146:147], s[42:43], 0, v[140:141]
	s_add_i32 m0, s30, 0xe000
	s_nop 0
	global_load_lds_dwordx4 v[146:147], off
	s_waitcnt vmcnt(8)
	s_waitcnt lgkmcnt(0)
	s_barrier
	s_setprio 1
	v_mfma_f32_16x16x32_bf16 v[124:127], v[152:155], v[184:187], v[124:127]
	v_mfma_f32_16x16x32_bf16 v[120:123], v[160:163], v[184:187], v[120:123]
	v_mfma_f32_16x16x32_bf16 v[108:111], v[152:155], v[192:195], v[108:111]
	v_mfma_f32_16x16x32_bf16 v[104:107], v[160:163], v[192:195], v[104:107]
	v_mfma_f32_16x16x32_bf16 v[92:95], v[152:155], v[200:203], v[92:95]
	v_mfma_f32_16x16x32_bf16 v[88:91], v[160:163], v[200:203], v[88:91]
	v_mfma_f32_16x16x32_bf16 v[76:79], v[152:155], v[208:211], v[76:79]
	v_mfma_f32_16x16x32_bf16 v[72:75], v[160:163], v[208:211], v[72:75]
	v_mfma_f32_16x16x32_bf16 v[124:127], v[156:159], v[188:191], v[124:127]
	v_mfma_f32_16x16x32_bf16 v[120:123], v[164:167], v[188:191], v[120:123]
	v_mfma_f32_16x16x32_bf16 v[108:111], v[156:159], v[196:199], v[108:111]
	v_mfma_f32_16x16x32_bf16 v[104:107], v[164:167], v[196:199], v[104:107]
	v_mfma_f32_16x16x32_bf16 v[92:95], v[156:159], v[204:207], v[92:95]
	v_mfma_f32_16x16x32_bf16 v[88:91], v[164:167], v[204:207], v[88:91]
	v_mfma_f32_16x16x32_bf16 v[76:79], v[156:159], v[212:215], v[76:79]
	v_mfma_f32_16x16x32_bf16 v[72:75], v[164:167], v[212:215], v[72:75]
	v_mfma_f32_16x16x32_bf16 v[116:119], v[168:171], v[184:187], v[116:119]
	v_mfma_f32_16x16x32_bf16 v[112:115], v[176:179], v[184:187], v[112:115]
	v_mfma_f32_16x16x32_bf16 v[100:103], v[168:171], v[192:195], v[100:103]
	v_mfma_f32_16x16x32_bf16 v[96:99], v[176:179], v[192:195], v[96:99]
	v_mfma_f32_16x16x32_bf16 v[84:87], v[168:171], v[200:203], v[84:87]
	v_mfma_f32_16x16x32_bf16 v[80:83], v[176:179], v[200:203], v[80:83]
	v_mfma_f32_16x16x32_bf16 v[68:71], v[168:171], v[208:211], v[68:71]
	v_mfma_f32_16x16x32_bf16 v[64:67], v[176:179], v[208:211], v[64:67]
	v_mfma_f32_16x16x32_bf16 v[116:119], v[172:175], v[188:191], v[116:119]
	v_mfma_f32_16x16x32_bf16 v[112:115], v[180:183], v[188:191], v[112:115]
	v_mfma_f32_16x16x32_bf16 v[100:103], v[172:175], v[196:199], v[100:103]
	v_mfma_f32_16x16x32_bf16 v[96:99], v[180:183], v[196:199], v[96:99]
	v_mfma_f32_16x16x32_bf16 v[84:87], v[172:175], v[204:207], v[84:87]
	v_mfma_f32_16x16x32_bf16 v[80:83], v[180:183], v[204:207], v[80:83]
	v_mfma_f32_16x16x32_bf16 v[68:71], v[172:175], v[212:215], v[68:71]
	v_mfma_f32_16x16x32_bf16 v[64:67], v[180:183], v[212:215], v[64:67]
	s_setprio 0
	s_barrier
	s_add_i32 s67, s62, s28
	v_lshl_add_u64 v[146:147], s[48:49], 0, v[132:133]
	s_mov_b32 m0, s67
	ds_read_b128 v[184:187], v151 offset:16384
	ds_read_b128 v[188:191], v151 offset:17408
	ds_read_b128 v[192:195], v151 offset:18432
	ds_read_b128 v[196:199], v151 offset:19456
	ds_read_b128 v[200:203], v151 offset:20480
	ds_read_b128 v[204:207], v151 offset:21504
	ds_read_b128 v[208:211], v151 offset:22528
	ds_read_b128 v[212:215], v151 offset:23552
	global_load_lds_dwordx4 v[146:147], off
	s_add_i32 m0, s67, 0x2000
	s_add_u32 s68, s48, 0x80000
	v_lshl_add_u64 v[216:217], s[48:49], 0, v[128:129]
	s_addc_u32 s69, s49, 0
	s_add_i32 s67, s63, s28
	global_load_lds_dwordx4 v[216:217], off
	v_lshl_add_u64 v[218:219], s[68:69], 0, v[132:133]
	s_mov_b32 m0, s67
	v_lshl_add_u64 v[220:221], s[50:51], 0, v[130:131]
	global_load_lds_dwordx4 v[218:219], off
	v_lshl_add_u64 v[218:219], s[68:69], 0, v[128:129]
	s_add_i32 m0, s67, 0x2000
	s_nop 0
	global_load_lds_dwordx4 v[218:219], off
	v_lshl_add_u64 v[218:219], s[50:51], 0, v[134:135]
	s_mov_b32 m0, s30
	s_nop 0
	global_load_lds_dwordx4 v[218:219], off
	s_mov_b32 m0, s31
	s_nop 0
	global_load_lds_dwordx4 v[220:221], off
	s_waitcnt vmcnt(8)
	s_waitcnt lgkmcnt(0)
	s_barrier
; #define PG8_STAGE(bufoff, gbase, voff) do { _Pragma("unroll") for (int _i = 0; _i < 2; ++_i) \
;         __builtin_amdgcn_global_load_lds((const unsigned*)((const char*)(gbase) + (voff)[_i]), (LAS unsigned*)(lds + (bufoff) + ldsw + _i * 8192), 16, 0, 0); } while (0)
; #define PG8_LDA(dst, b, h) do { _Pragma("unroll") for (int m = 0; m < 4; ++m) _Pragma("unroll") for (int k = 0; k < 2; ++k) dst[m][k] = *(const LAS bf16x8*)(lds + PG8_SA(b, h) + aoff + m * 2048 + k * 1024); } while (0)
; #define PG8_LDB(dst, b, h) do { _Pragma("unroll") for (int n = 0; n < 2; ++n) _Pragma("unroll") for (int k = 0; k < 2; ++k) dst[n][k] = *(const LAS bf16x8*)(lds + PG8_SB(b, h) + boff + n * 2048 + k * 1024); } while (0)
; #define PG8_MMA(ai, bj, At, Bt) do { __builtin_amdgcn_s_setprio(1); _Pragma("unroll") for (int m = 0; m < 4; ++m) _Pragma("unroll") for (int n = 0; n < 2; ++n) _Pragma("unroll") for (int k = 0; k < 2; ++k) \
;         acc[ai][bj][m][n] = __builtin_amdgcn_mfma_f32_16x16x32_bf16(Bt[n][k], At[m][k], acc[ai][bj][m][n], 0, 0, 0); __builtin_amdgcn_s_setprio(0); } while (0)
; #define PG8_WAIT_V(n) asm volatile("s_waitcnt vmcnt(" #n ")" ::: "memory")
; #define PG8_WAIT_L(n) asm volatile("s_waitcnt lgkmcnt(" #n ")" ::: "memory")
; #define PG8_BAR __builtin_amdgcn_s_barrier()
; #define PG8_SCHED __builtin_amdgcn_sched_barrier(0)
; template <class Desc, class Epi>
; DI void gemm_phase(LAS unsigned char* lds, const Desc& D, const Epi& E, int wv) {
;     ...
;             PG8_WAIT_V(8); PG8_WAIT_L(0); PG8_BAR; PG8_MMA(1, 0, At, B0); PG8_MMA(1, 1, At, B1); PG8_BAR; PG8_SCHED;
;             PG8_LDB(B0, 1, 0); PG8_LDB(B1, 1, 1); PG8_SCHED; PG8_LDA(At, 1, 0); PG8_STAGE(PG8_SA(0, 1), a2 + hstepA, voffA);
;             PG8_WAIT_V(8); PG8_WAIT_L(0); PG8_BAR; PG8_MMA(0, 0, At, B0); PG8_MMA(0, 1, At, B1); PG8_BAR; PG8_SCHED;
	s_setprio 1
	v_mfma_f32_16x16x32_bf16 v[60:63], v[152:155], v[184:187], v[60:63]
	v_mfma_f32_16x16x32_bf16 v[56:59], v[160:163], v[184:187], v[56:59]
	v_mfma_f32_16x16x32_bf16 v[44:47], v[152:155], v[192:195], v[44:47]
	v_mfma_f32_16x16x32_bf16 v[40:43], v[160:163], v[192:195], v[40:43]
	v_mfma_f32_16x16x32_bf16 v[28:31], v[152:155], v[200:203], v[28:31]
	v_mfma_f32_16x16x32_bf16 v[24:27], v[160:163], v[200:203], v[24:27]
	v_mfma_f32_16x16x32_bf16 v[12:15], v[152:155], v[208:211], v[12:15]
	v_mfma_f32_16x16x32_bf16 v[8:11], v[160:163], v[208:211], v[8:11]
	v_mfma_f32_16x16x32_bf16 v[60:63], v[156:159], v[188:191], v[60:63]
	v_mfma_f32_16x16x32_bf16 v[56:59], v[164:167], v[188:191], v[56:59]
	v_mfma_f32_16x16x32_bf16 v[44:47], v[156:159], v[196:199], v[44:47]
	v_mfma_f32_16x16x32_bf16 v[40:43], v[164:167], v[196:199], v[40:43]
	v_mfma_f32_16x16x32_bf16 v[28:31], v[156:159], v[204:207], v[28:31]
	v_mfma_f32_16x16x32_bf16 v[24:27], v[164:167], v[204:207], v[24:27]
	v_mfma_f32_16x16x32_bf16 v[12:15], v[156:159], v[212:215], v[12:15]
	v_mfma_f32_16x16x32_bf16 v[8:11], v[164:167], v[212:215], v[8:11]
	v_mfma_f32_16x16x32_bf16 v[52:55], v[168:171], v[184:187], v[52:55]
	v_mfma_f32_16x16x32_bf16 v[48:51], v[176:179], v[184:187], v[48:51]
	v_mfma_f32_16x16x32_bf16 v[36:39], v[168:171], v[192:195], v[36:39]
	v_mfma_f32_16x16x32_bf16 v[32:35], v[176:179], v[192:195], v[32:35]
	v_mfma_f32_16x16x32_bf16 v[20:23], v[168:171], v[200:203], v[20:23]
	v_mfma_f32_16x16x32_bf16 v[16:19], v[176:179], v[200:203], v[16:19]
	v_mfma_f32_16x16x32_bf16 v[4:7], v[168:171], v[208:211], v[4:7]
	v_mfma_f32_16x16x32_bf16 v[0:3], v[176:179], v[208:211], v[0:3]
	v_mfma_f32_16x16x32_bf16 v[52:55], v[172:175], v[188:191], v[52:55]
	v_mfma_f32_16x16x32_bf16 v[48:51], v[180:183], v[188:191], v[48:51]
	v_mfma_f32_16x16x32_bf16 v[36:39], v[172:175], v[196:199], v[36:39]
	v_mfma_f32_16x16x32_bf16 v[32:35], v[180:183], v[196:199], v[32:35]
	v_mfma_f32_16x16x32_bf16 v[20:23], v[172:175], v[204:207], v[20:23]
	v_mfma_f32_16x16x32_bf16 v[16:19], v[180:183], v[204:207], v[16:19]
	v_mfma_f32_16x16x32_bf16 v[4:7], v[172:175], v[212:215], v[4:7]
	v_mfma_f32_16x16x32_bf16 v[0:3], v[180:183], v[212:215], v[0:3]
	s_setprio 0
	s_barrier
	s_add_i32 s67, 0, 0x18000
	v_add_u32_e32 v136, s67, v148
	s_add_i32 s68, 0, 0x1c000
	ds_read_b128 v[152:155], v136
	ds_read_b128 v[156:159], v136 offset:1024
	ds_read_b128 v[160:163], v136 offset:2048
	ds_read_b128 v[164:167], v136 offset:3072
	v_add_u32_e32 v136, s68, v148
	ds_read_b128 v[168:171], v136
	ds_read_b128 v[172:175], v136 offset:1024
	ds_read_b128 v[176:179], v136 offset:2048
	ds_read_b128 v[180:183], v136 offset:3072
	s_add_u32 s50, s50, 0x80000
	s_addc_u32 s51, s51, 0
	s_mov_b32 m0, s34
	v_lshl_add_u64 v[222:223], s[50:51], 0, v[134:135]
	ds_read_b128 v[184:187], v151 offset:32768
	ds_read_b128 v[188:191], v151 offset:33792
	ds_read_b128 v[192:195], v151 offset:34816
	ds_read_b128 v[196:199], v151 offset:35840
	ds_read_b128 v[200:203], v151 offset:36864
	ds_read_b128 v[204:207], v151 offset:37888
	ds_read_b128 v[208:211], v151 offset:38912
	ds_read_b128 v[212:215], v151 offset:39936
	global_load_lds_dwordx4 v[222:223], off
	v_lshl_add_u64 v[222:223], s[50:51], 0, v[130:131]
	s_mov_b32 m0, s35
	s_nop 0
	global_load_lds_dwordx4 v[222:223], off
	s_waitcnt vmcnt(8)
	s_waitcnt lgkmcnt(0)
	s_barrier
	s_setprio 1
	v_mfma_f32_16x16x32_bf16 v[124:127], v[152:155], v[184:187], v[124:127]
	v_mfma_f32_16x16x32_bf16 v[120:123], v[160:163], v[184:187], v[120:123]
	v_mfma_f32_16x16x32_bf16 v[108:111], v[152:155], v[192:195], v[108:111]
	v_mfma_f32_16x16x32_bf16 v[104:107], v[160:163], v[192:195], v[104:107]
	v_mfma_f32_16x16x32_bf16 v[92:95], v[152:155], v[200:203], v[92:95]
	v_mfma_f32_16x16x32_bf16 v[88:91], v[160:163], v[200:203], v[88:91]
	v_mfma_f32_16x16x32_bf16 v[76:79], v[152:155], v[208:211], v[76:79]
	v_mfma_f32_16x16x32_bf16 v[72:75], v[160:163], v[208:211], v[72:75]
	v_mfma_f32_16x16x32_bf16 v[124:127], v[156:159], v[188:191], v[124:127]
	v_mfma_f32_16x16x32_bf16 v[120:123], v[164:167], v[188:191], v[120:123]
	v_mfma_f32_16x16x32_bf16 v[108:111], v[156:159], v[196:199], v[108:111]
	v_mfma_f32_16x16x32_bf16 v[104:107], v[164:167], v[196:199], v[104:107]
	v_mfma_f32_16x16x32_bf16 v[92:95], v[156:159], v[204:207], v[92:95]
	v_mfma_f32_16x16x32_bf16 v[88:91], v[164:167], v[204:207], v[88:91]
	v_mfma_f32_16x16x32_bf16 v[76:79], v[156:159], v[212:215], v[76:79]
	v_mfma_f32_16x16x32_bf16 v[72:75], v[164:167], v[212:215], v[72:75]
	v_mfma_f32_16x16x32_bf16 v[116:119], v[168:171], v[184:187], v[116:119]
	v_mfma_f32_16x16x32_bf16 v[112:115], v[176:179], v[184:187], v[112:115]
	v_mfma_f32_16x16x32_bf16 v[100:103], v[168:171], v[192:195], v[100:103]
	v_mfma_f32_16x16x32_bf16 v[96:99], v[176:179], v[192:195], v[96:99]
	v_mfma_f32_16x16x32_bf16 v[84:87], v[168:171], v[200:203], v[84:87]
	v_mfma_f32_16x16x32_bf16 v[80:83], v[176:179], v[200:203], v[80:83]
	v_mfma_f32_16x16x32_bf16 v[68:71], v[168:171], v[208:211], v[68:71]
	v_mfma_f32_16x16x32_bf16 v[64:67], v[176:179], v[208:211], v[64:67]
	v_mfma_f32_16x16x32_bf16 v[116:119], v[172:175], v[188:191], v[116:119]
	v_mfma_f32_16x16x32_bf16 v[112:115], v[180:183], v[188:191], v[112:115]
	v_mfma_f32_16x16x32_bf16 v[100:103], v[172:175], v[196:199], v[100:103]
	v_mfma_f32_16x16x32_bf16 v[96:99], v[180:183], v[196:199], v[96:99]
	v_mfma_f32_16x16x32_bf16 v[84:87], v[172:175], v[204:207], v[84:87]
	v_mfma_f32_16x16x32_bf16 v[80:83], v[180:183], v[204:207], v[80:83]
	v_mfma_f32_16x16x32_bf16 v[68:71], v[172:175], v[212:215], v[68:71]
	v_mfma_f32_16x16x32_bf16 v[64:67], v[180:183], v[212:215], v[64:67]
	s_setprio 0
	s_barrier
; #define PG8_STAGE(bufoff, gbase, voff) do { _Pragma("unroll") for (int _i = 0; _i < 2; ++_i) \
;         __builtin_amdgcn_global_load_lds((const unsigned*)((const char*)(gbase) + (voff)[_i]), (LAS unsigned*)(lds + (bufoff) + ldsw + _i * 8192), 16, 0, 0); } while (0)
; #define PG8_LDA(dst, b, h) do { _Pragma("unroll") for (int m = 0; m < 4; ++m) _Pragma("unroll") for (int k = 0; k < 2; ++k) dst[m][k] = *(const LAS bf16x8*)(lds + PG8_SA(b, h) + aoff + m * 2048 + k * 1024); } while (0)
; #define PG8_MMA(ai, bj, At, Bt) do { __builtin_amdgcn_s_setprio(1); _Pragma("unroll") for (int m = 0; m < 4; ++m) _Pragma("unroll") for (int n = 0; n < 2; ++n) _Pragma("unroll") for (int k = 0; k < 2; ++k) \
;         acc[ai][bj][m][n] = __builtin_amdgcn_mfma_f32_16x16x32_bf16(Bt[n][k], At[m][k], acc[ai][bj][m][n], 0, 0, 0); __builtin_amdgcn_s_setprio(0); } while (0)
; #define PG8_WAIT_V(n) asm volatile("s_waitcnt vmcnt(" #n ")" ::: "memory")
; #define PG8_WAIT_L(n) asm volatile("s_waitcnt lgkmcnt(" #n ")" ::: "memory")
; #define PG8_BAR __builtin_amdgcn_s_barrier()
; #define PG8_SCHED __builtin_amdgcn_sched_barrier(0)
; template <class Desc, class Epi>
; DI void gemm_phase(LAS unsigned char* lds, const Desc& D, const Epi& E, int wv) {
;     ...
;             PG8_LDA(At, 1, 1); PG8_STAGE(PG8_SB(1, 0), b3, voffB); PG8_STAGE(PG8_SB(1, 1), b3 + hstepB, voffB); PG8_STAGE(PG8_SA(1, 0), a3, voffA);
;             PG8_WAIT_V(8); PG8_WAIT_L(0); PG8_BAR; PG8_MMA(1, 0, At, B0); PG8_MMA(1, 1, At, B1); PG8_BAR; PG8_SCHED;
;         }
;         if (wr == 0) PG8_BAR;
	s_add_i32 s50, s67, s28
	v_lshl_add_u64 v[146:147], v[146:147], 0, s[8:9]
	s_mov_b32 m0, s50
	ds_read_b128 v[184:187], v151 offset:49152
	ds_read_b128 v[188:191], v151 offset:50176
	ds_read_b128 v[192:195], v151 offset:51200
	ds_read_b128 v[196:199], v151 offset:52224
	ds_read_b128 v[200:203], v151 offset:53248
	ds_read_b128 v[204:207], v151 offset:54272
	ds_read_b128 v[208:211], v151 offset:55296
	ds_read_b128 v[212:215], v151 offset:56320
	global_load_lds_dwordx4 v[146:147], off
	s_add_i32 m0, s50, 0x2000
	s_add_u32 s48, s48, 0x80080
	v_lshl_add_u64 v[146:147], v[216:217], 0, s[8:9]
	s_addc_u32 s49, s49, 0
	s_add_i32 s50, s68, s28
	global_load_lds_dwordx4 v[146:147], off
	v_lshl_add_u64 v[146:147], s[48:49], 0, v[132:133]
	s_mov_b32 m0, s50
	s_nop 0
	global_load_lds_dwordx4 v[146:147], off
	v_lshl_add_u64 v[146:147], s[48:49], 0, v[128:129]
	s_add_i32 m0, s50, 0x2000
	s_nop 0
	global_load_lds_dwordx4 v[146:147], off
	v_lshl_add_u64 v[146:147], v[218:219], 0, s[8:9]
	s_mov_b32 m0, s53
	s_nop 0
	global_load_lds_dwordx4 v[146:147], off
	v_lshl_add_u64 v[146:147], v[220:221], 0, s[8:9]
	s_mov_b32 m0, s60
	s_nop 0
	global_load_lds_dwordx4 v[146:147], off
	s_waitcnt vmcnt(8)
	s_waitcnt lgkmcnt(0)
	s_barrier
	s_setprio 1
	v_mfma_f32_16x16x32_bf16 v[60:63], v[152:155], v[184:187], v[60:63]
	v_mfma_f32_16x16x32_bf16 v[56:59], v[160:163], v[184:187], v[56:59]
	v_mfma_f32_16x16x32_bf16 v[44:47], v[152:155], v[192:195], v[44:47]
	v_mfma_f32_16x16x32_bf16 v[40:43], v[160:163], v[192:195], v[40:43]
	v_mfma_f32_16x16x32_bf16 v[28:31], v[152:155], v[200:203], v[28:31]
	v_mfma_f32_16x16x32_bf16 v[24:27], v[160:163], v[200:203], v[24:27]
	v_mfma_f32_16x16x32_bf16 v[12:15], v[152:155], v[208:211], v[12:15]
	v_mfma_f32_16x16x32_bf16 v[8:11], v[160:163], v[208:211], v[8:11]
	v_mfma_f32_16x16x32_bf16 v[60:63], v[156:159], v[188:191], v[60:63]
	v_mfma_f32_16x16x32_bf16 v[56:59], v[164:167], v[188:191], v[56:59]
	v_mfma_f32_16x16x32_bf16 v[44:47], v[156:159], v[196:199], v[44:47]
	v_mfma_f32_16x16x32_bf16 v[40:43], v[164:167], v[196:199], v[40:43]
	v_mfma_f32_16x16x32_bf16 v[28:31], v[156:159], v[204:207], v[28:31]
	v_mfma_f32_16x16x32_bf16 v[24:27], v[164:167], v[204:207], v[24:27]
	v_mfma_f32_16x16x32_bf16 v[12:15], v[156:159], v[212:215], v[12:15]
	v_mfma_f32_16x16x32_bf16 v[8:11], v[164:167], v[212:215], v[8:11]
	v_mfma_f32_16x16x32_bf16 v[52:55], v[168:171], v[184:187], v[52:55]
	v_mfma_f32_16x16x32_bf16 v[48:51], v[176:179], v[184:187], v[48:51]
	v_mfma_f32_16x16x32_bf16 v[36:39], v[168:171], v[192:195], v[36:39]
	v_mfma_f32_16x16x32_bf16 v[32:35], v[176:179], v[192:195], v[32:35]
	v_mfma_f32_16x16x32_bf16 v[20:23], v[168:171], v[200:203], v[20:23]
	v_mfma_f32_16x16x32_bf16 v[16:19], v[176:179], v[200:203], v[16:19]
	v_mfma_f32_16x16x32_bf16 v[4:7], v[168:171], v[208:211], v[4:7]
	v_mfma_f32_16x16x32_bf16 v[0:3], v[176:179], v[208:211], v[0:3]
	v_mfma_f32_16x16x32_bf16 v[52:55], v[172:175], v[188:191], v[52:55]
	v_mfma_f32_16x16x32_bf16 v[48:51], v[180:183], v[188:191], v[48:51]
	v_mfma_f32_16x16x32_bf16 v[36:39], v[172:175], v[196:199], v[36:39]
	v_mfma_f32_16x16x32_bf16 v[32:35], v[180:183], v[196:199], v[32:35]
	v_mfma_f32_16x16x32_bf16 v[20:23], v[172:175], v[204:207], v[20:23]
	v_mfma_f32_16x16x32_bf16 v[16:19], v[180:183], v[204:207], v[16:19]
	v_mfma_f32_16x16x32_bf16 v[4:7], v[172:175], v[212:215], v[4:7]
	v_mfma_f32_16x16x32_bf16 v[0:3], v[180:183], v[212:215], v[0:3]
	s_setprio 0
	s_barrier
	s_add_i32 s41, s41, 2
	s_add_u32 s42, s42, 0x100
	s_addc_u32 s43, s43, 0
	s_add_u32 s23, s23, 0x100
	s_addc_u32 s25, s25, 0
	s_cmp_gt_u32 s41, 29
	s_cbranch_scc0 .LBB0_2213
	s_and_b64 vcc, exec, s[12:13]
	s_cbranch_vccz .LBB0_2216
	s_barrier

; #define PG8_STAGE(bufoff, gbase, voff) do { _Pragma("unroll") for (int _i = 0; _i < 2; ++_i) \
;         __builtin_amdgcn_global_load_lds((const unsigned*)((const char*)(gbase) + (voff)[_i]), (LAS unsigned*)(lds + (bufoff) + ldsw + _i * 8192), 16, 0, 0); } while (0)
; #define PG8_LDA(dst, b, h) do { _Pragma("unroll") for (int m = 0; m < 4; ++m) _Pragma("unroll") for (int k = 0; k < 2; ++k) dst[m][k] = *(const LAS bf16x8*)(lds + PG8_SA(b, h) + aoff + m * 2048 + k * 1024); } while (0)
; #define PG8_LDB(dst, b, h) do { _Pragma("unroll") for (int n = 0; n < 2; ++n) _Pragma("unroll") for (int k = 0; k < 2; ++k) dst[n][k] = *(const LAS bf16x8*)(lds + PG8_SB(b, h) + boff + n * 2048 + k * 1024); } while (0)
; #define PG8_MMA(ai, bj, At, Bt) do { __builtin_amdgcn_s_setprio(1); _Pragma("unroll") for (int m = 0; m < 4; ++m) _Pragma("unroll") for (int n = 0; n < 2; ++n) _Pragma("unroll") for (int k = 0; k < 2; ++k) \
;         acc[ai][bj][m][n] = __builtin_amdgcn_mfma_f32_16x16x32_bf16(Bt[n][k], At[m][k], acc[ai][bj][m][n], 0, 0, 0); __builtin_amdgcn_s_setprio(0); } while (0)
; #define PG8_WAIT_V(n) asm volatile("s_waitcnt vmcnt(" #n ")" ::: "memory")
; #define PG8_WAIT_L(n) asm volatile("s_waitcnt lgkmcnt(" #n ")" ::: "memory")
; #define PG8_BAR __builtin_amdgcn_s_barrier()
; #define PG8_SCHED __builtin_amdgcn_sched_barrier(0)
; template <class Desc, class Epi>
; DI void gemm_phase(LAS unsigned char* lds, const Desc& D, const Epi& E, int wv) {
;     ...
;         for (int t = 0; t < nt; t += 2) {
;             const bool last = (t == nt - 2);
;             const char* a1 = cA + (size_t)(t + 1) * kstep;
;             const char* a2 = last ? nA : cA + (size_t)(t + 2) * kstep; const char* b2 = last ? nB : cB + (size_t)(t + 2) * kstep;
;             const char* a3 = a2 + kstep; const char* b3 = b2 + kstep;
;             PG8_LDB(B0, 0, 0); PG8_LDB(B1, 0, 1); PG8_SCHED; PG8_LDA(At, 0, 0); PG8_STAGE(PG8_SA(1, 1), a1 + hstepA, voffA);
;             PG8_WAIT_V(8); PG8_WAIT_L(0); PG8_BAR; PG8_MMA(0, 0, At, B0); PG8_MMA(0, 1, At, B1); PG8_BAR; PG8_SCHED;
;             PG8_LDA(At, 0, 1); PG8_STAGE(PG8_SB(0, 0), b2, voffB); PG8_STAGE(PG8_SB(0, 1), b2 + hstepB, voffB); PG8_STAGE(PG8_SA(0, 0), a2, voffA);
.LBB0_2239:
	ds_read_b128 v[142:145], v151
	ds_read_b128 v[146:149], v151 offset:1024
	ds_read_b128 v[158:161], v151 offset:2048
	ds_read_b128 v[162:165], v151 offset:3072
	ds_read_b128 v[166:169], v152
	ds_read_b128 v[170:173], v152 offset:1024
	ds_read_b128 v[174:177], v152 offset:2048
	ds_read_b128 v[178:181], v152 offset:3072
	s_add_u32 s8, s6, 0xfffe0080
	s_addc_u32 s9, s7, -1
	s_cmp_eq_u32 s50, 4
	s_cselect_b32 s43, s25, s9
	s_cselect_b32 s42, s24, s8
	s_cselect_b32 s9, s41, s49
	s_cselect_b32 s8, s40, s48
	v_lshl_add_u64 v[214:215], s[6:7], 0, v[138:139]
	s_add_i32 m0, s3, 0xc000
	ds_read_b128 v[182:185], v153
	ds_read_b128 v[186:189], v153 offset:1024
	ds_read_b128 v[190:193], v153 offset:2048
	ds_read_b128 v[194:197], v153 offset:3072
	ds_read_b128 v[198:201], v153 offset:4096
	ds_read_b128 v[202:205], v153 offset:5120
	ds_read_b128 v[206:209], v153 offset:6144
	ds_read_b128 v[210:213], v153 offset:7168
	global_load_lds_dwordx4 v[214:215], off
	v_lshl_add_u64 v[214:215], s[6:7], 0, v[140:141]
	s_add_i32 m0, s3, 0xe000
	s_nop 0
	global_load_lds_dwordx4 v[214:215], off
	s_waitcnt vmcnt(8)
	s_waitcnt lgkmcnt(0)
	s_barrier
	s_setprio 1
	v_mfma_f32_16x16x32_bf16 v[124:127], v[142:145], v[182:185], v[124:127]
	v_mfma_f32_16x16x32_bf16 v[120:123], v[158:161], v[182:185], v[120:123]
	v_mfma_f32_16x16x32_bf16 v[108:111], v[142:145], v[190:193], v[108:111]
	v_mfma_f32_16x16x32_bf16 v[104:107], v[158:161], v[190:193], v[104:107]
	v_mfma_f32_16x16x32_bf16 v[92:95], v[142:145], v[198:201], v[92:95]
	v_mfma_f32_16x16x32_bf16 v[88:91], v[158:161], v[198:201], v[88:91]
	v_mfma_f32_16x16x32_bf16 v[76:79], v[142:145], v[206:209], v[76:79]
	v_mfma_f32_16x16x32_bf16 v[72:75], v[158:161], v[206:209], v[72:75]
	v_mfma_f32_16x16x32_bf16 v[124:127], v[146:149], v[186:189], v[124:127]
	v_mfma_f32_16x16x32_bf16 v[120:123], v[162:165], v[186:189], v[120:123]
	v_mfma_f32_16x16x32_bf16 v[108:111], v[146:149], v[194:197], v[108:111]
	v_mfma_f32_16x16x32_bf16 v[104:107], v[162:165], v[194:197], v[104:107]
	v_mfma_f32_16x16x32_bf16 v[92:95], v[146:149], v[202:205], v[92:95]
	v_mfma_f32_16x16x32_bf16 v[88:91], v[162:165], v[202:205], v[88:91]
	v_mfma_f32_16x16x32_bf16 v[76:79], v[146:149], v[210:213], v[76:79]
	v_mfma_f32_16x16x32_bf16 v[72:75], v[162:165], v[210:213], v[72:75]
	v_mfma_f32_16x16x32_bf16 v[116:119], v[166:169], v[182:185], v[116:119]
	v_mfma_f32_16x16x32_bf16 v[112:115], v[174:177], v[182:185], v[112:115]
	v_mfma_f32_16x16x32_bf16 v[100:103], v[166:169], v[190:193], v[100:103]
	v_mfma_f32_16x16x32_bf16 v[96:99], v[174:177], v[190:193], v[96:99]
	v_mfma_f32_16x16x32_bf16 v[84:87], v[166:169], v[198:201], v[84:87]
	v_mfma_f32_16x16x32_bf16 v[80:83], v[174:177], v[198:201], v[80:83]
	v_mfma_f32_16x16x32_bf16 v[68:71], v[166:169], v[206:209], v[68:71]
	v_mfma_f32_16x16x32_bf16 v[64:67], v[174:177], v[206:209], v[64:67]
	v_mfma_f32_16x16x32_bf16 v[116:119], v[170:173], v[186:189], v[116:119]
	v_mfma_f32_16x16x32_bf16 v[112:115], v[178:181], v[186:189], v[112:115]
	v_mfma_f32_16x16x32_bf16 v[100:103], v[170:173], v[194:197], v[100:103]
	v_mfma_f32_16x16x32_bf16 v[96:99], v[178:181], v[194:197], v[96:99]
	v_mfma_f32_16x16x32_bf16 v[84:87], v[170:173], v[202:205], v[84:87]
	v_mfma_f32_16x16x32_bf16 v[80:83], v[178:181], v[202:205], v[80:83]
	v_mfma_f32_16x16x32_bf16 v[68:71], v[170:173], v[210:213], v[68:71]
	v_mfma_f32_16x16x32_bf16 v[64:67], v[178:181], v[210:213], v[64:67]
	s_setprio 0
	s_barrier
	s_add_i32 s51, s47, s2
	v_lshl_add_u64 v[214:215], s[8:9], 0, v[130:131]
	s_mov_b32 m0, s51
	ds_read_b128 v[182:185], v153 offset:16384
	ds_read_b128 v[186:189], v153 offset:17408
	ds_read_b128 v[190:193], v153 offset:18432
	ds_read_b128 v[194:197], v153 offset:19456
	ds_read_b128 v[198:201], v153 offset:20480
	ds_read_b128 v[202:205], v153 offset:21504
	ds_read_b128 v[206:209], v153 offset:22528
	ds_read_b128 v[210:213], v153 offset:23552
	global_load_lds_dwordx4 v[214:215], off
	s_add_i32 m0, s51, 0x2000
	s_add_u32 s64, s8, 0x80000
	v_lshl_add_u64 v[216:217], s[8:9], 0, v[134:135]
	s_addc_u32 s65, s9, 0
	s_add_i32 s51, s52, s2
	global_load_lds_dwordx4 v[216:217], off
	v_lshl_add_u64 v[218:219], s[64:65], 0, v[130:131]
	s_mov_b32 m0, s51
	v_lshl_add_u64 v[220:221], s[42:43], 0, v[132:133]
	global_load_lds_dwordx4 v[218:219], off
	v_lshl_add_u64 v[218:219], s[64:65], 0, v[134:135]
	s_add_i32 m0, s51, 0x2000
	s_nop 0
	global_load_lds_dwordx4 v[218:219], off
	v_lshl_add_u64 v[218:219], s[42:43], 0, v[128:129]
	s_mov_b32 m0, s3
	s_nop 0
	global_load_lds_dwordx4 v[218:219], off
	s_mov_b32 m0, s28
	s_nop 0
	global_load_lds_dwordx4 v[220:221], off
	s_waitcnt vmcnt(8)
	s_waitcnt lgkmcnt(0)
	s_barrier
; #define PG8_STAGE(bufoff, gbase, voff) do { _Pragma("unroll") for (int _i = 0; _i < 2; ++_i) \
;         __builtin_amdgcn_global_load_lds((const unsigned*)((const char*)(gbase) + (voff)[_i]), (LAS unsigned*)(lds + (bufoff) + ldsw + _i * 8192), 16, 0, 0); } while (0)
; #define PG8_LDA(dst, b, h) do { _Pragma("unroll") for (int m = 0; m < 4; ++m) _Pragma("unroll") for (int k = 0; k < 2; ++k) dst[m][k] = *(const LAS bf16x8*)(lds + PG8_SA(b, h) + aoff + m * 2048 + k * 1024); } while (0)
; #define PG8_LDB(dst, b, h) do { _Pragma("unroll") for (int n = 0; n < 2; ++n) _Pragma("unroll") for (int k = 0; k < 2; ++k) dst[n][k] = *(const LAS bf16x8*)(lds + PG8_SB(b, h) + boff + n * 2048 + k * 1024); } while (0)
; #define PG8_MMA(ai, bj, At, Bt) do { __builtin_amdgcn_s_setprio(1); _Pragma("unroll") for (int m = 0; m < 4; ++m) _Pragma("unroll") for (int n = 0; n < 2; ++n) _Pragma("unroll") for (int k = 0; k < 2; ++k) \
;         acc[ai][bj][m][n] = __builtin_amdgcn_mfma_f32_16x16x32_bf16(Bt[n][k], At[m][k], acc[ai][bj][m][n], 0, 0, 0); __builtin_amdgcn_s_setprio(0); } while (0)
; #define PG8_WAIT_V(n) asm volatile("s_waitcnt vmcnt(" #n ")" ::: "memory")
; #define PG8_WAIT_L(n) asm volatile("s_waitcnt lgkmcnt(" #n ")" ::: "memory")
; #define PG8_BAR __builtin_amdgcn_s_barrier()
; #define PG8_SCHED __builtin_amdgcn_sched_barrier(0)
; template <class Desc, class Epi>
; DI void gemm_phase(LAS unsigned char* lds, const Desc& D, const Epi& E, int wv) {
;     ...
;             PG8_WAIT_V(8); PG8_WAIT_L(0); PG8_BAR; PG8_MMA(1, 0, At, B0); PG8_MMA(1, 1, At, B1); PG8_BAR; PG8_SCHED;
;             PG8_LDB(B0, 1, 0); PG8_LDB(B1, 1, 1); PG8_SCHED; PG8_LDA(At, 1, 0); PG8_STAGE(PG8_SA(0, 1), a2 + hstepA, voffA);
;             PG8_WAIT_V(8); PG8_WAIT_L(0); PG8_BAR; PG8_MMA(0, 0, At, B0); PG8_MMA(0, 1, At, B1); PG8_BAR; PG8_SCHED;
	s_setprio 1
	v_mfma_f32_16x16x32_bf16 v[60:63], v[142:145], v[182:185], v[60:63]
	v_mfma_f32_16x16x32_bf16 v[56:59], v[158:161], v[182:185], v[56:59]
	v_mfma_f32_16x16x32_bf16 v[44:47], v[142:145], v[190:193], v[44:47]
	v_mfma_f32_16x16x32_bf16 v[40:43], v[158:161], v[190:193], v[40:43]
	v_mfma_f32_16x16x32_bf16 v[28:31], v[142:145], v[198:201], v[28:31]
	v_mfma_f32_16x16x32_bf16 v[24:27], v[158:161], v[198:201], v[24:27]
	v_mfma_f32_16x16x32_bf16 v[12:15], v[142:145], v[206:209], v[12:15]
	v_mfma_f32_16x16x32_bf16 v[8:11], v[158:161], v[206:209], v[8:11]
	v_mfma_f32_16x16x32_bf16 v[60:63], v[146:149], v[186:189], v[60:63]
	v_mfma_f32_16x16x32_bf16 v[56:59], v[162:165], v[186:189], v[56:59]
	v_mfma_f32_16x16x32_bf16 v[44:47], v[146:149], v[194:197], v[44:47]
	v_mfma_f32_16x16x32_bf16 v[40:43], v[162:165], v[194:197], v[40:43]
	v_mfma_f32_16x16x32_bf16 v[28:31], v[146:149], v[202:205], v[28:31]
	v_mfma_f32_16x16x32_bf16 v[24:27], v[162:165], v[202:205], v[24:27]
	v_mfma_f32_16x16x32_bf16 v[12:15], v[146:149], v[210:213], v[12:15]
	v_mfma_f32_16x16x32_bf16 v[8:11], v[162:165], v[210:213], v[8:11]
	v_mfma_f32_16x16x32_bf16 v[52:55], v[166:169], v[182:185], v[52:55]
	v_mfma_f32_16x16x32_bf16 v[48:51], v[174:177], v[182:185], v[48:51]
	v_mfma_f32_16x16x32_bf16 v[36:39], v[166:169], v[190:193], v[36:39]
	v_mfma_f32_16x16x32_bf16 v[32:35], v[174:177], v[190:193], v[32:35]
	v_mfma_f32_16x16x32_bf16 v[20:23], v[166:169], v[198:201], v[20:23]
	v_mfma_f32_16x16x32_bf16 v[16:19], v[174:177], v[198:201], v[16:19]
	v_mfma_f32_16x16x32_bf16 v[4:7], v[166:169], v[206:209], v[4:7]
	v_mfma_f32_16x16x32_bf16 v[0:3], v[174:177], v[206:209], v[0:3]
	v_mfma_f32_16x16x32_bf16 v[52:55], v[170:173], v[186:189], v[52:55]
	v_mfma_f32_16x16x32_bf16 v[48:51], v[178:181], v[186:189], v[48:51]
	v_mfma_f32_16x16x32_bf16 v[36:39], v[170:173], v[194:197], v[36:39]
	v_mfma_f32_16x16x32_bf16 v[32:35], v[178:181], v[194:197], v[32:35]
	v_mfma_f32_16x16x32_bf16 v[20:23], v[170:173], v[202:205], v[20:23]
	v_mfma_f32_16x16x32_bf16 v[16:19], v[178:181], v[202:205], v[16:19]
	v_mfma_f32_16x16x32_bf16 v[4:7], v[170:173], v[210:213], v[4:7]
	v_mfma_f32_16x16x32_bf16 v[0:3], v[178:181], v[210:213], v[0:3]
	s_setprio 0
	s_barrier
	s_add_i32 s51, 0, 0x18000
	v_add_u32_e32 v136, s51, v150
	s_add_i32 s64, 0, 0x1c000
	ds_read_b128 v[142:145], v136
	ds_read_b128 v[146:149], v136 offset:1024
	ds_read_b128 v[158:161], v136 offset:2048
	ds_read_b128 v[162:165], v136 offset:3072
	v_add_u32_e32 v136, s64, v150
	ds_read_b128 v[166:169], v136
	ds_read_b128 v[170:173], v136 offset:1024
	ds_read_b128 v[174:177], v136 offset:2048
	ds_read_b128 v[178:181], v136 offset:3072
	s_add_u32 s42, s42, 0x20000
	s_addc_u32 s43, s43, 0
	s_mov_b32 m0, s29
	v_lshl_add_u64 v[222:223], s[42:43], 0, v[128:129]
	ds_read_b128 v[182:185], v153 offset:32768
	ds_read_b128 v[186:189], v153 offset:33792
	ds_read_b128 v[190:193], v153 offset:34816
	ds_read_b128 v[194:197], v153 offset:35840
	ds_read_b128 v[198:201], v153 offset:36864
	ds_read_b128 v[202:205], v153 offset:37888
	ds_read_b128 v[206:209], v153 offset:38912
	ds_read_b128 v[210:213], v153 offset:39936
	global_load_lds_dwordx4 v[222:223], off
	v_lshl_add_u64 v[222:223], s[42:43], 0, v[132:133]
	s_mov_b32 m0, s30
	s_nop 0
	global_load_lds_dwordx4 v[222:223], off
	s_waitcnt vmcnt(8)
	s_waitcnt lgkmcnt(0)
	s_barrier
	s_setprio 1
	v_mfma_f32_16x16x32_bf16 v[124:127], v[142:145], v[182:185], v[124:127]
	v_mfma_f32_16x16x32_bf16 v[120:123], v[158:161], v[182:185], v[120:123]
	v_mfma_f32_16x16x32_bf16 v[108:111], v[142:145], v[190:193], v[108:111]
	v_mfma_f32_16x16x32_bf16 v[104:107], v[158:161], v[190:193], v[104:107]
	v_mfma_f32_16x16x32_bf16 v[92:95], v[142:145], v[198:201], v[92:95]
	v_mfma_f32_16x16x32_bf16 v[88:91], v[158:161], v[198:201], v[88:91]
	v_mfma_f32_16x16x32_bf16 v[76:79], v[142:145], v[206:209], v[76:79]
	v_mfma_f32_16x16x32_bf16 v[72:75], v[158:161], v[206:209], v[72:75]
	v_mfma_f32_16x16x32_bf16 v[124:127], v[146:149], v[186:189], v[124:127]
	v_mfma_f32_16x16x32_bf16 v[120:123], v[162:165], v[186:189], v[120:123]
	v_mfma_f32_16x16x32_bf16 v[108:111], v[146:149], v[194:197], v[108:111]
	v_mfma_f32_16x16x32_bf16 v[104:107], v[162:165], v[194:197], v[104:107]
	v_mfma_f32_16x16x32_bf16 v[92:95], v[146:149], v[202:205], v[92:95]
	v_mfma_f32_16x16x32_bf16 v[88:91], v[162:165], v[202:205], v[88:91]
	v_mfma_f32_16x16x32_bf16 v[76:79], v[146:149], v[210:213], v[76:79]
	v_mfma_f32_16x16x32_bf16 v[72:75], v[162:165], v[210:213], v[72:75]
	v_mfma_f32_16x16x32_bf16 v[116:119], v[166:169], v[182:185], v[116:119]
	v_mfma_f32_16x16x32_bf16 v[112:115], v[174:177], v[182:185], v[112:115]
	v_mfma_f32_16x16x32_bf16 v[100:103], v[166:169], v[190:193], v[100:103]
	v_mfma_f32_16x16x32_bf16 v[96:99], v[174:177], v[190:193], v[96:99]
	v_mfma_f32_16x16x32_bf16 v[84:87], v[166:169], v[198:201], v[84:87]
	v_mfma_f32_16x16x32_bf16 v[80:83], v[174:177], v[198:201], v[80:83]
	v_mfma_f32_16x16x32_bf16 v[68:71], v[166:169], v[206:209], v[68:71]
	v_mfma_f32_16x16x32_bf16 v[64:67], v[174:177], v[206:209], v[64:67]
	v_mfma_f32_16x16x32_bf16 v[116:119], v[170:173], v[186:189], v[116:119]
	v_mfma_f32_16x16x32_bf16 v[112:115], v[178:181], v[186:189], v[112:115]
	v_mfma_f32_16x16x32_bf16 v[100:103], v[170:173], v[194:197], v[100:103]
	v_mfma_f32_16x16x32_bf16 v[96:99], v[178:181], v[194:197], v[96:99]
	v_mfma_f32_16x16x32_bf16 v[84:87], v[170:173], v[202:205], v[84:87]
	v_mfma_f32_16x16x32_bf16 v[80:83], v[178:181], v[202:205], v[80:83]
	v_mfma_f32_16x16x32_bf16 v[68:71], v[170:173], v[210:213], v[68:71]
	v_mfma_f32_16x16x32_bf16 v[64:67], v[178:181], v[210:213], v[64:67]
	s_setprio 0
	s_barrier
; #define PG8_STAGE(bufoff, gbase, voff) do { _Pragma("unroll") for (int _i = 0; _i < 2; ++_i) \
;         __builtin_amdgcn_global_load_lds((const unsigned*)((const char*)(gbase) + (voff)[_i]), (LAS unsigned*)(lds + (bufoff) + ldsw + _i * 8192), 16, 0, 0); } while (0)
; #define PG8_LDA(dst, b, h) do { _Pragma("unroll") for (int m = 0; m < 4; ++m) _Pragma("unroll") for (int k = 0; k < 2; ++k) dst[m][k] = *(const LAS bf16x8*)(lds + PG8_SA(b, h) + aoff + m * 2048 + k * 1024); } while (0)
; #define PG8_MMA(ai, bj, At, Bt) do { __builtin_amdgcn_s_setprio(1); _Pragma("unroll") for (int m = 0; m < 4; ++m) _Pragma("unroll") for (int n = 0; n < 2; ++n) _Pragma("unroll") for (int k = 0; k < 2; ++k) \
;         acc[ai][bj][m][n] = __builtin_amdgcn_mfma_f32_16x16x32_bf16(Bt[n][k], At[m][k], acc[ai][bj][m][n], 0, 0, 0); __builtin_amdgcn_s_setprio(0); } while (0)
; #define PG8_WAIT_V(n) asm volatile("s_waitcnt vmcnt(" #n ")" ::: "memory")
; #define PG8_WAIT_L(n) asm volatile("s_waitcnt lgkmcnt(" #n ")" ::: "memory")
; #define PG8_BAR __builtin_amdgcn_s_barrier()
; #define PG8_SCHED __builtin_amdgcn_sched_barrier(0)
; template <class Desc, class Epi>
; DI void gemm_phase(LAS unsigned char* lds, const Desc& D, const Epi& E, int wv) {
;     ...
;             PG8_LDA(At, 1, 1); PG8_STAGE(PG8_SB(1, 0), b3, voffB); PG8_STAGE(PG8_SB(1, 1), b3 + hstepB, voffB); PG8_STAGE(PG8_SA(1, 0), a3, voffA);
;             PG8_WAIT_V(8); PG8_WAIT_L(0); PG8_BAR; PG8_MMA(1, 0, At, B0); PG8_MMA(1, 1, At, B1); PG8_BAR; PG8_SCHED;
;         }
;         if (wr == 0) PG8_BAR;
	s_add_i32 s42, s51, s2
	v_lshl_add_u64 v[214:215], v[214:215], 0, s[14:15]
	s_mov_b32 m0, s42
	ds_read_b128 v[182:185], v153 offset:49152
	ds_read_b128 v[186:189], v153 offset:50176
	ds_read_b128 v[190:193], v153 offset:51200
	ds_read_b128 v[194:197], v153 offset:52224
	ds_read_b128 v[198:201], v153 offset:53248
	ds_read_b128 v[202:205], v153 offset:54272
	ds_read_b128 v[206:209], v153 offset:55296
	ds_read_b128 v[210:213], v153 offset:56320
	global_load_lds_dwordx4 v[214:215], off
	s_add_i32 m0, s42, 0x2000
	s_add_u32 s8, s8, 0x80080
	v_lshl_add_u64 v[214:215], v[216:217], 0, s[14:15]
	s_addc_u32 s9, s9, 0
	s_add_i32 s42, s64, s2
	global_load_lds_dwordx4 v[214:215], off
	v_lshl_add_u64 v[214:215], s[8:9], 0, v[130:131]
	s_mov_b32 m0, s42
	s_nop 0
	global_load_lds_dwordx4 v[214:215], off
	v_lshl_add_u64 v[214:215], s[8:9], 0, v[134:135]
	s_add_i32 m0, s42, 0x2000
	s_nop 0
	global_load_lds_dwordx4 v[214:215], off
	v_lshl_add_u64 v[214:215], v[218:219], 0, s[14:15]
	s_mov_b32 m0, s35
	s_nop 0
	global_load_lds_dwordx4 v[214:215], off
	v_lshl_add_u64 v[214:215], v[220:221], 0, s[14:15]
	s_mov_b32 m0, s46
	s_nop 0
	global_load_lds_dwordx4 v[214:215], off
	s_waitcnt vmcnt(8)
	s_waitcnt lgkmcnt(0)
	s_barrier
	s_setprio 1
	v_mfma_f32_16x16x32_bf16 v[60:63], v[142:145], v[182:185], v[60:63]
	v_mfma_f32_16x16x32_bf16 v[56:59], v[158:161], v[182:185], v[56:59]
	v_mfma_f32_16x16x32_bf16 v[44:47], v[142:145], v[190:193], v[44:47]
	v_mfma_f32_16x16x32_bf16 v[40:43], v[158:161], v[190:193], v[40:43]
	v_mfma_f32_16x16x32_bf16 v[28:31], v[142:145], v[198:201], v[28:31]
	v_mfma_f32_16x16x32_bf16 v[24:27], v[158:161], v[198:201], v[24:27]
	v_mfma_f32_16x16x32_bf16 v[12:15], v[142:145], v[206:209], v[12:15]
	v_mfma_f32_16x16x32_bf16 v[8:11], v[158:161], v[206:209], v[8:11]
	v_mfma_f32_16x16x32_bf16 v[60:63], v[146:149], v[186:189], v[60:63]
	v_mfma_f32_16x16x32_bf16 v[56:59], v[162:165], v[186:189], v[56:59]
	v_mfma_f32_16x16x32_bf16 v[44:47], v[146:149], v[194:197], v[44:47]
	v_mfma_f32_16x16x32_bf16 v[40:43], v[162:165], v[194:197], v[40:43]
	v_mfma_f32_16x16x32_bf16 v[28:31], v[146:149], v[202:205], v[28:31]
	v_mfma_f32_16x16x32_bf16 v[24:27], v[162:165], v[202:205], v[24:27]
	v_mfma_f32_16x16x32_bf16 v[12:15], v[146:149], v[210:213], v[12:15]
	v_mfma_f32_16x16x32_bf16 v[8:11], v[162:165], v[210:213], v[8:11]
	v_mfma_f32_16x16x32_bf16 v[52:55], v[166:169], v[182:185], v[52:55]
	v_mfma_f32_16x16x32_bf16 v[48:51], v[174:177], v[182:185], v[48:51]
	v_mfma_f32_16x16x32_bf16 v[36:39], v[166:169], v[190:193], v[36:39]
	v_mfma_f32_16x16x32_bf16 v[32:35], v[174:177], v[190:193], v[32:35]
	v_mfma_f32_16x16x32_bf16 v[20:23], v[166:169], v[198:201], v[20:23]
	v_mfma_f32_16x16x32_bf16 v[16:19], v[174:177], v[198:201], v[16:19]
	v_mfma_f32_16x16x32_bf16 v[4:7], v[166:169], v[206:209], v[4:7]
	v_mfma_f32_16x16x32_bf16 v[0:3], v[174:177], v[206:209], v[0:3]
	v_mfma_f32_16x16x32_bf16 v[52:55], v[170:173], v[186:189], v[52:55]
	v_mfma_f32_16x16x32_bf16 v[48:51], v[178:181], v[186:189], v[48:51]
	v_mfma_f32_16x16x32_bf16 v[36:39], v[170:173], v[194:197], v[36:39]
	v_mfma_f32_16x16x32_bf16 v[32:35], v[178:181], v[194:197], v[32:35]
	v_mfma_f32_16x16x32_bf16 v[20:23], v[170:173], v[202:205], v[20:23]
	v_mfma_f32_16x16x32_bf16 v[16:19], v[178:181], v[202:205], v[16:19]
	v_mfma_f32_16x16x32_bf16 v[4:7], v[170:173], v[210:213], v[4:7]
	v_mfma_f32_16x16x32_bf16 v[0:3], v[178:181], v[210:213], v[0:3]
	s_setprio 0
	s_barrier
	s_add_i32 s50, s50, 2
	s_add_u32 s6, s6, 0x100
	s_addc_u32 s7, s7, 0
	s_add_u32 s48, s48, 0x100
	s_addc_u32 s49, s49, 0
	s_cmp_gt_u32 s50, 5
	s_cbranch_scc0 .LBB0_2239
	s_and_b64 vcc, exec, s[18:19]
	s_cbranch_vccz .LBB0_2242
	s_barrier

; #define PG8_STAGE(bufoff, gbase, voff) do { _Pragma("unroll") for (int _i = 0; _i < 2; ++_i) \
;         __builtin_amdgcn_global_load_lds((const unsigned*)((const char*)(gbase) + (voff)[_i]), (LAS unsigned*)(lds + (bufoff) + ldsw + _i * 8192), 16, 0, 0); } while (0)
; #define PG8_LDA(dst, b, h) do { _Pragma("unroll") for (int m = 0; m < 4; ++m) _Pragma("unroll") for (int k = 0; k < 2; ++k) dst[m][k] = *(const LAS bf16x8*)(lds + PG8_SA(b, h) + aoff + m * 2048 + k * 1024); } while (0)
; #define PG8_LDB(dst, b, h) do { _Pragma("unroll") for (int n = 0; n < 2; ++n) _Pragma("unroll") for (int k = 0; k < 2; ++k) dst[n][k] = *(const LAS bf16x8*)(lds + PG8_SB(b, h) + boff + n * 2048 + k * 1024); } while (0)
; #define PG8_MMA(ai, bj, At, Bt) do { __builtin_amdgcn_s_setprio(1); _Pragma("unroll") for (int m = 0; m < 4; ++m) _Pragma("unroll") for (int n = 0; n < 2; ++n) _Pragma("unroll") for (int k = 0; k < 2; ++k) \
;         acc[ai][bj][m][n] = __builtin_amdgcn_mfma_f32_16x16x32_bf16(Bt[n][k], At[m][k], acc[ai][bj][m][n], 0, 0, 0); __builtin_amdgcn_s_setprio(0); } while (0)
; #define PG8_WAIT_V(n) asm volatile("s_waitcnt vmcnt(" #n ")" ::: "memory")
; #define PG8_WAIT_L(n) asm volatile("s_waitcnt lgkmcnt(" #n ")" ::: "memory")
; #define PG8_BAR __builtin_amdgcn_s_barrier()
; #define PG8_SCHED __builtin_amdgcn_sched_barrier(0)
; template <class Desc, class Epi>
; DI void gemm_phase(LAS unsigned char* lds, const Desc& D, const Epi& E, int wv) {
;     ...
;         for (int t = 0; t < nt; t += 2) {
;             const bool last = (t == nt - 2);
;             const char* a1 = cA + (size_t)(t + 1) * kstep;
;             const char* a2 = last ? nA : cA + (size_t)(t + 2) * kstep; const char* b2 = last ? nB : cB + (size_t)(t + 2) * kstep;
;             const char* a3 = a2 + kstep; const char* b3 = b2 + kstep;
;             PG8_LDB(B0, 0, 0); PG8_LDB(B1, 0, 1); PG8_SCHED; PG8_LDA(At, 0, 0); PG8_STAGE(PG8_SA(1, 1), a1 + hstepA, voffA);
;             PG8_WAIT_V(8); PG8_WAIT_L(0); PG8_BAR; PG8_MMA(0, 0, At, B0); PG8_MMA(0, 1, At, B1); PG8_BAR; PG8_SCHED;
;             PG8_LDA(At, 0, 1); PG8_STAGE(PG8_SB(0, 0), b2, voffB); PG8_STAGE(PG8_SB(0, 1), b2 + hstepB, voffB); PG8_STAGE(PG8_SA(0, 0), a2, voffA);
.LBB0_2480:
	ds_read_b128 v[128:131], v185
	ds_read_b128 v[132:135], v185 offset:1024
	ds_read_b128 v[150:153], v185 offset:2048
	ds_read_b128 v[154:157], v185 offset:3072
	ds_read_b128 v[158:161], v186
	ds_read_b128 v[162:165], v186 offset:1024
	ds_read_b128 v[166:169], v186 offset:2048
	ds_read_b128 v[170:173], v186 offset:3072
	s_add_u32 s42, s40, 0xfff00080
	s_addc_u32 s43, s41, -1
	s_cmp_eq_u32 s48, 28
	s_cselect_b32 s47, s17, s43
	s_cselect_b32 s46, s16, s42
	s_cselect_b32 s43, s19, s23
	s_cselect_b32 s42, s18, s5
	v_lshl_add_u64 v[182:183], s[40:41], 0, v[146:147]
	s_add_i32 m0, s3, 0xc000
	ds_read_b128 v[174:177], v187
	ds_read_b128 v[178:181], v187 offset:1024
	ds_read_b128 v[190:193], v187 offset:2048
	ds_read_b128 v[194:197], v187 offset:3072
	ds_read_b128 v[198:201], v187 offset:4096
	ds_read_b128 v[202:205], v187 offset:5120
	ds_read_b128 v[206:209], v187 offset:6144
	ds_read_b128 v[210:213], v187 offset:7168
	global_load_lds_dwordx4 v[182:183], off
	v_lshl_add_u64 v[182:183], s[40:41], 0, v[148:149]
	s_add_i32 m0, s3, 0xe000
	s_nop 0
	global_load_lds_dwordx4 v[182:183], off
	s_waitcnt vmcnt(8)
	s_waitcnt lgkmcnt(0)
	s_barrier
	s_setprio 1
	v_mfma_f32_16x16x32_bf16 v[124:127], v[128:131], v[174:177], v[124:127]
	v_mfma_f32_16x16x32_bf16 v[120:123], v[150:153], v[174:177], v[120:123]
	v_mfma_f32_16x16x32_bf16 v[108:111], v[128:131], v[190:193], v[108:111]
	v_mfma_f32_16x16x32_bf16 v[104:107], v[150:153], v[190:193], v[104:107]
	v_mfma_f32_16x16x32_bf16 v[92:95], v[128:131], v[198:201], v[92:95]
	v_mfma_f32_16x16x32_bf16 v[88:91], v[150:153], v[198:201], v[88:91]
	v_mfma_f32_16x16x32_bf16 v[76:79], v[128:131], v[206:209], v[76:79]
	v_mfma_f32_16x16x32_bf16 v[72:75], v[150:153], v[206:209], v[72:75]
	v_mfma_f32_16x16x32_bf16 v[124:127], v[132:135], v[178:181], v[124:127]
	v_mfma_f32_16x16x32_bf16 v[120:123], v[154:157], v[178:181], v[120:123]
	v_mfma_f32_16x16x32_bf16 v[108:111], v[132:135], v[194:197], v[108:111]
	v_mfma_f32_16x16x32_bf16 v[104:107], v[154:157], v[194:197], v[104:107]
	v_mfma_f32_16x16x32_bf16 v[92:95], v[132:135], v[202:205], v[92:95]
	v_mfma_f32_16x16x32_bf16 v[88:91], v[154:157], v[202:205], v[88:91]
	v_mfma_f32_16x16x32_bf16 v[76:79], v[132:135], v[210:213], v[76:79]
	v_mfma_f32_16x16x32_bf16 v[72:75], v[154:157], v[210:213], v[72:75]
	v_mfma_f32_16x16x32_bf16 v[116:119], v[158:161], v[174:177], v[116:119]
	v_mfma_f32_16x16x32_bf16 v[112:115], v[166:169], v[174:177], v[112:115]
	v_mfma_f32_16x16x32_bf16 v[100:103], v[158:161], v[190:193], v[100:103]
	v_mfma_f32_16x16x32_bf16 v[96:99], v[166:169], v[190:193], v[96:99]
	v_mfma_f32_16x16x32_bf16 v[84:87], v[158:161], v[198:201], v[84:87]
	v_mfma_f32_16x16x32_bf16 v[80:83], v[166:169], v[198:201], v[80:83]
	v_mfma_f32_16x16x32_bf16 v[68:71], v[158:161], v[206:209], v[68:71]
	v_mfma_f32_16x16x32_bf16 v[64:67], v[166:169], v[206:209], v[64:67]
	v_mfma_f32_16x16x32_bf16 v[116:119], v[162:165], v[178:181], v[116:119]
	v_mfma_f32_16x16x32_bf16 v[112:115], v[170:173], v[178:181], v[112:115]
	v_mfma_f32_16x16x32_bf16 v[100:103], v[162:165], v[194:197], v[100:103]
	v_mfma_f32_16x16x32_bf16 v[96:99], v[170:173], v[194:197], v[96:99]
	v_mfma_f32_16x16x32_bf16 v[84:87], v[162:165], v[202:205], v[84:87]
	v_mfma_f32_16x16x32_bf16 v[80:83], v[170:173], v[202:205], v[80:83]
	v_mfma_f32_16x16x32_bf16 v[68:71], v[162:165], v[210:213], v[68:71]
	v_mfma_f32_16x16x32_bf16 v[64:67], v[170:173], v[210:213], v[64:67]
	s_setprio 0
	s_barrier
	s_add_i32 s49, s52, s2
	v_lshl_add_u64 v[182:183], s[42:43], 0, v[140:141]
	s_mov_b32 m0, s49
	ds_read_b128 v[174:177], v187 offset:16384
	ds_read_b128 v[178:181], v187 offset:17408
	ds_read_b128 v[190:193], v187 offset:18432
	ds_read_b128 v[194:197], v187 offset:19456
	ds_read_b128 v[198:201], v187 offset:20480
	ds_read_b128 v[202:205], v187 offset:21504
	ds_read_b128 v[206:209], v187 offset:22528
	ds_read_b128 v[210:213], v187 offset:23552
	global_load_lds_dwordx4 v[182:183], off
	s_add_i32 m0, s49, 0x2000
	s_add_u32 s62, s42, 0x100000
	v_lshl_add_u64 v[214:215], s[42:43], 0, v[136:137]
	s_addc_u32 s63, s43, 0
	s_add_i32 s49, s53, s2
	global_load_lds_dwordx4 v[214:215], off
	v_lshl_add_u64 v[216:217], s[62:63], 0, v[140:141]
	s_mov_b32 m0, s49
	v_lshl_add_u64 v[218:219], s[46:47], 0, v[138:139]
	global_load_lds_dwordx4 v[216:217], off
	v_lshl_add_u64 v[216:217], s[62:63], 0, v[136:137]
	s_add_i32 m0, s49, 0x2000
	s_nop 0
	global_load_lds_dwordx4 v[216:217], off
	v_lshl_add_u64 v[216:217], s[46:47], 0, v[142:143]
	s_mov_b32 m0, s3
	s_nop 0
	global_load_lds_dwordx4 v[216:217], off
	s_mov_b32 m0, s28
	s_nop 0
	global_load_lds_dwordx4 v[218:219], off
	s_waitcnt vmcnt(8)
	s_waitcnt lgkmcnt(0)
	s_barrier
; #define PG8_STAGE(bufoff, gbase, voff) do { _Pragma("unroll") for (int _i = 0; _i < 2; ++_i) \
;         __builtin_amdgcn_global_load_lds((const unsigned*)((const char*)(gbase) + (voff)[_i]), (LAS unsigned*)(lds + (bufoff) + ldsw + _i * 8192), 16, 0, 0); } while (0)
; #define PG8_LDA(dst, b, h) do { _Pragma("unroll") for (int m = 0; m < 4; ++m) _Pragma("unroll") for (int k = 0; k < 2; ++k) dst[m][k] = *(const LAS bf16x8*)(lds + PG8_SA(b, h) + aoff + m * 2048 + k * 1024); } while (0)
; #define PG8_LDB(dst, b, h) do { _Pragma("unroll") for (int n = 0; n < 2; ++n) _Pragma("unroll") for (int k = 0; k < 2; ++k) dst[n][k] = *(const LAS bf16x8*)(lds + PG8_SB(b, h) + boff + n * 2048 + k * 1024); } while (0)
; #define PG8_MMA(ai, bj, At, Bt) do { __builtin_amdgcn_s_setprio(1); _Pragma("unroll") for (int m = 0; m < 4; ++m) _Pragma("unroll") for (int n = 0; n < 2; ++n) _Pragma("unroll") for (int k = 0; k < 2; ++k) \
;         acc[ai][bj][m][n] = __builtin_amdgcn_mfma_f32_16x16x32_bf16(Bt[n][k], At[m][k], acc[ai][bj][m][n], 0, 0, 0); __builtin_amdgcn_s_setprio(0); } while (0)
; #define PG8_WAIT_V(n) asm volatile("s_waitcnt vmcnt(" #n ")" ::: "memory")
; #define PG8_WAIT_L(n) asm volatile("s_waitcnt lgkmcnt(" #n ")" ::: "memory")
; #define PG8_BAR __builtin_amdgcn_s_barrier()
; #define PG8_SCHED __builtin_amdgcn_sched_barrier(0)
; template <class Desc, class Epi>
; DI void gemm_phase(LAS unsigned char* lds, const Desc& D, const Epi& E, int wv) {
;     ...
;             PG8_WAIT_V(8); PG8_WAIT_L(0); PG8_BAR; PG8_MMA(1, 0, At, B0); PG8_MMA(1, 1, At, B1); PG8_BAR; PG8_SCHED;
;             PG8_LDB(B0, 1, 0); PG8_LDB(B1, 1, 1); PG8_SCHED; PG8_LDA(At, 1, 0); PG8_STAGE(PG8_SA(0, 1), a2 + hstepA, voffA);
;             PG8_WAIT_V(8); PG8_WAIT_L(0); PG8_BAR; PG8_MMA(0, 0, At, B0); PG8_MMA(0, 1, At, B1); PG8_BAR; PG8_SCHED;
	s_setprio 1
	v_mfma_f32_16x16x32_bf16 v[60:63], v[128:131], v[174:177], v[60:63]
	v_mfma_f32_16x16x32_bf16 v[56:59], v[150:153], v[174:177], v[56:59]
	v_mfma_f32_16x16x32_bf16 v[44:47], v[128:131], v[190:193], v[44:47]
	v_mfma_f32_16x16x32_bf16 v[40:43], v[150:153], v[190:193], v[40:43]
	v_mfma_f32_16x16x32_bf16 v[28:31], v[128:131], v[198:201], v[28:31]
	v_mfma_f32_16x16x32_bf16 v[24:27], v[150:153], v[198:201], v[24:27]
	v_mfma_f32_16x16x32_bf16 v[12:15], v[128:131], v[206:209], v[12:15]
	v_mfma_f32_16x16x32_bf16 v[8:11], v[150:153], v[206:209], v[8:11]
	v_mfma_f32_16x16x32_bf16 v[60:63], v[132:135], v[178:181], v[60:63]
	v_mfma_f32_16x16x32_bf16 v[56:59], v[154:157], v[178:181], v[56:59]
	v_mfma_f32_16x16x32_bf16 v[44:47], v[132:135], v[194:197], v[44:47]
	v_mfma_f32_16x16x32_bf16 v[40:43], v[154:157], v[194:197], v[40:43]
	v_mfma_f32_16x16x32_bf16 v[28:31], v[132:135], v[202:205], v[28:31]
	v_mfma_f32_16x16x32_bf16 v[24:27], v[154:157], v[202:205], v[24:27]
	v_mfma_f32_16x16x32_bf16 v[12:15], v[132:135], v[210:213], v[12:15]
	v_mfma_f32_16x16x32_bf16 v[8:11], v[154:157], v[210:213], v[8:11]
	v_mfma_f32_16x16x32_bf16 v[52:55], v[158:161], v[174:177], v[52:55]
	v_mfma_f32_16x16x32_bf16 v[48:51], v[166:169], v[174:177], v[48:51]
	v_mfma_f32_16x16x32_bf16 v[36:39], v[158:161], v[190:193], v[36:39]
	v_mfma_f32_16x16x32_bf16 v[32:35], v[166:169], v[190:193], v[32:35]
	v_mfma_f32_16x16x32_bf16 v[20:23], v[158:161], v[198:201], v[20:23]
	v_mfma_f32_16x16x32_bf16 v[16:19], v[166:169], v[198:201], v[16:19]
	v_mfma_f32_16x16x32_bf16 v[4:7], v[158:161], v[206:209], v[4:7]
	v_mfma_f32_16x16x32_bf16 v[0:3], v[166:169], v[206:209], v[0:3]
	v_mfma_f32_16x16x32_bf16 v[52:55], v[162:165], v[178:181], v[52:55]
	v_mfma_f32_16x16x32_bf16 v[48:51], v[170:173], v[178:181], v[48:51]
	v_mfma_f32_16x16x32_bf16 v[36:39], v[162:165], v[194:197], v[36:39]
	v_mfma_f32_16x16x32_bf16 v[32:35], v[170:173], v[194:197], v[32:35]
	v_mfma_f32_16x16x32_bf16 v[20:23], v[162:165], v[202:205], v[20:23]
	v_mfma_f32_16x16x32_bf16 v[16:19], v[170:173], v[202:205], v[16:19]
	v_mfma_f32_16x16x32_bf16 v[4:7], v[162:165], v[210:213], v[4:7]
	v_mfma_f32_16x16x32_bf16 v[0:3], v[170:173], v[210:213], v[0:3]
	s_setprio 0
	s_barrier
	s_add_i32 s49, 0, 0x18000
	v_add_u32_e32 v144, s49, v184
	s_add_i32 s61, 0, 0x1c000
	ds_read_b128 v[128:131], v144
	ds_read_b128 v[132:135], v144 offset:1024
	ds_read_b128 v[150:153], v144 offset:2048
	ds_read_b128 v[154:157], v144 offset:3072
	v_add_u32_e32 v144, s61, v184
	ds_read_b128 v[158:161], v144
	ds_read_b128 v[162:165], v144 offset:1024
	ds_read_b128 v[166:169], v144 offset:2048
	ds_read_b128 v[170:173], v144 offset:3072
	s_add_u32 s46, s46, 0x100000
	s_addc_u32 s47, s47, 0
	s_mov_b32 m0, s29
	v_lshl_add_u64 v[220:221], s[46:47], 0, v[142:143]
	ds_read_b128 v[174:177], v187 offset:32768
	ds_read_b128 v[178:181], v187 offset:33792
	ds_read_b128 v[190:193], v187 offset:34816
	ds_read_b128 v[194:197], v187 offset:35840
	ds_read_b128 v[198:201], v187 offset:36864
	ds_read_b128 v[202:205], v187 offset:37888
	ds_read_b128 v[206:209], v187 offset:38912
	ds_read_b128 v[210:213], v187 offset:39936
	global_load_lds_dwordx4 v[220:221], off
	v_lshl_add_u64 v[220:221], s[46:47], 0, v[138:139]
	s_mov_b32 m0, s30
	s_nop 0
	global_load_lds_dwordx4 v[220:221], off
	s_waitcnt vmcnt(8)
	s_waitcnt lgkmcnt(0)
	s_barrier
	s_setprio 1
	v_mfma_f32_16x16x32_bf16 v[124:127], v[128:131], v[174:177], v[124:127]
	v_mfma_f32_16x16x32_bf16 v[120:123], v[150:153], v[174:177], v[120:123]
	v_mfma_f32_16x16x32_bf16 v[108:111], v[128:131], v[190:193], v[108:111]
	v_mfma_f32_16x16x32_bf16 v[104:107], v[150:153], v[190:193], v[104:107]
	v_mfma_f32_16x16x32_bf16 v[92:95], v[128:131], v[198:201], v[92:95]
	v_mfma_f32_16x16x32_bf16 v[88:91], v[150:153], v[198:201], v[88:91]
	v_mfma_f32_16x16x32_bf16 v[76:79], v[128:131], v[206:209], v[76:79]
	v_mfma_f32_16x16x32_bf16 v[72:75], v[150:153], v[206:209], v[72:75]
	v_mfma_f32_16x16x32_bf16 v[124:127], v[132:135], v[178:181], v[124:127]
	v_mfma_f32_16x16x32_bf16 v[120:123], v[154:157], v[178:181], v[120:123]
	v_mfma_f32_16x16x32_bf16 v[108:111], v[132:135], v[194:197], v[108:111]
	v_mfma_f32_16x16x32_bf16 v[104:107], v[154:157], v[194:197], v[104:107]
	v_mfma_f32_16x16x32_bf16 v[92:95], v[132:135], v[202:205], v[92:95]
	v_mfma_f32_16x16x32_bf16 v[88:91], v[154:157], v[202:205], v[88:91]
	v_mfma_f32_16x16x32_bf16 v[76:79], v[132:135], v[210:213], v[76:79]
	v_mfma_f32_16x16x32_bf16 v[72:75], v[154:157], v[210:213], v[72:75]
	v_mfma_f32_16x16x32_bf16 v[116:119], v[158:161], v[174:177], v[116:119]
	v_mfma_f32_16x16x32_bf16 v[112:115], v[166:169], v[174:177], v[112:115]
	v_mfma_f32_16x16x32_bf16 v[100:103], v[158:161], v[190:193], v[100:103]
	v_mfma_f32_16x16x32_bf16 v[96:99], v[166:169], v[190:193], v[96:99]
	v_mfma_f32_16x16x32_bf16 v[84:87], v[158:161], v[198:201], v[84:87]
	v_mfma_f32_16x16x32_bf16 v[80:83], v[166:169], v[198:201], v[80:83]
	v_mfma_f32_16x16x32_bf16 v[68:71], v[158:161], v[206:209], v[68:71]
	v_mfma_f32_16x16x32_bf16 v[64:67], v[166:169], v[206:209], v[64:67]
	v_mfma_f32_16x16x32_bf16 v[116:119], v[162:165], v[178:181], v[116:119]
	v_mfma_f32_16x16x32_bf16 v[112:115], v[170:173], v[178:181], v[112:115]
	v_mfma_f32_16x16x32_bf16 v[100:103], v[162:165], v[194:197], v[100:103]
	v_mfma_f32_16x16x32_bf16 v[96:99], v[170:173], v[194:197], v[96:99]
	v_mfma_f32_16x16x32_bf16 v[84:87], v[162:165], v[202:205], v[84:87]
	v_mfma_f32_16x16x32_bf16 v[80:83], v[170:173], v[202:205], v[80:83]
	v_mfma_f32_16x16x32_bf16 v[68:71], v[162:165], v[210:213], v[68:71]
	v_mfma_f32_16x16x32_bf16 v[64:67], v[170:173], v[210:213], v[64:67]
	s_setprio 0
	s_barrier
; #define PG8_STAGE(bufoff, gbase, voff) do { _Pragma("unroll") for (int _i = 0; _i < 2; ++_i) \
;         __builtin_amdgcn_global_load_lds((const unsigned*)((const char*)(gbase) + (voff)[_i]), (LAS unsigned*)(lds + (bufoff) + ldsw + _i * 8192), 16, 0, 0); } while (0)
; #define PG8_LDA(dst, b, h) do { _Pragma("unroll") for (int m = 0; m < 4; ++m) _Pragma("unroll") for (int k = 0; k < 2; ++k) dst[m][k] = *(const LAS bf16x8*)(lds + PG8_SA(b, h) + aoff + m * 2048 + k * 1024); } while (0)
; #define PG8_MMA(ai, bj, At, Bt) do { __builtin_amdgcn_s_setprio(1); _Pragma("unroll") for (int m = 0; m < 4; ++m) _Pragma("unroll") for (int n = 0; n < 2; ++n) _Pragma("unroll") for (int k = 0; k < 2; ++k) \
;         acc[ai][bj][m][n] = __builtin_amdgcn_mfma_f32_16x16x32_bf16(Bt[n][k], At[m][k], acc[ai][bj][m][n], 0, 0, 0); __builtin_amdgcn_s_setprio(0); } while (0)
; #define PG8_WAIT_V(n) asm volatile("s_waitcnt vmcnt(" #n ")" ::: "memory")
; #define PG8_WAIT_L(n) asm volatile("s_waitcnt lgkmcnt(" #n ")" ::: "memory")
; #define PG8_BAR __builtin_amdgcn_s_barrier()
; #define PG8_SCHED __builtin_amdgcn_sched_barrier(0)
; template <class Desc, class Epi>
; DI void gemm_phase(LAS unsigned char* lds, const Desc& D, const Epi& E, int wv) {
;     ...
;             PG8_LDA(At, 1, 1); PG8_STAGE(PG8_SB(1, 0), b3, voffB); PG8_STAGE(PG8_SB(1, 1), b3 + hstepB, voffB); PG8_STAGE(PG8_SA(1, 0), a3, voffA);
;             PG8_WAIT_V(8); PG8_WAIT_L(0); PG8_BAR; PG8_MMA(1, 0, At, B0); PG8_MMA(1, 1, At, B1); PG8_BAR; PG8_SCHED;
;         }
;         if (wr == 0) PG8_BAR;
	s_add_i32 s46, s49, s2
	v_lshl_add_u64 v[182:183], v[182:183], 0, s[12:13]
	s_mov_b32 m0, s46
	ds_read_b128 v[174:177], v187 offset:49152
	ds_read_b128 v[178:181], v187 offset:50176
	ds_read_b128 v[190:193], v187 offset:51200
	ds_read_b128 v[194:197], v187 offset:52224
	ds_read_b128 v[198:201], v187 offset:53248
	ds_read_b128 v[202:205], v187 offset:54272
	ds_read_b128 v[206:209], v187 offset:55296
	ds_read_b128 v[210:213], v187 offset:56320
	global_load_lds_dwordx4 v[182:183], off
	s_add_i32 m0, s46, 0x2000
	s_add_u32 s42, s42, 0x100080
	v_lshl_add_u64 v[182:183], v[214:215], 0, s[12:13]
	s_addc_u32 s43, s43, 0
	s_add_i32 s46, s61, s2
	global_load_lds_dwordx4 v[182:183], off
	v_lshl_add_u64 v[182:183], s[42:43], 0, v[140:141]
	s_mov_b32 m0, s46
	s_nop 0
	global_load_lds_dwordx4 v[182:183], off
	v_lshl_add_u64 v[182:183], s[42:43], 0, v[136:137]
	s_add_i32 m0, s46, 0x2000
	s_nop 0
	global_load_lds_dwordx4 v[182:183], off
	v_lshl_add_u64 v[182:183], v[216:217], 0, s[12:13]
	s_mov_b32 m0, s50
	s_nop 0
	global_load_lds_dwordx4 v[182:183], off
	v_lshl_add_u64 v[182:183], v[218:219], 0, s[12:13]
	s_mov_b32 m0, s51
	s_nop 0
	global_load_lds_dwordx4 v[182:183], off
	s_waitcnt vmcnt(8)
	s_waitcnt lgkmcnt(0)
	s_barrier
	s_setprio 1
	v_mfma_f32_16x16x32_bf16 v[60:63], v[128:131], v[174:177], v[60:63]
	v_mfma_f32_16x16x32_bf16 v[56:59], v[150:153], v[174:177], v[56:59]
	v_mfma_f32_16x16x32_bf16 v[44:47], v[128:131], v[190:193], v[44:47]
	v_mfma_f32_16x16x32_bf16 v[40:43], v[150:153], v[190:193], v[40:43]
	v_mfma_f32_16x16x32_bf16 v[28:31], v[128:131], v[198:201], v[28:31]
	v_mfma_f32_16x16x32_bf16 v[24:27], v[150:153], v[198:201], v[24:27]
	v_mfma_f32_16x16x32_bf16 v[12:15], v[128:131], v[206:209], v[12:15]
	v_mfma_f32_16x16x32_bf16 v[8:11], v[150:153], v[206:209], v[8:11]
	v_mfma_f32_16x16x32_bf16 v[60:63], v[132:135], v[178:181], v[60:63]
	v_mfma_f32_16x16x32_bf16 v[56:59], v[154:157], v[178:181], v[56:59]
	v_mfma_f32_16x16x32_bf16 v[44:47], v[132:135], v[194:197], v[44:47]
	v_mfma_f32_16x16x32_bf16 v[40:43], v[154:157], v[194:197], v[40:43]
	v_mfma_f32_16x16x32_bf16 v[28:31], v[132:135], v[202:205], v[28:31]
	v_mfma_f32_16x16x32_bf16 v[24:27], v[154:157], v[202:205], v[24:27]
	v_mfma_f32_16x16x32_bf16 v[12:15], v[132:135], v[210:213], v[12:15]
	v_mfma_f32_16x16x32_bf16 v[8:11], v[154:157], v[210:213], v[8:11]
	v_mfma_f32_16x16x32_bf16 v[52:55], v[158:161], v[174:177], v[52:55]
	v_mfma_f32_16x16x32_bf16 v[48:51], v[166:169], v[174:177], v[48:51]
	v_mfma_f32_16x16x32_bf16 v[36:39], v[158:161], v[190:193], v[36:39]
	v_mfma_f32_16x16x32_bf16 v[32:35], v[166:169], v[190:193], v[32:35]
	v_mfma_f32_16x16x32_bf16 v[20:23], v[158:161], v[198:201], v[20:23]
	v_mfma_f32_16x16x32_bf16 v[16:19], v[166:169], v[198:201], v[16:19]
	v_mfma_f32_16x16x32_bf16 v[4:7], v[158:161], v[206:209], v[4:7]
	v_mfma_f32_16x16x32_bf16 v[0:3], v[166:169], v[206:209], v[0:3]
	v_mfma_f32_16x16x32_bf16 v[52:55], v[162:165], v[178:181], v[52:55]
	v_mfma_f32_16x16x32_bf16 v[48:51], v[170:173], v[178:181], v[48:51]
	v_mfma_f32_16x16x32_bf16 v[36:39], v[162:165], v[194:197], v[36:39]
	v_mfma_f32_16x16x32_bf16 v[32:35], v[170:173], v[194:197], v[32:35]
	v_mfma_f32_16x16x32_bf16 v[20:23], v[162:165], v[202:205], v[20:23]
	v_mfma_f32_16x16x32_bf16 v[16:19], v[170:173], v[202:205], v[16:19]
	v_mfma_f32_16x16x32_bf16 v[4:7], v[162:165], v[210:213], v[4:7]
	v_mfma_f32_16x16x32_bf16 v[0:3], v[170:173], v[210:213], v[0:3]
	s_setprio 0
	s_barrier
	s_add_i32 s48, s48, 2
	s_add_u32 s40, s40, 0x100
	s_addc_u32 s41, s41, 0
	s_add_u32 s5, s5, 0x100
	s_addc_u32 s23, s23, 0
	s_cmp_gt_u32 s48, 29
	s_cbranch_scc0 .LBB0_2480
	s_and_b64 vcc, exec, s[14:15]
	s_cbranch_vccz .LBB0_2483
	s_barrier

; #define PG8_STAGE(bufoff, gbase, voff) do { _Pragma("unroll") for (int _i = 0; _i < 2; ++_i) \
;         __builtin_amdgcn_global_load_lds((const unsigned*)((const char*)(gbase) + (voff)[_i]), (LAS unsigned*)(lds + (bufoff) + ldsw + _i * 8192), 16, 0, 0); } while (0)
; #define PG8_LDA(dst, b, h) do { _Pragma("unroll") for (int m = 0; m < 4; ++m) _Pragma("unroll") for (int k = 0; k < 2; ++k) dst[m][k] = *(const LAS bf16x8*)(lds + PG8_SA(b, h) + aoff + m * 2048 + k * 1024); } while (0)
; #define PG8_LDB(dst, b, h) do { _Pragma("unroll") for (int n = 0; n < 2; ++n) _Pragma("unroll") for (int k = 0; k < 2; ++k) dst[n][k] = *(const LAS bf16x8*)(lds + PG8_SB(b, h) + boff + n * 2048 + k * 1024); } while (0)
; #define PG8_MMA(ai, bj, At, Bt) do { __builtin_amdgcn_s_setprio(1); _Pragma("unroll") for (int m = 0; m < 4; ++m) _Pragma("unroll") for (int n = 0; n < 2; ++n) _Pragma("unroll") for (int k = 0; k < 2; ++k) \
;         acc[ai][bj][m][n] = __builtin_amdgcn_mfma_f32_16x16x32_bf16(Bt[n][k], At[m][k], acc[ai][bj][m][n], 0, 0, 0); __builtin_amdgcn_s_setprio(0); } while (0)
; #define PG8_WAIT_V(n) asm volatile("s_waitcnt vmcnt(" #n ")" ::: "memory")
; #define PG8_WAIT_L(n) asm volatile("s_waitcnt lgkmcnt(" #n ")" ::: "memory")
; #define PG8_BAR __builtin_amdgcn_s_barrier()
; #define PG8_SCHED __builtin_amdgcn_sched_barrier(0)
; template <class Desc, class Epi>
; DI void gemm_phase(LAS unsigned char* lds, const Desc& D, const Epi& E, int wv) {
;     ...
;         for (int t = 0; t < nt; t += 2) {
;             const bool last = (t == nt - 2);
;             const char* a1 = cA + (size_t)(t + 1) * kstep;
;             const char* a2 = last ? nA : cA + (size_t)(t + 2) * kstep; const char* b2 = last ? nB : cB + (size_t)(t + 2) * kstep;
;             const char* a3 = a2 + kstep; const char* b3 = b2 + kstep;
;             PG8_LDB(B0, 0, 0); PG8_LDB(B1, 0, 1); PG8_SCHED; PG8_LDA(At, 0, 0); PG8_STAGE(PG8_SA(1, 1), a1 + hstepA, voffA);
;             PG8_WAIT_V(8); PG8_WAIT_L(0); PG8_BAR; PG8_MMA(0, 0, At, B0); PG8_MMA(0, 1, At, B1); PG8_BAR; PG8_SCHED;
;             PG8_LDA(At, 0, 1); PG8_STAGE(PG8_SB(0, 0), b2, voffB); PG8_STAGE(PG8_SB(0, 1), b2 + hstepB, voffB); PG8_STAGE(PG8_SA(0, 0), a2, voffA);
.LBB0_2706:
	ds_read_b128 v[128:131], v205
	ds_read_b128 v[132:135], v205 offset:1024
	ds_read_b128 v[136:139], v205 offset:2048
	ds_read_b128 v[140:143], v205 offset:3072
	ds_read_b128 v[144:147], v206
	ds_read_b128 v[148:151], v206 offset:1024
	ds_read_b128 v[152:155], v206 offset:2048
	ds_read_b128 v[156:159], v206 offset:3072
	s_add_u32 s34, s24, 0xfff80080
	s_addc_u32 s35, s25, -1
	s_cmp_eq_u32 s66, 28
	s_cselect_b32 s41, s15, s35
	s_cselect_b32 s40, s14, s34
	s_cselect_b32 s35, s17, s21
	s_cselect_b32 s34, s16, s19
	v_lshl_add_u64 v[212:213], s[24:25], 0, v[192:193]
	s_add_i32 m0, s30, 0xc000
	ds_read_b128 v[160:163], v207
	ds_read_b128 v[164:167], v207 offset:1024
	ds_read_b128 v[168:171], v207 offset:2048
	ds_read_b128 v[172:175], v207 offset:3072
	ds_read_b128 v[176:179], v207 offset:4096
	ds_read_b128 v[180:183], v207 offset:5120
	ds_read_b128 v[200:203], v207 offset:6144
	ds_read_b128 v[208:211], v207 offset:7168
	global_load_lds_dwordx4 v[212:213], off
	v_lshl_add_u64 v[212:213], s[24:25], 0, v[194:195]
	s_add_i32 m0, s30, 0xe000
	s_nop 0
	global_load_lds_dwordx4 v[212:213], off
	s_waitcnt vmcnt(8)
	s_waitcnt lgkmcnt(0)
	s_barrier
	s_setprio 1
	v_mfma_f32_16x16x32_bf16 v[124:127], v[128:131], v[160:163], v[124:127]
	v_mfma_f32_16x16x32_bf16 v[120:123], v[136:139], v[160:163], v[120:123]
	v_mfma_f32_16x16x32_bf16 v[112:115], v[128:131], v[168:171], v[112:115]
	v_mfma_f32_16x16x32_bf16 v[104:107], v[136:139], v[168:171], v[104:107]
	v_mfma_f32_16x16x32_bf16 v[96:99], v[128:131], v[176:179], v[96:99]
	v_mfma_f32_16x16x32_bf16 v[88:91], v[136:139], v[176:179], v[88:91]
	v_mfma_f32_16x16x32_bf16 v[80:83], v[128:131], v[200:203], v[80:83]
	v_mfma_f32_16x16x32_bf16 v[72:75], v[136:139], v[200:203], v[72:75]
	v_mfma_f32_16x16x32_bf16 v[124:127], v[132:135], v[164:167], v[124:127]
	v_mfma_f32_16x16x32_bf16 v[120:123], v[140:143], v[164:167], v[120:123]
	v_mfma_f32_16x16x32_bf16 v[112:115], v[132:135], v[172:175], v[112:115]
	v_mfma_f32_16x16x32_bf16 v[104:107], v[140:143], v[172:175], v[104:107]
	v_mfma_f32_16x16x32_bf16 v[96:99], v[132:135], v[180:183], v[96:99]
	v_mfma_f32_16x16x32_bf16 v[88:91], v[140:143], v[180:183], v[88:91]
	v_mfma_f32_16x16x32_bf16 v[80:83], v[132:135], v[208:211], v[80:83]
	v_mfma_f32_16x16x32_bf16 v[72:75], v[140:143], v[208:211], v[72:75]
	v_mfma_f32_16x16x32_bf16 v[116:119], v[144:147], v[160:163], v[116:119]
	v_mfma_f32_16x16x32_bf16 v[108:111], v[152:155], v[160:163], v[108:111]
	v_mfma_f32_16x16x32_bf16 v[100:103], v[144:147], v[168:171], v[100:103]
	v_mfma_f32_16x16x32_bf16 v[92:95], v[152:155], v[168:171], v[92:95]
	v_mfma_f32_16x16x32_bf16 v[84:87], v[144:147], v[176:179], v[84:87]
	v_mfma_f32_16x16x32_bf16 v[76:79], v[152:155], v[176:179], v[76:79]
	v_mfma_f32_16x16x32_bf16 v[68:71], v[144:147], v[200:203], v[68:71]
	v_mfma_f32_16x16x32_bf16 v[64:67], v[152:155], v[200:203], v[64:67]
	v_mfma_f32_16x16x32_bf16 v[116:119], v[148:151], v[164:167], v[116:119]
	v_mfma_f32_16x16x32_bf16 v[108:111], v[156:159], v[164:167], v[108:111]
	v_mfma_f32_16x16x32_bf16 v[100:103], v[148:151], v[172:175], v[100:103]
	v_mfma_f32_16x16x32_bf16 v[92:95], v[156:159], v[172:175], v[92:95]
	v_mfma_f32_16x16x32_bf16 v[84:87], v[148:151], v[180:183], v[84:87]
	v_mfma_f32_16x16x32_bf16 v[76:79], v[156:159], v[180:183], v[76:79]
	v_mfma_f32_16x16x32_bf16 v[68:71], v[148:151], v[208:211], v[68:71]
	v_mfma_f32_16x16x32_bf16 v[64:67], v[156:159], v[208:211], v[64:67]
	s_setprio 0
	s_barrier
	s_add_i32 s67, s52, s28
	v_lshl_add_u64 v[212:213], s[34:35], 0, v[188:189]
	s_mov_b32 m0, s67
	ds_read_b128 v[160:163], v207 offset:16384
	ds_read_b128 v[164:167], v207 offset:17408
	ds_read_b128 v[168:171], v207 offset:18432
	ds_read_b128 v[172:175], v207 offset:19456
	ds_read_b128 v[176:179], v207 offset:20480
	ds_read_b128 v[180:183], v207 offset:21504
	ds_read_b128 v[200:203], v207 offset:22528
	ds_read_b128 v[208:211], v207 offset:23552
	global_load_lds_dwordx4 v[212:213], off
	s_add_i32 m0, s67, 0x2000
	s_add_u32 s68, s34, 0x80000
	v_lshl_add_u64 v[214:215], s[34:35], 0, v[184:185]
	s_addc_u32 s69, s35, 0
	s_add_i32 s67, s53, s28
	global_load_lds_dwordx4 v[214:215], off
	v_lshl_add_u64 v[216:217], s[68:69], 0, v[188:189]
	s_mov_b32 m0, s67
	v_lshl_add_u64 v[218:219], s[40:41], 0, v[186:187]
	global_load_lds_dwordx4 v[216:217], off
	v_lshl_add_u64 v[216:217], s[68:69], 0, v[184:185]
	s_add_i32 m0, s67, 0x2000
	s_nop 0
	global_load_lds_dwordx4 v[216:217], off
	v_lshl_add_u64 v[216:217], s[40:41], 0, v[190:191]
	s_mov_b32 m0, s30
	s_nop 0
	global_load_lds_dwordx4 v[216:217], off
	s_mov_b32 m0, s31
	s_nop 0
	global_load_lds_dwordx4 v[218:219], off
	s_waitcnt vmcnt(8)
	s_waitcnt lgkmcnt(0)
	s_barrier
; #define PG8_STAGE(bufoff, gbase, voff) do { _Pragma("unroll") for (int _i = 0; _i < 2; ++_i) \
;         __builtin_amdgcn_global_load_lds((const unsigned*)((const char*)(gbase) + (voff)[_i]), (LAS unsigned*)(lds + (bufoff) + ldsw + _i * 8192), 16, 0, 0); } while (0)
; #define PG8_LDA(dst, b, h) do { _Pragma("unroll") for (int m = 0; m < 4; ++m) _Pragma("unroll") for (int k = 0; k < 2; ++k) dst[m][k] = *(const LAS bf16x8*)(lds + PG8_SA(b, h) + aoff + m * 2048 + k * 1024); } while (0)
; #define PG8_LDB(dst, b, h) do { _Pragma("unroll") for (int n = 0; n < 2; ++n) _Pragma("unroll") for (int k = 0; k < 2; ++k) dst[n][k] = *(const LAS bf16x8*)(lds + PG8_SB(b, h) + boff + n * 2048 + k * 1024); } while (0)
; #define PG8_MMA(ai, bj, At, Bt) do { __builtin_amdgcn_s_setprio(1); _Pragma("unroll") for (int m = 0; m < 4; ++m) _Pragma("unroll") for (int n = 0; n < 2; ++n) _Pragma("unroll") for (int k = 0; k < 2; ++k) \
;         acc[ai][bj][m][n] = __builtin_amdgcn_mfma_f32_16x16x32_bf16(Bt[n][k], At[m][k], acc[ai][bj][m][n], 0, 0, 0); __builtin_amdgcn_s_setprio(0); } while (0)
; #define PG8_WAIT_V(n) asm volatile("s_waitcnt vmcnt(" #n ")" ::: "memory")
; #define PG8_WAIT_L(n) asm volatile("s_waitcnt lgkmcnt(" #n ")" ::: "memory")
; #define PG8_BAR __builtin_amdgcn_s_barrier()
; #define PG8_SCHED __builtin_amdgcn_sched_barrier(0)
; template <class Desc, class Epi>
; DI void gemm_phase(LAS unsigned char* lds, const Desc& D, const Epi& E, int wv) {
;     ...
;             PG8_WAIT_V(8); PG8_WAIT_L(0); PG8_BAR; PG8_MMA(1, 0, At, B0); PG8_MMA(1, 1, At, B1); PG8_BAR; PG8_SCHED;
;             PG8_LDB(B0, 1, 0); PG8_LDB(B1, 1, 1); PG8_SCHED; PG8_LDA(At, 1, 0); PG8_STAGE(PG8_SA(0, 1), a2 + hstepA, voffA);
;             PG8_WAIT_V(8); PG8_WAIT_L(0); PG8_BAR; PG8_MMA(0, 0, At, B0); PG8_MMA(0, 1, At, B1); PG8_BAR; PG8_SCHED;
	s_setprio 1
	v_mfma_f32_16x16x32_bf16 v[60:63], v[128:131], v[160:163], v[60:63]
	v_mfma_f32_16x16x32_bf16 v[56:59], v[136:139], v[160:163], v[56:59]
	v_mfma_f32_16x16x32_bf16 v[48:51], v[128:131], v[168:171], v[48:51]
	v_mfma_f32_16x16x32_bf16 v[40:43], v[136:139], v[168:171], v[40:43]
	v_mfma_f32_16x16x32_bf16 v[32:35], v[128:131], v[176:179], v[32:35]
	v_mfma_f32_16x16x32_bf16 v[24:27], v[136:139], v[176:179], v[24:27]
	v_mfma_f32_16x16x32_bf16 v[16:19], v[128:131], v[200:203], v[16:19]
	v_mfma_f32_16x16x32_bf16 v[8:11], v[136:139], v[200:203], v[8:11]
	v_mfma_f32_16x16x32_bf16 v[60:63], v[132:135], v[164:167], v[60:63]
	v_mfma_f32_16x16x32_bf16 v[56:59], v[140:143], v[164:167], v[56:59]
	v_mfma_f32_16x16x32_bf16 v[48:51], v[132:135], v[172:175], v[48:51]
	v_mfma_f32_16x16x32_bf16 v[40:43], v[140:143], v[172:175], v[40:43]
	v_mfma_f32_16x16x32_bf16 v[32:35], v[132:135], v[180:183], v[32:35]
	v_mfma_f32_16x16x32_bf16 v[24:27], v[140:143], v[180:183], v[24:27]
	v_mfma_f32_16x16x32_bf16 v[16:19], v[132:135], v[208:211], v[16:19]
	v_mfma_f32_16x16x32_bf16 v[8:11], v[140:143], v[208:211], v[8:11]
	v_mfma_f32_16x16x32_bf16 v[52:55], v[144:147], v[160:163], v[52:55]
	v_mfma_f32_16x16x32_bf16 v[44:47], v[152:155], v[160:163], v[44:47]
	v_mfma_f32_16x16x32_bf16 v[36:39], v[144:147], v[168:171], v[36:39]
	v_mfma_f32_16x16x32_bf16 v[28:31], v[152:155], v[168:171], v[28:31]
	v_mfma_f32_16x16x32_bf16 v[20:23], v[144:147], v[176:179], v[20:23]
	v_mfma_f32_16x16x32_bf16 v[12:15], v[152:155], v[176:179], v[12:15]
	v_mfma_f32_16x16x32_bf16 v[4:7], v[144:147], v[200:203], v[4:7]
	v_mfma_f32_16x16x32_bf16 v[0:3], v[152:155], v[200:203], v[0:3]
	v_mfma_f32_16x16x32_bf16 v[52:55], v[148:151], v[164:167], v[52:55]
	v_mfma_f32_16x16x32_bf16 v[44:47], v[156:159], v[164:167], v[44:47]
	v_mfma_f32_16x16x32_bf16 v[36:39], v[148:151], v[172:175], v[36:39]
	v_mfma_f32_16x16x32_bf16 v[28:31], v[156:159], v[172:175], v[28:31]
	v_mfma_f32_16x16x32_bf16 v[20:23], v[148:151], v[180:183], v[20:23]
	v_mfma_f32_16x16x32_bf16 v[12:15], v[156:159], v[180:183], v[12:15]
	v_mfma_f32_16x16x32_bf16 v[4:7], v[148:151], v[208:211], v[4:7]
	v_mfma_f32_16x16x32_bf16 v[0:3], v[156:159], v[208:211], v[0:3]
	s_setprio 0
	s_barrier
	s_add_i32 s67, 0, 0x18000
	s_add_i32 s68, 0, 0x1c000
	v_add_u32_e32 v140, s67, v204
	v_add_u32_e32 v156, s68, v204
	ds_read_b128 v[128:131], v140
	ds_read_b128 v[132:135], v140 offset:1024
	ds_read_b128 v[136:139], v140 offset:2048
	ds_read_b128 v[140:143], v140 offset:3072
	ds_read_b128 v[144:147], v156
	ds_read_b128 v[148:151], v156 offset:1024
	ds_read_b128 v[152:155], v156 offset:2048
	ds_read_b128 v[156:159], v156 offset:3072
	s_add_u32 s40, s40, 0x80000
	s_addc_u32 s41, s41, 0
	s_mov_b32 m0, s42
	v_lshl_add_u64 v[220:221], s[40:41], 0, v[190:191]
	ds_read_b128 v[160:163], v207 offset:32768
	ds_read_b128 v[164:167], v207 offset:33792
	ds_read_b128 v[168:171], v207 offset:34816
	ds_read_b128 v[172:175], v207 offset:35840
	ds_read_b128 v[176:179], v207 offset:36864
	ds_read_b128 v[180:183], v207 offset:37888
	ds_read_b128 v[200:203], v207 offset:38912
	ds_read_b128 v[208:211], v207 offset:39936
	global_load_lds_dwordx4 v[220:221], off
	v_lshl_add_u64 v[220:221], s[40:41], 0, v[186:187]
	s_mov_b32 m0, s43
	s_nop 0
	global_load_lds_dwordx4 v[220:221], off
	s_waitcnt vmcnt(8)
	s_waitcnt lgkmcnt(0)
	s_barrier
	s_setprio 1
	v_mfma_f32_16x16x32_bf16 v[124:127], v[128:131], v[160:163], v[124:127]
	v_mfma_f32_16x16x32_bf16 v[120:123], v[136:139], v[160:163], v[120:123]
	v_mfma_f32_16x16x32_bf16 v[112:115], v[128:131], v[168:171], v[112:115]
	v_mfma_f32_16x16x32_bf16 v[104:107], v[136:139], v[168:171], v[104:107]
	v_mfma_f32_16x16x32_bf16 v[96:99], v[128:131], v[176:179], v[96:99]
	v_mfma_f32_16x16x32_bf16 v[88:91], v[136:139], v[176:179], v[88:91]
	v_mfma_f32_16x16x32_bf16 v[80:83], v[128:131], v[200:203], v[80:83]
	v_mfma_f32_16x16x32_bf16 v[72:75], v[136:139], v[200:203], v[72:75]
	v_mfma_f32_16x16x32_bf16 v[124:127], v[132:135], v[164:167], v[124:127]
	v_mfma_f32_16x16x32_bf16 v[120:123], v[140:143], v[164:167], v[120:123]
	v_mfma_f32_16x16x32_bf16 v[112:115], v[132:135], v[172:175], v[112:115]
	v_mfma_f32_16x16x32_bf16 v[104:107], v[140:143], v[172:175], v[104:107]
	v_mfma_f32_16x16x32_bf16 v[96:99], v[132:135], v[180:183], v[96:99]
	v_mfma_f32_16x16x32_bf16 v[88:91], v[140:143], v[180:183], v[88:91]
	v_mfma_f32_16x16x32_bf16 v[80:83], v[132:135], v[208:211], v[80:83]
	v_mfma_f32_16x16x32_bf16 v[72:75], v[140:143], v[208:211], v[72:75]
	v_mfma_f32_16x16x32_bf16 v[116:119], v[144:147], v[160:163], v[116:119]
	v_mfma_f32_16x16x32_bf16 v[108:111], v[152:155], v[160:163], v[108:111]
	v_mfma_f32_16x16x32_bf16 v[100:103], v[144:147], v[168:171], v[100:103]
	v_mfma_f32_16x16x32_bf16 v[92:95], v[152:155], v[168:171], v[92:95]
	v_mfma_f32_16x16x32_bf16 v[84:87], v[144:147], v[176:179], v[84:87]
	v_mfma_f32_16x16x32_bf16 v[76:79], v[152:155], v[176:179], v[76:79]
	v_mfma_f32_16x16x32_bf16 v[68:71], v[144:147], v[200:203], v[68:71]
	v_mfma_f32_16x16x32_bf16 v[64:67], v[152:155], v[200:203], v[64:67]
	v_mfma_f32_16x16x32_bf16 v[116:119], v[148:151], v[164:167], v[116:119]
	v_mfma_f32_16x16x32_bf16 v[108:111], v[156:159], v[164:167], v[108:111]
	v_mfma_f32_16x16x32_bf16 v[100:103], v[148:151], v[172:175], v[100:103]
	v_mfma_f32_16x16x32_bf16 v[92:95], v[156:159], v[172:175], v[92:95]
	v_mfma_f32_16x16x32_bf16 v[84:87], v[148:151], v[180:183], v[84:87]
	v_mfma_f32_16x16x32_bf16 v[76:79], v[156:159], v[180:183], v[76:79]
	v_mfma_f32_16x16x32_bf16 v[68:71], v[148:151], v[208:211], v[68:71]
	v_mfma_f32_16x16x32_bf16 v[64:67], v[156:159], v[208:211], v[64:67]
	s_setprio 0
	s_barrier
; #define PG8_STAGE(bufoff, gbase, voff) do { _Pragma("unroll") for (int _i = 0; _i < 2; ++_i) \
;         __builtin_amdgcn_global_load_lds((const unsigned*)((const char*)(gbase) + (voff)[_i]), (LAS unsigned*)(lds + (bufoff) + ldsw + _i * 8192), 16, 0, 0); } while (0)
; #define PG8_LDA(dst, b, h) do { _Pragma("unroll") for (int m = 0; m < 4; ++m) _Pragma("unroll") for (int k = 0; k < 2; ++k) dst[m][k] = *(const LAS bf16x8*)(lds + PG8_SA(b, h) + aoff + m * 2048 + k * 1024); } while (0)
; #define PG8_MMA(ai, bj, At, Bt) do { __builtin_amdgcn_s_setprio(1); _Pragma("unroll") for (int m = 0; m < 4; ++m) _Pragma("unroll") for (int n = 0; n < 2; ++n) _Pragma("unroll") for (int k = 0; k < 2; ++k) \
;         acc[ai][bj][m][n] = __builtin_amdgcn_mfma_f32_16x16x32_bf16(Bt[n][k], At[m][k], acc[ai][bj][m][n], 0, 0, 0); __builtin_amdgcn_s_setprio(0); } while (0)
; #define PG8_WAIT_V(n) asm volatile("s_waitcnt vmcnt(" #n ")" ::: "memory")
; #define PG8_WAIT_L(n) asm volatile("s_waitcnt lgkmcnt(" #n ")" ::: "memory")
; #define PG8_BAR __builtin_amdgcn_s_barrier()
; #define PG8_SCHED __builtin_amdgcn_sched_barrier(0)
; template <class Desc, class Epi>
; DI void gemm_phase(LAS unsigned char* lds, const Desc& D, const Epi& E, int wv) {
;     ...
;             PG8_LDA(At, 1, 1); PG8_STAGE(PG8_SB(1, 0), b3, voffB); PG8_STAGE(PG8_SB(1, 1), b3 + hstepB, voffB); PG8_STAGE(PG8_SA(1, 0), a3, voffA);
;             PG8_WAIT_V(8); PG8_WAIT_L(0); PG8_BAR; PG8_MMA(1, 0, At, B0); PG8_MMA(1, 1, At, B1); PG8_BAR; PG8_SCHED;
;         }
;         if (wr == 0) PG8_BAR;
	s_add_i32 s40, s67, s28
	v_lshl_add_u64 v[212:213], v[212:213], 0, s[6:7]
	s_mov_b32 m0, s40
	ds_read_b128 v[160:163], v207 offset:49152
	ds_read_b128 v[164:167], v207 offset:50176
	ds_read_b128 v[168:171], v207 offset:51200
	ds_read_b128 v[172:175], v207 offset:52224
	ds_read_b128 v[176:179], v207 offset:53248
	ds_read_b128 v[180:183], v207 offset:54272
	ds_read_b128 v[200:203], v207 offset:55296
	ds_read_b128 v[208:211], v207 offset:56320
	global_load_lds_dwordx4 v[212:213], off
	s_add_i32 m0, s40, 0x2000
	s_add_u32 s34, s34, 0x80080
	v_lshl_add_u64 v[212:213], v[214:215], 0, s[6:7]
	s_addc_u32 s35, s35, 0
	s_add_i32 s40, s68, s28
	global_load_lds_dwordx4 v[212:213], off
	v_lshl_add_u64 v[212:213], s[34:35], 0, v[188:189]
	s_mov_b32 m0, s40
	s_nop 0
	global_load_lds_dwordx4 v[212:213], off
	v_lshl_add_u64 v[212:213], s[34:35], 0, v[184:185]
	s_add_i32 m0, s40, 0x2000
	s_nop 0
	global_load_lds_dwordx4 v[212:213], off
	v_lshl_add_u64 v[212:213], v[216:217], 0, s[6:7]
	s_mov_b32 m0, s49
	s_nop 0
	global_load_lds_dwordx4 v[212:213], off
	v_lshl_add_u64 v[212:213], v[218:219], 0, s[6:7]
	s_mov_b32 m0, s50
	s_nop 0
	global_load_lds_dwordx4 v[212:213], off
	s_waitcnt vmcnt(8)
	s_waitcnt lgkmcnt(0)
	s_barrier
	s_setprio 1
	v_mfma_f32_16x16x32_bf16 v[60:63], v[128:131], v[160:163], v[60:63]
	v_mfma_f32_16x16x32_bf16 v[56:59], v[136:139], v[160:163], v[56:59]
	v_mfma_f32_16x16x32_bf16 v[48:51], v[128:131], v[168:171], v[48:51]
	v_mfma_f32_16x16x32_bf16 v[40:43], v[136:139], v[168:171], v[40:43]
	v_mfma_f32_16x16x32_bf16 v[32:35], v[128:131], v[176:179], v[32:35]
	v_mfma_f32_16x16x32_bf16 v[24:27], v[136:139], v[176:179], v[24:27]
	v_mfma_f32_16x16x32_bf16 v[16:19], v[128:131], v[200:203], v[16:19]
	v_mfma_f32_16x16x32_bf16 v[8:11], v[136:139], v[200:203], v[8:11]
	v_mfma_f32_16x16x32_bf16 v[60:63], v[132:135], v[164:167], v[60:63]
	v_mfma_f32_16x16x32_bf16 v[56:59], v[140:143], v[164:167], v[56:59]
	v_mfma_f32_16x16x32_bf16 v[48:51], v[132:135], v[172:175], v[48:51]
	v_mfma_f32_16x16x32_bf16 v[40:43], v[140:143], v[172:175], v[40:43]
	v_mfma_f32_16x16x32_bf16 v[32:35], v[132:135], v[180:183], v[32:35]
	v_mfma_f32_16x16x32_bf16 v[24:27], v[140:143], v[180:183], v[24:27]
	v_mfma_f32_16x16x32_bf16 v[16:19], v[132:135], v[208:211], v[16:19]
	v_mfma_f32_16x16x32_bf16 v[8:11], v[140:143], v[208:211], v[8:11]
	v_mfma_f32_16x16x32_bf16 v[52:55], v[144:147], v[160:163], v[52:55]
	v_mfma_f32_16x16x32_bf16 v[44:47], v[152:155], v[160:163], v[44:47]
	v_mfma_f32_16x16x32_bf16 v[36:39], v[144:147], v[168:171], v[36:39]
	v_mfma_f32_16x16x32_bf16 v[28:31], v[152:155], v[168:171], v[28:31]
	v_mfma_f32_16x16x32_bf16 v[20:23], v[144:147], v[176:179], v[20:23]
	v_mfma_f32_16x16x32_bf16 v[12:15], v[152:155], v[176:179], v[12:15]
	v_mfma_f32_16x16x32_bf16 v[4:7], v[144:147], v[200:203], v[4:7]
	v_mfma_f32_16x16x32_bf16 v[0:3], v[152:155], v[200:203], v[0:3]
	v_mfma_f32_16x16x32_bf16 v[52:55], v[148:151], v[164:167], v[52:55]
	v_mfma_f32_16x16x32_bf16 v[44:47], v[156:159], v[164:167], v[44:47]
	v_mfma_f32_16x16x32_bf16 v[36:39], v[148:151], v[172:175], v[36:39]
	v_mfma_f32_16x16x32_bf16 v[28:31], v[156:159], v[172:175], v[28:31]
	v_mfma_f32_16x16x32_bf16 v[20:23], v[148:151], v[180:183], v[20:23]
	v_mfma_f32_16x16x32_bf16 v[12:15], v[156:159], v[180:183], v[12:15]
	v_mfma_f32_16x16x32_bf16 v[4:7], v[148:151], v[208:211], v[4:7]
	v_mfma_f32_16x16x32_bf16 v[0:3], v[156:159], v[208:211], v[0:3]
	s_setprio 0
	s_barrier
	s_add_i32 s66, s66, 2
	s_add_u32 s24, s24, 0x100
	s_addc_u32 s25, s25, 0
	s_add_u32 s19, s19, 0x100
	s_addc_u32 s21, s21, 0
	s_cmp_gt_u32 s66, 29
	s_cbranch_scc0 .LBB0_2706
	s_and_b64 vcc, exec, s[8:9]
	s_cbranch_vccz .LBB0_2709
	s_barrier
